# GEMM mainloops: M0 write moved ahead of the VALU address add so the s_nop pad before each second LDS-DMA goes away (120 sites)
# speedup vs baseline: 1.0153x; 1.0068x over previous
; #define PG8_STAGE(bufoff, gbase, voff) do { _Pragma("unroll") for (int _i = 0; _i < 2; ++_i) \
;         __builtin_amdgcn_global_load_lds((const unsigned*)((const char*)(gbase) + (voff)[_i]), (LAS unsigned*)(lds + (bufoff) + ldsw + _i * 8192), 16, 0, 0); } while (0)
; #define PG8_LDA(dst, b, h) do { _Pragma("unroll") for (int m = 0; m < 4; ++m) _Pragma("unroll") for (int k = 0; k < 2; ++k) dst[m][k] = *(const LAS bf16x8*)(lds + PG8_SA(b, h) + aoff + m * 2048 + k * 1024); } while (0)
; #define PG8_LDB(dst, b, h) do { _Pragma("unroll") for (int n = 0; n < 2; ++n) _Pragma("unroll") for (int k = 0; k < 2; ++k) dst[n][k] = *(const LAS bf16x8*)(lds + PG8_SB(b, h) + boff + n * 2048 + k * 1024); } while (0)
; #define PG8_MMA(ai, bj, At, Bt) do { __builtin_amdgcn_s_setprio(1); _Pragma("unroll") for (int m = 0; m < 4; ++m) _Pragma("unroll") for (int n = 0; n < 2; ++n) _Pragma("unroll") for (int k = 0; k < 2; ++k) \
;         acc[ai][bj][m][n] = __builtin_amdgcn_mfma_f32_16x16x32_bf16(Bt[n][k], At[m][k], acc[ai][bj][m][n], 0, 0, 0); __builtin_amdgcn_s_setprio(0); } while (0)
; #define PG8_WAIT_V(n) asm volatile("s_waitcnt vmcnt(" #n ")" ::: "memory")
; #define PG8_WAIT_L(n) asm volatile("s_waitcnt lgkmcnt(" #n ")" ::: "memory")
; #define PG8_BAR __builtin_amdgcn_s_barrier()
; #define PG8_SCHED __builtin_amdgcn_sched_barrier(0)
; template <class Epi>
; DEVI void gemm_phase(LAS unsigned char* lds, const Gemm g, const Epi& E) {
;     ...
;             PG8_LDB(B0, 0, 0); PG8_SCHED; PG8_LDA(At, 0, 0); PG8_STAGE(PG8_SA(1, 1), a1 + hstepA, voffA);
;             PG8_WAIT_L(8); PG8_BAR; PG8_WAIT_L(0); PG8_MMA(0, 0, At, B0); PG8_BAR; PG8_SCHED;
;             PG8_LDB(B1, 0, 1); PG8_STAGE(PG8_SB(0, 0), b2, voffB);
;             PG8_BAR; PG8_WAIT_L(0); PG8_MMA(0, 1, At, B1); PG8_BAR;
;             PG8_LDA(At, 0, 1); PG8_STAGE(PG8_SA(0, 0), a2, voffA);
;             PG8_BAR; PG8_WAIT_L(0); PG8_MMA(1, 0, At, B0); PG8_BAR; PG8_SCHED;
;             PG8_STAGE(PG8_SB(0, 1), b2 + hstepB, voffB);
;             PG8_WAIT_V(6); PG8_BAR; PG8_MMA(1, 1, At, B1); PG8_BAR;
.LBB0_187:
	ds_read_b128 v[156:159], v150
	ds_read_b128 v[160:163], v150 offset:1024
	ds_read_b128 v[164:167], v150 offset:2048
	ds_read_b128 v[168:171], v150 offset:3072
	s_add_u32 s26, s0, 0xfffc0080
	s_addc_u32 s27, s1, -1
	s_cmp_eq_u32 s50, 12
	s_cselect_b32 s29, s13, s27
	s_cselect_b32 s28, s15, s26
	s_cselect_b32 s27, s19, s49
	s_cselect_b32 s26, s18, s17
	v_lshl_add_u64 v[204:205], s[0:1], 0, v[138:139]
	s_add_i32 m0, s38, 0xc000
	ds_read_b128 v[172:175], v151
	ds_read_b128 v[176:179], v151 offset:1024
	ds_read_b128 v[180:183], v151 offset:2048
	ds_read_b128 v[184:187], v151 offset:3072
	ds_read_b128 v[188:191], v151 offset:4096
	ds_read_b128 v[192:195], v151 offset:5120
	ds_read_b128 v[196:199], v151 offset:6144
	ds_read_b128 v[200:203], v151 offset:7168
	global_load_lds_dwordx4 v[204:205], off
	s_add_i32 m0, s38, 0xe000
	v_lshl_add_u64 v[204:205], s[0:1], 0, v[140:141]
	global_load_lds_dwordx4 v[204:205], off
	s_waitcnt lgkmcnt(8)
	s_barrier
	s_waitcnt lgkmcnt(0)
	v_mfma_f32_16x16x32_bf16 v[124:127], v[156:159], v[172:175], v[124:127]
	v_mfma_f32_16x16x32_bf16 v[120:123], v[164:167], v[172:175], v[120:123]
	v_mfma_f32_16x16x32_bf16 v[116:119], v[156:159], v[180:183], v[116:119]
	v_mfma_f32_16x16x32_bf16 v[108:111], v[164:167], v[180:183], v[108:111]
	v_mfma_f32_16x16x32_bf16 v[100:103], v[156:159], v[188:191], v[100:103]
	v_mfma_f32_16x16x32_bf16 v[96:99], v[164:167], v[188:191], v[96:99]
	v_mfma_f32_16x16x32_bf16 v[84:87], v[156:159], v[196:199], v[84:87]
	v_mfma_f32_16x16x32_bf16 v[80:83], v[164:167], v[196:199], v[80:83]
	v_mfma_f32_16x16x32_bf16 v[124:127], v[160:163], v[176:179], v[124:127]
	v_mfma_f32_16x16x32_bf16 v[120:123], v[168:171], v[176:179], v[120:123]
	v_mfma_f32_16x16x32_bf16 v[116:119], v[160:163], v[184:187], v[116:119]
	v_mfma_f32_16x16x32_bf16 v[108:111], v[168:171], v[184:187], v[108:111]
	v_mfma_f32_16x16x32_bf16 v[100:103], v[160:163], v[192:195], v[100:103]
	v_mfma_f32_16x16x32_bf16 v[96:99], v[168:171], v[192:195], v[96:99]
	v_mfma_f32_16x16x32_bf16 v[84:87], v[160:163], v[200:203], v[84:87]
	v_mfma_f32_16x16x32_bf16 v[80:83], v[168:171], v[200:203], v[80:83]
	s_barrier
	s_add_i32 s51, s46, s35
	v_lshl_add_u64 v[220:221], s[26:27], 0, v[130:131]
	s_mov_b32 m0, s51
	ds_read_b128 v[204:207], v152
	ds_read_b128 v[208:211], v152 offset:1024
	ds_read_b128 v[212:215], v152 offset:2048
	ds_read_b128 v[216:219], v152 offset:3072
	global_load_lds_dwordx4 v[220:221], off
	s_add_i32 m0, s51, 0x2000
	v_lshl_add_u64 v[222:223], s[26:27], 0, v[134:135]
	global_load_lds_dwordx4 v[222:223], off
	s_barrier
	s_waitcnt lgkmcnt(0)
	v_mfma_f32_16x16x32_bf16 v[112:115], v[204:207], v[172:175], v[112:115]
	v_mfma_f32_16x16x32_bf16 v[104:107], v[212:215], v[172:175], v[104:107]
	v_mfma_f32_16x16x32_bf16 v[92:95], v[204:207], v[180:183], v[92:95]
	v_mfma_f32_16x16x32_bf16 v[88:91], v[212:215], v[180:183], v[88:91]
	v_mfma_f32_16x16x32_bf16 v[76:79], v[204:207], v[188:191], v[76:79]
	v_mfma_f32_16x16x32_bf16 v[72:75], v[212:215], v[188:191], v[72:75]
	v_mfma_f32_16x16x32_bf16 v[68:71], v[204:207], v[196:199], v[68:71]
	v_mfma_f32_16x16x32_bf16 v[64:67], v[212:215], v[196:199], v[64:67]
	v_mfma_f32_16x16x32_bf16 v[112:115], v[208:211], v[176:179], v[112:115]
	v_mfma_f32_16x16x32_bf16 v[104:107], v[216:219], v[176:179], v[104:107]
	v_mfma_f32_16x16x32_bf16 v[92:95], v[208:211], v[184:187], v[92:95]
	v_mfma_f32_16x16x32_bf16 v[88:91], v[216:219], v[184:187], v[88:91]
	v_mfma_f32_16x16x32_bf16 v[76:79], v[208:211], v[192:195], v[76:79]
	v_mfma_f32_16x16x32_bf16 v[72:75], v[216:219], v[192:195], v[72:75]
	v_mfma_f32_16x16x32_bf16 v[68:71], v[208:211], v[200:203], v[68:71]
	v_mfma_f32_16x16x32_bf16 v[64:67], v[216:219], v[200:203], v[64:67]
	s_mov_b32 m0, s38
	v_lshl_add_u64 v[224:225], s[28:29], 0, v[128:129]
	s_barrier
	ds_read_b128 v[172:175], v151 offset:16384
	ds_read_b128 v[176:179], v151 offset:17408
	ds_read_b128 v[180:183], v151 offset:18432
	ds_read_b128 v[184:187], v151 offset:19456
	ds_read_b128 v[188:191], v151 offset:20480
	ds_read_b128 v[192:195], v151 offset:21504
	ds_read_b128 v[196:199], v151 offset:22528
	ds_read_b128 v[200:203], v151 offset:23552
	global_load_lds_dwordx4 v[224:225], off
	s_mov_b32 m0, s39
	v_lshl_add_u64 v[226:227], s[28:29], 0, v[132:133]
	global_load_lds_dwordx4 v[226:227], off
	s_barrier
	s_waitcnt lgkmcnt(0)
	v_mfma_f32_16x16x32_bf16 v[60:63], v[156:159], v[172:175], v[60:63]
	v_mfma_f32_16x16x32_bf16 v[56:59], v[164:167], v[172:175], v[56:59]
	v_mfma_f32_16x16x32_bf16 v[52:55], v[156:159], v[180:183], v[52:55]
	v_mfma_f32_16x16x32_bf16 v[48:51], v[164:167], v[180:183], v[48:51]
	v_mfma_f32_16x16x32_bf16 v[36:39], v[156:159], v[188:191], v[36:39]
	v_mfma_f32_16x16x32_bf16 v[32:35], v[164:167], v[188:191], v[32:35]
	v_mfma_f32_16x16x32_bf16 v[20:23], v[156:159], v[196:199], v[20:23]
	v_mfma_f32_16x16x32_bf16 v[16:19], v[164:167], v[196:199], v[16:19]
	v_mfma_f32_16x16x32_bf16 v[60:63], v[160:163], v[176:179], v[60:63]
	v_mfma_f32_16x16x32_bf16 v[56:59], v[168:171], v[176:179], v[56:59]
	v_mfma_f32_16x16x32_bf16 v[52:55], v[160:163], v[184:187], v[52:55]
	v_mfma_f32_16x16x32_bf16 v[48:51], v[168:171], v[184:187], v[48:51]
	v_mfma_f32_16x16x32_bf16 v[36:39], v[160:163], v[192:195], v[36:39]
	v_mfma_f32_16x16x32_bf16 v[32:35], v[168:171], v[192:195], v[32:35]
	v_mfma_f32_16x16x32_bf16 v[20:23], v[160:163], v[200:203], v[20:23]
	v_mfma_f32_16x16x32_bf16 v[16:19], v[168:171], v[200:203], v[16:19]
	s_barrier
	s_add_u32 s52, s26, 0x40000
	s_addc_u32 s53, s27, 0
	s_add_i32 s51, s47, s35
	s_mov_b32 m0, s51
	v_lshl_add_u64 v[156:157], s[52:53], 0, v[130:131]
	global_load_lds_dwordx4 v[156:157], off
	s_add_i32 m0, s51, 0x2000
	v_lshl_add_u64 v[156:157], s[52:53], 0, v[134:135]
	global_load_lds_dwordx4 v[156:157], off
	s_waitcnt vmcnt(6)
	s_barrier
; #define PG8_STAGE(bufoff, gbase, voff) do { _Pragma("unroll") for (int _i = 0; _i < 2; ++_i) \
;         __builtin_amdgcn_global_load_lds((const unsigned*)((const char*)(gbase) + (voff)[_i]), (LAS unsigned*)(lds + (bufoff) + ldsw + _i * 8192), 16, 0, 0); } while (0)
; #define PG8_LDA(dst, b, h) do { _Pragma("unroll") for (int m = 0; m < 4; ++m) _Pragma("unroll") for (int k = 0; k < 2; ++k) dst[m][k] = *(const LAS bf16x8*)(lds + PG8_SA(b, h) + aoff + m * 2048 + k * 1024); } while (0)
; #define PG8_LDB(dst, b, h) do { _Pragma("unroll") for (int n = 0; n < 2; ++n) _Pragma("unroll") for (int k = 0; k < 2; ++k) dst[n][k] = *(const LAS bf16x8*)(lds + PG8_SB(b, h) + boff + n * 2048 + k * 1024); } while (0)
; #define PG8_MMA(ai, bj, At, Bt) do { __builtin_amdgcn_s_setprio(1); _Pragma("unroll") for (int m = 0; m < 4; ++m) _Pragma("unroll") for (int n = 0; n < 2; ++n) _Pragma("unroll") for (int k = 0; k < 2; ++k) \
;         acc[ai][bj][m][n] = __builtin_amdgcn_mfma_f32_16x16x32_bf16(Bt[n][k], At[m][k], acc[ai][bj][m][n], 0, 0, 0); __builtin_amdgcn_s_setprio(0); } while (0)
; #define PG8_WAIT_V(n) asm volatile("s_waitcnt vmcnt(" #n ")" ::: "memory")
; #define PG8_WAIT_L(n) asm volatile("s_waitcnt lgkmcnt(" #n ")" ::: "memory")
; #define PG8_BAR __builtin_amdgcn_s_barrier()
; #define PG8_SCHED __builtin_amdgcn_sched_barrier(0)
; template <class Epi>
; DEVI void gemm_phase(LAS unsigned char* lds, const Gemm g, const Epi& E) {
;     ...
;             PG8_WAIT_V(6); PG8_BAR; PG8_MMA(1, 1, At, B1); PG8_BAR;
;             PG8_LDB(B0, 1, 0); PG8_SCHED; PG8_LDA(At, 1, 0); PG8_STAGE(PG8_SA(0, 1), a2 + hstepA, voffA);
;             PG8_WAIT_L(8); PG8_BAR; PG8_WAIT_L(0); PG8_MMA(0, 0, At, B0); PG8_BAR; PG8_SCHED;
;             PG8_LDB(B1, 1, 1); PG8_STAGE(PG8_SB(1, 0), b3, voffB);
;             PG8_BAR; PG8_WAIT_L(0); PG8_MMA(0, 1, At, B1); PG8_BAR;
;             PG8_LDA(At, 1, 1); PG8_STAGE(PG8_SA(1, 0), a3, voffA);
;             PG8_BAR; PG8_WAIT_L(0); PG8_MMA(1, 0, At, B0); PG8_BAR; PG8_SCHED;
	v_mfma_f32_16x16x32_bf16 v[44:47], v[204:207], v[172:175], v[44:47]
	v_mfma_f32_16x16x32_bf16 v[40:43], v[212:215], v[172:175], v[40:43]
	v_mfma_f32_16x16x32_bf16 v[28:31], v[204:207], v[180:183], v[28:31]
	v_mfma_f32_16x16x32_bf16 v[24:27], v[212:215], v[180:183], v[24:27]
	v_mfma_f32_16x16x32_bf16 v[12:15], v[204:207], v[188:191], v[12:15]
	v_mfma_f32_16x16x32_bf16 v[8:11], v[212:215], v[188:191], v[8:11]
	v_mfma_f32_16x16x32_bf16 v[4:7], v[204:207], v[196:199], v[4:7]
	v_mfma_f32_16x16x32_bf16 v[0:3], v[212:215], v[196:199], v[0:3]
	v_mfma_f32_16x16x32_bf16 v[44:47], v[208:211], v[176:179], v[44:47]
	v_mfma_f32_16x16x32_bf16 v[40:43], v[216:219], v[176:179], v[40:43]
	v_mfma_f32_16x16x32_bf16 v[28:31], v[208:211], v[184:187], v[28:31]
	v_mfma_f32_16x16x32_bf16 v[24:27], v[216:219], v[184:187], v[24:27]
	v_mfma_f32_16x16x32_bf16 v[12:15], v[208:211], v[192:195], v[12:15]
	v_mfma_f32_16x16x32_bf16 v[8:11], v[216:219], v[192:195], v[8:11]
	v_mfma_f32_16x16x32_bf16 v[4:7], v[208:211], v[200:203], v[4:7]
	v_mfma_f32_16x16x32_bf16 v[0:3], v[216:219], v[200:203], v[0:3]
	s_add_i32 s51, 0, 0x18000
	v_add_u32_e32 v136, s51, v148
	s_barrier
	ds_read_b128 v[156:159], v136
	ds_read_b128 v[160:163], v136 offset:1024
	ds_read_b128 v[164:167], v136 offset:2048
	ds_read_b128 v[168:171], v136 offset:3072
	s_add_u32 s28, s28, 0x40000
	s_addc_u32 s29, s29, 0
	s_mov_b32 m0, s40
	v_lshl_add_u64 v[204:205], s[28:29], 0, v[128:129]
	ds_read_b128 v[172:175], v151 offset:32768
	ds_read_b128 v[176:179], v151 offset:33792
	ds_read_b128 v[180:183], v151 offset:34816
	ds_read_b128 v[184:187], v151 offset:35840
	ds_read_b128 v[188:191], v151 offset:36864
	ds_read_b128 v[192:195], v151 offset:37888
	ds_read_b128 v[196:199], v151 offset:38912
	ds_read_b128 v[200:203], v151 offset:39936
	global_load_lds_dwordx4 v[204:205], off
	s_mov_b32 m0, s41
	v_lshl_add_u64 v[204:205], s[28:29], 0, v[132:133]
	global_load_lds_dwordx4 v[204:205], off
	s_waitcnt lgkmcnt(8)
	s_barrier
	s_waitcnt lgkmcnt(0)
	v_mfma_f32_16x16x32_bf16 v[124:127], v[156:159], v[172:175], v[124:127]
	v_mfma_f32_16x16x32_bf16 v[120:123], v[164:167], v[172:175], v[120:123]
	v_mfma_f32_16x16x32_bf16 v[116:119], v[156:159], v[180:183], v[116:119]
	v_mfma_f32_16x16x32_bf16 v[108:111], v[164:167], v[180:183], v[108:111]
	v_mfma_f32_16x16x32_bf16 v[100:103], v[156:159], v[188:191], v[100:103]
	v_mfma_f32_16x16x32_bf16 v[96:99], v[164:167], v[188:191], v[96:99]
	v_mfma_f32_16x16x32_bf16 v[84:87], v[156:159], v[196:199], v[84:87]
	v_mfma_f32_16x16x32_bf16 v[80:83], v[164:167], v[196:199], v[80:83]
	v_mfma_f32_16x16x32_bf16 v[124:127], v[160:163], v[176:179], v[124:127]
	v_mfma_f32_16x16x32_bf16 v[120:123], v[168:171], v[176:179], v[120:123]
	v_mfma_f32_16x16x32_bf16 v[116:119], v[160:163], v[184:187], v[116:119]
	v_mfma_f32_16x16x32_bf16 v[108:111], v[168:171], v[184:187], v[108:111]
	v_mfma_f32_16x16x32_bf16 v[100:103], v[160:163], v[192:195], v[100:103]
	v_mfma_f32_16x16x32_bf16 v[96:99], v[168:171], v[192:195], v[96:99]
	v_mfma_f32_16x16x32_bf16 v[84:87], v[160:163], v[200:203], v[84:87]
	v_mfma_f32_16x16x32_bf16 v[80:83], v[168:171], v[200:203], v[80:83]
	s_barrier
	s_add_i32 s28, 0, 0x1c000
	s_add_i32 s29, s51, s35
	v_add_u32_e32 v136, s28, v148
	v_lshl_add_u64 v[220:221], v[220:221], 0, s[8:9]
	s_mov_b32 m0, s29
	ds_read_b128 v[204:207], v136
	ds_read_b128 v[208:211], v136 offset:1024
	ds_read_b128 v[212:215], v136 offset:2048
	ds_read_b128 v[216:219], v136 offset:3072
	global_load_lds_dwordx4 v[220:221], off
	s_add_i32 m0, s29, 0x2000
	v_lshl_add_u64 v[220:221], v[222:223], 0, s[8:9]
	global_load_lds_dwordx4 v[220:221], off
	s_barrier
	s_waitcnt lgkmcnt(0)
	v_mfma_f32_16x16x32_bf16 v[112:115], v[204:207], v[172:175], v[112:115]
	v_mfma_f32_16x16x32_bf16 v[104:107], v[212:215], v[172:175], v[104:107]
	v_mfma_f32_16x16x32_bf16 v[92:95], v[204:207], v[180:183], v[92:95]
	v_mfma_f32_16x16x32_bf16 v[88:91], v[212:215], v[180:183], v[88:91]
	v_mfma_f32_16x16x32_bf16 v[76:79], v[204:207], v[188:191], v[76:79]
	v_mfma_f32_16x16x32_bf16 v[72:75], v[212:215], v[188:191], v[72:75]
	v_mfma_f32_16x16x32_bf16 v[68:71], v[204:207], v[196:199], v[68:71]
	v_mfma_f32_16x16x32_bf16 v[64:67], v[212:215], v[196:199], v[64:67]
	v_mfma_f32_16x16x32_bf16 v[112:115], v[208:211], v[176:179], v[112:115]
	v_mfma_f32_16x16x32_bf16 v[104:107], v[216:219], v[176:179], v[104:107]
	v_mfma_f32_16x16x32_bf16 v[92:95], v[208:211], v[184:187], v[92:95]
	v_mfma_f32_16x16x32_bf16 v[88:91], v[216:219], v[184:187], v[88:91]
	v_mfma_f32_16x16x32_bf16 v[76:79], v[208:211], v[192:195], v[76:79]
	v_mfma_f32_16x16x32_bf16 v[72:75], v[216:219], v[192:195], v[72:75]
	v_mfma_f32_16x16x32_bf16 v[68:71], v[208:211], v[200:203], v[68:71]
	v_mfma_f32_16x16x32_bf16 v[64:67], v[216:219], v[200:203], v[64:67]
	s_mov_b32 m0, s44
	v_lshl_add_u64 v[220:221], v[224:225], 0, s[8:9]
	s_barrier
	ds_read_b128 v[172:175], v151 offset:49152
	ds_read_b128 v[176:179], v151 offset:50176
	ds_read_b128 v[180:183], v151 offset:51200
	ds_read_b128 v[184:187], v151 offset:52224
	ds_read_b128 v[188:191], v151 offset:53248
	ds_read_b128 v[192:195], v151 offset:54272
	ds_read_b128 v[196:199], v151 offset:55296
	ds_read_b128 v[200:203], v151 offset:56320
	global_load_lds_dwordx4 v[220:221], off
	s_mov_b32 m0, s45
	v_lshl_add_u64 v[220:221], v[226:227], 0, s[8:9]
	global_load_lds_dwordx4 v[220:221], off
	s_barrier
; #define PG8_STAGE(bufoff, gbase, voff) do { _Pragma("unroll") for (int _i = 0; _i < 2; ++_i) \
;         __builtin_amdgcn_global_load_lds((const unsigned*)((const char*)(gbase) + (voff)[_i]), (LAS unsigned*)(lds + (bufoff) + ldsw + _i * 8192), 16, 0, 0); } while (0)
; #define PG8_MMA(ai, bj, At, Bt) do { __builtin_amdgcn_s_setprio(1); _Pragma("unroll") for (int m = 0; m < 4; ++m) _Pragma("unroll") for (int n = 0; n < 2; ++n) _Pragma("unroll") for (int k = 0; k < 2; ++k) \
;         acc[ai][bj][m][n] = __builtin_amdgcn_mfma_f32_16x16x32_bf16(Bt[n][k], At[m][k], acc[ai][bj][m][n], 0, 0, 0); __builtin_amdgcn_s_setprio(0); } while (0)
; #define PG8_WAIT_V(n) asm volatile("s_waitcnt vmcnt(" #n ")" ::: "memory")
; #define PG8_WAIT_L(n) asm volatile("s_waitcnt lgkmcnt(" #n ")" ::: "memory")
; #define PG8_BAR __builtin_amdgcn_s_barrier()
; #define PG8_SCHED __builtin_amdgcn_sched_barrier(0)
; template <class Epi>
; DEVI void gemm_phase(LAS unsigned char* lds, const Gemm g, const Epi& E) {
;     ...
;             PG8_BAR; PG8_WAIT_L(0); PG8_MMA(1, 0, At, B0); PG8_BAR; PG8_SCHED;
;             PG8_STAGE(PG8_SB(1, 1), b3 + hstepB, voffB);
;             PG8_WAIT_V(6); PG8_BAR; PG8_MMA(1, 1, At, B1); PG8_BAR;
;         }
	s_waitcnt lgkmcnt(0)
	v_mfma_f32_16x16x32_bf16 v[60:63], v[156:159], v[172:175], v[60:63]
	v_mfma_f32_16x16x32_bf16 v[56:59], v[164:167], v[172:175], v[56:59]
	v_mfma_f32_16x16x32_bf16 v[52:55], v[156:159], v[180:183], v[52:55]
	v_mfma_f32_16x16x32_bf16 v[48:51], v[164:167], v[180:183], v[48:51]
	v_mfma_f32_16x16x32_bf16 v[36:39], v[156:159], v[188:191], v[36:39]
	v_mfma_f32_16x16x32_bf16 v[32:35], v[164:167], v[188:191], v[32:35]
	v_mfma_f32_16x16x32_bf16 v[20:23], v[156:159], v[196:199], v[20:23]
	v_mfma_f32_16x16x32_bf16 v[16:19], v[164:167], v[196:199], v[16:19]
	v_mfma_f32_16x16x32_bf16 v[60:63], v[160:163], v[176:179], v[60:63]
	v_mfma_f32_16x16x32_bf16 v[56:59], v[168:171], v[176:179], v[56:59]
	v_mfma_f32_16x16x32_bf16 v[52:55], v[160:163], v[184:187], v[52:55]
	v_mfma_f32_16x16x32_bf16 v[48:51], v[168:171], v[184:187], v[48:51]
	v_mfma_f32_16x16x32_bf16 v[36:39], v[160:163], v[192:195], v[36:39]
	v_mfma_f32_16x16x32_bf16 v[32:35], v[168:171], v[192:195], v[32:35]
	v_mfma_f32_16x16x32_bf16 v[20:23], v[160:163], v[200:203], v[20:23]
	v_mfma_f32_16x16x32_bf16 v[16:19], v[168:171], v[200:203], v[16:19]
	s_barrier
	s_add_u32 s26, s26, 0x40080
	s_addc_u32 s27, s27, 0
	s_add_i32 s28, s28, s35
	s_mov_b32 m0, s28
	v_lshl_add_u64 v[156:157], s[26:27], 0, v[130:131]
	global_load_lds_dwordx4 v[156:157], off
	s_add_i32 m0, s28, 0x2000
	v_lshl_add_u64 v[156:157], s[26:27], 0, v[134:135]
	global_load_lds_dwordx4 v[156:157], off
	s_waitcnt vmcnt(6)
	s_barrier
	v_mfma_f32_16x16x32_bf16 v[44:47], v[204:207], v[172:175], v[44:47]
	v_mfma_f32_16x16x32_bf16 v[40:43], v[212:215], v[172:175], v[40:43]
	v_mfma_f32_16x16x32_bf16 v[28:31], v[204:207], v[180:183], v[28:31]
	v_mfma_f32_16x16x32_bf16 v[24:27], v[212:215], v[180:183], v[24:27]
	v_mfma_f32_16x16x32_bf16 v[12:15], v[204:207], v[188:191], v[12:15]
	v_mfma_f32_16x16x32_bf16 v[8:11], v[212:215], v[188:191], v[8:11]
	v_mfma_f32_16x16x32_bf16 v[4:7], v[204:207], v[196:199], v[4:7]
	v_mfma_f32_16x16x32_bf16 v[0:3], v[212:215], v[196:199], v[0:3]
	v_mfma_f32_16x16x32_bf16 v[44:47], v[208:211], v[176:179], v[44:47]
	v_mfma_f32_16x16x32_bf16 v[40:43], v[216:219], v[176:179], v[40:43]
	v_mfma_f32_16x16x32_bf16 v[28:31], v[208:211], v[184:187], v[28:31]
	v_mfma_f32_16x16x32_bf16 v[24:27], v[216:219], v[184:187], v[24:27]
	v_mfma_f32_16x16x32_bf16 v[12:15], v[208:211], v[192:195], v[12:15]
	v_mfma_f32_16x16x32_bf16 v[8:11], v[216:219], v[192:195], v[8:11]
	v_mfma_f32_16x16x32_bf16 v[4:7], v[208:211], v[200:203], v[4:7]
	v_mfma_f32_16x16x32_bf16 v[0:3], v[216:219], v[200:203], v[0:3]
	s_add_i32 s50, s50, 2
	s_add_u32 s0, s0, 0x100
	s_addc_u32 s1, s1, 0
	s_add_u32 s17, s17, 0x100
	s_addc_u32 s49, s49, 0
	s_cmp_gt_u32 s50, 13
	s_barrier
	s_cbranch_scc0 .LBB0_187
; #define PG8_WAIT_V(n) asm volatile("s_waitcnt vmcnt(" #n ")" ::: "memory")
; #define PG8_BAR __builtin_amdgcn_s_barrier()
; template <class Epi>
; DEVI void gemm_phase(LAS unsigned char* lds, const Gemm g, const Epi& E) {
;     ...
;                     for (int bj = 0; bj < 2; ++bj) {
;                         const int c = col0 + bj * HALF; f32x4 v0 = acc[ai][bj][m][0], v1 = acc[ai][bj][m][1];
;                         if constexpr (Epi::RS) { v0 = v0 * rs; v1 = v1 * rs; }
;                         if constexpr (Epi::PRE) part += E.frag_pre8(cur.b, r, c, v0, v1, pre[mm][bj][0], pre[mm][bj][1]);
;                         else if constexpr (Epi::PERM) E.frag8(cur.b, r, c, v0, v1);
;                         else { E.frag(cur.b, r, c, v0); E.frag(cur.b, r, c + 16, v1); }
;                     }
;     ...
;         if (!has_next) break;
; #pragma unroll
;         for (int a = 0; a < 2; ++a)
; #pragma unroll
;             for (int b = 0; b < 2; ++b)
; #pragma unroll
;                 for (int m = 0; m < 4; ++m)
; #pragma unroll
;                     for (int n = 0; n < 2; ++n) acc[a][b][m][n] = (f32x4){0.f, 0.f, 0.f, 0.f};
;         cur = nxt; cA = nA; cB = nB; ++ui;
;     }
;     PG8_WAIT_V(0);
;     if (wr == 0) PG8_BAR;
;     PG8_BAR;
	s_setprio 0
	v_lshl_add_u32 v156, s48, 8, v147
	v_ashrrev_i32_e32 v157, 31, v156
	v_readlane_b32 s2, v252, 39
	v_lshlrev_b64 v[158:159], 11, v[156:157]
	v_lshl_or_b32 v155, s11, 8, v149
	v_mov_b32_e32 v157, s2
	v_readlane_b32 s2, v252, 37
	s_ashr_i32 s11, s10, 31
	v_cmp_gt_i32_e32 vcc, s42, v155
	v_mov_b32_e32 v162, s2
	v_readlane_b32 s2, v252, 38
	s_lshl_b64 s[0:1], s[10:11], 21
	v_cndmask_b32_e32 v161, v157, v162, vcc
	v_mov_b32_e32 v163, s2
	v_readlane_b32 s2, v252, 36
	v_cvt_pk_bf16_f32 v124, v124, v125
	v_cvt_pk_bf16_f32 v125, v126, v127
	v_mov_b32_e32 v164, s2
	v_cndmask_b32_e32 v160, v163, v164, vcc
	v_cvt_pk_bf16_f32 v126, v120, v121
	v_lshl_add_u64 v[120:121], v[160:161], 0, s[0:1]
	v_and_b32_e32 v136, 0x378, v155
	v_cvt_pk_bf16_f32 v127, v122, v123
	v_lshl_add_u64 v[122:123], v[120:121], 0, v[158:159]
	v_lshlrev_b32_e32 v136, 1, v136
	v_lshl_add_u64 v[122:123], v[122:123], 0, v[136:137]
	global_store_dwordx4 v[122:123], v[124:127], off
	v_or_b32_e32 v122, 0x80, v155
	v_cmp_gt_i32_e32 vcc, s42, v122
	v_cvt_pk_bf16_f32 v112, v112, v113
	v_cvt_pk_bf16_f32 v113, v114, v115
	v_cndmask_b32_e32 v123, v157, v162, vcc
	v_cndmask_b32_e32 v122, v163, v164, vcc
	v_lshl_add_u64 v[122:123], v[122:123], 0, s[0:1]
	s_movk_i32 s0, 0x3f8
	v_cvt_pk_bf16_f32 v115, v106, v107
	v_bitop3_b32 v106, v155, s0, v153 bitop3:0xc8
	v_cvt_pk_bf16_f32 v114, v104, v105
	v_lshl_add_u64 v[104:105], v[122:123], 0, v[158:159]
	v_lshlrev_b32_e32 v124, 1, v106
	v_mov_b32_e32 v125, v137
	v_lshl_add_u64 v[104:105], v[104:105], 0, v[124:125]
	global_store_dwordx4 v[104:105], v[112:115], off
	v_or_b32_e32 v104, 16, v156
	v_ashrrev_i32_e32 v105, 31, v104
	v_lshlrev_b64 v[112:113], 11, v[104:105]
	v_cvt_pk_bf16_f32 v106, v108, v109
	v_lshl_add_u64 v[108:109], v[120:121], 0, v[112:113]
	v_cvt_pk_bf16_f32 v92, v92, v93
	v_cvt_pk_bf16_f32 v93, v94, v95
	v_cvt_pk_bf16_f32 v94, v88, v89
	v_lshl_add_u64 v[88:89], v[122:123], 0, v[112:113]
	v_cvt_pk_bf16_f32 v104, v116, v117
	v_cvt_pk_bf16_f32 v105, v118, v119
	v_cvt_pk_bf16_f32 v107, v110, v111
	v_lshl_add_u64 v[108:109], v[108:109], 0, v[136:137]
	v_cvt_pk_bf16_f32 v95, v90, v91
	v_lshl_add_u64 v[88:89], v[88:89], 0, v[124:125]
	global_store_dwordx4 v[108:109], v[104:107], off
	global_store_dwordx4 v[88:89], v[92:95], off
	v_or_b32_e32 v88, 32, v156
	v_ashrrev_i32_e32 v89, 31, v88
	v_lshlrev_b64 v[92:93], 11, v[88:89]
	v_lshl_add_u64 v[94:95], v[120:121], 0, v[92:93]
	v_cvt_pk_bf16_f32 v76, v76, v77
	v_cvt_pk_bf16_f32 v77, v78, v79
	v_cvt_pk_bf16_f32 v78, v72, v73
	v_lshl_add_u64 v[72:73], v[122:123], 0, v[92:93]
	v_cvt_pk_bf16_f32 v88, v100, v101
	v_cvt_pk_bf16_f32 v89, v102, v103
	v_cvt_pk_bf16_f32 v90, v96, v97
	v_cvt_pk_bf16_f32 v91, v98, v99
	v_lshl_add_u64 v[94:95], v[94:95], 0, v[136:137]
	v_cvt_pk_bf16_f32 v79, v74, v75
	v_lshl_add_u64 v[72:73], v[72:73], 0, v[124:125]
	global_store_dwordx4 v[94:95], v[88:91], off
	global_store_dwordx4 v[72:73], v[76:79], off
	v_or_b32_e32 v72, 48, v156
	v_ashrrev_i32_e32 v73, 31, v72
	v_lshlrev_b64 v[76:77], 11, v[72:73]
	v_lshl_add_u64 v[78:79], v[120:121], 0, v[76:77]
	v_cvt_pk_bf16_f32 v68, v68, v69
	v_cvt_pk_bf16_f32 v69, v70, v71
	v_cvt_pk_bf16_f32 v70, v64, v65
	v_lshl_add_u64 v[64:65], v[122:123], 0, v[76:77]
	v_cvt_pk_bf16_f32 v72, v84, v85
	v_cvt_pk_bf16_f32 v73, v86, v87
	v_cvt_pk_bf16_f32 v74, v80, v81
	v_cvt_pk_bf16_f32 v75, v82, v83
	v_lshl_add_u64 v[78:79], v[78:79], 0, v[136:137]
	v_cvt_pk_bf16_f32 v71, v66, v67
	v_lshl_add_u64 v[64:65], v[64:65], 0, v[124:125]
	s_mov_b64 s[0:1], 0x40000
	global_store_dwordx4 v[78:79], v[72:75], off
	global_store_dwordx4 v[64:65], v[68:71], off
	v_lshl_add_u64 v[64:65], v[158:159], 0, s[0:1]
	v_cvt_pk_bf16_f32 v60, v60, v61
	v_cvt_pk_bf16_f32 v61, v62, v63
	v_cvt_pk_bf16_f32 v62, v56, v57
	v_lshl_add_u64 v[56:57], v[120:121], 0, v[64:65]
	v_cvt_pk_bf16_f32 v44, v44, v45
	v_cvt_pk_bf16_f32 v45, v46, v47
	v_cvt_pk_bf16_f32 v46, v40, v41
	v_lshl_add_u64 v[40:41], v[122:123], 0, v[64:65]
	v_cvt_pk_bf16_f32 v63, v58, v59
	v_lshl_add_u64 v[56:57], v[56:57], 0, v[136:137]
	v_cvt_pk_bf16_f32 v47, v42, v43
	v_lshl_add_u64 v[40:41], v[40:41], 0, v[124:125]
	s_mov_b64 s[0:1], 0x48000
	global_store_dwordx4 v[56:57], v[60:63], off
	global_store_dwordx4 v[40:41], v[44:47], off
	v_cvt_pk_bf16_f32 v28, v28, v29
	v_cvt_pk_bf16_f32 v29, v30, v31
	v_lshl_add_u64 v[44:45], v[158:159], 0, s[0:1]
	v_lshl_add_u64 v[46:47], v[120:121], 0, v[44:45]
	v_cvt_pk_bf16_f32 v30, v24, v25
	v_lshl_add_u64 v[24:25], v[122:123], 0, v[44:45]
	v_cvt_pk_bf16_f32 v40, v52, v53
	v_cvt_pk_bf16_f32 v41, v54, v55
	v_cvt_pk_bf16_f32 v42, v48, v49
	v_cvt_pk_bf16_f32 v43, v50, v51
	v_lshl_add_u64 v[46:47], v[46:47], 0, v[136:137]
	v_cvt_pk_bf16_f32 v31, v26, v27
	v_lshl_add_u64 v[24:25], v[24:25], 0, v[124:125]
	s_mov_b64 s[0:1], 0x50000
	global_store_dwordx4 v[46:47], v[40:43], off
	global_store_dwordx4 v[24:25], v[28:31], off
	v_cvt_pk_bf16_f32 v12, v12, v13
	v_cvt_pk_bf16_f32 v13, v14, v15
	v_lshl_add_u64 v[28:29], v[158:159], 0, s[0:1]
	v_lshl_add_u64 v[30:31], v[120:121], 0, v[28:29]
	v_cvt_pk_bf16_f32 v14, v8, v9
	v_lshl_add_u64 v[8:9], v[122:123], 0, v[28:29]
	v_cvt_pk_bf16_f32 v24, v36, v37
	v_cvt_pk_bf16_f32 v25, v38, v39
	v_cvt_pk_bf16_f32 v26, v32, v33
	v_cvt_pk_bf16_f32 v27, v34, v35
	v_lshl_add_u64 v[30:31], v[30:31], 0, v[136:137]
	v_cvt_pk_bf16_f32 v15, v10, v11
	v_lshl_add_u64 v[8:9], v[8:9], 0, v[124:125]
	s_mov_b64 s[0:1], 0x58000
	global_store_dwordx4 v[30:31], v[24:27], off
	global_store_dwordx4 v[8:9], v[12:15], off
	v_cvt_pk_bf16_f32 v4, v4, v5
	v_cvt_pk_bf16_f32 v5, v6, v7
	v_lshl_add_u64 v[12:13], v[158:159], 0, s[0:1]
	v_lshl_add_u64 v[14:15], v[120:121], 0, v[12:13]
	v_cvt_pk_bf16_f32 v6, v0, v1
	v_lshl_add_u64 v[0:1], v[122:123], 0, v[12:13]
	v_cvt_pk_bf16_f32 v8, v20, v21
	v_cvt_pk_bf16_f32 v9, v22, v23
	v_cvt_pk_bf16_f32 v10, v16, v17
	v_cvt_pk_bf16_f32 v11, v18, v19
	v_lshl_add_u64 v[14:15], v[14:15], 0, v[136:137]
	v_cvt_pk_bf16_f32 v7, v2, v3
	v_lshl_add_u64 v[0:1], v[0:1], 0, v[124:125]
	s_and_b64 vcc, exec, s[4:5]
	s_mov_b32 s10, s12
	s_mov_b32 s11, s14
	s_mov_b32 s48, s16
	s_mov_b64 s[28:29], s[18:19]
	s_mov_b64 s[26:27], s[24:25]
	global_store_dwordx4 v[14:15], v[8:11], off
	global_store_dwordx4 v[0:1], v[4:7], off
	s_cbranch_vccz .LBB0_178
	s_waitcnt vmcnt(0)
	s_cmpk_gt_u32 s34, 0xff
	s_cbranch_scc1 .LBB0_191
	s_barrier

; #define PG8_STAGE(bufoff, gbase, voff) do { _Pragma("unroll") for (int _i = 0; _i < 2; ++_i) \
;         __builtin_amdgcn_global_load_lds((const unsigned*)((const char*)(gbase) + (voff)[_i]), (LAS unsigned*)(lds + (bufoff) + ldsw + _i * 8192), 16, 0, 0); } while (0)
; #define PG8_LDA(dst, b, h) do { _Pragma("unroll") for (int m = 0; m < 4; ++m) _Pragma("unroll") for (int k = 0; k < 2; ++k) dst[m][k] = *(const LAS bf16x8*)(lds + PG8_SA(b, h) + aoff + m * 2048 + k * 1024); } while (0)
; #define PG8_LDB(dst, b, h) do { _Pragma("unroll") for (int n = 0; n < 2; ++n) _Pragma("unroll") for (int k = 0; k < 2; ++k) dst[n][k] = *(const LAS bf16x8*)(lds + PG8_SB(b, h) + boff + n * 2048 + k * 1024); } while (0)
; #define PG8_MMA(ai, bj, At, Bt) do { __builtin_amdgcn_s_setprio(1); _Pragma("unroll") for (int m = 0; m < 4; ++m) _Pragma("unroll") for (int n = 0; n < 2; ++n) _Pragma("unroll") for (int k = 0; k < 2; ++k) \
;         acc[ai][bj][m][n] = __builtin_amdgcn_mfma_f32_16x16x32_bf16(Bt[n][k], At[m][k], acc[ai][bj][m][n], 0, 0, 0); __builtin_amdgcn_s_setprio(0); } while (0)
; #define PG8_WAIT_V(n) asm volatile("s_waitcnt vmcnt(" #n ")" ::: "memory")
; #define PG8_WAIT_L(n) asm volatile("s_waitcnt lgkmcnt(" #n ")" ::: "memory")
; #define PG8_BAR __builtin_amdgcn_s_barrier()
; #define PG8_SCHED __builtin_amdgcn_sched_barrier(0)
; template <class Epi>
; DEVI void gemm_phase(LAS unsigned char* lds, const Gemm g, const Epi& E) {
;     ...
;             PG8_LDB(B0, 0, 0); PG8_SCHED; PG8_LDA(At, 0, 0); PG8_STAGE(PG8_SA(1, 1), a1 + hstepA, voffA);
;             PG8_WAIT_L(8); PG8_BAR; PG8_WAIT_L(0); PG8_MMA(0, 0, At, B0); PG8_BAR; PG8_SCHED;
;             PG8_LDB(B1, 0, 1); PG8_STAGE(PG8_SB(0, 0), b2, voffB);
;             PG8_BAR; PG8_WAIT_L(0); PG8_MMA(0, 1, At, B1); PG8_BAR;
;             PG8_LDA(At, 0, 1); PG8_STAGE(PG8_SA(0, 0), a2, voffA);
;             PG8_BAR; PG8_WAIT_L(0); PG8_MMA(1, 0, At, B0); PG8_BAR; PG8_SCHED;
;             PG8_STAGE(PG8_SB(0, 1), b2 + hstepB, voffB);
;             PG8_WAIT_V(6); PG8_BAR; PG8_MMA(1, 1, At, B1); PG8_BAR;
.LBB0_276:
	s_add_u32 s19, s8, 0xfffc0080
	s_addc_u32 s26, s9, -1
	s_add_i32 s27, 0, 0x10000
	v_add_u32_e32 v8, s27, v214
	ds_read_b128 v[130:133], v8
	ds_read_b128 v[134:137], v8 offset:1024
	ds_read_b128 v[138:141], v8 offset:2048
	ds_read_b128 v[142:145], v8 offset:3072
	s_cmp_eq_u32 s18, 12
	s_cselect_b32 s69, s0, s26
	s_cselect_b32 s68, s1, s19
	s_cselect_b32 s47, s5, s15
	s_cselect_b32 s46, s7, s13
	v_lshl_add_u64 v[208:209], s[8:9], 0, v[184:185]
	s_add_i32 m0, s81, 0xc000
	ds_read_b128 v[146:149], v216
	ds_read_b128 v[150:153], v216 offset:1024
	ds_read_b128 v[188:191], v216 offset:2048
	ds_read_b128 v[192:195], v216 offset:3072
	ds_read_b128 v[196:199], v216 offset:4096
	ds_read_b128 v[200:203], v216 offset:5120
	ds_read_b128 v[204:207], v216 offset:6144
	ds_read_b128 v[218:221], v216 offset:7168
	global_load_lds_dwordx4 v[208:209], off
	s_add_i32 m0, s81, 0xe000
	v_lshl_add_u64 v[208:209], s[8:9], 0, v[186:187]
	global_load_lds_dwordx4 v[208:209], off
	s_waitcnt lgkmcnt(8)
	s_barrier
	s_waitcnt lgkmcnt(0)
	s_waitcnt lgkmcnt(0)
	s_cmp_lg_u32 s101, 0
	s_cbranch_scc1 .Lip13_a_0
	v_mfma_f32_16x16x32_bf16 v[126:129], v[130:133], v[146:149], v[126:129]
	v_mfma_f32_16x16x32_bf16 v[122:125], v[138:141], v[146:149], v[122:125]
	v_mfma_f32_16x16x32_bf16 v[114:117], v[130:133], v[188:191], v[114:117]
	v_mfma_f32_16x16x32_bf16 v[106:109], v[138:141], v[188:191], v[106:109]
	v_mfma_f32_16x16x32_bf16 v[94:97], v[130:133], v[196:199], v[94:97]
	v_mfma_f32_16x16x32_bf16 v[90:93], v[138:141], v[196:199], v[90:93]
	v_mfma_f32_16x16x32_bf16 v[82:85], v[130:133], v[204:207], v[82:85]
	v_mfma_f32_16x16x32_bf16 v[74:77], v[138:141], v[204:207], v[74:77]
	v_mfma_f32_16x16x32_bf16 v[126:129], v[134:137], v[150:153], v[126:129]
	v_mfma_f32_16x16x32_bf16 v[122:125], v[142:145], v[150:153], v[122:125]
	v_mfma_f32_16x16x32_bf16 v[114:117], v[134:137], v[192:195], v[114:117]
	v_mfma_f32_16x16x32_bf16 v[106:109], v[142:145], v[192:195], v[106:109]
	v_mfma_f32_16x16x32_bf16 v[94:97], v[134:137], v[200:203], v[94:97]
	v_mfma_f32_16x16x32_bf16 v[90:93], v[142:145], v[200:203], v[90:93]
	v_mfma_f32_16x16x32_bf16 v[82:85], v[134:137], v[218:221], v[82:85]
	v_mfma_f32_16x16x32_bf16 v[74:77], v[142:145], v[218:221], v[74:77]
.Lip13_a_0:
	s_barrier
	s_add_i32 s19, 0, 0x14000
	s_add_i32 s26, s27, s80
	v_add_u32_e32 v8, s19, v214
	v_lshl_add_u64 v[208:209], s[46:47], 0, v[178:179]
	s_mov_b32 m0, s26
	ds_read_b128 v[222:225], v8
	ds_read_b128 v[226:229], v8 offset:1024
	ds_read_b128 v[230:233], v8 offset:2048
	ds_read_b128 v[234:237], v8 offset:3072
	global_load_lds_dwordx4 v[208:209], off
	s_add_i32 m0, s26, 0x2000
	v_lshl_add_u64 v[238:239], s[46:47], 0, v[182:183]
	global_load_lds_dwordx4 v[238:239], off
	s_barrier
	s_waitcnt lgkmcnt(0)
	s_waitcnt lgkmcnt(0)
	s_cmp_lg_u32 s100, 0
	s_cbranch_scc1 .Lip13_a_1
	v_mfma_f32_16x16x32_bf16 v[118:121], v[222:225], v[146:149], v[118:121]
	v_mfma_f32_16x16x32_bf16 v[110:113], v[230:233], v[146:149], v[110:113]
	v_mfma_f32_16x16x32_bf16 v[102:105], v[222:225], v[188:191], v[102:105]
	v_mfma_f32_16x16x32_bf16 v[98:101], v[230:233], v[188:191], v[98:101]
	v_mfma_f32_16x16x32_bf16 v[86:89], v[222:225], v[196:199], v[86:89]
	v_mfma_f32_16x16x32_bf16 v[78:81], v[230:233], v[196:199], v[78:81]
	v_mfma_f32_16x16x32_bf16 v[62:65], v[222:225], v[204:207], v[62:65]
	v_mfma_f32_16x16x32_bf16 v[58:61], v[230:233], v[204:207], v[58:61]
	v_mfma_f32_16x16x32_bf16 v[118:121], v[226:229], v[150:153], v[118:121]
	v_mfma_f32_16x16x32_bf16 v[110:113], v[234:237], v[150:153], v[110:113]
	v_mfma_f32_16x16x32_bf16 v[102:105], v[226:229], v[192:195], v[102:105]
	v_mfma_f32_16x16x32_bf16 v[98:101], v[234:237], v[192:195], v[98:101]
	v_mfma_f32_16x16x32_bf16 v[86:89], v[226:229], v[200:203], v[86:89]
	v_mfma_f32_16x16x32_bf16 v[78:81], v[234:237], v[200:203], v[78:81]
	v_mfma_f32_16x16x32_bf16 v[62:65], v[226:229], v[218:221], v[62:65]
	v_mfma_f32_16x16x32_bf16 v[58:61], v[234:237], v[218:221], v[58:61]
.Lip13_a_1:
	s_mov_b32 m0, s81
	v_lshl_add_u64 v[240:241], s[68:69], 0, v[176:177]
	s_barrier
	ds_read_b128 v[146:149], v216 offset:16384
	ds_read_b128 v[150:153], v216 offset:17408
	ds_read_b128 v[188:191], v216 offset:18432
	ds_read_b128 v[192:195], v216 offset:19456
	ds_read_b128 v[196:199], v216 offset:20480
	ds_read_b128 v[200:203], v216 offset:21504
	ds_read_b128 v[204:207], v216 offset:22528
	ds_read_b128 v[218:221], v216 offset:23552
	global_load_lds_dwordx4 v[240:241], off
	s_mov_b32 m0, s82
	v_lshl_add_u64 v[242:243], s[68:69], 0, v[180:181]
	global_load_lds_dwordx4 v[242:243], off
	s_barrier
	s_waitcnt lgkmcnt(0)
	s_waitcnt lgkmcnt(0)
	s_cmp_lg_u32 s101, 0
	s_cbranch_scc1 .Lip13_a_2
	v_mfma_f32_16x16x32_bf16 v[70:73], v[130:133], v[146:149], v[70:73]
	v_mfma_f32_16x16x32_bf16 v[66:69], v[138:141], v[146:149], v[66:69]
	v_mfma_f32_16x16x32_bf16 v[46:49], v[130:133], v[188:191], v[46:49]
	v_mfma_f32_16x16x32_bf16 v[42:45], v[138:141], v[188:191], v[42:45]
	v_mfma_f32_16x16x32_bf16 v[30:33], v[130:133], v[196:199], v[30:33]
	v_mfma_f32_16x16x32_bf16 v[26:29], v[138:141], v[196:199], v[26:29]
	v_mfma_f32_16x16x32_bf16 v[14:17], v[130:133], v[204:207], v[14:17]
	v_mfma_f32_16x16x32_bf16 v[10:13], v[138:141], v[204:207], v[10:13]
	v_mfma_f32_16x16x32_bf16 v[70:73], v[134:137], v[150:153], v[70:73]
	v_mfma_f32_16x16x32_bf16 v[66:69], v[142:145], v[150:153], v[66:69]
	v_mfma_f32_16x16x32_bf16 v[46:49], v[134:137], v[192:195], v[46:49]
	v_mfma_f32_16x16x32_bf16 v[42:45], v[142:145], v[192:195], v[42:45]
	v_mfma_f32_16x16x32_bf16 v[30:33], v[134:137], v[200:203], v[30:33]
	v_mfma_f32_16x16x32_bf16 v[26:29], v[142:145], v[200:203], v[26:29]
	v_mfma_f32_16x16x32_bf16 v[14:17], v[134:137], v[218:221], v[14:17]
	v_mfma_f32_16x16x32_bf16 v[10:13], v[142:145], v[218:221], v[10:13]
; #define PG8_STAGE(bufoff, gbase, voff) do { _Pragma("unroll") for (int _i = 0; _i < 2; ++_i) \
;         __builtin_amdgcn_global_load_lds((const unsigned*)((const char*)(gbase) + (voff)[_i]), (LAS unsigned*)(lds + (bufoff) + ldsw + _i * 8192), 16, 0, 0); } while (0)
; #define PG8_LDA(dst, b, h) do { _Pragma("unroll") for (int m = 0; m < 4; ++m) _Pragma("unroll") for (int k = 0; k < 2; ++k) dst[m][k] = *(const LAS bf16x8*)(lds + PG8_SA(b, h) + aoff + m * 2048 + k * 1024); } while (0)
; #define PG8_LDB(dst, b, h) do { _Pragma("unroll") for (int n = 0; n < 2; ++n) _Pragma("unroll") for (int k = 0; k < 2; ++k) dst[n][k] = *(const LAS bf16x8*)(lds + PG8_SB(b, h) + boff + n * 2048 + k * 1024); } while (0)
; #define PG8_MMA(ai, bj, At, Bt) do { __builtin_amdgcn_s_setprio(1); _Pragma("unroll") for (int m = 0; m < 4; ++m) _Pragma("unroll") for (int n = 0; n < 2; ++n) _Pragma("unroll") for (int k = 0; k < 2; ++k) \
;         acc[ai][bj][m][n] = __builtin_amdgcn_mfma_f32_16x16x32_bf16(Bt[n][k], At[m][k], acc[ai][bj][m][n], 0, 0, 0); __builtin_amdgcn_s_setprio(0); } while (0)
; #define PG8_WAIT_V(n) asm volatile("s_waitcnt vmcnt(" #n ")" ::: "memory")
; #define PG8_WAIT_L(n) asm volatile("s_waitcnt lgkmcnt(" #n ")" ::: "memory")
; #define PG8_BAR __builtin_amdgcn_s_barrier()
; #define PG8_SCHED __builtin_amdgcn_sched_barrier(0)
; template <class Epi>
; DEVI void gemm_phase(LAS unsigned char* lds, const Gemm g, const Epi& E) {
;     ...
;             PG8_WAIT_V(6); PG8_BAR; PG8_MMA(1, 1, At, B1); PG8_BAR;
;             PG8_LDB(B0, 1, 0); PG8_SCHED; PG8_LDA(At, 1, 0); PG8_STAGE(PG8_SA(0, 1), a2 + hstepA, voffA);
;             PG8_WAIT_L(8); PG8_BAR; PG8_WAIT_L(0); PG8_MMA(0, 0, At, B0); PG8_BAR; PG8_SCHED;
;             PG8_LDB(B1, 1, 1); PG8_STAGE(PG8_SB(1, 0), b3, voffB);
;             PG8_BAR; PG8_WAIT_L(0); PG8_MMA(0, 1, At, B1); PG8_BAR;
;             PG8_LDA(At, 1, 1); PG8_STAGE(PG8_SA(1, 0), a3, voffA);
;             PG8_BAR; PG8_WAIT_L(0); PG8_MMA(1, 0, At, B0); PG8_BAR; PG8_SCHED;
.Lip13_a_2:
	s_barrier
	s_add_u32 s26, s46, 0x40000
	s_addc_u32 s27, s47, 0
	s_add_i32 s19, s19, s80
	s_mov_b32 m0, s19
	v_lshl_add_u64 v[130:131], s[26:27], 0, v[178:179]
	global_load_lds_dwordx4 v[130:131], off
	s_add_i32 m0, s19, 0x2000
	v_lshl_add_u64 v[130:131], s[26:27], 0, v[182:183]
	global_load_lds_dwordx4 v[130:131], off
	s_waitcnt vmcnt(6)
	s_barrier
	s_cmp_lg_u32 s100, 0
	s_cbranch_scc1 .Lip13_a_3
	v_mfma_f32_16x16x32_bf16 v[50:53], v[222:225], v[146:149], v[50:53]
	v_mfma_f32_16x16x32_bf16 v[54:57], v[230:233], v[146:149], v[54:57]
	v_mfma_f32_16x16x32_bf16 v[34:37], v[222:225], v[188:191], v[34:37]
	v_mfma_f32_16x16x32_bf16 v[38:41], v[230:233], v[188:191], v[38:41]
	v_mfma_f32_16x16x32_bf16 v[18:21], v[222:225], v[196:199], v[18:21]
	v_mfma_f32_16x16x32_bf16 v[22:25], v[230:233], v[196:199], v[22:25]
	v_mfma_f32_16x16x32_bf16 v[0:3], v[222:225], v[204:207], v[0:3]
	v_mfma_f32_16x16x32_bf16 v[4:7], v[230:233], v[204:207], v[4:7]
	v_mfma_f32_16x16x32_bf16 v[50:53], v[226:229], v[150:153], v[50:53]
	v_mfma_f32_16x16x32_bf16 v[54:57], v[234:237], v[150:153], v[54:57]
	v_mfma_f32_16x16x32_bf16 v[34:37], v[226:229], v[192:195], v[34:37]
	v_mfma_f32_16x16x32_bf16 v[38:41], v[234:237], v[192:195], v[38:41]
	v_mfma_f32_16x16x32_bf16 v[18:21], v[226:229], v[200:203], v[18:21]
	v_mfma_f32_16x16x32_bf16 v[22:25], v[234:237], v[200:203], v[22:25]
	v_mfma_f32_16x16x32_bf16 v[0:3], v[226:229], v[218:221], v[0:3]
	v_mfma_f32_16x16x32_bf16 v[4:7], v[234:237], v[218:221], v[4:7]
.Lip13_a_3:
	s_add_i32 s19, 0, 0x18000
	v_add_u32_e32 v8, s19, v214
	s_barrier
	ds_read_b128 v[130:133], v8
	ds_read_b128 v[134:137], v8 offset:1024
	ds_read_b128 v[138:141], v8 offset:2048
	ds_read_b128 v[142:145], v8 offset:3072
	s_add_u32 s26, s68, 0x40000
	s_addc_u32 s27, s69, 0
	s_mov_b32 m0, s83
	v_lshl_add_u64 v[222:223], s[26:27], 0, v[176:177]
	ds_read_b128 v[146:149], v216 offset:32768
	ds_read_b128 v[150:153], v216 offset:33792
	ds_read_b128 v[188:191], v216 offset:34816
	ds_read_b128 v[192:195], v216 offset:35840
	ds_read_b128 v[196:199], v216 offset:36864
	ds_read_b128 v[200:203], v216 offset:37888
	ds_read_b128 v[204:207], v216 offset:38912
	ds_read_b128 v[218:221], v216 offset:39936
	global_load_lds_dwordx4 v[222:223], off
	s_mov_b32 m0, s84
	v_lshl_add_u64 v[222:223], s[26:27], 0, v[180:181]
	global_load_lds_dwordx4 v[222:223], off
	s_waitcnt lgkmcnt(8)
	s_barrier
	s_waitcnt lgkmcnt(0)
	s_waitcnt lgkmcnt(0)
	s_cmp_lg_u32 s101, 0
	s_cbranch_scc1 .Lip13_a_4
	v_mfma_f32_16x16x32_bf16 v[126:129], v[130:133], v[146:149], v[126:129]
	v_mfma_f32_16x16x32_bf16 v[122:125], v[138:141], v[146:149], v[122:125]
	v_mfma_f32_16x16x32_bf16 v[114:117], v[130:133], v[188:191], v[114:117]
	v_mfma_f32_16x16x32_bf16 v[106:109], v[138:141], v[188:191], v[106:109]
	v_mfma_f32_16x16x32_bf16 v[94:97], v[130:133], v[196:199], v[94:97]
	v_mfma_f32_16x16x32_bf16 v[90:93], v[138:141], v[196:199], v[90:93]
	v_mfma_f32_16x16x32_bf16 v[82:85], v[130:133], v[204:207], v[82:85]
	v_mfma_f32_16x16x32_bf16 v[74:77], v[138:141], v[204:207], v[74:77]
	v_mfma_f32_16x16x32_bf16 v[126:129], v[134:137], v[150:153], v[126:129]
	v_mfma_f32_16x16x32_bf16 v[122:125], v[142:145], v[150:153], v[122:125]
	v_mfma_f32_16x16x32_bf16 v[114:117], v[134:137], v[192:195], v[114:117]
	v_mfma_f32_16x16x32_bf16 v[106:109], v[142:145], v[192:195], v[106:109]
	v_mfma_f32_16x16x32_bf16 v[94:97], v[134:137], v[200:203], v[94:97]
	v_mfma_f32_16x16x32_bf16 v[90:93], v[142:145], v[200:203], v[90:93]
	v_mfma_f32_16x16x32_bf16 v[82:85], v[134:137], v[218:221], v[82:85]
	v_mfma_f32_16x16x32_bf16 v[74:77], v[142:145], v[218:221], v[74:77]
; #define PG8_STAGE(bufoff, gbase, voff) do { _Pragma("unroll") for (int _i = 0; _i < 2; ++_i) \
;         __builtin_amdgcn_global_load_lds((const unsigned*)((const char*)(gbase) + (voff)[_i]), (LAS unsigned*)(lds + (bufoff) + ldsw + _i * 8192), 16, 0, 0); } while (0)
; #define PG8_MMA(ai, bj, At, Bt) do { __builtin_amdgcn_s_setprio(1); _Pragma("unroll") for (int m = 0; m < 4; ++m) _Pragma("unroll") for (int n = 0; n < 2; ++n) _Pragma("unroll") for (int k = 0; k < 2; ++k) \
;         acc[ai][bj][m][n] = __builtin_amdgcn_mfma_f32_16x16x32_bf16(Bt[n][k], At[m][k], acc[ai][bj][m][n], 0, 0, 0); __builtin_amdgcn_s_setprio(0); } while (0)
; #define PG8_WAIT_V(n) asm volatile("s_waitcnt vmcnt(" #n ")" ::: "memory")
; #define PG8_WAIT_L(n) asm volatile("s_waitcnt lgkmcnt(" #n ")" ::: "memory")
; #define PG8_BAR __builtin_amdgcn_s_barrier()
; #define PG8_SCHED __builtin_amdgcn_sched_barrier(0)
; template <class Epi>
; DEVI void gemm_phase(LAS unsigned char* lds, const Gemm g, const Epi& E) {
;     ...
;             PG8_BAR; PG8_WAIT_L(0); PG8_MMA(1, 0, At, B0); PG8_BAR; PG8_SCHED;
;             PG8_STAGE(PG8_SB(1, 1), b3 + hstepB, voffB);
;             PG8_WAIT_V(6); PG8_BAR; PG8_MMA(1, 1, At, B1); PG8_BAR;
;         }
.Lip13_a_4:
	s_barrier
	s_add_i32 s38, 0, 0x1c000
	s_add_i32 s19, s19, s80
	v_add_u32_e32 v8, s38, v214
	v_lshl_add_u64 v[208:209], v[208:209], 0, s[70:71]
	s_mov_b32 m0, s19
	ds_read_b128 v[222:225], v8
	ds_read_b128 v[226:229], v8 offset:1024
	ds_read_b128 v[230:233], v8 offset:2048
	ds_read_b128 v[234:237], v8 offset:3072
	global_load_lds_dwordx4 v[208:209], off
	s_add_i32 m0, s19, 0x2000
	v_lshl_add_u64 v[208:209], v[238:239], 0, s[70:71]
	global_load_lds_dwordx4 v[208:209], off
	s_barrier
	s_waitcnt lgkmcnt(0)
	s_waitcnt lgkmcnt(0)
	s_cmp_lg_u32 s100, 0
	s_cbranch_scc1 .Lip13_a_5
	v_mfma_f32_16x16x32_bf16 v[118:121], v[222:225], v[146:149], v[118:121]
	v_mfma_f32_16x16x32_bf16 v[110:113], v[230:233], v[146:149], v[110:113]
	v_mfma_f32_16x16x32_bf16 v[102:105], v[222:225], v[188:191], v[102:105]
	v_mfma_f32_16x16x32_bf16 v[98:101], v[230:233], v[188:191], v[98:101]
	v_mfma_f32_16x16x32_bf16 v[86:89], v[222:225], v[196:199], v[86:89]
	v_mfma_f32_16x16x32_bf16 v[78:81], v[230:233], v[196:199], v[78:81]
	v_mfma_f32_16x16x32_bf16 v[62:65], v[222:225], v[204:207], v[62:65]
	v_mfma_f32_16x16x32_bf16 v[58:61], v[230:233], v[204:207], v[58:61]
	v_mfma_f32_16x16x32_bf16 v[118:121], v[226:229], v[150:153], v[118:121]
	v_mfma_f32_16x16x32_bf16 v[110:113], v[234:237], v[150:153], v[110:113]
	v_mfma_f32_16x16x32_bf16 v[102:105], v[226:229], v[192:195], v[102:105]
	v_mfma_f32_16x16x32_bf16 v[98:101], v[234:237], v[192:195], v[98:101]
	v_mfma_f32_16x16x32_bf16 v[86:89], v[226:229], v[200:203], v[86:89]
	v_mfma_f32_16x16x32_bf16 v[78:81], v[234:237], v[200:203], v[78:81]
	v_mfma_f32_16x16x32_bf16 v[62:65], v[226:229], v[218:221], v[62:65]
	v_mfma_f32_16x16x32_bf16 v[58:61], v[234:237], v[218:221], v[58:61]
.Lip13_a_5:
	s_mov_b32 m0, s85
	v_lshl_add_u64 v[208:209], v[240:241], 0, s[70:71]
	s_barrier
	ds_read_b128 v[146:149], v216 offset:49152
	ds_read_b128 v[150:153], v216 offset:50176
	ds_read_b128 v[188:191], v216 offset:51200
	ds_read_b128 v[192:195], v216 offset:52224
	ds_read_b128 v[196:199], v216 offset:53248
	ds_read_b128 v[200:203], v216 offset:54272
	ds_read_b128 v[204:207], v216 offset:55296
	ds_read_b128 v[218:221], v216 offset:56320
	global_load_lds_dwordx4 v[208:209], off
	s_mov_b32 m0, s86
	v_lshl_add_u64 v[208:209], v[242:243], 0, s[70:71]
	global_load_lds_dwordx4 v[208:209], off
	s_barrier
	s_waitcnt lgkmcnt(0)
	s_waitcnt lgkmcnt(0)
	s_cmp_lg_u32 s101, 0
	s_cbranch_scc1 .Lip13_a_6
	v_mfma_f32_16x16x32_bf16 v[70:73], v[130:133], v[146:149], v[70:73]
	v_mfma_f32_16x16x32_bf16 v[66:69], v[138:141], v[146:149], v[66:69]
	v_mfma_f32_16x16x32_bf16 v[46:49], v[130:133], v[188:191], v[46:49]
	v_mfma_f32_16x16x32_bf16 v[42:45], v[138:141], v[188:191], v[42:45]
	v_mfma_f32_16x16x32_bf16 v[30:33], v[130:133], v[196:199], v[30:33]
	v_mfma_f32_16x16x32_bf16 v[26:29], v[138:141], v[196:199], v[26:29]
	v_mfma_f32_16x16x32_bf16 v[14:17], v[130:133], v[204:207], v[14:17]
	v_mfma_f32_16x16x32_bf16 v[10:13], v[138:141], v[204:207], v[10:13]
	v_mfma_f32_16x16x32_bf16 v[70:73], v[134:137], v[150:153], v[70:73]
	v_mfma_f32_16x16x32_bf16 v[66:69], v[142:145], v[150:153], v[66:69]
	v_mfma_f32_16x16x32_bf16 v[46:49], v[134:137], v[192:195], v[46:49]
	v_mfma_f32_16x16x32_bf16 v[42:45], v[142:145], v[192:195], v[42:45]
	v_mfma_f32_16x16x32_bf16 v[30:33], v[134:137], v[200:203], v[30:33]
	v_mfma_f32_16x16x32_bf16 v[26:29], v[142:145], v[200:203], v[26:29]
	v_mfma_f32_16x16x32_bf16 v[14:17], v[134:137], v[218:221], v[14:17]
	v_mfma_f32_16x16x32_bf16 v[10:13], v[142:145], v[218:221], v[10:13]
.Lip13_a_6:
	s_barrier
	s_add_u32 s26, s46, 0x40080
	s_addc_u32 s27, s47, 0
	s_add_i32 s19, s38, s80
	s_mov_b32 m0, s19
	v_lshl_add_u64 v[130:131], s[26:27], 0, v[178:179]
	global_load_lds_dwordx4 v[130:131], off
	s_add_i32 m0, s19, 0x2000
	v_lshl_add_u64 v[130:131], s[26:27], 0, v[182:183]
	global_load_lds_dwordx4 v[130:131], off
	s_waitcnt vmcnt(6)
	s_barrier
	s_cmp_lg_u32 s100, 0
	s_cbranch_scc1 .Lip13_a_7
	v_mfma_f32_16x16x32_bf16 v[50:53], v[222:225], v[146:149], v[50:53]
	v_mfma_f32_16x16x32_bf16 v[54:57], v[230:233], v[146:149], v[54:57]
	v_mfma_f32_16x16x32_bf16 v[34:37], v[222:225], v[188:191], v[34:37]
	v_mfma_f32_16x16x32_bf16 v[38:41], v[230:233], v[188:191], v[38:41]
	v_mfma_f32_16x16x32_bf16 v[18:21], v[222:225], v[196:199], v[18:21]
	v_mfma_f32_16x16x32_bf16 v[22:25], v[230:233], v[196:199], v[22:25]
	v_mfma_f32_16x16x32_bf16 v[0:3], v[222:225], v[204:207], v[0:3]
	v_mfma_f32_16x16x32_bf16 v[4:7], v[230:233], v[204:207], v[4:7]
	v_mfma_f32_16x16x32_bf16 v[50:53], v[226:229], v[150:153], v[50:53]
	v_mfma_f32_16x16x32_bf16 v[54:57], v[234:237], v[150:153], v[54:57]
	v_mfma_f32_16x16x32_bf16 v[34:37], v[226:229], v[192:195], v[34:37]
	v_mfma_f32_16x16x32_bf16 v[38:41], v[234:237], v[192:195], v[38:41]
	v_mfma_f32_16x16x32_bf16 v[18:21], v[226:229], v[200:203], v[18:21]
	v_mfma_f32_16x16x32_bf16 v[22:25], v[234:237], v[200:203], v[22:25]
	v_mfma_f32_16x16x32_bf16 v[0:3], v[226:229], v[218:221], v[0:3]
	v_mfma_f32_16x16x32_bf16 v[4:7], v[234:237], v[218:221], v[4:7]

; #define PG8_STAGE(bufoff, gbase, voff) do { _Pragma("unroll") for (int _i = 0; _i < 2; ++_i) \
;         __builtin_amdgcn_global_load_lds((const unsigned*)((const char*)(gbase) + (voff)[_i]), (LAS unsigned*)(lds + (bufoff) + ldsw + _i * 8192), 16, 0, 0); } while (0)
; #define PG8_LDA(dst, b, h) do { _Pragma("unroll") for (int m = 0; m < 4; ++m) _Pragma("unroll") for (int k = 0; k < 2; ++k) dst[m][k] = *(const LAS bf16x8*)(lds + PG8_SA(b, h) + aoff + m * 2048 + k * 1024); } while (0)
; #define PG8_LDB(dst, b, h) do { _Pragma("unroll") for (int n = 0; n < 2; ++n) _Pragma("unroll") for (int k = 0; k < 2; ++k) dst[n][k] = *(const LAS bf16x8*)(lds + PG8_SB(b, h) + boff + n * 2048 + k * 1024); } while (0)
; #define PG8_MMA(ai, bj, At, Bt) do { __builtin_amdgcn_s_setprio(1); _Pragma("unroll") for (int m = 0; m < 4; ++m) _Pragma("unroll") for (int n = 0; n < 2; ++n) _Pragma("unroll") for (int k = 0; k < 2; ++k) \
;         acc[ai][bj][m][n] = __builtin_amdgcn_mfma_f32_16x16x32_bf16(Bt[n][k], At[m][k], acc[ai][bj][m][n], 0, 0, 0); __builtin_amdgcn_s_setprio(0); } while (0)
; #define PG8_WAIT_V(n) asm volatile("s_waitcnt vmcnt(" #n ")" ::: "memory")
; #define PG8_WAIT_L(n) asm volatile("s_waitcnt lgkmcnt(" #n ")" ::: "memory")
; #define PG8_BAR __builtin_amdgcn_s_barrier()
; #define PG8_SCHED __builtin_amdgcn_sched_barrier(0)
; template <class Epi>
; DEVI void gemm_phase(LAS unsigned char* lds, const Gemm g, const Epi& E) {
;     ...
;             PG8_LDB(B0, 0, 0); PG8_SCHED; PG8_LDA(At, 0, 0); PG8_STAGE(PG8_SA(1, 1), a1 + hstepA, voffA);
;             PG8_WAIT_L(8); PG8_BAR; PG8_WAIT_L(0); PG8_MMA(0, 0, At, B0); PG8_BAR; PG8_SCHED;
;             PG8_LDB(B1, 0, 1); PG8_STAGE(PG8_SB(0, 0), b2, voffB);
;             PG8_BAR; PG8_WAIT_L(0); PG8_MMA(0, 1, At, B1); PG8_BAR;
;             PG8_LDA(At, 0, 1); PG8_STAGE(PG8_SA(0, 0), a2, voffA);
;             PG8_BAR; PG8_WAIT_L(0); PG8_MMA(1, 0, At, B0); PG8_BAR; PG8_SCHED;
;             PG8_STAGE(PG8_SB(0, 1), b2 + hstepB, voffB);
;             PG8_WAIT_V(6); PG8_BAR; PG8_MMA(1, 1, At, B1); PG8_BAR;
.LBB0_356:
	s_add_u32 s19, s8, 0xfffc0080
	s_addc_u32 s26, s9, -1
	s_add_i32 s27, 0, 0x10000
	v_add_u32_e32 v142, s27, v209
	ds_read_b128 v[130:133], v142
	ds_read_b128 v[134:137], v142 offset:1024
	ds_read_b128 v[138:141], v142 offset:2048
	ds_read_b128 v[142:145], v142 offset:3072
	s_cmp_eq_u32 s18, 12
	s_cselect_b32 s69, s0, s26
	s_cselect_b32 s68, s1, s19
	s_cselect_b32 s47, s5, s13
	s_cselect_b32 s46, s7, s11
	v_lshl_add_u64 v[206:207], s[8:9], 0, v[182:183]
	s_add_i32 m0, s85, 0xc000
	ds_read_b128 v[146:149], v214
	ds_read_b128 v[150:153], v214 offset:1024
	ds_read_b128 v[186:189], v214 offset:2048
	ds_read_b128 v[190:193], v214 offset:3072
	ds_read_b128 v[194:197], v214 offset:4096
	ds_read_b128 v[198:201], v214 offset:5120
	ds_read_b128 v[202:205], v214 offset:6144
	ds_read_b128 v[216:219], v214 offset:7168
	global_load_lds_dwordx4 v[206:207], off
	s_add_i32 m0, s85, 0xe000
	v_lshl_add_u64 v[206:207], s[8:9], 0, v[184:185]
	global_load_lds_dwordx4 v[206:207], off
	s_waitcnt lgkmcnt(8)
	s_barrier
	s_waitcnt lgkmcnt(0)
	s_waitcnt lgkmcnt(0)
	s_cmp_lg_u32 s101, 0
	s_cbranch_scc1 .Lip13_b_0
	v_mfma_f32_16x16x32_bf16 v[126:129], v[130:133], v[146:149], v[126:129]
	v_mfma_f32_16x16x32_bf16 v[122:125], v[138:141], v[146:149], v[122:125]
	v_mfma_f32_16x16x32_bf16 v[114:117], v[130:133], v[186:189], v[114:117]
	v_mfma_f32_16x16x32_bf16 v[106:109], v[138:141], v[186:189], v[106:109]
	v_mfma_f32_16x16x32_bf16 v[94:97], v[130:133], v[194:197], v[94:97]
	v_mfma_f32_16x16x32_bf16 v[90:93], v[138:141], v[194:197], v[90:93]
	v_mfma_f32_16x16x32_bf16 v[82:85], v[130:133], v[202:205], v[82:85]
	v_mfma_f32_16x16x32_bf16 v[74:77], v[138:141], v[202:205], v[74:77]
	v_mfma_f32_16x16x32_bf16 v[126:129], v[134:137], v[150:153], v[126:129]
	v_mfma_f32_16x16x32_bf16 v[122:125], v[142:145], v[150:153], v[122:125]
	v_mfma_f32_16x16x32_bf16 v[114:117], v[134:137], v[190:193], v[114:117]
	v_mfma_f32_16x16x32_bf16 v[106:109], v[142:145], v[190:193], v[106:109]
	v_mfma_f32_16x16x32_bf16 v[94:97], v[134:137], v[198:201], v[94:97]
	v_mfma_f32_16x16x32_bf16 v[90:93], v[142:145], v[198:201], v[90:93]
	v_mfma_f32_16x16x32_bf16 v[82:85], v[134:137], v[216:219], v[82:85]
	v_mfma_f32_16x16x32_bf16 v[74:77], v[142:145], v[216:219], v[74:77]
.Lip13_b_0:
	s_barrier
	s_add_i32 s19, 0, 0x14000
	s_add_i32 s26, s27, s84
	v_add_u32_e32 v162, s19, v209
	v_lshl_add_u64 v[206:207], s[46:47], 0, v[8:9]
	s_mov_b32 m0, s26
	ds_read_b128 v[220:223], v162
	ds_read_b128 v[224:227], v162 offset:1024
	ds_read_b128 v[228:231], v162 offset:2048
	ds_read_b128 v[232:235], v162 offset:3072
	global_load_lds_dwordx4 v[206:207], off
	s_add_i32 m0, s26, 0x2000
	v_lshl_add_u64 v[236:237], s[46:47], 0, v[180:181]
	global_load_lds_dwordx4 v[236:237], off
	s_barrier
	s_waitcnt lgkmcnt(0)
	s_waitcnt lgkmcnt(0)
	s_cmp_lg_u32 s100, 0
	s_cbranch_scc1 .Lip13_b_1
	v_mfma_f32_16x16x32_bf16 v[118:121], v[220:223], v[146:149], v[118:121]
	v_mfma_f32_16x16x32_bf16 v[110:113], v[228:231], v[146:149], v[110:113]
	v_mfma_f32_16x16x32_bf16 v[102:105], v[220:223], v[186:189], v[102:105]
	v_mfma_f32_16x16x32_bf16 v[98:101], v[228:231], v[186:189], v[98:101]
	v_mfma_f32_16x16x32_bf16 v[86:89], v[220:223], v[194:197], v[86:89]
	v_mfma_f32_16x16x32_bf16 v[78:81], v[228:231], v[194:197], v[78:81]
	v_mfma_f32_16x16x32_bf16 v[62:65], v[220:223], v[202:205], v[62:65]
	v_mfma_f32_16x16x32_bf16 v[58:61], v[228:231], v[202:205], v[58:61]
	v_mfma_f32_16x16x32_bf16 v[118:121], v[224:227], v[150:153], v[118:121]
	v_mfma_f32_16x16x32_bf16 v[110:113], v[232:235], v[150:153], v[110:113]
	v_mfma_f32_16x16x32_bf16 v[102:105], v[224:227], v[190:193], v[102:105]
	v_mfma_f32_16x16x32_bf16 v[98:101], v[232:235], v[190:193], v[98:101]
	v_mfma_f32_16x16x32_bf16 v[86:89], v[224:227], v[198:201], v[86:89]
	v_mfma_f32_16x16x32_bf16 v[78:81], v[232:235], v[198:201], v[78:81]
	v_mfma_f32_16x16x32_bf16 v[62:65], v[224:227], v[216:219], v[62:65]
	v_mfma_f32_16x16x32_bf16 v[58:61], v[232:235], v[216:219], v[58:61]
.Lip13_b_1:
	s_mov_b32 m0, s85
	v_lshl_add_u64 v[238:239], s[68:69], 0, v[176:177]
	s_barrier
	ds_read_b128 v[146:149], v214 offset:16384
	ds_read_b128 v[150:153], v214 offset:17408
	ds_read_b128 v[186:189], v214 offset:18432
	ds_read_b128 v[190:193], v214 offset:19456
	ds_read_b128 v[194:197], v214 offset:20480
	ds_read_b128 v[198:201], v214 offset:21504
	ds_read_b128 v[202:205], v214 offset:22528
	ds_read_b128 v[216:219], v214 offset:23552
	global_load_lds_dwordx4 v[238:239], off
	s_mov_b32 m0, s86
	v_lshl_add_u64 v[240:241], s[68:69], 0, v[178:179]
	global_load_lds_dwordx4 v[240:241], off
	s_barrier
	s_waitcnt lgkmcnt(0)
	s_waitcnt lgkmcnt(0)
	s_cmp_lg_u32 s101, 0
	s_cbranch_scc1 .Lip13_b_2
	v_mfma_f32_16x16x32_bf16 v[70:73], v[130:133], v[146:149], v[70:73]
	v_mfma_f32_16x16x32_bf16 v[66:69], v[138:141], v[146:149], v[66:69]
	v_mfma_f32_16x16x32_bf16 v[46:49], v[130:133], v[186:189], v[46:49]
	v_mfma_f32_16x16x32_bf16 v[42:45], v[138:141], v[186:189], v[42:45]
	v_mfma_f32_16x16x32_bf16 v[30:33], v[130:133], v[194:197], v[30:33]
	v_mfma_f32_16x16x32_bf16 v[26:29], v[138:141], v[194:197], v[26:29]
	v_mfma_f32_16x16x32_bf16 v[14:17], v[130:133], v[202:205], v[14:17]
	v_mfma_f32_16x16x32_bf16 v[10:13], v[138:141], v[202:205], v[10:13]
	v_mfma_f32_16x16x32_bf16 v[70:73], v[134:137], v[150:153], v[70:73]
	v_mfma_f32_16x16x32_bf16 v[66:69], v[142:145], v[150:153], v[66:69]
	v_mfma_f32_16x16x32_bf16 v[46:49], v[134:137], v[190:193], v[46:49]
	v_mfma_f32_16x16x32_bf16 v[42:45], v[142:145], v[190:193], v[42:45]
	v_mfma_f32_16x16x32_bf16 v[30:33], v[134:137], v[198:201], v[30:33]
	v_mfma_f32_16x16x32_bf16 v[26:29], v[142:145], v[198:201], v[26:29]
	v_mfma_f32_16x16x32_bf16 v[14:17], v[134:137], v[216:219], v[14:17]
	v_mfma_f32_16x16x32_bf16 v[10:13], v[142:145], v[216:219], v[10:13]
; #define PG8_STAGE(bufoff, gbase, voff) do { _Pragma("unroll") for (int _i = 0; _i < 2; ++_i) \
;         __builtin_amdgcn_global_load_lds((const unsigned*)((const char*)(gbase) + (voff)[_i]), (LAS unsigned*)(lds + (bufoff) + ldsw + _i * 8192), 16, 0, 0); } while (0)
; #define PG8_LDA(dst, b, h) do { _Pragma("unroll") for (int m = 0; m < 4; ++m) _Pragma("unroll") for (int k = 0; k < 2; ++k) dst[m][k] = *(const LAS bf16x8*)(lds + PG8_SA(b, h) + aoff + m * 2048 + k * 1024); } while (0)
; #define PG8_LDB(dst, b, h) do { _Pragma("unroll") for (int n = 0; n < 2; ++n) _Pragma("unroll") for (int k = 0; k < 2; ++k) dst[n][k] = *(const LAS bf16x8*)(lds + PG8_SB(b, h) + boff + n * 2048 + k * 1024); } while (0)
; #define PG8_MMA(ai, bj, At, Bt) do { __builtin_amdgcn_s_setprio(1); _Pragma("unroll") for (int m = 0; m < 4; ++m) _Pragma("unroll") for (int n = 0; n < 2; ++n) _Pragma("unroll") for (int k = 0; k < 2; ++k) \
;         acc[ai][bj][m][n] = __builtin_amdgcn_mfma_f32_16x16x32_bf16(Bt[n][k], At[m][k], acc[ai][bj][m][n], 0, 0, 0); __builtin_amdgcn_s_setprio(0); } while (0)
; #define PG8_WAIT_V(n) asm volatile("s_waitcnt vmcnt(" #n ")" ::: "memory")
; #define PG8_WAIT_L(n) asm volatile("s_waitcnt lgkmcnt(" #n ")" ::: "memory")
; #define PG8_BAR __builtin_amdgcn_s_barrier()
; #define PG8_SCHED __builtin_amdgcn_sched_barrier(0)
; template <class Epi>
; DEVI void gemm_phase(LAS unsigned char* lds, const Gemm g, const Epi& E) {
;     ...
;             PG8_WAIT_V(6); PG8_BAR; PG8_MMA(1, 1, At, B1); PG8_BAR;
;             PG8_LDB(B0, 1, 0); PG8_SCHED; PG8_LDA(At, 1, 0); PG8_STAGE(PG8_SA(0, 1), a2 + hstepA, voffA);
;             PG8_WAIT_L(8); PG8_BAR; PG8_WAIT_L(0); PG8_MMA(0, 0, At, B0); PG8_BAR; PG8_SCHED;
;             PG8_LDB(B1, 1, 1); PG8_STAGE(PG8_SB(1, 0), b3, voffB);
;             PG8_BAR; PG8_WAIT_L(0); PG8_MMA(0, 1, At, B1); PG8_BAR;
;             PG8_LDA(At, 1, 1); PG8_STAGE(PG8_SA(1, 0), a3, voffA);
;             PG8_BAR; PG8_WAIT_L(0); PG8_MMA(1, 0, At, B0); PG8_BAR; PG8_SCHED;
.Lip13_b_2:
	s_barrier
	s_add_u32 s26, s46, 0x40000
	s_addc_u32 s27, s47, 0
	s_add_i32 s19, s19, s84
	s_mov_b32 m0, s19
	v_lshl_add_u64 v[130:131], s[26:27], 0, v[8:9]
	global_load_lds_dwordx4 v[130:131], off
	s_add_i32 m0, s19, 0x2000
	v_lshl_add_u64 v[130:131], s[26:27], 0, v[180:181]
	global_load_lds_dwordx4 v[130:131], off
	s_waitcnt vmcnt(6)
	s_barrier
	s_cmp_lg_u32 s100, 0
	s_cbranch_scc1 .Lip13_b_3
	v_mfma_f32_16x16x32_bf16 v[50:53], v[220:223], v[146:149], v[50:53]
	v_mfma_f32_16x16x32_bf16 v[54:57], v[228:231], v[146:149], v[54:57]
	v_mfma_f32_16x16x32_bf16 v[34:37], v[220:223], v[186:189], v[34:37]
	v_mfma_f32_16x16x32_bf16 v[38:41], v[228:231], v[186:189], v[38:41]
	v_mfma_f32_16x16x32_bf16 v[18:21], v[220:223], v[194:197], v[18:21]
	v_mfma_f32_16x16x32_bf16 v[22:25], v[228:231], v[194:197], v[22:25]
	v_mfma_f32_16x16x32_bf16 v[0:3], v[220:223], v[202:205], v[0:3]
	v_mfma_f32_16x16x32_bf16 v[4:7], v[228:231], v[202:205], v[4:7]
	v_mfma_f32_16x16x32_bf16 v[50:53], v[224:227], v[150:153], v[50:53]
	v_mfma_f32_16x16x32_bf16 v[54:57], v[232:235], v[150:153], v[54:57]
	v_mfma_f32_16x16x32_bf16 v[34:37], v[224:227], v[190:193], v[34:37]
	v_mfma_f32_16x16x32_bf16 v[38:41], v[232:235], v[190:193], v[38:41]
	v_mfma_f32_16x16x32_bf16 v[18:21], v[224:227], v[198:201], v[18:21]
	v_mfma_f32_16x16x32_bf16 v[22:25], v[232:235], v[198:201], v[22:25]
	v_mfma_f32_16x16x32_bf16 v[0:3], v[224:227], v[216:219], v[0:3]
	v_mfma_f32_16x16x32_bf16 v[4:7], v[232:235], v[216:219], v[4:7]
.Lip13_b_3:
	s_add_i32 s19, 0, 0x18000
	v_add_u32_e32 v142, s19, v209
	s_barrier
	ds_read_b128 v[130:133], v142
	ds_read_b128 v[134:137], v142 offset:1024
	ds_read_b128 v[138:141], v142 offset:2048
	ds_read_b128 v[142:145], v142 offset:3072
	s_add_u32 s26, s68, 0x40000
	s_addc_u32 s27, s69, 0
	s_mov_b32 m0, s87
	v_lshl_add_u64 v[220:221], s[26:27], 0, v[176:177]
	ds_read_b128 v[146:149], v214 offset:32768
	ds_read_b128 v[150:153], v214 offset:33792
	ds_read_b128 v[186:189], v214 offset:34816
	ds_read_b128 v[190:193], v214 offset:35840
	ds_read_b128 v[194:197], v214 offset:36864
	ds_read_b128 v[198:201], v214 offset:37888
	ds_read_b128 v[202:205], v214 offset:38912
	ds_read_b128 v[216:219], v214 offset:39936
	global_load_lds_dwordx4 v[220:221], off
	s_mov_b32 m0, s88
	v_lshl_add_u64 v[220:221], s[26:27], 0, v[178:179]
	global_load_lds_dwordx4 v[220:221], off
	s_waitcnt lgkmcnt(8)
	s_barrier
	s_waitcnt lgkmcnt(0)
	s_waitcnt lgkmcnt(0)
	s_cmp_lg_u32 s101, 0
	s_cbranch_scc1 .Lip13_b_4
	v_mfma_f32_16x16x32_bf16 v[126:129], v[130:133], v[146:149], v[126:129]
	v_mfma_f32_16x16x32_bf16 v[122:125], v[138:141], v[146:149], v[122:125]
	v_mfma_f32_16x16x32_bf16 v[114:117], v[130:133], v[186:189], v[114:117]
	v_mfma_f32_16x16x32_bf16 v[106:109], v[138:141], v[186:189], v[106:109]
	v_mfma_f32_16x16x32_bf16 v[94:97], v[130:133], v[194:197], v[94:97]
	v_mfma_f32_16x16x32_bf16 v[90:93], v[138:141], v[194:197], v[90:93]
	v_mfma_f32_16x16x32_bf16 v[82:85], v[130:133], v[202:205], v[82:85]
	v_mfma_f32_16x16x32_bf16 v[74:77], v[138:141], v[202:205], v[74:77]
	v_mfma_f32_16x16x32_bf16 v[126:129], v[134:137], v[150:153], v[126:129]
	v_mfma_f32_16x16x32_bf16 v[122:125], v[142:145], v[150:153], v[122:125]
	v_mfma_f32_16x16x32_bf16 v[114:117], v[134:137], v[190:193], v[114:117]
	v_mfma_f32_16x16x32_bf16 v[106:109], v[142:145], v[190:193], v[106:109]
	v_mfma_f32_16x16x32_bf16 v[94:97], v[134:137], v[198:201], v[94:97]
	v_mfma_f32_16x16x32_bf16 v[90:93], v[142:145], v[198:201], v[90:93]
	v_mfma_f32_16x16x32_bf16 v[82:85], v[134:137], v[216:219], v[82:85]
	v_mfma_f32_16x16x32_bf16 v[74:77], v[142:145], v[216:219], v[74:77]
; #define PG8_STAGE(bufoff, gbase, voff) do { _Pragma("unroll") for (int _i = 0; _i < 2; ++_i) \
;         __builtin_amdgcn_global_load_lds((const unsigned*)((const char*)(gbase) + (voff)[_i]), (LAS unsigned*)(lds + (bufoff) + ldsw + _i * 8192), 16, 0, 0); } while (0)
; #define PG8_MMA(ai, bj, At, Bt) do { __builtin_amdgcn_s_setprio(1); _Pragma("unroll") for (int m = 0; m < 4; ++m) _Pragma("unroll") for (int n = 0; n < 2; ++n) _Pragma("unroll") for (int k = 0; k < 2; ++k) \
;         acc[ai][bj][m][n] = __builtin_amdgcn_mfma_f32_16x16x32_bf16(Bt[n][k], At[m][k], acc[ai][bj][m][n], 0, 0, 0); __builtin_amdgcn_s_setprio(0); } while (0)
; #define PG8_WAIT_V(n) asm volatile("s_waitcnt vmcnt(" #n ")" ::: "memory")
; #define PG8_WAIT_L(n) asm volatile("s_waitcnt lgkmcnt(" #n ")" ::: "memory")
; #define PG8_BAR __builtin_amdgcn_s_barrier()
; #define PG8_SCHED __builtin_amdgcn_sched_barrier(0)
; template <class Epi>
; DEVI void gemm_phase(LAS unsigned char* lds, const Gemm g, const Epi& E) {
;     ...
;             PG8_BAR; PG8_WAIT_L(0); PG8_MMA(1, 0, At, B0); PG8_BAR; PG8_SCHED;
;             PG8_STAGE(PG8_SB(1, 1), b3 + hstepB, voffB);
;             PG8_WAIT_V(6); PG8_BAR; PG8_MMA(1, 1, At, B1); PG8_BAR;
;         }
.Lip13_b_4:
	s_barrier
	s_add_i32 s38, 0, 0x1c000
	s_add_i32 s19, s19, s84
	v_add_u32_e32 v162, s38, v209
	v_lshl_add_u64 v[206:207], v[206:207], 0, s[70:71]
	s_mov_b32 m0, s19
	ds_read_b128 v[220:223], v162
	ds_read_b128 v[224:227], v162 offset:1024
	ds_read_b128 v[228:231], v162 offset:2048
	ds_read_b128 v[232:235], v162 offset:3072
	global_load_lds_dwordx4 v[206:207], off
	s_add_i32 m0, s19, 0x2000
	v_lshl_add_u64 v[206:207], v[236:237], 0, s[70:71]
	global_load_lds_dwordx4 v[206:207], off
	s_barrier
	s_waitcnt lgkmcnt(0)
	s_waitcnt lgkmcnt(0)
	s_cmp_lg_u32 s100, 0
	s_cbranch_scc1 .Lip13_b_5
	v_mfma_f32_16x16x32_bf16 v[118:121], v[220:223], v[146:149], v[118:121]
	v_mfma_f32_16x16x32_bf16 v[110:113], v[228:231], v[146:149], v[110:113]
	v_mfma_f32_16x16x32_bf16 v[102:105], v[220:223], v[186:189], v[102:105]
	v_mfma_f32_16x16x32_bf16 v[98:101], v[228:231], v[186:189], v[98:101]
	v_mfma_f32_16x16x32_bf16 v[86:89], v[220:223], v[194:197], v[86:89]
	v_mfma_f32_16x16x32_bf16 v[78:81], v[228:231], v[194:197], v[78:81]
	v_mfma_f32_16x16x32_bf16 v[62:65], v[220:223], v[202:205], v[62:65]
	v_mfma_f32_16x16x32_bf16 v[58:61], v[228:231], v[202:205], v[58:61]
	v_mfma_f32_16x16x32_bf16 v[118:121], v[224:227], v[150:153], v[118:121]
	v_mfma_f32_16x16x32_bf16 v[110:113], v[232:235], v[150:153], v[110:113]
	v_mfma_f32_16x16x32_bf16 v[102:105], v[224:227], v[190:193], v[102:105]
	v_mfma_f32_16x16x32_bf16 v[98:101], v[232:235], v[190:193], v[98:101]
	v_mfma_f32_16x16x32_bf16 v[86:89], v[224:227], v[198:201], v[86:89]
	v_mfma_f32_16x16x32_bf16 v[78:81], v[232:235], v[198:201], v[78:81]
	v_mfma_f32_16x16x32_bf16 v[62:65], v[224:227], v[216:219], v[62:65]
	v_mfma_f32_16x16x32_bf16 v[58:61], v[232:235], v[216:219], v[58:61]
.Lip13_b_5:
	s_mov_b32 m0, s89
	v_lshl_add_u64 v[206:207], v[238:239], 0, s[70:71]
	s_barrier
	ds_read_b128 v[146:149], v214 offset:49152
	ds_read_b128 v[150:153], v214 offset:50176
	ds_read_b128 v[186:189], v214 offset:51200
	ds_read_b128 v[190:193], v214 offset:52224
	ds_read_b128 v[194:197], v214 offset:53248
	ds_read_b128 v[198:201], v214 offset:54272
	ds_read_b128 v[202:205], v214 offset:55296
	ds_read_b128 v[216:219], v214 offset:56320
	global_load_lds_dwordx4 v[206:207], off
	s_mov_b32 m0, s90
	v_lshl_add_u64 v[206:207], v[240:241], 0, s[70:71]
	global_load_lds_dwordx4 v[206:207], off
	s_barrier
	s_waitcnt lgkmcnt(0)
	s_waitcnt lgkmcnt(0)
	s_cmp_lg_u32 s101, 0
	s_cbranch_scc1 .Lip13_b_6
	v_mfma_f32_16x16x32_bf16 v[70:73], v[130:133], v[146:149], v[70:73]
	v_mfma_f32_16x16x32_bf16 v[66:69], v[138:141], v[146:149], v[66:69]
	v_mfma_f32_16x16x32_bf16 v[46:49], v[130:133], v[186:189], v[46:49]
	v_mfma_f32_16x16x32_bf16 v[42:45], v[138:141], v[186:189], v[42:45]
	v_mfma_f32_16x16x32_bf16 v[30:33], v[130:133], v[194:197], v[30:33]
	v_mfma_f32_16x16x32_bf16 v[26:29], v[138:141], v[194:197], v[26:29]
	v_mfma_f32_16x16x32_bf16 v[14:17], v[130:133], v[202:205], v[14:17]
	v_mfma_f32_16x16x32_bf16 v[10:13], v[138:141], v[202:205], v[10:13]
	v_mfma_f32_16x16x32_bf16 v[70:73], v[134:137], v[150:153], v[70:73]
	v_mfma_f32_16x16x32_bf16 v[66:69], v[142:145], v[150:153], v[66:69]
	v_mfma_f32_16x16x32_bf16 v[46:49], v[134:137], v[190:193], v[46:49]
	v_mfma_f32_16x16x32_bf16 v[42:45], v[142:145], v[190:193], v[42:45]
	v_mfma_f32_16x16x32_bf16 v[30:33], v[134:137], v[198:201], v[30:33]
	v_mfma_f32_16x16x32_bf16 v[26:29], v[142:145], v[198:201], v[26:29]
	v_mfma_f32_16x16x32_bf16 v[14:17], v[134:137], v[216:219], v[14:17]
	v_mfma_f32_16x16x32_bf16 v[10:13], v[142:145], v[216:219], v[10:13]
.Lip13_b_6:
	s_barrier
	s_add_u32 s26, s46, 0x40080
	s_addc_u32 s27, s47, 0
	s_add_i32 s19, s38, s84
	s_mov_b32 m0, s19
	v_lshl_add_u64 v[130:131], s[26:27], 0, v[8:9]
	global_load_lds_dwordx4 v[130:131], off
	s_add_i32 m0, s19, 0x2000
	v_lshl_add_u64 v[130:131], s[26:27], 0, v[180:181]
	global_load_lds_dwordx4 v[130:131], off
	s_waitcnt vmcnt(6)
	s_barrier
	s_cmp_lg_u32 s100, 0
	s_cbranch_scc1 .Lip13_b_7
	v_mfma_f32_16x16x32_bf16 v[50:53], v[220:223], v[146:149], v[50:53]
	v_mfma_f32_16x16x32_bf16 v[54:57], v[228:231], v[146:149], v[54:57]
	v_mfma_f32_16x16x32_bf16 v[34:37], v[220:223], v[186:189], v[34:37]
	v_mfma_f32_16x16x32_bf16 v[38:41], v[228:231], v[186:189], v[38:41]
	v_mfma_f32_16x16x32_bf16 v[18:21], v[220:223], v[194:197], v[18:21]
	v_mfma_f32_16x16x32_bf16 v[22:25], v[228:231], v[194:197], v[22:25]
	v_mfma_f32_16x16x32_bf16 v[0:3], v[220:223], v[202:205], v[0:3]
	v_mfma_f32_16x16x32_bf16 v[4:7], v[228:231], v[202:205], v[4:7]
	v_mfma_f32_16x16x32_bf16 v[50:53], v[224:227], v[150:153], v[50:53]
	v_mfma_f32_16x16x32_bf16 v[54:57], v[232:235], v[150:153], v[54:57]
	v_mfma_f32_16x16x32_bf16 v[34:37], v[224:227], v[190:193], v[34:37]
	v_mfma_f32_16x16x32_bf16 v[38:41], v[232:235], v[190:193], v[38:41]
	v_mfma_f32_16x16x32_bf16 v[18:21], v[224:227], v[198:201], v[18:21]
	v_mfma_f32_16x16x32_bf16 v[22:25], v[232:235], v[198:201], v[22:25]
	v_mfma_f32_16x16x32_bf16 v[0:3], v[224:227], v[216:219], v[0:3]
	v_mfma_f32_16x16x32_bf16 v[4:7], v[232:235], v[216:219], v[4:7]

; #define PG8_STAGE(bufoff, gbase, voff) do { _Pragma("unroll") for (int _i = 0; _i < 2; ++_i) \
;         __builtin_amdgcn_global_load_lds((const unsigned*)((const char*)(gbase) + (voff)[_i]), (LAS unsigned*)(lds + (bufoff) + ldsw + _i * 8192), 16, 0, 0); } while (0)
; #define PG8_LDA(dst, b, h) do { _Pragma("unroll") for (int m = 0; m < 4; ++m) _Pragma("unroll") for (int k = 0; k < 2; ++k) dst[m][k] = *(const LAS bf16x8*)(lds + PG8_SA(b, h) + aoff + m * 2048 + k * 1024); } while (0)
; #define PG8_LDB(dst, b, h) do { _Pragma("unroll") for (int n = 0; n < 2; ++n) _Pragma("unroll") for (int k = 0; k < 2; ++k) dst[n][k] = *(const LAS bf16x8*)(lds + PG8_SB(b, h) + boff + n * 2048 + k * 1024); } while (0)
; #define PG8_MMA(ai, bj, At, Bt) do { __builtin_amdgcn_s_setprio(1); _Pragma("unroll") for (int m = 0; m < 4; ++m) _Pragma("unroll") for (int n = 0; n < 2; ++n) _Pragma("unroll") for (int k = 0; k < 2; ++k) \
;         acc[ai][bj][m][n] = __builtin_amdgcn_mfma_f32_16x16x32_bf16(Bt[n][k], At[m][k], acc[ai][bj][m][n], 0, 0, 0); __builtin_amdgcn_s_setprio(0); } while (0)
; #define PG8_WAIT_V(n) asm volatile("s_waitcnt vmcnt(" #n ")" ::: "memory")
; #define PG8_WAIT_L(n) asm volatile("s_waitcnt lgkmcnt(" #n ")" ::: "memory")
; #define PG8_BAR __builtin_amdgcn_s_barrier()
; #define PG8_SCHED __builtin_amdgcn_sched_barrier(0)
; template <class Epi>
; DEVI void gemm_phase(LAS unsigned char* lds, const Gemm g, const Epi& E) {
;     ...
;             PG8_LDB(B0, 0, 0); PG8_SCHED; PG8_LDA(At, 0, 0); PG8_STAGE(PG8_SA(1, 1), a1 + hstepA, voffA);
;             PG8_WAIT_L(8); PG8_BAR; PG8_WAIT_L(0); PG8_MMA(0, 0, At, B0); PG8_BAR; PG8_SCHED;
;             PG8_LDB(B1, 0, 1); PG8_STAGE(PG8_SB(0, 0), b2, voffB);
;             PG8_BAR; PG8_WAIT_L(0); PG8_MMA(0, 1, At, B1); PG8_BAR;
;             PG8_LDA(At, 0, 1); PG8_STAGE(PG8_SA(0, 0), a2, voffA);
;             PG8_BAR; PG8_WAIT_L(0); PG8_MMA(1, 0, At, B0); PG8_BAR; PG8_SCHED;
;             PG8_STAGE(PG8_SB(0, 1), b2 + hstepB, voffB);
;             PG8_WAIT_V(6); PG8_BAR; PG8_MMA(1, 1, At, B1); PG8_BAR;
.LBB0_968:
	s_add_u32 s26, s68, 0xfffc0080
	s_addc_u32 s27, s69, -1
	s_add_i32 s38, 0, 0x10000
	v_add_u32_e32 v142, s38, v193
	ds_read_b128 v[130:133], v142
	ds_read_b128 v[134:137], v142 offset:1024
	ds_read_b128 v[138:141], v142 offset:2048
	ds_read_b128 v[142:145], v142 offset:3072
	s_cmp_eq_u32 s19, 12
	s_cselect_b32 s83, s0, s27
	s_cselect_b32 s82, s1, s26
	s_cselect_b32 s81, s9, s18
	s_cselect_b32 s80, s13, s15
	v_lshl_add_u64 v[162:163], s[68:69], 0, v[178:179]
	s_add_i32 m0, s85, 0xc000
	ds_read_b128 v[146:149], v198
	ds_read_b128 v[182:185], v198 offset:1024
	ds_read_b128 v[186:189], v198 offset:2048
	ds_read_b128 v[200:203], v198 offset:3072
	ds_read_b128 v[204:207], v198 offset:4096
	ds_read_b128 v[214:217], v198 offset:5120
	ds_read_b128 v[218:221], v198 offset:6144
	ds_read_b128 v[222:225], v198 offset:7168
	global_load_lds_dwordx4 v[162:163], off
	s_add_i32 m0, s85, 0xe000
	v_lshl_add_u64 v[162:163], s[68:69], 0, v[180:181]
	global_load_lds_dwordx4 v[162:163], off
	s_waitcnt lgkmcnt(8)
	s_barrier
	s_waitcnt lgkmcnt(0)
	v_mfma_f32_16x16x32_bf16 v[126:129], v[130:133], v[146:149], v[126:129]
	v_mfma_f32_16x16x32_bf16 v[122:125], v[138:141], v[146:149], v[122:125]
	v_mfma_f32_16x16x32_bf16 v[110:113], v[130:133], v[186:189], v[110:113]
	v_mfma_f32_16x16x32_bf16 v[106:109], v[138:141], v[186:189], v[106:109]
	v_mfma_f32_16x16x32_bf16 v[94:97], v[130:133], v[204:207], v[94:97]
	v_mfma_f32_16x16x32_bf16 v[90:93], v[138:141], v[204:207], v[90:93]
	v_mfma_f32_16x16x32_bf16 v[78:81], v[130:133], v[218:221], v[78:81]
	v_mfma_f32_16x16x32_bf16 v[74:77], v[138:141], v[218:221], v[74:77]
	v_mfma_f32_16x16x32_bf16 v[126:129], v[134:137], v[182:185], v[126:129]
	v_mfma_f32_16x16x32_bf16 v[122:125], v[142:145], v[182:185], v[122:125]
	v_mfma_f32_16x16x32_bf16 v[110:113], v[134:137], v[200:203], v[110:113]
	v_mfma_f32_16x16x32_bf16 v[106:109], v[142:145], v[200:203], v[106:109]
	v_mfma_f32_16x16x32_bf16 v[94:97], v[134:137], v[214:217], v[94:97]
	v_mfma_f32_16x16x32_bf16 v[90:93], v[142:145], v[214:217], v[90:93]
	v_mfma_f32_16x16x32_bf16 v[78:81], v[134:137], v[222:225], v[78:81]
	v_mfma_f32_16x16x32_bf16 v[74:77], v[142:145], v[222:225], v[74:77]
	s_barrier
	s_add_i32 s39, 0, 0x14000
	v_add_u32_e32 v162, s39, v193
	s_add_i32 s26, s38, s84
	ds_read_b128 v[226:229], v162
	ds_read_b128 v[230:233], v162 offset:1024
	ds_read_b128 v[234:237], v162 offset:2048
	ds_read_b128 v[238:241], v162 offset:3072
	v_lshl_add_u64 v[162:163], s[80:81], 0, v[8:9]
	s_mov_b32 m0, s26
	v_lshl_add_u64 v[164:165], s[80:81], 0, v[176:177]
	global_load_lds_dwordx4 v[162:163], off
	s_add_i32 m0, s26, 0x2000
	s_nop 0
	global_load_lds_dwordx4 v[164:165], off
	s_barrier
	s_waitcnt lgkmcnt(0)
	v_mfma_f32_16x16x32_bf16 v[118:121], v[226:229], v[146:149], v[118:121]
	v_mfma_f32_16x16x32_bf16 v[114:117], v[234:237], v[146:149], v[114:117]
	v_mfma_f32_16x16x32_bf16 v[102:105], v[226:229], v[186:189], v[102:105]
	v_mfma_f32_16x16x32_bf16 v[98:101], v[234:237], v[186:189], v[98:101]
	v_mfma_f32_16x16x32_bf16 v[86:89], v[226:229], v[204:207], v[86:89]
	v_mfma_f32_16x16x32_bf16 v[82:85], v[234:237], v[204:207], v[82:85]
	v_mfma_f32_16x16x32_bf16 v[70:73], v[226:229], v[218:221], v[70:73]
	v_mfma_f32_16x16x32_bf16 v[66:69], v[234:237], v[218:221], v[66:69]
	v_mfma_f32_16x16x32_bf16 v[118:121], v[230:233], v[182:185], v[118:121]
	v_mfma_f32_16x16x32_bf16 v[114:117], v[238:241], v[182:185], v[114:117]
	v_mfma_f32_16x16x32_bf16 v[102:105], v[230:233], v[200:203], v[102:105]
	v_mfma_f32_16x16x32_bf16 v[98:101], v[238:241], v[200:203], v[98:101]
	v_mfma_f32_16x16x32_bf16 v[86:89], v[230:233], v[214:217], v[86:89]
	v_mfma_f32_16x16x32_bf16 v[82:85], v[238:241], v[214:217], v[82:85]
	v_mfma_f32_16x16x32_bf16 v[70:73], v[230:233], v[222:225], v[70:73]
	v_mfma_f32_16x16x32_bf16 v[66:69], v[238:241], v[222:225], v[66:69]
	s_mov_b32 m0, s85
	v_lshl_add_u64 v[190:191], s[82:83], 0, v[150:151]
	s_barrier
	ds_read_b128 v[146:149], v198 offset:16384
	ds_read_b128 v[182:185], v198 offset:17408
	ds_read_b128 v[186:189], v198 offset:18432
	ds_read_b128 v[200:203], v198 offset:19456
	ds_read_b128 v[204:207], v198 offset:20480
	ds_read_b128 v[214:217], v198 offset:21504
	ds_read_b128 v[218:221], v198 offset:22528
	ds_read_b128 v[222:225], v198 offset:23552
	global_load_lds_dwordx4 v[190:191], off
	s_mov_b32 m0, s86
	v_lshl_add_u64 v[208:209], s[82:83], 0, v[152:153]
	global_load_lds_dwordx4 v[208:209], off
	s_barrier
	s_waitcnt lgkmcnt(0)
	v_mfma_f32_16x16x32_bf16 v[62:65], v[130:133], v[146:149], v[62:65]
	v_mfma_f32_16x16x32_bf16 v[58:61], v[138:141], v[146:149], v[58:61]
	v_mfma_f32_16x16x32_bf16 v[46:49], v[130:133], v[186:189], v[46:49]
	v_mfma_f32_16x16x32_bf16 v[42:45], v[138:141], v[186:189], v[42:45]
	v_mfma_f32_16x16x32_bf16 v[30:33], v[130:133], v[204:207], v[30:33]
	v_mfma_f32_16x16x32_bf16 v[26:29], v[138:141], v[204:207], v[26:29]
	v_mfma_f32_16x16x32_bf16 v[14:17], v[130:133], v[218:221], v[14:17]
	v_mfma_f32_16x16x32_bf16 v[10:13], v[138:141], v[218:221], v[10:13]
	v_mfma_f32_16x16x32_bf16 v[62:65], v[134:137], v[182:185], v[62:65]
	v_mfma_f32_16x16x32_bf16 v[58:61], v[142:145], v[182:185], v[58:61]
	v_mfma_f32_16x16x32_bf16 v[46:49], v[134:137], v[200:203], v[46:49]
	v_mfma_f32_16x16x32_bf16 v[42:45], v[142:145], v[200:203], v[42:45]
	v_mfma_f32_16x16x32_bf16 v[30:33], v[134:137], v[214:217], v[30:33]
	v_mfma_f32_16x16x32_bf16 v[26:29], v[142:145], v[214:217], v[26:29]
	v_mfma_f32_16x16x32_bf16 v[14:17], v[134:137], v[222:225], v[14:17]
	v_mfma_f32_16x16x32_bf16 v[10:13], v[142:145], v[222:225], v[10:13]
	s_barrier
; #define PG8_STAGE(bufoff, gbase, voff) do { _Pragma("unroll") for (int _i = 0; _i < 2; ++_i) \
;         __builtin_amdgcn_global_load_lds((const unsigned*)((const char*)(gbase) + (voff)[_i]), (LAS unsigned*)(lds + (bufoff) + ldsw + _i * 8192), 16, 0, 0); } while (0)
; #define PG8_LDA(dst, b, h) do { _Pragma("unroll") for (int m = 0; m < 4; ++m) _Pragma("unroll") for (int k = 0; k < 2; ++k) dst[m][k] = *(const LAS bf16x8*)(lds + PG8_SA(b, h) + aoff + m * 2048 + k * 1024); } while (0)
; #define PG8_LDB(dst, b, h) do { _Pragma("unroll") for (int n = 0; n < 2; ++n) _Pragma("unroll") for (int k = 0; k < 2; ++k) dst[n][k] = *(const LAS bf16x8*)(lds + PG8_SB(b, h) + boff + n * 2048 + k * 1024); } while (0)
; #define PG8_MMA(ai, bj, At, Bt) do { __builtin_amdgcn_s_setprio(1); _Pragma("unroll") for (int m = 0; m < 4; ++m) _Pragma("unroll") for (int n = 0; n < 2; ++n) _Pragma("unroll") for (int k = 0; k < 2; ++k) \
;         acc[ai][bj][m][n] = __builtin_amdgcn_mfma_f32_16x16x32_bf16(Bt[n][k], At[m][k], acc[ai][bj][m][n], 0, 0, 0); __builtin_amdgcn_s_setprio(0); } while (0)
; #define PG8_WAIT_V(n) asm volatile("s_waitcnt vmcnt(" #n ")" ::: "memory")
; #define PG8_WAIT_L(n) asm volatile("s_waitcnt lgkmcnt(" #n ")" ::: "memory")
; #define PG8_BAR __builtin_amdgcn_s_barrier()
; #define PG8_SCHED __builtin_amdgcn_sched_barrier(0)
; template <class Epi>
; DEVI void gemm_phase(LAS unsigned char* lds, const Gemm g, const Epi& E) {
;     ...
;             PG8_WAIT_V(6); PG8_BAR; PG8_MMA(1, 1, At, B1); PG8_BAR;
;             PG8_LDB(B0, 1, 0); PG8_SCHED; PG8_LDA(At, 1, 0); PG8_STAGE(PG8_SA(0, 1), a2 + hstepA, voffA);
;             PG8_WAIT_L(8); PG8_BAR; PG8_WAIT_L(0); PG8_MMA(0, 0, At, B0); PG8_BAR; PG8_SCHED;
;             PG8_LDB(B1, 1, 1); PG8_STAGE(PG8_SB(1, 0), b3, voffB);
;             PG8_BAR; PG8_WAIT_L(0); PG8_MMA(0, 1, At, B1); PG8_BAR;
;             PG8_LDA(At, 1, 1); PG8_STAGE(PG8_SA(1, 0), a3, voffA);
;             PG8_BAR; PG8_WAIT_L(0); PG8_MMA(1, 0, At, B0); PG8_BAR; PG8_SCHED;
	s_add_u32 s26, s80, 0x40000
	s_addc_u32 s27, s81, 0
	s_add_i32 s38, s39, s84
	s_mov_b32 m0, s38
	v_lshl_add_u64 v[130:131], s[26:27], 0, v[8:9]
	global_load_lds_dwordx4 v[130:131], off
	s_add_i32 m0, s38, 0x2000
	v_lshl_add_u64 v[130:131], s[26:27], 0, v[176:177]
	global_load_lds_dwordx4 v[130:131], off
	s_waitcnt vmcnt(6)
	s_barrier
	v_mfma_f32_16x16x32_bf16 v[54:57], v[226:229], v[146:149], v[54:57]
	v_mfma_f32_16x16x32_bf16 v[50:53], v[234:237], v[146:149], v[50:53]
	v_mfma_f32_16x16x32_bf16 v[38:41], v[226:229], v[186:189], v[38:41]
	v_mfma_f32_16x16x32_bf16 v[34:37], v[234:237], v[186:189], v[34:37]
	v_mfma_f32_16x16x32_bf16 v[22:25], v[226:229], v[204:207], v[22:25]
	v_mfma_f32_16x16x32_bf16 v[18:21], v[234:237], v[204:207], v[18:21]
	v_mfma_f32_16x16x32_bf16 v[4:7], v[226:229], v[218:221], v[4:7]
	v_mfma_f32_16x16x32_bf16 v[0:3], v[234:237], v[218:221], v[0:3]
	v_mfma_f32_16x16x32_bf16 v[54:57], v[230:233], v[182:185], v[54:57]
	v_mfma_f32_16x16x32_bf16 v[50:53], v[238:241], v[182:185], v[50:53]
	v_mfma_f32_16x16x32_bf16 v[38:41], v[230:233], v[200:203], v[38:41]
	v_mfma_f32_16x16x32_bf16 v[34:37], v[238:241], v[200:203], v[34:37]
	v_mfma_f32_16x16x32_bf16 v[22:25], v[230:233], v[214:217], v[22:25]
	v_mfma_f32_16x16x32_bf16 v[18:21], v[238:241], v[214:217], v[18:21]
	v_mfma_f32_16x16x32_bf16 v[4:7], v[230:233], v[222:225], v[4:7]
	v_mfma_f32_16x16x32_bf16 v[0:3], v[238:241], v[222:225], v[0:3]
	s_add_i32 s38, 0, 0x18000
	v_add_u32_e32 v142, s38, v193
	s_barrier
	ds_read_b128 v[130:133], v142
	ds_read_b128 v[134:137], v142 offset:1024
	ds_read_b128 v[138:141], v142 offset:2048
	ds_read_b128 v[142:145], v142 offset:3072
	s_add_u32 s26, s82, 0x40000
	s_addc_u32 s27, s83, 0
	s_mov_b32 m0, s87
	v_lshl_add_u64 v[226:227], s[26:27], 0, v[150:151]
	ds_read_b128 v[146:149], v198 offset:32768
	ds_read_b128 v[182:185], v198 offset:33792
	ds_read_b128 v[186:189], v198 offset:34816
	ds_read_b128 v[200:203], v198 offset:35840
	ds_read_b128 v[204:207], v198 offset:36864
	ds_read_b128 v[214:217], v198 offset:37888
	ds_read_b128 v[218:221], v198 offset:38912
	ds_read_b128 v[222:225], v198 offset:39936
	global_load_lds_dwordx4 v[226:227], off
	s_mov_b32 m0, s88
	v_lshl_add_u64 v[226:227], s[26:27], 0, v[152:153]
	global_load_lds_dwordx4 v[226:227], off
	s_waitcnt lgkmcnt(8)
	s_barrier
	s_waitcnt lgkmcnt(0)
	v_mfma_f32_16x16x32_bf16 v[126:129], v[130:133], v[146:149], v[126:129]
	v_mfma_f32_16x16x32_bf16 v[122:125], v[138:141], v[146:149], v[122:125]
	v_mfma_f32_16x16x32_bf16 v[110:113], v[130:133], v[186:189], v[110:113]
	v_mfma_f32_16x16x32_bf16 v[106:109], v[138:141], v[186:189], v[106:109]
	v_mfma_f32_16x16x32_bf16 v[94:97], v[130:133], v[204:207], v[94:97]
	v_mfma_f32_16x16x32_bf16 v[90:93], v[138:141], v[204:207], v[90:93]
	v_mfma_f32_16x16x32_bf16 v[78:81], v[130:133], v[218:221], v[78:81]
	v_mfma_f32_16x16x32_bf16 v[74:77], v[138:141], v[218:221], v[74:77]
	v_mfma_f32_16x16x32_bf16 v[126:129], v[134:137], v[182:185], v[126:129]
	v_mfma_f32_16x16x32_bf16 v[122:125], v[142:145], v[182:185], v[122:125]
	v_mfma_f32_16x16x32_bf16 v[110:113], v[134:137], v[200:203], v[110:113]
	v_mfma_f32_16x16x32_bf16 v[106:109], v[142:145], v[200:203], v[106:109]
	v_mfma_f32_16x16x32_bf16 v[94:97], v[134:137], v[214:217], v[94:97]
	v_mfma_f32_16x16x32_bf16 v[90:93], v[142:145], v[214:217], v[90:93]
	v_mfma_f32_16x16x32_bf16 v[78:81], v[134:137], v[222:225], v[78:81]
	v_mfma_f32_16x16x32_bf16 v[74:77], v[142:145], v[222:225], v[74:77]
	s_barrier
	s_add_i32 s39, 0, 0x1c000
	s_add_i32 s26, s38, s84
	v_add_u32_e32 v199, s39, v193
	v_lshl_add_u64 v[162:163], v[162:163], 0, s[70:71]
	s_mov_b32 m0, s26
	ds_read_b128 v[226:229], v199
	ds_read_b128 v[230:233], v199 offset:1024
	ds_read_b128 v[234:237], v199 offset:2048
	ds_read_b128 v[238:241], v199 offset:3072
	global_load_lds_dwordx4 v[162:163], off
	s_add_i32 m0, s26, 0x2000
	v_lshl_add_u64 v[162:163], v[164:165], 0, s[70:71]
	global_load_lds_dwordx4 v[162:163], off
	s_barrier
	s_waitcnt lgkmcnt(0)
	v_mfma_f32_16x16x32_bf16 v[118:121], v[226:229], v[146:149], v[118:121]
	v_mfma_f32_16x16x32_bf16 v[114:117], v[234:237], v[146:149], v[114:117]
	v_mfma_f32_16x16x32_bf16 v[102:105], v[226:229], v[186:189], v[102:105]
	v_mfma_f32_16x16x32_bf16 v[98:101], v[234:237], v[186:189], v[98:101]
	v_mfma_f32_16x16x32_bf16 v[86:89], v[226:229], v[204:207], v[86:89]
	v_mfma_f32_16x16x32_bf16 v[82:85], v[234:237], v[204:207], v[82:85]
	v_mfma_f32_16x16x32_bf16 v[70:73], v[226:229], v[218:221], v[70:73]
	v_mfma_f32_16x16x32_bf16 v[66:69], v[234:237], v[218:221], v[66:69]
	v_mfma_f32_16x16x32_bf16 v[118:121], v[230:233], v[182:185], v[118:121]
	v_mfma_f32_16x16x32_bf16 v[114:117], v[238:241], v[182:185], v[114:117]
	v_mfma_f32_16x16x32_bf16 v[102:105], v[230:233], v[200:203], v[102:105]
	v_mfma_f32_16x16x32_bf16 v[98:101], v[238:241], v[200:203], v[98:101]
	v_mfma_f32_16x16x32_bf16 v[86:89], v[230:233], v[214:217], v[86:89]
	v_mfma_f32_16x16x32_bf16 v[82:85], v[238:241], v[214:217], v[82:85]
	v_mfma_f32_16x16x32_bf16 v[70:73], v[230:233], v[222:225], v[70:73]
	v_mfma_f32_16x16x32_bf16 v[66:69], v[238:241], v[222:225], v[66:69]
	s_mov_b32 m0, s89
	v_lshl_add_u64 v[162:163], v[190:191], 0, s[70:71]
	s_barrier
	ds_read_b128 v[146:149], v198 offset:49152
	ds_read_b128 v[182:185], v198 offset:50176
	ds_read_b128 v[186:189], v198 offset:51200
	ds_read_b128 v[200:203], v198 offset:52224
	ds_read_b128 v[204:207], v198 offset:53248
	ds_read_b128 v[214:217], v198 offset:54272
	ds_read_b128 v[218:221], v198 offset:55296
	ds_read_b128 v[222:225], v198 offset:56320
	global_load_lds_dwordx4 v[162:163], off
	s_mov_b32 m0, s90
	v_lshl_add_u64 v[162:163], v[208:209], 0, s[70:71]
	global_load_lds_dwordx4 v[162:163], off
	s_barrier
; #define LAS __attribute__((address_space(3)))
; #define PG8_WAIT_V(n) asm volatile("s_waitcnt vmcnt(" #n ")" ::: "memory")
; #define PG8_WAIT_L(n) asm volatile("s_waitcnt lgkmcnt(" #n ")" ::: "memory")
; #define PG8_BAR __builtin_amdgcn_s_barrier()
; template <class Epi>
; DEVI void gemm_phase(LAS unsigned char* lds, const Gemm g, const Epi& E) {
;     ...
;             PG8_BAR; PG8_WAIT_L(0); PG8_MMA(1, 0, At, B0); PG8_BAR; PG8_SCHED;
;             PG8_STAGE(PG8_SB(1, 1), b3 + hstepB, voffB);
;             PG8_WAIT_V(6); PG8_BAR; PG8_MMA(1, 1, At, B1); PG8_BAR;
;         }
;     ...
;             for (int am = 0; am < 4; ++am) {
;                 const int ai = am >> 1, m0 = (am & 1) * 2;
;                 f32x4 pre[2][2][2];
;                 if constexpr (Epi::PRE) {
; #pragma unroll
;                     for (int m = 0; m < 2; ++m)
; #pragma unroll
;                         for (int bj = 0; bj < 2; ++bj)
; #pragma unroll
;                             for (int n = 0; n < 2; ++n) pre[m][bj][n] = E.load(row0 + ai * HALF + (m0 + m) * 16, col0 + bj * HALF + n * NST);
;                 }
; #pragma unroll
;                 for (int mm = 0; mm < 2; ++mm) {
;                     const int m = m0 + mm;
;                     const int r = row0 + ai * HALF + m * 16; float rs = 1.f, part = 0.f;
;                     if constexpr (Epi::RS) rs = rsv[ai * 4 + m];
;                     if constexpr (Epi::PAIR) E.pair8(cur.b, r, cur.pn * HALF + wc * 32 + 8 * fq, acc[ai][0][m][0] * rs, acc[ai][0][m][1] * rs, acc[ai][1][m][0] * rs, acc[ai][1][m][1] * rs);
;                     else
; #pragma unroll
;                     for (int bj = 0; bj < 2; ++bj) {
;                         const int c = col0 + bj * HALF; f32x4 v0 = acc[ai][bj][m][0], v1 = acc[ai][bj][m][1];
;                         if constexpr (Epi::RS) { v0 = v0 * rs; v1 = v1 * rs; }
;                         if constexpr (Epi::PRE) part += E.frag_pre8(cur.b, r, c, v0, v1, pre[mm][bj][0], pre[mm][bj][1]);
;                         else if constexpr (Epi::PERM) E.frag8(cur.b, r, c, v0, v1);
;                         else { E.frag(cur.b, r, c, v0); E.frag(cur.b, r, c + 16, v1); }
;                     }
;                     if constexpr (Epi::SSQ) { part += __shfl_xor(part, 16); part += __shfl_xor(part, 32); if (fq == 0) ((LAS float*)(lds + 131072))[(wr * 4 + wc) * 128 + ai * 64 + m * 16 + fr] = part; }
	s_waitcnt lgkmcnt(0)
	v_mfma_f32_16x16x32_bf16 v[62:65], v[130:133], v[146:149], v[62:65]
	v_mfma_f32_16x16x32_bf16 v[58:61], v[138:141], v[146:149], v[58:61]
	v_mfma_f32_16x16x32_bf16 v[46:49], v[130:133], v[186:189], v[46:49]
	v_mfma_f32_16x16x32_bf16 v[42:45], v[138:141], v[186:189], v[42:45]
	v_mfma_f32_16x16x32_bf16 v[30:33], v[130:133], v[204:207], v[30:33]
	v_mfma_f32_16x16x32_bf16 v[26:29], v[138:141], v[204:207], v[26:29]
	v_mfma_f32_16x16x32_bf16 v[14:17], v[130:133], v[218:221], v[14:17]
	v_mfma_f32_16x16x32_bf16 v[10:13], v[138:141], v[218:221], v[10:13]
	v_mfma_f32_16x16x32_bf16 v[62:65], v[134:137], v[182:185], v[62:65]
	v_mfma_f32_16x16x32_bf16 v[58:61], v[142:145], v[182:185], v[58:61]
	v_mfma_f32_16x16x32_bf16 v[46:49], v[134:137], v[200:203], v[46:49]
	v_mfma_f32_16x16x32_bf16 v[42:45], v[142:145], v[200:203], v[42:45]
	v_mfma_f32_16x16x32_bf16 v[30:33], v[134:137], v[214:217], v[30:33]
	v_mfma_f32_16x16x32_bf16 v[26:29], v[142:145], v[214:217], v[26:29]
	v_mfma_f32_16x16x32_bf16 v[14:17], v[134:137], v[222:225], v[14:17]
	v_mfma_f32_16x16x32_bf16 v[10:13], v[142:145], v[222:225], v[10:13]
	s_barrier
	s_add_u32 s26, s80, 0x40080
	s_addc_u32 s27, s81, 0
	s_add_i32 s38, s39, s84
	s_mov_b32 m0, s38
	v_lshl_add_u64 v[130:131], s[26:27], 0, v[8:9]
	global_load_lds_dwordx4 v[130:131], off
	s_add_i32 m0, s38, 0x2000
	v_lshl_add_u64 v[130:131], s[26:27], 0, v[176:177]
	global_load_lds_dwordx4 v[130:131], off
	s_waitcnt vmcnt(6)
	s_barrier
	v_mfma_f32_16x16x32_bf16 v[54:57], v[226:229], v[146:149], v[54:57]
	v_mfma_f32_16x16x32_bf16 v[50:53], v[234:237], v[146:149], v[50:53]
	v_mfma_f32_16x16x32_bf16 v[38:41], v[226:229], v[186:189], v[38:41]
	v_mfma_f32_16x16x32_bf16 v[34:37], v[234:237], v[186:189], v[34:37]
	v_mfma_f32_16x16x32_bf16 v[22:25], v[226:229], v[204:207], v[22:25]
	v_mfma_f32_16x16x32_bf16 v[18:21], v[234:237], v[204:207], v[18:21]
	v_mfma_f32_16x16x32_bf16 v[4:7], v[226:229], v[218:221], v[4:7]
	v_mfma_f32_16x16x32_bf16 v[0:3], v[234:237], v[218:221], v[0:3]
	v_mfma_f32_16x16x32_bf16 v[54:57], v[230:233], v[182:185], v[54:57]
	v_mfma_f32_16x16x32_bf16 v[50:53], v[238:241], v[182:185], v[50:53]
	v_mfma_f32_16x16x32_bf16 v[38:41], v[230:233], v[200:203], v[38:41]
	v_mfma_f32_16x16x32_bf16 v[34:37], v[238:241], v[200:203], v[34:37]
	v_mfma_f32_16x16x32_bf16 v[22:25], v[230:233], v[214:217], v[22:25]
	v_mfma_f32_16x16x32_bf16 v[18:21], v[238:241], v[214:217], v[18:21]
	v_mfma_f32_16x16x32_bf16 v[4:7], v[230:233], v[222:225], v[4:7]
	v_mfma_f32_16x16x32_bf16 v[0:3], v[238:241], v[222:225], v[0:3]
	s_add_i32 s19, s19, 2
	s_add_u32 s68, s68, 0x100
	s_addc_u32 s69, s69, 0
	s_add_u32 s15, s15, 0x100
	s_addc_u32 s18, s18, 0
	s_cmp_gt_u32 s19, 13
	s_barrier
	s_cbranch_scc0 .LBB0_968
	s_setprio 0
	v_and_b32_e32 v131, 64, v155
	v_xor_b32_e32 v130, 16, v155
	v_add_u32_e32 v131, 64, v131
	v_cmp_lt_i32_e32 vcc, v130, v131
	s_lshl_b32 s9, s46, 8
	v_add_u32_e32 v186, s9, v192
	v_cndmask_b32_e32 v130, v155, v130, vcc
	v_lshlrev_b32_e32 v200, 2, v130
	v_xor_b32_e32 v130, 32, v155
	v_cmp_lt_i32_e32 vcc, v130, v131
	v_lshl_or_b32 v184, s8, 8, v197
	v_ashrrev_i32_e32 v187, 31, v186
	v_cndmask_b32_e32 v130, v155, v130, vcc
	v_lshlrev_b32_e32 v199, 2, v130
	v_lshlrev_b64 v[130:131], 12, v[186:187]
	v_ashrrev_i32_e32 v185, 31, v184
	v_lshl_add_u64 v[130:131], s[78:79], 0, v[130:131]
	v_lshlrev_b64 v[188:189], 2, v[184:185]
	v_lshl_add_u64 v[130:131], v[130:131], 0, v[188:189]
	global_load_dwordx4 v[202:205], v[130:131], off offset:16
	global_load_dwordx4 v[206:209], v[130:131], off
	global_load_dwordx4 v[146:149], v[130:131], off offset:528
	global_load_dwordx4 v[214:217], v[130:131], off offset:512
	v_or_b32_e32 v190, 16, v186
	v_ashrrev_i32_e32 v191, 31, v190
	v_lshlrev_b64 v[130:131], 12, v[190:191]
	v_lshl_add_u64 v[130:131], s[78:79], 0, v[130:131]
	v_lshl_add_u64 v[134:135], v[130:131], 0, v[188:189]
	global_load_dwordx4 v[138:141], v[134:135], off offset:16
	global_load_dwordx4 v[142:145], v[134:135], off
	global_load_dwordx4 v[130:133], v[134:135], off offset:528
	s_nop 0
	global_load_dwordx4 v[134:137], v[134:135], off offset:512
	v_lshlrev_b64 v[162:163], 10, v[186:187]
	v_lshl_add_u64 v[164:165], v[162:163], 0, v[184:185]
	v_or_b32_e32 v182, 0x80, v184
	v_ashrrev_i32_e32 v183, 31, v182
	s_waitcnt vmcnt(0)
	v_pk_add_f32 v[122:123], v[122:123], v[202:203]
	v_pk_add_f32 v[128:129], v[128:129], v[208:209]
	v_pk_add_f32 v[126:127], v[126:127], v[206:207]
	v_lshl_add_u64 v[206:207], v[164:165], 2, s[30:31]
	v_pk_add_f32 v[124:125], v[124:125], v[204:205]
	global_store_dwordx4 v[206:207], v[126:129], off
	global_store_dwordx4 v[206:207], v[122:125], off offset:16
	v_cvt_pk_bf16_f32 v202, v126, v127
	v_cvt_pk_bf16_f32 v204, v122, v123
	v_mul_f32_e32 v127, v127, v127
	v_mul_f32_e32 v123, v123, v123
	v_fmac_f32_e32 v127, v126, v126
	v_mul_f32_e32 v126, v129, v129
	v_fmac_f32_e32 v123, v122, v122
	v_mul_f32_e32 v122, v125, v125
	v_fmac_f32_e32 v126, v128, v128
	v_fmac_f32_e32 v122, v124, v124
	v_cvt_pk_bf16_f32 v203, v128, v129
	v_cvt_pk_bf16_f32 v205, v124, v125
	v_lshl_add_u64 v[164:165], v[164:165], 1, s[28:29]
	v_add_f32_e32 v126, v127, v126
	v_add_f32_e32 v122, v123, v122
	v_pk_add_f32 v[120:121], v[120:121], v[216:217]
	v_pk_add_f32 v[118:119], v[118:119], v[214:215]
	v_pk_add_f32 v[114:115], v[114:115], v[146:147]
	global_store_dwordx4 v[164:165], v[202:205], off
	v_add_f32_e32 v128, v126, v122
	v_pk_add_f32 v[116:117], v[116:117], v[148:149]
	global_store_dwordx4 v[206:207], v[118:121], off offset:512
	global_store_dwordx4 v[206:207], v[114:117], off offset:528
	v_cvt_pk_bf16_f32 v122, v118, v119
	v_cvt_pk_bf16_f32 v124, v114, v115
	v_mul_f32_e32 v119, v119, v119
	v_mul_f32_e32 v115, v115, v115
	v_fmac_f32_e32 v119, v118, v118
	v_mul_f32_e32 v118, v121, v121
	v_fmac_f32_e32 v115, v114, v114
	v_mul_f32_e32 v114, v117, v117
	v_fmac_f32_e32 v118, v120, v120
	v_fmac_f32_e32 v114, v116, v116
	v_add_f32_e32 v118, v119, v118
	v_add_f32_e32 v114, v115, v114
	v_add_f32_e32 v114, v118, v114
	v_add_f32_e32 v114, v128, v114
	ds_bpermute_b32 v115, v200, v114
	v_lshl_add_u64 v[126:127], v[162:163], 0, v[182:183]
	v_cvt_pk_bf16_f32 v123, v120, v121
	v_cvt_pk_bf16_f32 v125, v116, v117
	v_lshl_add_u64 v[126:127], v[126:127], 1, s[28:29]
	s_waitcnt lgkmcnt(0)
	v_add_f32_e32 v114, v114, v115
	ds_bpermute_b32 v115, v199, v114
	global_store_dwordx4 v[126:127], v[122:125], off
	s_and_saveexec_b64 s[46:47], s[2:3]
	s_cbranch_execz .LBB0_971
	s_waitcnt lgkmcnt(0)
	v_add_f32_e32 v114, v114, v115
	ds_write_b32 v194, v114

; #define PG8_STAGE(bufoff, gbase, voff) do { _Pragma("unroll") for (int _i = 0; _i < 2; ++_i) \
;         __builtin_amdgcn_global_load_lds((const unsigned*)((const char*)(gbase) + (voff)[_i]), (LAS unsigned*)(lds + (bufoff) + ldsw + _i * 8192), 16, 0, 0); } while (0)
; #define PG8_LDA(dst, b, h) do { _Pragma("unroll") for (int m = 0; m < 4; ++m) _Pragma("unroll") for (int k = 0; k < 2; ++k) dst[m][k] = *(const LAS bf16x8*)(lds + PG8_SA(b, h) + aoff + m * 2048 + k * 1024); } while (0)
; #define PG8_LDB(dst, b, h) do { _Pragma("unroll") for (int n = 0; n < 2; ++n) _Pragma("unroll") for (int k = 0; k < 2; ++k) dst[n][k] = *(const LAS bf16x8*)(lds + PG8_SB(b, h) + boff + n * 2048 + k * 1024); } while (0)
; #define PG8_MMA(ai, bj, At, Bt) do { __builtin_amdgcn_s_setprio(1); _Pragma("unroll") for (int m = 0; m < 4; ++m) _Pragma("unroll") for (int n = 0; n < 2; ++n) _Pragma("unroll") for (int k = 0; k < 2; ++k) \
;         acc[ai][bj][m][n] = __builtin_amdgcn_mfma_f32_16x16x32_bf16(Bt[n][k], At[m][k], acc[ai][bj][m][n], 0, 0, 0); __builtin_amdgcn_s_setprio(0); } while (0)
; #define PG8_WAIT_V(n) asm volatile("s_waitcnt vmcnt(" #n ")" ::: "memory")
; #define PG8_WAIT_L(n) asm volatile("s_waitcnt lgkmcnt(" #n ")" ::: "memory")
; #define PG8_BAR __builtin_amdgcn_s_barrier()
; #define PG8_SCHED __builtin_amdgcn_sched_barrier(0)
; template <class Epi>
; DEVI void gemm_phase(LAS unsigned char* lds, const Gemm g, const Epi& E) {
;     ...
;             PG8_LDB(B0, 0, 0); PG8_SCHED; PG8_LDA(At, 0, 0); PG8_STAGE(PG8_SA(1, 1), a1 + hstepA, voffA);
;             PG8_WAIT_L(8); PG8_BAR; PG8_WAIT_L(0); PG8_MMA(0, 0, At, B0); PG8_BAR; PG8_SCHED;
;             PG8_LDB(B1, 0, 1); PG8_STAGE(PG8_SB(0, 0), b2, voffB);
;             PG8_BAR; PG8_WAIT_L(0); PG8_MMA(0, 1, At, B1); PG8_BAR;
;             PG8_LDA(At, 0, 1); PG8_STAGE(PG8_SA(0, 0), a2, voffA);
;             PG8_BAR; PG8_WAIT_L(0); PG8_MMA(1, 0, At, B0); PG8_BAR; PG8_SCHED;
;             PG8_STAGE(PG8_SB(0, 1), b2 + hstepB, voffB);
;             PG8_WAIT_V(6); PG8_BAR; PG8_MMA(1, 1, At, B1); PG8_BAR;
.LBB0_1007:
	s_add_u32 s16, s14, 0xfffc0080
	s_addc_u32 s17, s15, -1
	s_add_i32 s26, 0, 0x10000
	v_add_u32_e32 v8, s26, v199
	ds_read_b128 v[130:133], v8
	ds_read_b128 v[134:137], v8 offset:1024
	ds_read_b128 v[138:141], v8 offset:2048
	ds_read_b128 v[142:145], v8 offset:3072
	s_cmp_eq_u32 s19, 12
	s_cselect_b32 s37, s0, s17
	s_cselect_b32 s36, s1, s16
	s_cselect_b32 s17, s5, s18
	s_cselect_b32 s16, s7, s9
	v_lshl_add_u64 v[162:163], s[14:15], 0, v[180:181]
	s_add_i32 m0, s66, 0xc000
	ds_read_b128 v[184:187], v204
	ds_read_b128 v[188:191], v204 offset:1024
	ds_read_b128 v[192:195], v204 offset:2048
	ds_read_b128 v[206:209], v204 offset:3072
	ds_read_b128 v[214:217], v204 offset:4096
	ds_read_b128 v[218:221], v204 offset:5120
	ds_read_b128 v[222:225], v204 offset:6144
	ds_read_b128 v[226:229], v204 offset:7168
	global_load_lds_dwordx4 v[162:163], off
	s_add_i32 m0, s66, 0xe000
	v_lshl_add_u64 v[162:163], s[14:15], 0, v[182:183]
	global_load_lds_dwordx4 v[162:163], off
	s_waitcnt lgkmcnt(8)
	s_barrier
	s_waitcnt lgkmcnt(0)
	v_mfma_f32_16x16x32_bf16 v[126:129], v[130:133], v[184:187], v[126:129]
	v_mfma_f32_16x16x32_bf16 v[122:125], v[138:141], v[184:187], v[122:125]
	v_mfma_f32_16x16x32_bf16 v[114:117], v[130:133], v[192:195], v[114:117]
	v_mfma_f32_16x16x32_bf16 v[106:109], v[138:141], v[192:195], v[106:109]
	v_mfma_f32_16x16x32_bf16 v[102:105], v[130:133], v[214:217], v[102:105]
	v_mfma_f32_16x16x32_bf16 v[94:97], v[138:141], v[214:217], v[94:97]
	v_mfma_f32_16x16x32_bf16 v[82:85], v[130:133], v[222:225], v[82:85]
	v_mfma_f32_16x16x32_bf16 v[74:77], v[138:141], v[222:225], v[74:77]
	v_mfma_f32_16x16x32_bf16 v[126:129], v[134:137], v[188:191], v[126:129]
	v_mfma_f32_16x16x32_bf16 v[122:125], v[142:145], v[188:191], v[122:125]
	v_mfma_f32_16x16x32_bf16 v[114:117], v[134:137], v[206:209], v[114:117]
	v_mfma_f32_16x16x32_bf16 v[106:109], v[142:145], v[206:209], v[106:109]
	v_mfma_f32_16x16x32_bf16 v[102:105], v[134:137], v[218:221], v[102:105]
	v_mfma_f32_16x16x32_bf16 v[94:97], v[142:145], v[218:221], v[94:97]
	v_mfma_f32_16x16x32_bf16 v[82:85], v[134:137], v[226:229], v[82:85]
	v_mfma_f32_16x16x32_bf16 v[74:77], v[142:145], v[226:229], v[74:77]
	s_barrier
	s_add_i32 s38, 0, 0x14000
	s_add_i32 s26, s26, s47
	v_add_u32_e32 v8, s38, v199
	v_lshl_add_u64 v[162:163], s[16:17], 0, v[148:149]
	s_mov_b32 m0, s26
	ds_read_b128 v[230:233], v8
	ds_read_b128 v[234:237], v8 offset:1024
	ds_read_b128 v[238:241], v8 offset:2048
	ds_read_b128 v[242:245], v8 offset:3072
	global_load_lds_dwordx4 v[162:163], off
	s_add_i32 m0, s26, 0x2000
	v_lshl_add_u64 v[164:165], s[16:17], 0, v[152:153]
	global_load_lds_dwordx4 v[164:165], off
	s_barrier
	s_waitcnt lgkmcnt(0)
	v_mfma_f32_16x16x32_bf16 v[118:121], v[230:233], v[184:187], v[118:121]
	v_mfma_f32_16x16x32_bf16 v[110:113], v[238:241], v[184:187], v[110:113]
	v_mfma_f32_16x16x32_bf16 v[98:101], v[230:233], v[192:195], v[98:101]
	v_mfma_f32_16x16x32_bf16 v[90:93], v[238:241], v[192:195], v[90:93]
	v_mfma_f32_16x16x32_bf16 v[86:89], v[230:233], v[214:217], v[86:89]
	v_mfma_f32_16x16x32_bf16 v[78:81], v[238:241], v[214:217], v[78:81]
	v_mfma_f32_16x16x32_bf16 v[54:57], v[230:233], v[222:225], v[54:57]
	v_mfma_f32_16x16x32_bf16 v[34:37], v[238:241], v[222:225], v[34:37]
	v_mfma_f32_16x16x32_bf16 v[118:121], v[234:237], v[188:191], v[118:121]
	v_mfma_f32_16x16x32_bf16 v[110:113], v[242:245], v[188:191], v[110:113]
	v_mfma_f32_16x16x32_bf16 v[98:101], v[234:237], v[206:209], v[98:101]
	v_mfma_f32_16x16x32_bf16 v[90:93], v[242:245], v[206:209], v[90:93]
	v_mfma_f32_16x16x32_bf16 v[86:89], v[234:237], v[218:221], v[86:89]
	v_mfma_f32_16x16x32_bf16 v[78:81], v[242:245], v[218:221], v[78:81]
	v_mfma_f32_16x16x32_bf16 v[54:57], v[234:237], v[226:229], v[54:57]
	v_mfma_f32_16x16x32_bf16 v[34:37], v[242:245], v[226:229], v[34:37]
	s_mov_b32 m0, s66
	v_lshl_add_u64 v[202:203], s[36:37], 0, v[146:147]
	s_barrier
	ds_read_b128 v[184:187], v204 offset:16384
	ds_read_b128 v[188:191], v204 offset:17408
	ds_read_b128 v[192:195], v204 offset:18432
	ds_read_b128 v[206:209], v204 offset:19456
	ds_read_b128 v[214:217], v204 offset:20480
	ds_read_b128 v[218:221], v204 offset:21504
	ds_read_b128 v[222:225], v204 offset:22528
	ds_read_b128 v[226:229], v204 offset:23552
	global_load_lds_dwordx4 v[202:203], off
	s_mov_b32 m0, s68
	v_lshl_add_u64 v[246:247], s[36:37], 0, v[150:151]
	global_load_lds_dwordx4 v[246:247], off
	s_barrier
	s_waitcnt lgkmcnt(0)
	v_mfma_f32_16x16x32_bf16 v[58:61], v[130:133], v[184:187], v[58:61]
	v_mfma_f32_16x16x32_bf16 v[62:65], v[138:141], v[184:187], v[62:65]
	v_mfma_f32_16x16x32_bf16 v[38:41], v[130:133], v[192:195], v[38:41]
	v_mfma_f32_16x16x32_bf16 v[42:45], v[138:141], v[192:195], v[42:45]
	v_mfma_f32_16x16x32_bf16 v[18:21], v[130:133], v[214:217], v[18:21]
	v_mfma_f32_16x16x32_bf16 v[22:25], v[138:141], v[214:217], v[22:25]
	v_mfma_f32_16x16x32_bf16 v[0:3], v[130:133], v[222:225], v[0:3]
	v_mfma_f32_16x16x32_bf16 v[4:7], v[138:141], v[222:225], v[4:7]
	v_mfma_f32_16x16x32_bf16 v[58:61], v[134:137], v[188:191], v[58:61]
	v_mfma_f32_16x16x32_bf16 v[62:65], v[142:145], v[188:191], v[62:65]
	v_mfma_f32_16x16x32_bf16 v[38:41], v[134:137], v[206:209], v[38:41]
	v_mfma_f32_16x16x32_bf16 v[42:45], v[142:145], v[206:209], v[42:45]
	v_mfma_f32_16x16x32_bf16 v[18:21], v[134:137], v[218:221], v[18:21]
	v_mfma_f32_16x16x32_bf16 v[22:25], v[142:145], v[218:221], v[22:25]
	v_mfma_f32_16x16x32_bf16 v[0:3], v[134:137], v[226:229], v[0:3]
	v_mfma_f32_16x16x32_bf16 v[4:7], v[142:145], v[226:229], v[4:7]
	s_barrier
; #define PG8_STAGE(bufoff, gbase, voff) do { _Pragma("unroll") for (int _i = 0; _i < 2; ++_i) \
;         __builtin_amdgcn_global_load_lds((const unsigned*)((const char*)(gbase) + (voff)[_i]), (LAS unsigned*)(lds + (bufoff) + ldsw + _i * 8192), 16, 0, 0); } while (0)
; #define PG8_LDA(dst, b, h) do { _Pragma("unroll") for (int m = 0; m < 4; ++m) _Pragma("unroll") for (int k = 0; k < 2; ++k) dst[m][k] = *(const LAS bf16x8*)(lds + PG8_SA(b, h) + aoff + m * 2048 + k * 1024); } while (0)
; #define PG8_LDB(dst, b, h) do { _Pragma("unroll") for (int n = 0; n < 2; ++n) _Pragma("unroll") for (int k = 0; k < 2; ++k) dst[n][k] = *(const LAS bf16x8*)(lds + PG8_SB(b, h) + boff + n * 2048 + k * 1024); } while (0)
; #define PG8_MMA(ai, bj, At, Bt) do { __builtin_amdgcn_s_setprio(1); _Pragma("unroll") for (int m = 0; m < 4; ++m) _Pragma("unroll") for (int n = 0; n < 2; ++n) _Pragma("unroll") for (int k = 0; k < 2; ++k) \
;         acc[ai][bj][m][n] = __builtin_amdgcn_mfma_f32_16x16x32_bf16(Bt[n][k], At[m][k], acc[ai][bj][m][n], 0, 0, 0); __builtin_amdgcn_s_setprio(0); } while (0)
; #define PG8_WAIT_V(n) asm volatile("s_waitcnt vmcnt(" #n ")" ::: "memory")
; #define PG8_WAIT_L(n) asm volatile("s_waitcnt lgkmcnt(" #n ")" ::: "memory")
; #define PG8_BAR __builtin_amdgcn_s_barrier()
; #define PG8_SCHED __builtin_amdgcn_sched_barrier(0)
; template <class Epi>
; DEVI void gemm_phase(LAS unsigned char* lds, const Gemm g, const Epi& E) {
;     ...
;             PG8_WAIT_V(6); PG8_BAR; PG8_MMA(1, 1, At, B1); PG8_BAR;
;             PG8_LDB(B0, 1, 0); PG8_SCHED; PG8_LDA(At, 1, 0); PG8_STAGE(PG8_SA(0, 1), a2 + hstepA, voffA);
;             PG8_WAIT_L(8); PG8_BAR; PG8_WAIT_L(0); PG8_MMA(0, 0, At, B0); PG8_BAR; PG8_SCHED;
;             PG8_LDB(B1, 1, 1); PG8_STAGE(PG8_SB(1, 0), b3, voffB);
;             PG8_BAR; PG8_WAIT_L(0); PG8_MMA(0, 1, At, B1); PG8_BAR;
;             PG8_LDA(At, 1, 1); PG8_STAGE(PG8_SA(1, 0), a3, voffA);
;             PG8_BAR; PG8_WAIT_L(0); PG8_MMA(1, 0, At, B0); PG8_BAR; PG8_SCHED;
	s_add_u32 s26, s16, 0x40000
	s_addc_u32 s27, s17, 0
	s_add_i32 s38, s38, s47
	s_mov_b32 m0, s38
	v_lshl_add_u64 v[130:131], s[26:27], 0, v[148:149]
	global_load_lds_dwordx4 v[130:131], off
	s_add_i32 m0, s38, 0x2000
	v_lshl_add_u64 v[130:131], s[26:27], 0, v[152:153]
	global_load_lds_dwordx4 v[130:131], off
	s_waitcnt vmcnt(6)
	s_barrier
	v_mfma_f32_16x16x32_bf16 v[66:69], v[230:233], v[184:187], v[66:69]
	v_mfma_f32_16x16x32_bf16 v[70:73], v[238:241], v[184:187], v[70:73]
	v_mfma_f32_16x16x32_bf16 v[46:49], v[230:233], v[192:195], v[46:49]
	v_mfma_f32_16x16x32_bf16 v[50:53], v[238:241], v[192:195], v[50:53]
	v_mfma_f32_16x16x32_bf16 v[26:29], v[230:233], v[214:217], v[26:29]
	v_mfma_f32_16x16x32_bf16 v[30:33], v[238:241], v[214:217], v[30:33]
	v_mfma_f32_16x16x32_bf16 v[10:13], v[230:233], v[222:225], v[10:13]
	v_mfma_f32_16x16x32_bf16 v[14:17], v[238:241], v[222:225], v[14:17]
	v_mfma_f32_16x16x32_bf16 v[66:69], v[234:237], v[188:191], v[66:69]
	v_mfma_f32_16x16x32_bf16 v[70:73], v[242:245], v[188:191], v[70:73]
	v_mfma_f32_16x16x32_bf16 v[46:49], v[234:237], v[206:209], v[46:49]
	v_mfma_f32_16x16x32_bf16 v[50:53], v[242:245], v[206:209], v[50:53]
	v_mfma_f32_16x16x32_bf16 v[26:29], v[234:237], v[218:221], v[26:29]
	v_mfma_f32_16x16x32_bf16 v[30:33], v[242:245], v[218:221], v[30:33]
	v_mfma_f32_16x16x32_bf16 v[10:13], v[234:237], v[226:229], v[10:13]
	v_mfma_f32_16x16x32_bf16 v[14:17], v[242:245], v[226:229], v[14:17]
	s_add_i32 s38, 0, 0x18000
	v_add_u32_e32 v8, s38, v199
	s_barrier
	ds_read_b128 v[130:133], v8
	ds_read_b128 v[134:137], v8 offset:1024
	ds_read_b128 v[138:141], v8 offset:2048
	ds_read_b128 v[142:145], v8 offset:3072
	s_add_u32 s26, s36, 0x40000
	s_addc_u32 s27, s37, 0
	s_mov_b32 m0, s69
	v_lshl_add_u64 v[230:231], s[26:27], 0, v[146:147]
	ds_read_b128 v[184:187], v204 offset:32768
	ds_read_b128 v[188:191], v204 offset:33792
	ds_read_b128 v[192:195], v204 offset:34816
	ds_read_b128 v[206:209], v204 offset:35840
	ds_read_b128 v[214:217], v204 offset:36864
	ds_read_b128 v[218:221], v204 offset:37888
	ds_read_b128 v[222:225], v204 offset:38912
	ds_read_b128 v[226:229], v204 offset:39936
	global_load_lds_dwordx4 v[230:231], off
	s_mov_b32 m0, s80
	v_lshl_add_u64 v[230:231], s[26:27], 0, v[150:151]
	global_load_lds_dwordx4 v[230:231], off
	s_waitcnt lgkmcnt(8)
	s_barrier
	s_waitcnt lgkmcnt(0)
	v_mfma_f32_16x16x32_bf16 v[126:129], v[130:133], v[184:187], v[126:129]
	v_mfma_f32_16x16x32_bf16 v[122:125], v[138:141], v[184:187], v[122:125]
	v_mfma_f32_16x16x32_bf16 v[114:117], v[130:133], v[192:195], v[114:117]
	v_mfma_f32_16x16x32_bf16 v[106:109], v[138:141], v[192:195], v[106:109]
	v_mfma_f32_16x16x32_bf16 v[102:105], v[130:133], v[214:217], v[102:105]
	v_mfma_f32_16x16x32_bf16 v[94:97], v[138:141], v[214:217], v[94:97]
	v_mfma_f32_16x16x32_bf16 v[82:85], v[130:133], v[222:225], v[82:85]
	v_mfma_f32_16x16x32_bf16 v[74:77], v[138:141], v[222:225], v[74:77]
	v_mfma_f32_16x16x32_bf16 v[126:129], v[134:137], v[188:191], v[126:129]
	v_mfma_f32_16x16x32_bf16 v[122:125], v[142:145], v[188:191], v[122:125]
	v_mfma_f32_16x16x32_bf16 v[114:117], v[134:137], v[206:209], v[114:117]
	v_mfma_f32_16x16x32_bf16 v[106:109], v[142:145], v[206:209], v[106:109]
	v_mfma_f32_16x16x32_bf16 v[102:105], v[134:137], v[218:221], v[102:105]
	v_mfma_f32_16x16x32_bf16 v[94:97], v[142:145], v[218:221], v[94:97]
	v_mfma_f32_16x16x32_bf16 v[82:85], v[134:137], v[226:229], v[82:85]
	v_mfma_f32_16x16x32_bf16 v[74:77], v[142:145], v[226:229], v[74:77]
	s_barrier
	s_add_i32 s26, 0, 0x1c000
	s_add_i32 s27, s38, s47
	v_add_u32_e32 v8, s26, v199
	v_lshl_add_u64 v[162:163], v[162:163], 0, s[70:71]
	s_mov_b32 m0, s27
	ds_read_b128 v[230:233], v8
	ds_read_b128 v[234:237], v8 offset:1024
	ds_read_b128 v[238:241], v8 offset:2048
	ds_read_b128 v[242:245], v8 offset:3072
	global_load_lds_dwordx4 v[162:163], off
	s_add_i32 m0, s27, 0x2000
	v_lshl_add_u64 v[162:163], v[164:165], 0, s[70:71]
	global_load_lds_dwordx4 v[162:163], off
	s_barrier
	s_waitcnt lgkmcnt(0)
	v_mfma_f32_16x16x32_bf16 v[118:121], v[230:233], v[184:187], v[118:121]
	v_mfma_f32_16x16x32_bf16 v[110:113], v[238:241], v[184:187], v[110:113]
	v_mfma_f32_16x16x32_bf16 v[98:101], v[230:233], v[192:195], v[98:101]
	v_mfma_f32_16x16x32_bf16 v[90:93], v[238:241], v[192:195], v[90:93]
	v_mfma_f32_16x16x32_bf16 v[86:89], v[230:233], v[214:217], v[86:89]
	v_mfma_f32_16x16x32_bf16 v[78:81], v[238:241], v[214:217], v[78:81]
	v_mfma_f32_16x16x32_bf16 v[54:57], v[230:233], v[222:225], v[54:57]
	v_mfma_f32_16x16x32_bf16 v[34:37], v[238:241], v[222:225], v[34:37]
	v_mfma_f32_16x16x32_bf16 v[118:121], v[234:237], v[188:191], v[118:121]
	v_mfma_f32_16x16x32_bf16 v[110:113], v[242:245], v[188:191], v[110:113]
	v_mfma_f32_16x16x32_bf16 v[98:101], v[234:237], v[206:209], v[98:101]
	v_mfma_f32_16x16x32_bf16 v[90:93], v[242:245], v[206:209], v[90:93]
	v_mfma_f32_16x16x32_bf16 v[86:89], v[234:237], v[218:221], v[86:89]
	v_mfma_f32_16x16x32_bf16 v[78:81], v[242:245], v[218:221], v[78:81]
	v_mfma_f32_16x16x32_bf16 v[54:57], v[234:237], v[226:229], v[54:57]
	v_mfma_f32_16x16x32_bf16 v[34:37], v[242:245], v[226:229], v[34:37]
	s_mov_b32 m0, s81
	v_lshl_add_u64 v[162:163], v[202:203], 0, s[70:71]
	s_barrier
	ds_read_b128 v[184:187], v204 offset:49152
	ds_read_b128 v[188:191], v204 offset:50176
	ds_read_b128 v[192:195], v204 offset:51200
	ds_read_b128 v[206:209], v204 offset:52224
	ds_read_b128 v[214:217], v204 offset:53248
	ds_read_b128 v[218:221], v204 offset:54272
	ds_read_b128 v[222:225], v204 offset:55296
	ds_read_b128 v[226:229], v204 offset:56320
	global_load_lds_dwordx4 v[162:163], off
	s_mov_b32 m0, s82
	v_lshl_add_u64 v[162:163], v[246:247], 0, s[70:71]
	global_load_lds_dwordx4 v[162:163], off
	s_barrier
; #define PG8_STAGE(bufoff, gbase, voff) do { _Pragma("unroll") for (int _i = 0; _i < 2; ++_i) \
;         __builtin_amdgcn_global_load_lds((const unsigned*)((const char*)(gbase) + (voff)[_i]), (LAS unsigned*)(lds + (bufoff) + ldsw + _i * 8192), 16, 0, 0); } while (0)
; #define PG8_MMA(ai, bj, At, Bt) do { __builtin_amdgcn_s_setprio(1); _Pragma("unroll") for (int m = 0; m < 4; ++m) _Pragma("unroll") for (int n = 0; n < 2; ++n) _Pragma("unroll") for (int k = 0; k < 2; ++k) \
;         acc[ai][bj][m][n] = __builtin_amdgcn_mfma_f32_16x16x32_bf16(Bt[n][k], At[m][k], acc[ai][bj][m][n], 0, 0, 0); __builtin_amdgcn_s_setprio(0); } while (0)
; #define PG8_WAIT_V(n) asm volatile("s_waitcnt vmcnt(" #n ")" ::: "memory")
; #define PG8_WAIT_L(n) asm volatile("s_waitcnt lgkmcnt(" #n ")" ::: "memory")
; #define PG8_BAR __builtin_amdgcn_s_barrier()
; #define PG8_SCHED __builtin_amdgcn_sched_barrier(0)
; template <class Epi>
; DEVI void gemm_phase(LAS unsigned char* lds, const Gemm g, const Epi& E) {
;     ...
;             PG8_BAR; PG8_WAIT_L(0); PG8_MMA(1, 0, At, B0); PG8_BAR; PG8_SCHED;
;             PG8_STAGE(PG8_SB(1, 1), b3 + hstepB, voffB);
;             PG8_WAIT_V(6); PG8_BAR; PG8_MMA(1, 1, At, B1); PG8_BAR;
;         }
;     ...
;                 for (int i = 0; i < 8; ++i) q4[i] = *(const f32x4*)(E.ssq_in + (size_t)(row0 + (i >> 2) * HALF + (i & 3) * 16) * 4);
; #pragma unroll
;                 for (int i = 0; i < 8; ++i) rsv[i] = rsqrtf((((q4[i][0] + q4[i][1]) + q4[i][2]) + q4[i][3]) * (1.f / DM) + 1e-6f); }
	s_waitcnt lgkmcnt(0)
	v_mfma_f32_16x16x32_bf16 v[58:61], v[130:133], v[184:187], v[58:61]
	v_mfma_f32_16x16x32_bf16 v[62:65], v[138:141], v[184:187], v[62:65]
	v_mfma_f32_16x16x32_bf16 v[38:41], v[130:133], v[192:195], v[38:41]
	v_mfma_f32_16x16x32_bf16 v[42:45], v[138:141], v[192:195], v[42:45]
	v_mfma_f32_16x16x32_bf16 v[18:21], v[130:133], v[214:217], v[18:21]
	v_mfma_f32_16x16x32_bf16 v[22:25], v[138:141], v[214:217], v[22:25]
	v_mfma_f32_16x16x32_bf16 v[0:3], v[130:133], v[222:225], v[0:3]
	v_mfma_f32_16x16x32_bf16 v[4:7], v[138:141], v[222:225], v[4:7]
	v_mfma_f32_16x16x32_bf16 v[58:61], v[134:137], v[188:191], v[58:61]
	v_mfma_f32_16x16x32_bf16 v[62:65], v[142:145], v[188:191], v[62:65]
	v_mfma_f32_16x16x32_bf16 v[38:41], v[134:137], v[206:209], v[38:41]
	v_mfma_f32_16x16x32_bf16 v[42:45], v[142:145], v[206:209], v[42:45]
	v_mfma_f32_16x16x32_bf16 v[18:21], v[134:137], v[218:221], v[18:21]
	v_mfma_f32_16x16x32_bf16 v[22:25], v[142:145], v[218:221], v[22:25]
	v_mfma_f32_16x16x32_bf16 v[0:3], v[134:137], v[226:229], v[0:3]
	v_mfma_f32_16x16x32_bf16 v[4:7], v[142:145], v[226:229], v[4:7]
	s_barrier
	s_add_u32 s16, s16, 0x40080
	s_addc_u32 s17, s17, 0
	s_add_i32 s26, s26, s47
	s_mov_b32 m0, s26
	v_lshl_add_u64 v[130:131], s[16:17], 0, v[148:149]
	global_load_lds_dwordx4 v[130:131], off
	s_add_i32 m0, s26, 0x2000
	v_lshl_add_u64 v[130:131], s[16:17], 0, v[152:153]
	global_load_lds_dwordx4 v[130:131], off
	s_waitcnt vmcnt(6)
	s_barrier
	v_mfma_f32_16x16x32_bf16 v[66:69], v[230:233], v[184:187], v[66:69]
	v_mfma_f32_16x16x32_bf16 v[70:73], v[238:241], v[184:187], v[70:73]
	v_mfma_f32_16x16x32_bf16 v[46:49], v[230:233], v[192:195], v[46:49]
	v_mfma_f32_16x16x32_bf16 v[50:53], v[238:241], v[192:195], v[50:53]
	v_mfma_f32_16x16x32_bf16 v[26:29], v[230:233], v[214:217], v[26:29]
	v_mfma_f32_16x16x32_bf16 v[30:33], v[238:241], v[214:217], v[30:33]
	v_mfma_f32_16x16x32_bf16 v[10:13], v[230:233], v[222:225], v[10:13]
	v_mfma_f32_16x16x32_bf16 v[14:17], v[238:241], v[222:225], v[14:17]
	v_mfma_f32_16x16x32_bf16 v[66:69], v[234:237], v[188:191], v[66:69]
	v_mfma_f32_16x16x32_bf16 v[70:73], v[242:245], v[188:191], v[70:73]
	v_mfma_f32_16x16x32_bf16 v[46:49], v[234:237], v[206:209], v[46:49]
	v_mfma_f32_16x16x32_bf16 v[50:53], v[242:245], v[206:209], v[50:53]
	v_mfma_f32_16x16x32_bf16 v[26:29], v[234:237], v[218:221], v[26:29]
	v_mfma_f32_16x16x32_bf16 v[30:33], v[242:245], v[218:221], v[30:33]
	v_mfma_f32_16x16x32_bf16 v[10:13], v[234:237], v[226:229], v[10:13]
	v_mfma_f32_16x16x32_bf16 v[14:17], v[242:245], v[226:229], v[14:17]
	s_add_i32 s19, s19, 2
	s_add_u32 s14, s14, 0x100
	s_addc_u32 s15, s15, 0
	s_add_u32 s9, s9, 0x100
	s_addc_u32 s18, s18, 0
	s_cmp_gt_u32 s19, 13
	s_barrier
	s_cbranch_scc0 .LBB0_1007
	s_setprio 0
	v_lshl_add_u32 v194, s4, 8, v197
	v_add_u32_e32 v184, 0xb0, v194
	v_ashrrev_i32_e32 v195, 31, v194
	v_ashrrev_i32_e32 v185, 31, v184
	v_lshl_add_u64 v[130:131], v[194:195], 4, s[76:77]
	v_lshl_add_u64 v[134:135], v[184:185], 4, s[76:77]
	global_load_dwordx4 v[206:209], v[130:131], off
	v_or_b32_e32 v192, 48, v194
	global_load_dwordx4 v[134:137], v[134:135], off
	v_or_b32_e32 v130, 16, v194
	v_ashrrev_i32_e32 v131, 31, v130
	v_lshl_add_u64 v[130:131], v[130:131], 4, s[76:77]
	global_load_dwordx4 v[214:217], v[130:131], off
	v_or_b32_e32 v130, 32, v194
	v_ashrrev_i32_e32 v131, 31, v130
	v_lshl_add_u64 v[130:131], v[130:131], 4, s[76:77]
	v_ashrrev_i32_e32 v193, 31, v192
	global_load_dwordx4 v[218:221], v[130:131], off
	v_lshl_add_u64 v[130:131], v[192:193], 4, s[76:77]
	global_load_dwordx4 v[222:225], v[130:131], off
	v_add_u32_e32 v190, 0x80, v194
	v_ashrrev_i32_e32 v191, 31, v190
	v_add_u32_e32 v188, 0x90, v194
	v_lshl_add_u64 v[130:131], v[190:191], 4, s[76:77]
	v_ashrrev_i32_e32 v189, 31, v188
	global_load_dwordx4 v[138:141], v[130:131], off
	v_lshl_add_u64 v[130:131], v[188:189], 4, s[76:77]
	global_load_dwordx4 v[142:145], v[130:131], off
	v_add_u32_e32 v186, 0xa0, v194
	v_ashrrev_i32_e32 v187, 31, v186
	v_lshl_add_u64 v[130:131], v[186:187], 4, s[76:77]
	global_load_dwordx4 v[130:133], v[130:131], off
	s_mov_b32 s0, 0x358637bd
	v_mov_b64_e32 v[202:203], s[0:1]
	s_mov_b64 s[16:17], s[12:13]
	s_mov_b64 s[14:15], s[10:11]
	s_waitcnt vmcnt(0)
; template <class Epi>
; DEVI void gemm_phase(LAS unsigned char* lds, const Gemm g, const Epi& E) {
;     ...
;                 for (int i = 0; i < 8; ++i) q4[i] = *(const f32x4*)(E.ssq_in + (size_t)(row0 + (i >> 2) * HALF + (i & 3) * 16) * 4);
; #pragma unroll
;                 for (int i = 0; i < 8; ++i) rsv[i] = rsqrtf((((q4[i][0] + q4[i][1]) + q4[i][2]) + q4[i][3]) * (1.f / DM) + 1e-6f); }
;     ...
;                     const int r = row0 + ai * HALF + m * 16; float rs = 1.f, part = 0.f;
;                     if constexpr (Epi::RS) rs = rsv[ai * 4 + m];
;                     if constexpr (Epi::PAIR) E.pair8(cur.b, r, cur.pn * HALF + wc * 32 + 8 * fq, acc[ai][0][m][0] * rs, acc[ai][0][m][1] * rs, acc[ai][1][m][0] * rs, acc[ai][1][m][1] * rs);
;                     else
; #pragma unroll
;                     for (int bj = 0; bj < 2; ++bj) {
;                         const int c = col0 + bj * HALF; f32x4 v0 = acc[ai][bj][m][0], v1 = acc[ai][bj][m][1];
;                         if constexpr (Epi::RS) { v0 = v0 * rs; v1 = v1 * rs; }
;                         if constexpr (Epi::PRE) part += E.frag_pre8(cur.b, r, c, v0, v1, pre[mm][bj][0], pre[mm][bj][1]);
;                         else if constexpr (Epi::PERM) E.frag8(cur.b, r, c, v0, v1);
;                         else { E.frag(cur.b, r, c, v0); E.frag(cur.b, r, c + 16, v1); }
	v_mov_b32_e32 v163, v206
	v_mov_b32_e32 v165, v208
	v_mov_b32_e32 v162, v214
	v_mov_b32_e32 v206, v215
	v_pk_add_f32 v[162:163], v[162:163], v[206:207]
	v_mov_b32_e32 v164, v216
	v_pk_add_f32 v[162:163], v[164:165], v[162:163]
	v_mov_b32_e32 v208, v217
	v_pk_add_f32 v[162:163], v[208:209], v[162:163]
	v_mov_b32_e32 v164, v224
	v_pk_fma_f32 v[162:163], v[162:163], s[72:73], v[202:203] op_sel_hi:[1,0,0]
	v_mov_b32_e32 v165, v220
	v_mul_f32_e32 v8, 0x4b800000, v163
	v_cmp_gt_f32_e64 s[4:5], s94, v163
	v_cmp_gt_f32_e32 vcc, s94, v162
	v_mov_b32_e32 v220, v225
	v_cndmask_b32_e64 v8, v163, v8, s[4:5]
	v_rsq_f32_e32 v8, v8
	s_nop 0
	v_mul_f32_e32 v163, 0x45800000, v8
	v_cndmask_b32_e64 v198, v8, v163, s[4:5]
	v_mul_f32_e32 v8, 0x4b800000, v162
	v_cndmask_b32_e32 v8, v162, v8, vcc
	v_rsq_f32_e32 v8, v8
	v_mov_b32_e32 v163, v218
	v_mov_b32_e32 v218, v223
	v_pk_mul_f32 v[128:129], v[128:129], v[198:199] op_sel_hi:[1,0]
	v_mul_f32_e32 v162, 0x45800000, v8
	v_cndmask_b32_e32 v8, v8, v162, vcc
	v_mov_b32_e32 v162, v222
	v_pk_add_f32 v[162:163], v[162:163], v[218:219]
	v_pk_mul_f32 v[126:127], v[126:127], v[198:199] op_sel_hi:[1,0]
	v_pk_add_f32 v[162:163], v[164:165], v[162:163]
	v_pk_mul_f32 v[122:123], v[122:123], v[198:199] op_sel_hi:[1,0]
	v_pk_add_f32 v[162:163], v[220:221], v[162:163]
	v_pk_mul_f32 v[120:121], v[120:121], v[198:199] op_sel_hi:[1,0]
	v_pk_fma_f32 v[162:163], v[162:163], s[72:73], v[202:203] op_sel_hi:[1,0,0]
	v_pk_mul_f32 v[118:119], v[118:119], v[198:199] op_sel_hi:[1,0]
	v_mul_f32_e32 v164, 0x4b800000, v163
	v_cmp_gt_f32_e64 s[4:5], s94, v163
	v_cmp_gt_f32_e32 vcc, s94, v162
	v_pk_mul_f32 v[110:111], v[110:111], v[198:199] op_sel_hi:[1,0]
	v_cndmask_b32_e64 v163, v163, v164, s[4:5]
	v_rsq_f32_e32 v163, v163
	v_cvt_pk_bf16_f32 v118, v118, v119
	v_cvt_pk_bf16_f32 v119, v120, v121
	v_cvt_pk_bf16_f32 v120, v110, v111
	v_mul_f32_e32 v164, 0x45800000, v163
	v_cndmask_b32_e64 v200, v163, v164, s[4:5]
	v_mul_f32_e32 v163, 0x4b800000, v162
	v_cndmask_b32_e32 v162, v162, v163, vcc
	v_rsq_f32_e32 v162, v162
	v_pk_mul_f32 v[112:113], v[112:113], v[198:199] op_sel_hi:[1,0]
	v_pk_mul_f32 v[114:115], v[114:115], v[8:9] op_sel_hi:[1,0]
	v_cvt_pk_bf16_f32 v121, v112, v113
	v_mul_f32_e32 v163, 0x45800000, v162
	v_cndmask_b32_e32 v196, v162, v163, vcc
	v_mov_b32_e32 v162, v142
	v_mov_b32_e32 v163, v138
	v_mov_b32_e32 v138, v143
	v_pk_add_f32 v[138:139], v[162:163], v[138:139]
	v_mov_b32_e32 v142, v144
	v_mov_b32_e32 v143, v140
	v_pk_add_f32 v[138:139], v[142:143], v[138:139]
	v_mov_b32_e32 v140, v145
	v_pk_add_f32 v[138:139], v[140:141], v[138:139]
	v_mov_b32_e32 v142, v134
	v_pk_fma_f32 v[140:141], v[138:139], s[72:73], v[202:203] op_sel_hi:[1,0,0]
	v_mov_b32_e32 v143, v130
	v_mul_f32_e32 v138, 0x4b800000, v141
	v_cmp_gt_f32_e64 s[4:5], s94, v141
	v_mov_b32_e32 v130, v135
	v_pk_add_f32 v[130:131], v[142:143], v[130:131]
	v_cndmask_b32_e64 v138, v141, v138, s[4:5]
	v_rsq_f32_e32 v138, v138
	v_mov_b32_e32 v134, v136
	v_mov_b32_e32 v135, v132
	v_pk_add_f32 v[130:131], v[134:135], v[130:131]
	v_mov_b32_e32 v132, v137
	v_pk_add_f32 v[130:131], v[132:133], v[130:131]
	v_mul_f32_e32 v139, 0x45800000, v138
	v_pk_fma_f32 v[130:131], v[130:131], s[72:73], v[202:203] op_sel_hi:[1,0,0]
	v_cmp_gt_f32_e32 vcc, s94, v140
	v_cndmask_b32_e64 v138, v138, v139, s[4:5]
	v_mul_f32_e32 v139, 0x4b800000, v140
	v_mul_f32_e32 v132, 0x4b800000, v131
	v_cmp_gt_f32_e64 s[4:5], s94, v131
	v_cndmask_b32_e32 v139, v140, v139, vcc
	v_rsq_f32_e32 v139, v139
	v_cndmask_b32_e64 v131, v131, v132, s[4:5]
	v_rsq_f32_e32 v131, v131
	v_pk_mul_f32 v[136:137], v[124:125], v[198:199] op_sel_hi:[1,0]
	v_mul_f32_e32 v140, 0x45800000, v139
	v_cndmask_b32_e32 v140, v139, v140, vcc
	v_mul_f32_e32 v132, 0x45800000, v131
	v_cmp_gt_f32_e32 vcc, s94, v130
	v_cndmask_b32_e64 v132, v131, v132, s[4:5]
	v_mul_f32_e32 v131, 0x4b800000, v130
	v_cndmask_b32_e32 v130, v130, v131, vcc
	v_rsq_f32_e32 v130, v130
	v_cvt_pk_bf16_f32 v125, v128, v129
	v_ashrrev_i32_e32 v134, 5, v194
	v_ashrrev_i32_e32 v135, 31, v134
	v_mul_f32_e32 v131, 0x45800000, v130
	v_cndmask_b32_e32 v130, v130, v131, vcc
	v_lshl_or_b32 v131, s84, 8, v201
	v_ashrrev_i32_e32 v128, 4, v131
	v_ashrrev_i32_e32 v129, 31, v128
	v_cvt_pk_bf16_f32 v124, v126, v127
	v_cvt_pk_bf16_f32 v126, v122, v123
	v_lshlrev_b64 v[122:123], 10, v[128:129]
	v_or_b32_e32 v110, 8, v128
	v_cvt_pk_bf16_f32 v127, v136, v137
	v_lshl_add_u64 v[136:137], v[122:123], 0, v[134:135]
	v_ashrrev_i32_e32 v111, 31, v110
	v_mad_u64_u32 v[142:143], s[0:1], v136, s34, v[178:179]
	v_lshlrev_b64 v[110:111], 10, v[110:111]
	v_mad_i32_i24 v143, v137, s34, v143
	v_lshl_add_u64 v[112:113], v[110:111], 0, v[134:135]
	global_store_dwordx4 v[142:143], v[124:127], off
	v_pk_mul_f32 v[100:101], v[100:101], v[8:9] op_sel_hi:[1,0]
	v_pk_mul_f32 v[98:99], v[98:99], v[8:9] op_sel_hi:[1,0]
	v_mad_u64_u32 v[124:125], s[0:1], v112, s34, v[178:179]
	v_mad_i32_i24 v125, v113, s34, v125
	v_pk_mul_f32 v[112:113], v[116:117], v[8:9] op_sel_hi:[1,0]
	v_pk_mul_f32 v[116:117], v[108:109], v[8:9] op_sel_hi:[1,0]
	v_pk_mul_f32 v[108:109], v[106:107], v[8:9] op_sel_hi:[1,0]
	v_cvt_pk_bf16_f32 v106, v114, v115
	v_cvt_pk_bf16_f32 v107, v112, v113
	v_cvt_pk_bf16_f32 v108, v108, v109
	v_cvt_pk_bf16_f32 v109, v116, v117
	global_store_dwordx4 v[142:143], v[106:109], off offset:512
	v_pk_mul_f32 v[94:95], v[94:95], v[200:201] op_sel_hi:[1,0]
	v_pk_mul_f32 v[96:97], v[96:97], v[200:201] op_sel_hi:[1,0]
	v_pk_mul_f32 v[106:107], v[92:93], v[8:9] op_sel_hi:[1,0]
	v_pk_mul_f32 v[92:93], v[90:91], v[8:9] op_sel_hi:[1,0]
	v_cvt_pk_bf16_f32 v90, v98, v99
	v_cvt_pk_bf16_f32 v91, v100, v101
	v_cvt_pk_bf16_f32 v92, v92, v93
; template <class Epi>
; DEVI void gemm_phase(LAS unsigned char* lds, const Gemm g, const Epi& E) {
;     ...
;                     for (int bj = 0; bj < 2; ++bj) {
;                         const int c = col0 + bj * HALF; f32x4 v0 = acc[ai][bj][m][0], v1 = acc[ai][bj][m][1];
;                         if constexpr (Epi::RS) { v0 = v0 * rs; v1 = v1 * rs; }
;                         if constexpr (Epi::PRE) part += E.frag_pre8(cur.b, r, c, v0, v1, pre[mm][bj][0], pre[mm][bj][1]);
;                         else if constexpr (Epi::PERM) E.frag8(cur.b, r, c, v0, v1);
;                         else { E.frag(cur.b, r, c, v0); E.frag(cur.b, r, c + 16, v1); }
	v_cvt_pk_bf16_f32 v93, v106, v107
	v_or_b32_e32 v98, 1, v134
	global_store_dwordx4 v[124:125], v[90:93], off offset:512
	v_ashrrev_i32_e32 v99, 31, v98
	v_pk_mul_f32 v[86:87], v[86:87], v[200:201] op_sel_hi:[1,0]
	v_pk_mul_f32 v[92:93], v[104:105], v[200:201] op_sel_hi:[1,0]
	v_pk_mul_f32 v[90:91], v[102:103], v[200:201] op_sel_hi:[1,0]
	v_pk_mul_f32 v[88:89], v[88:89], v[200:201] op_sel_hi:[1,0]
	v_cvt_pk_bf16_f32 v90, v90, v91
	v_cvt_pk_bf16_f32 v91, v92, v93
	v_cvt_pk_bf16_f32 v92, v94, v95
	v_lshl_add_u64 v[94:95], v[122:123], 0, v[98:99]
	v_cvt_pk_bf16_f32 v93, v96, v97
	v_mad_u64_u32 v[96:97], s[0:1], v94, s34, v[178:179]
	v_mad_i32_i24 v97, v95, s34, v97
	global_store_dwordx4 v[96:97], v[90:93], off
	v_lshlrev_b32_e32 v8, 5, v192
	v_and_b32_e32 v8, 0x3e0, v8
	v_pk_mul_f32 v[90:91], v[80:81], v[200:201] op_sel_hi:[1,0]
	v_pk_mul_f32 v[80:81], v[78:79], v[200:201] op_sel_hi:[1,0]
	v_cvt_pk_bf16_f32 v78, v86, v87
	v_lshl_add_u64 v[86:87], v[110:111], 0, v[98:99]
	v_cvt_pk_bf16_f32 v79, v88, v89
	v_mad_u64_u32 v[88:89], s[0:1], v86, s34, v[178:179]
	v_cvt_pk_bf16_f32 v80, v80, v81
	v_cvt_pk_bf16_f32 v81, v90, v91
	v_mad_i32_i24 v89, v87, s34, v89
	global_store_dwordx4 v[88:89], v[78:81], off
	v_pk_mul_f32 v[82:83], v[82:83], v[196:197] op_sel_hi:[1,0]
	v_pk_mul_f32 v[84:85], v[84:85], v[196:197] op_sel_hi:[1,0]
	v_ashrrev_i32_e32 v78, 5, v192
	v_ashrrev_i32_e32 v79, 31, v78
	v_lshl_add_u64 v[80:81], v[176:177], 0, v[8:9]
	v_pk_mul_f32 v[86:87], v[76:77], v[196:197] op_sel_hi:[1,0]
	v_pk_mul_f32 v[76:77], v[74:75], v[196:197] op_sel_hi:[1,0]
	v_cvt_pk_bf16_f32 v74, v82, v83
	v_lshl_add_u64 v[82:83], v[122:123], 0, v[78:79]
	v_cvt_pk_bf16_f32 v75, v84, v85
	v_mad_u64_u32 v[84:85], s[0:1], v82, s34, v[80:81]
	v_cvt_pk_bf16_f32 v76, v76, v77
	v_cvt_pk_bf16_f32 v77, v86, v87
	v_mad_i32_i24 v85, v83, s34, v85
	v_pk_mul_f32 v[54:55], v[54:55], v[196:197] op_sel_hi:[1,0]
	global_store_dwordx4 v[124:125], v[118:121], off
	global_store_dwordx4 v[84:85], v[74:77], off
	v_pk_mul_f32 v[56:57], v[56:57], v[196:197] op_sel_hi:[1,0]
	v_lshlrev_b32_e32 v8, 5, v188
	v_pk_mul_f32 v[74:75], v[36:37], v[196:197] op_sel_hi:[1,0]
	v_pk_mul_f32 v[36:37], v[34:35], v[196:197] op_sel_hi:[1,0]
	v_cvt_pk_bf16_f32 v34, v54, v55
	v_lshl_add_u64 v[54:55], v[110:111], 0, v[78:79]
	v_cvt_pk_bf16_f32 v35, v56, v57
	v_mad_u64_u32 v[56:57], s[0:1], v54, s34, v[80:81]
	v_cvt_pk_bf16_f32 v36, v36, v37
	v_cvt_pk_bf16_f32 v37, v74, v75
	v_mad_i32_i24 v57, v55, s34, v57
	v_ashrrev_i32_e32 v54, 5, v190
	global_store_dwordx4 v[56:57], v[34:37], off
	v_ashrrev_i32_e32 v55, 31, v54
	v_pk_mul_f32 v[56:57], v[64:65], v[138:139] op_sel_hi:[1,0]
	v_pk_mul_f32 v[36:37], v[60:61], v[138:139] op_sel_hi:[1,0]
	v_pk_mul_f32 v[34:35], v[58:59], v[138:139] op_sel_hi:[1,0]
	v_pk_mul_f32 v[58:59], v[62:63], v[138:139] op_sel_hi:[1,0]
	v_cvt_pk_bf16_f32 v34, v34, v35
	v_cvt_pk_bf16_f32 v35, v36, v37
	v_cvt_pk_bf16_f32 v37, v56, v57
	v_lshl_add_u64 v[56:57], v[122:123], 0, v[54:55]
	v_cvt_pk_bf16_f32 v36, v58, v59
	v_mad_u64_u32 v[58:59], s[0:1], v56, s34, v[178:179]
	v_mad_i32_i24 v59, v57, s34, v59
	global_store_dwordx4 v[58:59], v[34:37], off
	v_pk_mul_f32 v[56:57], v[72:73], v[138:139] op_sel_hi:[1,0]
	v_lshl_add_u64 v[54:55], v[110:111], 0, v[54:55]
	v_pk_mul_f32 v[36:37], v[68:69], v[138:139] op_sel_hi:[1,0]
	v_pk_mul_f32 v[34:35], v[66:67], v[138:139] op_sel_hi:[1,0]
	v_pk_mul_f32 v[58:59], v[70:71], v[138:139] op_sel_hi:[1,0]
	v_cvt_pk_bf16_f32 v34, v34, v35
	v_cvt_pk_bf16_f32 v35, v36, v37
	v_cvt_pk_bf16_f32 v37, v56, v57
	v_mad_u64_u32 v[56:57], s[0:1], v54, s34, v[178:179]
	v_cvt_pk_bf16_f32 v36, v58, v59
	v_mad_i32_i24 v57, v55, s34, v57
	v_ashrrev_i32_e32 v54, 5, v188
	global_store_dwordx4 v[56:57], v[34:37], off
	v_ashrrev_i32_e32 v55, 31, v54
; #define PG8_WAIT_V(n) asm volatile("s_waitcnt vmcnt(" #n ")" ::: "memory")
; #define PG8_BAR __builtin_amdgcn_s_barrier()
; template <class Epi>
; DEVI void gemm_phase(LAS unsigned char* lds, const Gemm g, const Epi& E) {
;     ...
;         if (!has_next) break;
; #pragma unroll
;         for (int a = 0; a < 2; ++a)
; #pragma unroll
;             for (int b = 0; b < 2; ++b)
; #pragma unroll
;                 for (int m = 0; m < 4; ++m)
; #pragma unroll
;                     for (int n = 0; n < 2; ++n) acc[a][b][m][n] = (f32x4){0.f, 0.f, 0.f, 0.f};
;         cur = nxt; cA = nA; cB = nB; ++ui;
;     }
;     PG8_WAIT_V(0);
;     if (wr == 0) PG8_BAR;
;     PG8_BAR;
	v_and_b32_e32 v8, 0x3e0, v8
	v_pk_mul_f32 v[36:37], v[40:41], v[140:141] op_sel_hi:[1,0]
	v_pk_mul_f32 v[34:35], v[38:39], v[140:141] op_sel_hi:[1,0]
	v_pk_mul_f32 v[38:39], v[44:45], v[140:141] op_sel_hi:[1,0]
	v_lshl_add_u64 v[56:57], v[176:177], 0, v[8:9]
	v_pk_mul_f32 v[40:41], v[42:43], v[140:141] op_sel_hi:[1,0]
	v_cvt_pk_bf16_f32 v34, v34, v35
	v_cvt_pk_bf16_f32 v35, v36, v37
	v_cvt_pk_bf16_f32 v37, v38, v39
	v_lshl_add_u64 v[38:39], v[122:123], 0, v[54:55]
	v_cvt_pk_bf16_f32 v36, v40, v41
	v_mad_u64_u32 v[40:41], s[0:1], v38, s34, v[56:57]
	v_mad_i32_i24 v41, v39, s34, v41
	global_store_dwordx4 v[40:41], v[34:37], off
	v_pk_mul_f32 v[38:39], v[52:53], v[140:141] op_sel_hi:[1,0]
	v_pk_mul_f32 v[40:41], v[50:51], v[140:141] op_sel_hi:[1,0]
	v_pk_mul_f32 v[36:37], v[48:49], v[140:141] op_sel_hi:[1,0]
	v_pk_mul_f32 v[34:35], v[46:47], v[140:141] op_sel_hi:[1,0]
	v_pk_mul_f32 v[20:21], v[20:21], v[132:133] op_sel_hi:[1,0]
	v_cvt_pk_bf16_f32 v34, v34, v35
	v_cvt_pk_bf16_f32 v35, v36, v37
	v_cvt_pk_bf16_f32 v37, v38, v39
	v_lshl_add_u64 v[38:39], v[110:111], 0, v[54:55]
	v_cvt_pk_bf16_f32 v36, v40, v41
	v_mad_u64_u32 v[40:41], s[0:1], v38, s34, v[56:57]
	v_mad_i32_i24 v41, v39, s34, v41
	global_store_dwordx4 v[40:41], v[34:37], off
	v_pk_mul_f32 v[18:19], v[18:19], v[132:133] op_sel_hi:[1,0]
	v_pk_mul_f32 v[22:23], v[22:23], v[132:133] op_sel_hi:[1,0]
	v_ashrrev_i32_e32 v34, 5, v186
	v_ashrrev_i32_e32 v35, 31, v34
	v_pk_mul_f32 v[24:25], v[24:25], v[132:133] op_sel_hi:[1,0]
	v_cvt_pk_bf16_f32 v18, v18, v19
	v_cvt_pk_bf16_f32 v19, v20, v21
	v_cvt_pk_bf16_f32 v20, v22, v23
	v_lshl_add_u64 v[22:23], v[122:123], 0, v[34:35]
	v_cvt_pk_bf16_f32 v21, v24, v25
	v_mad_u64_u32 v[24:25], s[0:1], v22, s34, v[178:179]
	v_mad_i32_i24 v25, v23, s34, v25
	global_store_dwordx4 v[24:25], v[18:21], off
	v_pk_mul_f32 v[22:23], v[32:33], v[132:133] op_sel_hi:[1,0]
	v_pk_mul_f32 v[24:25], v[30:31], v[132:133] op_sel_hi:[1,0]
	v_pk_mul_f32 v[20:21], v[28:29], v[132:133] op_sel_hi:[1,0]
	v_pk_mul_f32 v[18:19], v[26:27], v[132:133] op_sel_hi:[1,0]
	v_lshlrev_b32_e32 v8, 5, v184
	v_cvt_pk_bf16_f32 v18, v18, v19
	v_cvt_pk_bf16_f32 v19, v20, v21
	v_cvt_pk_bf16_f32 v21, v22, v23
	v_lshl_add_u64 v[22:23], v[110:111], 0, v[34:35]
	v_cvt_pk_bf16_f32 v20, v24, v25
	v_mad_u64_u32 v[24:25], s[0:1], v22, s34, v[178:179]
	v_mad_i32_i24 v25, v23, s34, v25
	global_store_dwordx4 v[24:25], v[18:21], off
	v_and_b32_e32 v8, 0x3e0, v8
	v_pk_mul_f32 v[2:3], v[2:3], v[130:131] op_sel_hi:[1,0]
	v_ashrrev_i32_e32 v18, 5, v184
	v_ashrrev_i32_e32 v19, 31, v18
	v_pk_mul_f32 v[0:1], v[0:1], v[130:131] op_sel_hi:[1,0]
	v_pk_mul_f32 v[4:5], v[4:5], v[130:131] op_sel_hi:[1,0]
	v_lshl_add_u64 v[20:21], v[176:177], 0, v[8:9]
	v_pk_mul_f32 v[6:7], v[6:7], v[130:131] op_sel_hi:[1,0]
	v_cvt_pk_bf16_f32 v0, v0, v1
	v_cvt_pk_bf16_f32 v1, v2, v3
	v_cvt_pk_bf16_f32 v2, v4, v5
	v_lshl_add_u64 v[4:5], v[122:123], 0, v[18:19]
	v_cvt_pk_bf16_f32 v3, v6, v7
	v_mad_u64_u32 v[6:7], s[0:1], v4, s34, v[20:21]
	v_mad_i32_i24 v7, v5, s34, v7
	global_store_dwordx4 v[6:7], v[0:3], off
	v_pk_mul_f32 v[4:5], v[16:17], v[130:131] op_sel_hi:[1,0]
	v_pk_mul_f32 v[6:7], v[14:15], v[130:131] op_sel_hi:[1,0]
	v_pk_mul_f32 v[2:3], v[12:13], v[130:131] op_sel_hi:[1,0]
	v_pk_mul_f32 v[0:1], v[10:11], v[130:131] op_sel_hi:[1,0]
	s_and_b64 vcc, exec, s[2:3]
	v_cvt_pk_bf16_f32 v0, v0, v1
	v_cvt_pk_bf16_f32 v1, v2, v3
	v_cvt_pk_bf16_f32 v3, v4, v5
	v_lshl_add_u64 v[4:5], v[110:111], 0, v[18:19]
	v_cvt_pk_bf16_f32 v2, v6, v7
	v_mad_u64_u32 v[6:7], s[0:1], v4, s34, v[20:21]
	v_mad_i32_i24 v7, v5, s34, v7
	s_mov_b32 s84, s8
	s_mov_b32 s4, s6
	global_store_dwordx4 v[6:7], v[0:3], off
	s_cbranch_vccz .LBB0_1000
	s_waitcnt vmcnt(0)
	s_cmpk_gt_u32 s46, 0xff
	s_cbranch_scc1 .LBB0_1011
	s_barrier

; #define PG8_STAGE(bufoff, gbase, voff) do { _Pragma("unroll") for (int _i = 0; _i < 2; ++_i) \
;         __builtin_amdgcn_global_load_lds((const unsigned*)((const char*)(gbase) + (voff)[_i]), (LAS unsigned*)(lds + (bufoff) + ldsw + _i * 8192), 16, 0, 0); } while (0)
; #define PG8_LDA(dst, b, h) do { _Pragma("unroll") for (int m = 0; m < 4; ++m) _Pragma("unroll") for (int k = 0; k < 2; ++k) dst[m][k] = *(const LAS bf16x8*)(lds + PG8_SA(b, h) + aoff + m * 2048 + k * 1024); } while (0)
; #define PG8_LDB(dst, b, h) do { _Pragma("unroll") for (int n = 0; n < 2; ++n) _Pragma("unroll") for (int k = 0; k < 2; ++k) dst[n][k] = *(const LAS bf16x8*)(lds + PG8_SB(b, h) + boff + n * 2048 + k * 1024); } while (0)
; #define PG8_MMA(ai, bj, At, Bt) do { __builtin_amdgcn_s_setprio(1); _Pragma("unroll") for (int m = 0; m < 4; ++m) _Pragma("unroll") for (int n = 0; n < 2; ++n) _Pragma("unroll") for (int k = 0; k < 2; ++k) \
;         acc[ai][bj][m][n] = __builtin_amdgcn_mfma_f32_16x16x32_bf16(Bt[n][k], At[m][k], acc[ai][bj][m][n], 0, 0, 0); __builtin_amdgcn_s_setprio(0); } while (0)
; #define PG8_WAIT_L(n) asm volatile("s_waitcnt lgkmcnt(" #n ")" ::: "memory")
; #define PG8_BAR __builtin_amdgcn_s_barrier()
; #define PG8_SCHED __builtin_amdgcn_sched_barrier(0)
; template <class Epi>
; DEVI void gemm_phase(LAS unsigned char* lds, const Gemm g, const Epi& E) {
;     ...
;         for (int t = 0; t < nt; t += 2) {
;             const bool last = (t == nt - 2);
;             const char* a1 = cA + (size_t)(t + 1) * kstep;
;             const char* a2 = last ? nA : cA + (size_t)(t + 2) * kstep; const char* b2 = last ? nB : cB + (size_t)(t + 2) * kstep;
;             const char* a3 = a2 + kstep; const char* b3 = b2 + kstep;
;             PG8_LDB(B0, 0, 0); PG8_SCHED; PG8_LDA(At, 0, 0); PG8_STAGE(PG8_SA(1, 1), a1 + hstepA, voffA);
;             PG8_WAIT_L(8); PG8_BAR; PG8_WAIT_L(0); PG8_MMA(0, 0, At, B0); PG8_BAR; PG8_SCHED;
;             PG8_LDB(B1, 0, 1); PG8_STAGE(PG8_SB(0, 0), b2, voffB);
;             PG8_BAR; PG8_WAIT_L(0); PG8_MMA(0, 1, At, B1); PG8_BAR;
;             PG8_LDA(At, 0, 1); PG8_STAGE(PG8_SA(0, 0), a2, voffA);
;             PG8_BAR; PG8_WAIT_L(0); PG8_MMA(1, 0, At, B0); PG8_BAR; PG8_SCHED;
;             PG8_STAGE(PG8_SB(0, 1), b2 + hstepB, voffB);
.LBB0_1127:
	s_add_u32 s14, s12, 0x100
	s_addc_u32 s15, s13, 0
	s_add_i32 s48, 0, 0x10000
	v_add_u32_e32 v81, s48, v79
	ds_read_b128 v[82:85], v81
	ds_read_b128 v[86:89], v81 offset:1024
	ds_read_b128 v[90:93], v81 offset:2048
	ds_read_b128 v[94:97], v81 offset:3072
	s_cmp_eq_u32 s47, 4
	s_cselect_b32 s37, s9, s15
	s_cselect_b32 s36, s8, s14
	s_cselect_b32 s17, s11, s7
	s_cselect_b32 s16, s10, s5
	v_lshl_add_u64 v[130:131], s[12:13], 0, v[74:75]
	s_add_i32 m0, s18, 0xc000
	ds_read_b128 v[98:101], v80
	ds_read_b128 v[102:105], v80 offset:1024
	ds_read_b128 v[106:109], v80 offset:2048
	ds_read_b128 v[110:113], v80 offset:3072
	ds_read_b128 v[114:117], v80 offset:4096
	ds_read_b128 v[118:121], v80 offset:5120
	ds_read_b128 v[122:125], v80 offset:6144
	ds_read_b128 v[126:129], v80 offset:7168
	global_load_lds_dwordx4 v[130:131], off
	s_add_i32 m0, s18, 0xe000
	v_lshl_add_u64 v[130:131], s[12:13], 0, v[76:77]
	global_load_lds_dwordx4 v[130:131], off
	s_waitcnt lgkmcnt(8)
	s_barrier
	s_waitcnt lgkmcnt(0)
	v_mfma_f32_16x16x32_bf16 v[62:65], v[82:85], v[98:101], v[62:65]
	v_mfma_f32_16x16x32_bf16 v[58:61], v[90:93], v[98:101], v[58:61]
	v_mfma_f32_16x16x32_bf16 v[54:57], v[82:85], v[106:109], v[54:57]
	v_mfma_f32_16x16x32_bf16 v[50:53], v[90:93], v[106:109], v[50:53]
	v_mfma_f32_16x16x32_bf16 v[46:49], v[82:85], v[114:117], v[46:49]
	v_mfma_f32_16x16x32_bf16 v[42:45], v[90:93], v[114:117], v[42:45]
	v_mfma_f32_16x16x32_bf16 v[38:41], v[82:85], v[122:125], v[38:41]
	v_mfma_f32_16x16x32_bf16 v[34:37], v[90:93], v[122:125], v[34:37]
	v_mfma_f32_16x16x32_bf16 v[62:65], v[86:89], v[102:105], v[62:65]
	v_mfma_f32_16x16x32_bf16 v[58:61], v[94:97], v[102:105], v[58:61]
	v_mfma_f32_16x16x32_bf16 v[54:57], v[86:89], v[110:113], v[54:57]
	v_mfma_f32_16x16x32_bf16 v[50:53], v[94:97], v[110:113], v[50:53]
	v_mfma_f32_16x16x32_bf16 v[46:49], v[86:89], v[118:121], v[46:49]
	v_mfma_f32_16x16x32_bf16 v[42:45], v[94:97], v[118:121], v[42:45]
	v_mfma_f32_16x16x32_bf16 v[38:41], v[86:89], v[126:129], v[38:41]
	v_mfma_f32_16x16x32_bf16 v[34:37], v[94:97], v[126:129], v[34:37]
	s_barrier
	s_add_i32 s12, s48, s1
	v_lshl_add_u64 v[130:131], s[16:17], 0, v[70:71]
	s_mov_b32 m0, s12
	v_lshl_add_u64 v[132:133], s[16:17], 0, v[66:67]
	global_load_lds_dwordx4 v[130:131], off
	s_add_i32 m0, s12, 0x2000
	s_nop 0
	global_load_lds_dwordx4 v[132:133], off
	s_barrier
	s_waitcnt lgkmcnt(0)
	s_mov_b32 m0, s18
	v_lshl_add_u64 v[134:135], s[36:37], 0, v[72:73]
	s_barrier
	ds_read_b128 v[98:101], v80 offset:16384
	ds_read_b128 v[102:105], v80 offset:17408
	ds_read_b128 v[106:109], v80 offset:18432
	ds_read_b128 v[110:113], v80 offset:19456
	ds_read_b128 v[114:117], v80 offset:20480
	ds_read_b128 v[118:121], v80 offset:21504
	ds_read_b128 v[122:125], v80 offset:22528
	ds_read_b128 v[126:129], v80 offset:23552
	global_load_lds_dwordx4 v[134:135], off
	s_mov_b32 m0, s19
	v_lshl_add_u64 v[136:137], s[36:37], 0, v[68:69]
	global_load_lds_dwordx4 v[136:137], off
	s_barrier
	s_waitcnt lgkmcnt(0)
	v_mfma_f32_16x16x32_bf16 v[30:33], v[82:85], v[98:101], v[30:33]
	v_mfma_f32_16x16x32_bf16 v[26:29], v[90:93], v[98:101], v[26:29]
	v_mfma_f32_16x16x32_bf16 v[22:25], v[82:85], v[106:109], v[22:25]
	v_mfma_f32_16x16x32_bf16 v[18:21], v[90:93], v[106:109], v[18:21]
	v_mfma_f32_16x16x32_bf16 v[14:17], v[82:85], v[114:117], v[14:17]
	v_mfma_f32_16x16x32_bf16 v[10:13], v[90:93], v[114:117], v[10:13]
	v_mfma_f32_16x16x32_bf16 v[4:7], v[82:85], v[122:125], v[4:7]
	v_mfma_f32_16x16x32_bf16 v[0:3], v[90:93], v[122:125], v[0:3]
	v_mfma_f32_16x16x32_bf16 v[30:33], v[86:89], v[102:105], v[30:33]
	v_mfma_f32_16x16x32_bf16 v[26:29], v[94:97], v[102:105], v[26:29]
	v_mfma_f32_16x16x32_bf16 v[22:25], v[86:89], v[110:113], v[22:25]
	v_mfma_f32_16x16x32_bf16 v[18:21], v[94:97], v[110:113], v[18:21]
	v_mfma_f32_16x16x32_bf16 v[14:17], v[86:89], v[118:121], v[14:17]
	v_mfma_f32_16x16x32_bf16 v[10:13], v[94:97], v[118:121], v[10:13]
	v_mfma_f32_16x16x32_bf16 v[4:7], v[86:89], v[126:129], v[4:7]
	v_mfma_f32_16x16x32_bf16 v[0:3], v[94:97], v[126:129], v[0:3]
	s_barrier
	s_add_u32 s12, s16, 0x20000
	s_addc_u32 s13, s17, 0
	s_mov_b32 m0, s26
	v_lshl_add_u64 v[82:83], s[12:13], 0, v[70:71]
	global_load_lds_dwordx4 v[82:83], off
	s_mov_b32 m0, s27
	v_lshl_add_u64 v[82:83], s[12:13], 0, v[66:67]
	global_load_lds_dwordx4 v[82:83], off
	s_waitcnt vmcnt(6)
	s_barrier
	s_add_i32 s48, 0, 0x18000
	v_add_u32_e32 v81, s48, v79
	s_barrier
	ds_read_b128 v[82:85], v81
	ds_read_b128 v[86:89], v81 offset:1024
	ds_read_b128 v[90:93], v81 offset:2048
	ds_read_b128 v[94:97], v81 offset:3072
	s_add_u32 s12, s36, 0x28000
	s_addc_u32 s13, s37, 0
	s_mov_b32 m0, s38
	v_lshl_add_u64 v[138:139], s[12:13], 0, v[72:73]
	ds_read_b128 v[98:101], v80 offset:32768
	ds_read_b128 v[102:105], v80 offset:33792
	ds_read_b128 v[106:109], v80 offset:34816
	ds_read_b128 v[110:113], v80 offset:35840
	ds_read_b128 v[114:117], v80 offset:36864
	ds_read_b128 v[118:121], v80 offset:37888
	ds_read_b128 v[122:125], v80 offset:38912
	ds_read_b128 v[126:129], v80 offset:39936
	global_load_lds_dwordx4 v[138:139], off
	s_mov_b32 m0, s39
	v_lshl_add_u64 v[138:139], s[12:13], 0, v[68:69]
	global_load_lds_dwordx4 v[138:139], off
	s_waitcnt lgkmcnt(8)
	s_barrier
; #define PG8_STAGE(bufoff, gbase, voff) do { _Pragma("unroll") for (int _i = 0; _i < 2; ++_i) \
;         __builtin_amdgcn_global_load_lds((const unsigned*)((const char*)(gbase) + (voff)[_i]), (LAS unsigned*)(lds + (bufoff) + ldsw + _i * 8192), 16, 0, 0); } while (0)
; #define PG8_LDA(dst, b, h) do { _Pragma("unroll") for (int m = 0; m < 4; ++m) _Pragma("unroll") for (int k = 0; k < 2; ++k) dst[m][k] = *(const LAS bf16x8*)(lds + PG8_SA(b, h) + aoff + m * 2048 + k * 1024); } while (0)
; #define PG8_LDB(dst, b, h) do { _Pragma("unroll") for (int n = 0; n < 2; ++n) _Pragma("unroll") for (int k = 0; k < 2; ++k) dst[n][k] = *(const LAS bf16x8*)(lds + PG8_SB(b, h) + boff + n * 2048 + k * 1024); } while (0)
; #define PG8_MMA(ai, bj, At, Bt) do { __builtin_amdgcn_s_setprio(1); _Pragma("unroll") for (int m = 0; m < 4; ++m) _Pragma("unroll") for (int n = 0; n < 2; ++n) _Pragma("unroll") for (int k = 0; k < 2; ++k) \
;         acc[ai][bj][m][n] = __builtin_amdgcn_mfma_f32_16x16x32_bf16(Bt[n][k], At[m][k], acc[ai][bj][m][n], 0, 0, 0); __builtin_amdgcn_s_setprio(0); } while (0)
; #define PG8_WAIT_V(n) asm volatile("s_waitcnt vmcnt(" #n ")" ::: "memory")
; #define PG8_WAIT_L(n) asm volatile("s_waitcnt lgkmcnt(" #n ")" ::: "memory")
; template <class Epi>
; DEVI void gemm_phase(LAS unsigned char* lds, const Gemm g, const Epi& E) {
;     ...
;             PG8_WAIT_V(6); PG8_BAR; PG8_MMA(1, 1, At, B1); PG8_BAR;
;             PG8_LDB(B0, 1, 0); PG8_SCHED; PG8_LDA(At, 1, 0); PG8_STAGE(PG8_SA(0, 1), a2 + hstepA, voffA);
;             PG8_WAIT_L(8); PG8_BAR; PG8_WAIT_L(0); PG8_MMA(0, 0, At, B0); PG8_BAR; PG8_SCHED;
;             PG8_LDB(B1, 1, 1); PG8_STAGE(PG8_SB(1, 0), b3, voffB);
;             PG8_BAR; PG8_WAIT_L(0); PG8_MMA(0, 1, At, B1); PG8_BAR;
;             PG8_LDA(At, 1, 1); PG8_STAGE(PG8_SA(1, 0), a3, voffA);
;             PG8_BAR; PG8_WAIT_L(0); PG8_MMA(1, 0, At, B0); PG8_BAR; PG8_SCHED;
;             PG8_STAGE(PG8_SB(1, 1), b3 + hstepB, voffB);
;             PG8_WAIT_V(6); PG8_BAR; PG8_MMA(1, 1, At, B1); PG8_BAR;
;     ...
;         if (!has_next) break;
; #pragma unroll
;         for (int a = 0; a < 2; ++a)
; #pragma unroll
;             for (int b = 0; b < 2; ++b)
; #pragma unroll
;                 for (int m = 0; m < 4; ++m)
; #pragma unroll
;                     for (int n = 0; n < 2; ++n) acc[a][b][m][n] = (f32x4){0.f, 0.f, 0.f, 0.f};
;         cur = nxt; cA = nA; cB = nB; ++ui;
	s_waitcnt lgkmcnt(0)
	v_mfma_f32_16x16x32_bf16 v[62:65], v[82:85], v[98:101], v[62:65]
	v_mfma_f32_16x16x32_bf16 v[58:61], v[90:93], v[98:101], v[58:61]
	v_mfma_f32_16x16x32_bf16 v[54:57], v[82:85], v[106:109], v[54:57]
	v_mfma_f32_16x16x32_bf16 v[50:53], v[90:93], v[106:109], v[50:53]
	v_mfma_f32_16x16x32_bf16 v[46:49], v[82:85], v[114:117], v[46:49]
	v_mfma_f32_16x16x32_bf16 v[42:45], v[90:93], v[114:117], v[42:45]
	v_mfma_f32_16x16x32_bf16 v[38:41], v[82:85], v[122:125], v[38:41]
	v_mfma_f32_16x16x32_bf16 v[34:37], v[90:93], v[122:125], v[34:37]
	v_mfma_f32_16x16x32_bf16 v[62:65], v[86:89], v[102:105], v[62:65]
	v_mfma_f32_16x16x32_bf16 v[58:61], v[94:97], v[102:105], v[58:61]
	v_mfma_f32_16x16x32_bf16 v[54:57], v[86:89], v[110:113], v[54:57]
	v_mfma_f32_16x16x32_bf16 v[50:53], v[94:97], v[110:113], v[50:53]
	v_mfma_f32_16x16x32_bf16 v[46:49], v[86:89], v[118:121], v[46:49]
	v_mfma_f32_16x16x32_bf16 v[42:45], v[94:97], v[118:121], v[42:45]
	v_mfma_f32_16x16x32_bf16 v[38:41], v[86:89], v[126:129], v[38:41]
	v_mfma_f32_16x16x32_bf16 v[34:37], v[94:97], v[126:129], v[34:37]
	s_barrier
	s_add_i32 s12, s48, s1
	s_mov_b32 m0, s12
	v_lshl_add_u64 v[98:99], v[130:131], 0, s[70:71]
	global_load_lds_dwordx4 v[98:99], off
	s_add_i32 m0, s12, 0x2000
	v_lshl_add_u64 v[98:99], v[132:133], 0, s[70:71]
	global_load_lds_dwordx4 v[98:99], off
	s_barrier
	s_waitcnt lgkmcnt(0)
	s_mov_b32 m0, s41
	v_lshl_add_u64 v[130:131], v[134:135], 0, s[70:71]
	s_barrier
	ds_read_b128 v[98:101], v80 offset:49152
	ds_read_b128 v[102:105], v80 offset:50176
	ds_read_b128 v[106:109], v80 offset:51200
	ds_read_b128 v[110:113], v80 offset:52224
	ds_read_b128 v[114:117], v80 offset:53248
	ds_read_b128 v[118:121], v80 offset:54272
	ds_read_b128 v[122:125], v80 offset:55296
	ds_read_b128 v[126:129], v80 offset:56320
	global_load_lds_dwordx4 v[130:131], off
	s_mov_b32 m0, s42
	v_lshl_add_u64 v[130:131], v[136:137], 0, s[70:71]
	global_load_lds_dwordx4 v[130:131], off
	s_barrier
	s_waitcnt lgkmcnt(0)
	v_mfma_f32_16x16x32_bf16 v[30:33], v[82:85], v[98:101], v[30:33]
	v_mfma_f32_16x16x32_bf16 v[26:29], v[90:93], v[98:101], v[26:29]
	v_mfma_f32_16x16x32_bf16 v[22:25], v[82:85], v[106:109], v[22:25]
	v_mfma_f32_16x16x32_bf16 v[18:21], v[90:93], v[106:109], v[18:21]
	v_mfma_f32_16x16x32_bf16 v[14:17], v[82:85], v[114:117], v[14:17]
	v_mfma_f32_16x16x32_bf16 v[10:13], v[90:93], v[114:117], v[10:13]
	v_mfma_f32_16x16x32_bf16 v[4:7], v[82:85], v[122:125], v[4:7]
	v_mfma_f32_16x16x32_bf16 v[0:3], v[90:93], v[122:125], v[0:3]
	v_mfma_f32_16x16x32_bf16 v[30:33], v[86:89], v[102:105], v[30:33]
	v_mfma_f32_16x16x32_bf16 v[26:29], v[94:97], v[102:105], v[26:29]
	v_mfma_f32_16x16x32_bf16 v[22:25], v[86:89], v[110:113], v[22:25]
	v_mfma_f32_16x16x32_bf16 v[18:21], v[94:97], v[110:113], v[18:21]
	v_mfma_f32_16x16x32_bf16 v[14:17], v[86:89], v[118:121], v[14:17]
	v_mfma_f32_16x16x32_bf16 v[10:13], v[94:97], v[118:121], v[10:13]
	v_mfma_f32_16x16x32_bf16 v[4:7], v[86:89], v[126:129], v[4:7]
	v_mfma_f32_16x16x32_bf16 v[0:3], v[94:97], v[126:129], v[0:3]
	s_barrier
	s_add_u32 s12, s16, 0x20080
	s_addc_u32 s13, s17, 0
	s_mov_b32 m0, s43
	v_lshl_add_u64 v[82:83], s[12:13], 0, v[70:71]
	global_load_lds_dwordx4 v[82:83], off
	s_mov_b32 m0, s44
	v_lshl_add_u64 v[82:83], s[12:13], 0, v[66:67]
	global_load_lds_dwordx4 v[82:83], off
	s_waitcnt vmcnt(6)
	s_barrier
	s_add_i32 s47, s47, 2
	s_add_u32 s5, s5, 0x100
	s_addc_u32 s7, s7, 0
	s_cmp_gt_u32 s47, 5
	s_mov_b64 s[12:13], s[14:15]
	s_barrier
	s_cbranch_scc0 .LBB0_1127
	s_setprio 0
	s_ashr_i32 s5, s4, 31
	v_lshl_add_u32 v82, s40, 8, v78
	s_lshl_b64 s[4:5], s[4:5], 19
	v_readlane_b32 s7, v253, 50
	s_add_u32 s4, s7, s4
	v_readlane_b32 s7, v253, 51
	v_ashrrev_i32_e32 v83, 31, v82
	s_addc_u32 s5, s7, s5
	v_lshlrev_b64 v[84:85], 9, v[82:83]
	v_lshl_add_u64 v[84:85], s[4:5], 0, v[84:85]
	v_lshl_add_u64 v[84:85], v[84:85], 0, v[8:9]
	global_store_dwordx4 v[84:85], v[62:65], off
	global_store_dwordx4 v[84:85], v[58:61], off offset:64
	s_mov_b32 s40, s46
	s_mov_b64 s[14:15], s[10:11]
	v_or_b32_e32 v58, 16, v82
	v_ashrrev_i32_e32 v59, 31, v58
	v_lshlrev_b64 v[58:59], 9, v[58:59]
	v_lshl_add_u64 v[58:59], s[4:5], 0, v[58:59]
	v_lshl_add_u64 v[58:59], v[58:59], 0, v[8:9]
	global_store_dwordx4 v[58:59], v[54:57], off
	global_store_dwordx4 v[58:59], v[50:53], off offset:64
	s_mov_b64 s[12:13], s[8:9]
	s_nop 0
	v_or_b32_e32 v50, 32, v82
	v_ashrrev_i32_e32 v51, 31, v50
	v_lshlrev_b64 v[50:51], 9, v[50:51]
	v_lshl_add_u64 v[50:51], s[4:5], 0, v[50:51]
	v_lshl_add_u64 v[50:51], v[50:51], 0, v[8:9]
	global_store_dwordx4 v[50:51], v[46:49], off
	global_store_dwordx4 v[50:51], v[42:45], off offset:64
	s_nop 1
	v_or_b32_e32 v42, 48, v82
	v_ashrrev_i32_e32 v43, 31, v42
	v_lshlrev_b64 v[42:43], 9, v[42:43]
	v_lshl_add_u64 v[42:43], s[4:5], 0, v[42:43]
	v_lshl_add_u64 v[42:43], v[42:43], 0, v[8:9]
	s_mov_b64 s[4:5], 0x10000
	global_store_dwordx4 v[42:43], v[38:41], off
	global_store_dwordx4 v[42:43], v[34:37], off offset:64
	s_nop 1
	v_lshl_add_u64 v[34:35], v[84:85], 0, s[4:5]
	s_mov_b32 s4, 0x10000
	v_add_co_u32_e32 v36, vcc, s4, v84
	s_mov_b64 s[4:5], 0x12000
	s_nop 0
	v_addc_co_u32_e32 v37, vcc, 0, v85, vcc
	global_store_dwordx4 v[36:37], v[30:33], off
	global_store_dwordx4 v[34:35], v[26:29], off offset:64
	s_nop 1
	v_lshl_add_u64 v[26:27], v[84:85], 0, s[4:5]
	s_mov_b32 s4, 0x12000
	v_add_co_u32_e32 v28, vcc, s4, v84
	s_mov_b64 s[4:5], 0x14000
	s_nop 0
	v_addc_co_u32_e32 v29, vcc, 0, v85, vcc
	global_store_dwordx4 v[28:29], v[22:25], off
	global_store_dwordx4 v[26:27], v[18:21], off offset:64
	s_nop 1
	v_add_co_u32_e32 v20, vcc, 0x14000, v84
	v_lshl_add_u64 v[18:19], v[84:85], 0, s[4:5]
	s_nop 0
	v_addc_co_u32_e32 v21, vcc, 0, v85, vcc
	global_store_dwordx4 v[20:21], v[14:17], off
	global_store_dwordx4 v[18:19], v[10:13], off offset:64
	s_mov_b64 s[4:5], 0x16000
	s_nop 0
	v_add_co_u32_e32 v12, vcc, 0x16000, v84
	v_lshl_add_u64 v[10:11], v[84:85], 0, s[4:5]
	s_nop 0
	v_addc_co_u32_e32 v13, vcc, 0, v85, vcc
	s_and_b64 vcc, exec, s[2:3]
	s_mov_b32 s4, s6
	global_store_dwordx4 v[12:13], v[4:7], off
	global_store_dwordx4 v[10:11], v[0:3], off offset:64
	s_cbranch_vccz .LBB0_1122
	s_branch .LBB0_1131

; #define PG8_STAGE(bufoff, gbase, voff) do { _Pragma("unroll") for (int _i = 0; _i < 2; ++_i) \
;         __builtin_amdgcn_global_load_lds((const unsigned*)((const char*)(gbase) + (voff)[_i]), (LAS unsigned*)(lds + (bufoff) + ldsw + _i * 8192), 16, 0, 0); } while (0)
; #define PG8_LDA(dst, b, h) do { _Pragma("unroll") for (int m = 0; m < 4; ++m) _Pragma("unroll") for (int k = 0; k < 2; ++k) dst[m][k] = *(const LAS bf16x8*)(lds + PG8_SA(b, h) + aoff + m * 2048 + k * 1024); } while (0)
; #define PG8_LDB(dst, b, h) do { _Pragma("unroll") for (int n = 0; n < 2; ++n) _Pragma("unroll") for (int k = 0; k < 2; ++k) dst[n][k] = *(const LAS bf16x8*)(lds + PG8_SB(b, h) + boff + n * 2048 + k * 1024); } while (0)
; #define PG8_WAIT_V(n) asm volatile("s_waitcnt vmcnt(" #n ")" ::: "memory")
; #define PG8_WAIT_L(n) asm volatile("s_waitcnt lgkmcnt(" #n ")" ::: "memory")
; #define PG8_BAR __builtin_amdgcn_s_barrier()
; #define PG8_SCHED __builtin_amdgcn_sched_barrier(0)
; template <class Epi>
; DEVI void gemm_phase(LAS unsigned char* lds, const Gemm g, const Epi& E) {
;     ...
;         for (int t = 0; t < nt; t += 2) {
;             const bool last = (t == nt - 2);
;             const char* a1 = cA + (size_t)(t + 1) * kstep;
;             const char* a2 = last ? nA : cA + (size_t)(t + 2) * kstep; const char* b2 = last ? nB : cB + (size_t)(t + 2) * kstep;
;             const char* a3 = a2 + kstep; const char* b3 = b2 + kstep;
;             PG8_LDB(B0, 0, 0); PG8_SCHED; PG8_LDA(At, 0, 0); PG8_STAGE(PG8_SA(1, 1), a1 + hstepA, voffA);
;             PG8_WAIT_L(8); PG8_BAR; PG8_WAIT_L(0); PG8_MMA(0, 0, At, B0); PG8_BAR; PG8_SCHED;
;             PG8_LDB(B1, 0, 1); PG8_STAGE(PG8_SB(0, 0), b2, voffB);
;             PG8_BAR; PG8_WAIT_L(0); PG8_MMA(0, 1, At, B1); PG8_BAR;
;             PG8_LDA(At, 0, 1); PG8_STAGE(PG8_SA(0, 0), a2, voffA);
;             PG8_BAR; PG8_WAIT_L(0); PG8_MMA(1, 0, At, B0); PG8_BAR; PG8_SCHED;
;             PG8_STAGE(PG8_SB(0, 1), b2 + hstepB, voffB);
;             PG8_WAIT_V(6); PG8_BAR; PG8_MMA(1, 1, At, B1); PG8_BAR;
;             PG8_LDB(B0, 1, 0); PG8_SCHED; PG8_LDA(At, 1, 0); PG8_STAGE(PG8_SA(0, 1), a2 + hstepA, voffA);
;             PG8_WAIT_L(8); PG8_BAR; PG8_WAIT_L(0); PG8_MMA(0, 0, At, B0); PG8_BAR; PG8_SCHED;
;             PG8_LDB(B1, 1, 1); PG8_STAGE(PG8_SB(1, 0), b3, voffB);
;             PG8_BAR; PG8_WAIT_L(0); PG8_MMA(0, 1, At, B1); PG8_BAR;
.LBB0_1278:
	s_add_u32 s12, s10, 0x100
	s_addc_u32 s13, s11, 0
	s_add_i32 s38, 0, 0x10000
	v_add_u32_e32 v146, s38, v149
	ds_read_b128 v[142:145], v146
	ds_read_b128 v[176:179], v146 offset:1024
	ds_read_b128 v[180:183], v146 offset:2048
	ds_read_b128 v[184:187], v146 offset:3072
	s_cmp_eq_u32 s27, 6
	s_cselect_b32 s17, s5, s13
	s_cselect_b32 s16, s4, s12
	s_cselect_b32 s15, s7, s26
	s_cselect_b32 s14, s6, s19
	v_lshl_add_u64 v[146:147], s[10:11], 0, v[138:139]
	s_add_i32 m0, s46, 0xc000
	ds_read_b128 v[188:191], v151
	ds_read_b128 v[192:195], v151 offset:1024
	ds_read_b128 v[196:199], v151 offset:2048
	ds_read_b128 v[200:203], v151 offset:3072
	ds_read_b128 v[204:207], v151 offset:4096
	ds_read_b128 v[214:217], v151 offset:5120
	ds_read_b128 v[218:221], v151 offset:6144
	ds_read_b128 v[222:225], v151 offset:7168
	global_load_lds_dwordx4 v[146:147], off
	s_add_i32 m0, s46, 0xe000
	v_lshl_add_u64 v[146:147], s[10:11], 0, v[140:141]
	global_load_lds_dwordx4 v[146:147], off
	s_waitcnt lgkmcnt(8)
	s_barrier
	s_waitcnt lgkmcnt(0)
	v_mfma_f32_16x16x32_bf16 v[126:129], v[142:145], v[188:191], v[126:129]
	v_mfma_f32_16x16x32_bf16 v[122:125], v[180:183], v[188:191], v[122:125]
	v_mfma_f32_16x16x32_bf16 v[110:113], v[142:145], v[196:199], v[110:113]
	v_mfma_f32_16x16x32_bf16 v[106:109], v[180:183], v[196:199], v[106:109]
	v_mfma_f32_16x16x32_bf16 v[94:97], v[142:145], v[204:207], v[94:97]
	v_mfma_f32_16x16x32_bf16 v[90:93], v[180:183], v[204:207], v[90:93]
	v_mfma_f32_16x16x32_bf16 v[78:81], v[142:145], v[218:221], v[78:81]
	v_mfma_f32_16x16x32_bf16 v[74:77], v[180:183], v[218:221], v[74:77]
	v_mfma_f32_16x16x32_bf16 v[126:129], v[176:179], v[192:195], v[126:129]
	v_mfma_f32_16x16x32_bf16 v[122:125], v[184:187], v[192:195], v[122:125]
	v_mfma_f32_16x16x32_bf16 v[110:113], v[176:179], v[200:203], v[110:113]
	v_mfma_f32_16x16x32_bf16 v[106:109], v[184:187], v[200:203], v[106:109]
	v_mfma_f32_16x16x32_bf16 v[94:97], v[176:179], v[214:217], v[94:97]
	v_mfma_f32_16x16x32_bf16 v[90:93], v[184:187], v[214:217], v[90:93]
	v_mfma_f32_16x16x32_bf16 v[78:81], v[176:179], v[222:225], v[78:81]
	v_mfma_f32_16x16x32_bf16 v[74:77], v[184:187], v[222:225], v[74:77]
	s_barrier
	s_add_i32 s39, 0, 0x14000
	v_add_u32_e32 v146, s39, v149
	s_add_i32 s10, s38, s37
	ds_read_b128 v[226:229], v146
	ds_read_b128 v[230:233], v146 offset:1024
	ds_read_b128 v[234:237], v146 offset:2048
	ds_read_b128 v[238:241], v146 offset:3072
	v_lshl_add_u64 v[146:147], s[14:15], 0, v[8:9]
	s_mov_b32 m0, s10
	v_lshl_add_u64 v[152:153], s[14:15], 0, v[130:131]
	global_load_lds_dwordx4 v[146:147], off
	s_add_i32 m0, s10, 0x2000
	s_nop 0
	global_load_lds_dwordx4 v[152:153], off
	s_barrier
	s_waitcnt lgkmcnt(0)
	v_mfma_f32_16x16x32_bf16 v[118:121], v[226:229], v[188:191], v[118:121]
	v_mfma_f32_16x16x32_bf16 v[114:117], v[234:237], v[188:191], v[114:117]
	v_mfma_f32_16x16x32_bf16 v[102:105], v[226:229], v[196:199], v[102:105]
	v_mfma_f32_16x16x32_bf16 v[98:101], v[234:237], v[196:199], v[98:101]
	v_mfma_f32_16x16x32_bf16 v[86:89], v[226:229], v[204:207], v[86:89]
	v_mfma_f32_16x16x32_bf16 v[82:85], v[234:237], v[204:207], v[82:85]
	v_mfma_f32_16x16x32_bf16 v[70:73], v[226:229], v[218:221], v[70:73]
	v_mfma_f32_16x16x32_bf16 v[66:69], v[234:237], v[218:221], v[66:69]
	v_mfma_f32_16x16x32_bf16 v[118:121], v[230:233], v[192:195], v[118:121]
	v_mfma_f32_16x16x32_bf16 v[114:117], v[238:241], v[192:195], v[114:117]
	v_mfma_f32_16x16x32_bf16 v[102:105], v[230:233], v[200:203], v[102:105]
	v_mfma_f32_16x16x32_bf16 v[98:101], v[238:241], v[200:203], v[98:101]
	v_mfma_f32_16x16x32_bf16 v[86:89], v[230:233], v[214:217], v[86:89]
	v_mfma_f32_16x16x32_bf16 v[82:85], v[238:241], v[214:217], v[82:85]
	v_mfma_f32_16x16x32_bf16 v[70:73], v[230:233], v[222:225], v[70:73]
	v_mfma_f32_16x16x32_bf16 v[66:69], v[238:241], v[222:225], v[66:69]
	s_mov_b32 m0, s46
	v_lshl_add_u64 v[162:163], s[16:17], 0, v[134:135]
	s_barrier
	ds_read_b128 v[188:191], v151 offset:16384
	ds_read_b128 v[192:195], v151 offset:17408
	ds_read_b128 v[196:199], v151 offset:18432
	ds_read_b128 v[200:203], v151 offset:19456
	ds_read_b128 v[204:207], v151 offset:20480
	ds_read_b128 v[214:217], v151 offset:21504
	ds_read_b128 v[218:221], v151 offset:22528
	ds_read_b128 v[222:225], v151 offset:23552
	global_load_lds_dwordx4 v[162:163], off
	s_mov_b32 m0, s47
	v_lshl_add_u64 v[164:165], s[16:17], 0, v[132:133]
	global_load_lds_dwordx4 v[164:165], off
	s_barrier
	s_waitcnt lgkmcnt(0)
	v_mfma_f32_16x16x32_bf16 v[62:65], v[142:145], v[188:191], v[62:65]
	v_mfma_f32_16x16x32_bf16 v[58:61], v[180:183], v[188:191], v[58:61]
	v_mfma_f32_16x16x32_bf16 v[46:49], v[142:145], v[196:199], v[46:49]
	v_mfma_f32_16x16x32_bf16 v[42:45], v[180:183], v[196:199], v[42:45]
	v_mfma_f32_16x16x32_bf16 v[30:33], v[142:145], v[204:207], v[30:33]
	v_mfma_f32_16x16x32_bf16 v[26:29], v[180:183], v[204:207], v[26:29]
	v_mfma_f32_16x16x32_bf16 v[14:17], v[142:145], v[218:221], v[14:17]
	v_mfma_f32_16x16x32_bf16 v[10:13], v[180:183], v[218:221], v[10:13]
	v_mfma_f32_16x16x32_bf16 v[62:65], v[176:179], v[192:195], v[62:65]
	v_mfma_f32_16x16x32_bf16 v[58:61], v[184:187], v[192:195], v[58:61]
	v_mfma_f32_16x16x32_bf16 v[46:49], v[176:179], v[200:203], v[46:49]
	v_mfma_f32_16x16x32_bf16 v[42:45], v[184:187], v[200:203], v[42:45]
	v_mfma_f32_16x16x32_bf16 v[30:33], v[176:179], v[214:217], v[30:33]
	v_mfma_f32_16x16x32_bf16 v[26:29], v[184:187], v[214:217], v[26:29]
	v_mfma_f32_16x16x32_bf16 v[14:17], v[176:179], v[222:225], v[14:17]
	v_mfma_f32_16x16x32_bf16 v[10:13], v[184:187], v[222:225], v[10:13]
	s_barrier
; #define PG8_STAGE(bufoff, gbase, voff) do { _Pragma("unroll") for (int _i = 0; _i < 2; ++_i) \
;         __builtin_amdgcn_global_load_lds((const unsigned*)((const char*)(gbase) + (voff)[_i]), (LAS unsigned*)(lds + (bufoff) + ldsw + _i * 8192), 16, 0, 0); } while (0)
; #define PG8_LDA(dst, b, h) do { _Pragma("unroll") for (int m = 0; m < 4; ++m) _Pragma("unroll") for (int k = 0; k < 2; ++k) dst[m][k] = *(const LAS bf16x8*)(lds + PG8_SA(b, h) + aoff + m * 2048 + k * 1024); } while (0)
; #define PG8_LDB(dst, b, h) do { _Pragma("unroll") for (int n = 0; n < 2; ++n) _Pragma("unroll") for (int k = 0; k < 2; ++k) dst[n][k] = *(const LAS bf16x8*)(lds + PG8_SB(b, h) + boff + n * 2048 + k * 1024); } while (0)
; #define PG8_MMA(ai, bj, At, Bt) do { __builtin_amdgcn_s_setprio(1); _Pragma("unroll") for (int m = 0; m < 4; ++m) _Pragma("unroll") for (int n = 0; n < 2; ++n) _Pragma("unroll") for (int k = 0; k < 2; ++k) \
;         acc[ai][bj][m][n] = __builtin_amdgcn_mfma_f32_16x16x32_bf16(Bt[n][k], At[m][k], acc[ai][bj][m][n], 0, 0, 0); __builtin_amdgcn_s_setprio(0); } while (0)
; #define PG8_WAIT_V(n) asm volatile("s_waitcnt vmcnt(" #n ")" ::: "memory")
; #define PG8_WAIT_L(n) asm volatile("s_waitcnt lgkmcnt(" #n ")" ::: "memory")
; #define PG8_BAR __builtin_amdgcn_s_barrier()
; #define PG8_SCHED __builtin_amdgcn_sched_barrier(0)
; template <class Epi>
; DEVI void gemm_phase(LAS unsigned char* lds, const Gemm g, const Epi& E) {
;     ...
;             PG8_STAGE(PG8_SB(0, 1), b2 + hstepB, voffB);
;             PG8_WAIT_V(6); PG8_BAR; PG8_MMA(1, 1, At, B1); PG8_BAR;
;             PG8_LDB(B0, 1, 0); PG8_SCHED; PG8_LDA(At, 1, 0); PG8_STAGE(PG8_SA(0, 1), a2 + hstepA, voffA);
;             PG8_WAIT_L(8); PG8_BAR; PG8_WAIT_L(0); PG8_MMA(0, 0, At, B0); PG8_BAR; PG8_SCHED;
;             PG8_LDB(B1, 1, 1); PG8_STAGE(PG8_SB(1, 0), b3, voffB);
;             PG8_BAR; PG8_WAIT_L(0); PG8_MMA(0, 1, At, B1); PG8_BAR;
;             PG8_LDA(At, 1, 1); PG8_STAGE(PG8_SA(1, 0), a3, voffA);
;             PG8_BAR; PG8_WAIT_L(0); PG8_MMA(1, 0, At, B0); PG8_BAR; PG8_SCHED;
	s_add_u32 s10, s14, 0x28000
	s_addc_u32 s11, s15, 0
	s_add_i32 s38, s39, s37
	s_mov_b32 m0, s38
	v_lshl_add_u64 v[142:143], s[10:11], 0, v[8:9]
	global_load_lds_dwordx4 v[142:143], off
	s_add_i32 m0, s38, 0x2000
	v_lshl_add_u64 v[142:143], s[10:11], 0, v[130:131]
	global_load_lds_dwordx4 v[142:143], off
	s_waitcnt vmcnt(6)
	s_barrier
	v_mfma_f32_16x16x32_bf16 v[54:57], v[226:229], v[188:191], v[54:57]
	v_mfma_f32_16x16x32_bf16 v[50:53], v[234:237], v[188:191], v[50:53]
	v_mfma_f32_16x16x32_bf16 v[38:41], v[226:229], v[196:199], v[38:41]
	v_mfma_f32_16x16x32_bf16 v[34:37], v[234:237], v[196:199], v[34:37]
	v_mfma_f32_16x16x32_bf16 v[22:25], v[226:229], v[204:207], v[22:25]
	v_mfma_f32_16x16x32_bf16 v[18:21], v[234:237], v[204:207], v[18:21]
	v_mfma_f32_16x16x32_bf16 v[4:7], v[226:229], v[218:221], v[4:7]
	v_mfma_f32_16x16x32_bf16 v[0:3], v[234:237], v[218:221], v[0:3]
	v_mfma_f32_16x16x32_bf16 v[54:57], v[230:233], v[192:195], v[54:57]
	v_mfma_f32_16x16x32_bf16 v[50:53], v[238:241], v[192:195], v[50:53]
	v_mfma_f32_16x16x32_bf16 v[38:41], v[230:233], v[200:203], v[38:41]
	v_mfma_f32_16x16x32_bf16 v[34:37], v[238:241], v[200:203], v[34:37]
	v_mfma_f32_16x16x32_bf16 v[22:25], v[230:233], v[214:217], v[22:25]
	v_mfma_f32_16x16x32_bf16 v[18:21], v[238:241], v[214:217], v[18:21]
	v_mfma_f32_16x16x32_bf16 v[4:7], v[230:233], v[222:225], v[4:7]
	v_mfma_f32_16x16x32_bf16 v[0:3], v[238:241], v[222:225], v[0:3]
	s_add_i32 s38, 0, 0x18000
	v_add_u32_e32 v184, s38, v149
	s_barrier
	ds_read_b128 v[142:145], v184
	ds_read_b128 v[176:179], v184 offset:1024
	ds_read_b128 v[180:183], v184 offset:2048
	ds_read_b128 v[184:187], v184 offset:3072
	s_add_u32 s10, s16, 0x28000
	s_addc_u32 s11, s17, 0
	s_mov_b32 m0, s66
	v_lshl_add_u64 v[208:209], s[10:11], 0, v[134:135]
	ds_read_b128 v[188:191], v151 offset:32768
	ds_read_b128 v[192:195], v151 offset:33792
	ds_read_b128 v[196:199], v151 offset:34816
	ds_read_b128 v[200:203], v151 offset:35840
	ds_read_b128 v[204:207], v151 offset:36864
	ds_read_b128 v[214:217], v151 offset:37888
	ds_read_b128 v[218:221], v151 offset:38912
	ds_read_b128 v[222:225], v151 offset:39936
	global_load_lds_dwordx4 v[208:209], off
	s_mov_b32 m0, s68
	v_lshl_add_u64 v[208:209], s[10:11], 0, v[132:133]
	global_load_lds_dwordx4 v[208:209], off
	s_waitcnt lgkmcnt(8)
	s_barrier
	s_waitcnt lgkmcnt(0)
	v_mfma_f32_16x16x32_bf16 v[126:129], v[142:145], v[188:191], v[126:129]
	v_mfma_f32_16x16x32_bf16 v[122:125], v[180:183], v[188:191], v[122:125]
	v_mfma_f32_16x16x32_bf16 v[110:113], v[142:145], v[196:199], v[110:113]
	v_mfma_f32_16x16x32_bf16 v[106:109], v[180:183], v[196:199], v[106:109]
	v_mfma_f32_16x16x32_bf16 v[94:97], v[142:145], v[204:207], v[94:97]
	v_mfma_f32_16x16x32_bf16 v[90:93], v[180:183], v[204:207], v[90:93]
	v_mfma_f32_16x16x32_bf16 v[78:81], v[142:145], v[218:221], v[78:81]
	v_mfma_f32_16x16x32_bf16 v[74:77], v[180:183], v[218:221], v[74:77]
	v_mfma_f32_16x16x32_bf16 v[126:129], v[176:179], v[192:195], v[126:129]
	v_mfma_f32_16x16x32_bf16 v[122:125], v[184:187], v[192:195], v[122:125]
	v_mfma_f32_16x16x32_bf16 v[110:113], v[176:179], v[200:203], v[110:113]
	v_mfma_f32_16x16x32_bf16 v[106:109], v[184:187], v[200:203], v[106:109]
	v_mfma_f32_16x16x32_bf16 v[94:97], v[176:179], v[214:217], v[94:97]
	v_mfma_f32_16x16x32_bf16 v[90:93], v[184:187], v[214:217], v[90:93]
	v_mfma_f32_16x16x32_bf16 v[78:81], v[176:179], v[222:225], v[78:81]
	v_mfma_f32_16x16x32_bf16 v[74:77], v[184:187], v[222:225], v[74:77]
	s_barrier
	s_add_i32 s16, 0, 0x1c000
	s_add_i32 s10, s38, s37
	v_add_u32_e32 v208, s16, v149
	v_lshl_add_u64 v[146:147], v[146:147], 0, s[70:71]
	s_mov_b32 m0, s10
	ds_read_b128 v[226:229], v208
	ds_read_b128 v[230:233], v208 offset:1024
	ds_read_b128 v[234:237], v208 offset:2048
	ds_read_b128 v[238:241], v208 offset:3072
	global_load_lds_dwordx4 v[146:147], off
	s_add_i32 m0, s10, 0x2000
	v_lshl_add_u64 v[146:147], v[152:153], 0, s[70:71]
	global_load_lds_dwordx4 v[146:147], off
	s_barrier
	s_waitcnt lgkmcnt(0)
	v_mfma_f32_16x16x32_bf16 v[118:121], v[226:229], v[188:191], v[118:121]
	v_mfma_f32_16x16x32_bf16 v[114:117], v[234:237], v[188:191], v[114:117]
	v_mfma_f32_16x16x32_bf16 v[102:105], v[226:229], v[196:199], v[102:105]
	v_mfma_f32_16x16x32_bf16 v[98:101], v[234:237], v[196:199], v[98:101]
	v_mfma_f32_16x16x32_bf16 v[86:89], v[226:229], v[204:207], v[86:89]
	v_mfma_f32_16x16x32_bf16 v[82:85], v[234:237], v[204:207], v[82:85]
	v_mfma_f32_16x16x32_bf16 v[70:73], v[226:229], v[218:221], v[70:73]
	v_mfma_f32_16x16x32_bf16 v[66:69], v[234:237], v[218:221], v[66:69]
	v_mfma_f32_16x16x32_bf16 v[118:121], v[230:233], v[192:195], v[118:121]
	v_mfma_f32_16x16x32_bf16 v[114:117], v[238:241], v[192:195], v[114:117]
	v_mfma_f32_16x16x32_bf16 v[102:105], v[230:233], v[200:203], v[102:105]
	v_mfma_f32_16x16x32_bf16 v[98:101], v[238:241], v[200:203], v[98:101]
	v_mfma_f32_16x16x32_bf16 v[86:89], v[230:233], v[214:217], v[86:89]
	v_mfma_f32_16x16x32_bf16 v[82:85], v[238:241], v[214:217], v[82:85]
	v_mfma_f32_16x16x32_bf16 v[70:73], v[230:233], v[222:225], v[70:73]
	v_mfma_f32_16x16x32_bf16 v[66:69], v[238:241], v[222:225], v[66:69]
	s_mov_b32 m0, s69
	v_lshl_add_u64 v[146:147], v[162:163], 0, s[70:71]
	s_barrier
	ds_read_b128 v[188:191], v151 offset:49152
	ds_read_b128 v[192:195], v151 offset:50176
	ds_read_b128 v[196:199], v151 offset:51200
	ds_read_b128 v[200:203], v151 offset:52224
	ds_read_b128 v[204:207], v151 offset:53248
	ds_read_b128 v[214:217], v151 offset:54272
	ds_read_b128 v[218:221], v151 offset:55296
	ds_read_b128 v[222:225], v151 offset:56320
	global_load_lds_dwordx4 v[146:147], off
	s_mov_b32 m0, s80
	v_lshl_add_u64 v[146:147], v[164:165], 0, s[70:71]
	global_load_lds_dwordx4 v[146:147], off
	s_barrier
; #define PG8_STAGE(bufoff, gbase, voff) do { _Pragma("unroll") for (int _i = 0; _i < 2; ++_i) \
;         __builtin_amdgcn_global_load_lds((const unsigned*)((const char*)(gbase) + (voff)[_i]), (LAS unsigned*)(lds + (bufoff) + ldsw + _i * 8192), 16, 0, 0); } while (0)
; #define PG8_MMA(ai, bj, At, Bt) do { __builtin_amdgcn_s_setprio(1); _Pragma("unroll") for (int m = 0; m < 4; ++m) _Pragma("unroll") for (int n = 0; n < 2; ++n) _Pragma("unroll") for (int k = 0; k < 2; ++k) \
;         acc[ai][bj][m][n] = __builtin_amdgcn_mfma_f32_16x16x32_bf16(Bt[n][k], At[m][k], acc[ai][bj][m][n], 0, 0, 0); __builtin_amdgcn_s_setprio(0); } while (0)
; #define PG8_WAIT_V(n) asm volatile("s_waitcnt vmcnt(" #n ")" ::: "memory")
; #define PG8_BAR __builtin_amdgcn_s_barrier()
; template <class Epi>
; DEVI void gemm_phase(LAS unsigned char* lds, const Gemm g, const Epi& E) {
;     ...
;             PG8_STAGE(PG8_SB(1, 1), b3 + hstepB, voffB);
;             PG8_WAIT_V(6); PG8_BAR; PG8_MMA(1, 1, At, B1); PG8_BAR;
;     ...
;                 for (int mm = 0; mm < 2; ++mm) {
;                     const int m = m0 + mm;
;                     const int r = row0 + ai * HALF + m * 16; float rs = 1.f, part = 0.f;
;                     if constexpr (Epi::RS) rs = rsv[ai * 4 + m];
;                     if constexpr (Epi::PAIR) E.pair8(cur.b, r, cur.pn * HALF + wc * 32 + 8 * fq, acc[ai][0][m][0] * rs, acc[ai][0][m][1] * rs, acc[ai][1][m][0] * rs, acc[ai][1][m][1] * rs);
;                     else
; #pragma unroll
;                     for (int bj = 0; bj < 2; ++bj) {
;                         const int c = col0 + bj * HALF; f32x4 v0 = acc[ai][bj][m][0], v1 = acc[ai][bj][m][1];
;                         if constexpr (Epi::RS) { v0 = v0 * rs; v1 = v1 * rs; }
;                         if constexpr (Epi::PRE) part += E.frag_pre8(cur.b, r, c, v0, v1, pre[mm][bj][0], pre[mm][bj][1]);
;                         else if constexpr (Epi::PERM) E.frag8(cur.b, r, c, v0, v1);
;                         else { E.frag(cur.b, r, c, v0); E.frag(cur.b, r, c + 16, v1); }
;                     }
	s_waitcnt lgkmcnt(0)
	v_mfma_f32_16x16x32_bf16 v[62:65], v[142:145], v[188:191], v[62:65]
	v_mfma_f32_16x16x32_bf16 v[58:61], v[180:183], v[188:191], v[58:61]
	v_mfma_f32_16x16x32_bf16 v[46:49], v[142:145], v[196:199], v[46:49]
	v_mfma_f32_16x16x32_bf16 v[42:45], v[180:183], v[196:199], v[42:45]
	v_mfma_f32_16x16x32_bf16 v[30:33], v[142:145], v[204:207], v[30:33]
	v_mfma_f32_16x16x32_bf16 v[26:29], v[180:183], v[204:207], v[26:29]
	v_mfma_f32_16x16x32_bf16 v[14:17], v[142:145], v[218:221], v[14:17]
	v_mfma_f32_16x16x32_bf16 v[10:13], v[180:183], v[218:221], v[10:13]
	v_mfma_f32_16x16x32_bf16 v[62:65], v[176:179], v[192:195], v[62:65]
	v_mfma_f32_16x16x32_bf16 v[58:61], v[184:187], v[192:195], v[58:61]
	v_mfma_f32_16x16x32_bf16 v[46:49], v[176:179], v[200:203], v[46:49]
	v_mfma_f32_16x16x32_bf16 v[42:45], v[184:187], v[200:203], v[42:45]
	v_mfma_f32_16x16x32_bf16 v[30:33], v[176:179], v[214:217], v[30:33]
	v_mfma_f32_16x16x32_bf16 v[26:29], v[184:187], v[214:217], v[26:29]
	v_mfma_f32_16x16x32_bf16 v[14:17], v[176:179], v[222:225], v[14:17]
	v_mfma_f32_16x16x32_bf16 v[10:13], v[184:187], v[222:225], v[10:13]
	s_barrier
	s_add_u32 s10, s14, 0x28080
	s_addc_u32 s11, s15, 0
	s_add_i32 s14, s16, s37
	s_mov_b32 m0, s14
	v_lshl_add_u64 v[142:143], s[10:11], 0, v[8:9]
	global_load_lds_dwordx4 v[142:143], off
	s_add_i32 m0, s14, 0x2000
	v_lshl_add_u64 v[142:143], s[10:11], 0, v[130:131]
	global_load_lds_dwordx4 v[142:143], off
	s_waitcnt vmcnt(6)
	s_barrier
	v_mfma_f32_16x16x32_bf16 v[54:57], v[226:229], v[188:191], v[54:57]
	v_mfma_f32_16x16x32_bf16 v[50:53], v[234:237], v[188:191], v[50:53]
	v_mfma_f32_16x16x32_bf16 v[38:41], v[226:229], v[196:199], v[38:41]
	v_mfma_f32_16x16x32_bf16 v[34:37], v[234:237], v[196:199], v[34:37]
	v_mfma_f32_16x16x32_bf16 v[22:25], v[226:229], v[204:207], v[22:25]
	v_mfma_f32_16x16x32_bf16 v[18:21], v[234:237], v[204:207], v[18:21]
	v_mfma_f32_16x16x32_bf16 v[4:7], v[226:229], v[218:221], v[4:7]
	v_mfma_f32_16x16x32_bf16 v[0:3], v[234:237], v[218:221], v[0:3]
	v_mfma_f32_16x16x32_bf16 v[54:57], v[230:233], v[192:195], v[54:57]
	v_mfma_f32_16x16x32_bf16 v[50:53], v[238:241], v[192:195], v[50:53]
	v_mfma_f32_16x16x32_bf16 v[38:41], v[230:233], v[200:203], v[38:41]
	v_mfma_f32_16x16x32_bf16 v[34:37], v[238:241], v[200:203], v[34:37]
	v_mfma_f32_16x16x32_bf16 v[22:25], v[230:233], v[214:217], v[22:25]
	v_mfma_f32_16x16x32_bf16 v[18:21], v[238:241], v[214:217], v[18:21]
	v_mfma_f32_16x16x32_bf16 v[4:7], v[230:233], v[222:225], v[4:7]
	v_mfma_f32_16x16x32_bf16 v[0:3], v[238:241], v[222:225], v[0:3]
	s_add_i32 s27, s27, 2
	s_add_u32 s19, s19, 0x100
	s_addc_u32 s26, s26, 0
	s_cmp_gt_u32 s27, 7
	s_mov_b64 s[10:11], s[12:13]
	s_barrier
	s_cbranch_scc0 .LBB0_1278
	s_setprio 0
	v_lshl_add_u32 v144, s18, 8, v148
	v_ashrrev_i32_e32 v145, 31, v144
	v_lshlrev_b64 v[142:143], 16, v[144:145]
	v_mul_f32_e32 v145, 0x3d372713, v126
	v_mul_f32_e32 v145, v126, v145
	v_fma_f32 v145, v126, v145, v126
	v_mul_f32_e32 v145, 0x3f4c422a, v145
	v_add_f32_e32 v145, v145, v145
	v_mul_f32_e32 v145, 0xbfb8aa3b, v145
	v_exp_f32_e32 v145, v145
	v_lshl_or_b32 v164, s1, 8, v150
	s_lshl_b32 s0, s0, 4
	s_ashr_i32 s1, s0, 31
	v_add_f32_e32 v145, 1.0, v145
	v_rcp_f32_e32 v152, v145
	v_mul_f32_e32 v145, 0x3d372713, v122
	v_mul_f32_e32 v145, v122, v145
	v_fma_f32 v145, v122, v145, v122
	v_mul_f32_e32 v145, 0x3f4c422a, v145
	v_add_f32_e32 v145, v145, v145
	v_mul_f32_e32 v145, 0xbfb8aa3b, v145
	v_exp_f32_e32 v145, v145
	v_lshl_add_u64 v[146:147], s[0:1], 1, v[136:137]
	v_lshl_add_u64 v[142:143], v[146:147], 0, v[142:143]
	s_mov_b64 s[0:1], 0x800000
	v_add_f32_e32 v145, 1.0, v145
	v_rcp_f32_e32 v162, v145
	v_mul_f32_e32 v145, 0x3d372713, v127
	v_mul_f32_e32 v145, v127, v145
	v_fma_f32 v145, v127, v145, v127
	v_mul_f32_e32 v145, 0x3f4c422a, v145
	v_add_f32_e32 v145, v145, v145
	v_mul_f32_e32 v145, 0xbfb8aa3b, v145
	v_exp_f32_e32 v145, v145
	s_and_b64 vcc, exec, s[2:3]
	s_mov_b32 s18, s82
	s_mov_b64 s[12:13], s[6:7]
	v_add_f32_e32 v145, 1.0, v145
	v_rcp_f32_e32 v153, v145
	v_mul_f32_e32 v145, 0x3d372713, v123
	v_mul_f32_e32 v145, v123, v145
	v_fma_f32 v145, v123, v145, v123
	v_mul_f32_e32 v145, 0x3f4c422a, v145
	v_add_f32_e32 v145, v145, v145
	v_mul_f32_e32 v145, 0xbfb8aa3b, v145
	v_exp_f32_e32 v145, v145
	v_pk_mul_f32 v[126:127], v[126:127], v[152:153]
	s_mov_b64 s[10:11], s[4:5]
	v_add_f32_e32 v145, 1.0, v145
	v_rcp_f32_e32 v163, v145
	v_mul_f32_e32 v145, 0x3d372713, v128
	v_mul_f32_e32 v145, v128, v145
	v_fma_f32 v145, v128, v145, v128
	v_mul_f32_e32 v145, 0x3f4c422a, v145
	v_add_f32_e32 v145, v145, v145
	v_mul_f32_e32 v145, 0xbfb8aa3b, v145
	v_exp_f32_e32 v145, v145
	v_pk_mul_f32 v[122:123], v[122:123], v[162:163]
	v_add_f32_e32 v145, 1.0, v145
	v_rcp_f32_e32 v152, v145
	v_mul_f32_e32 v145, 0x3d372713, v124
	v_mul_f32_e32 v145, v124, v145
	v_fma_f32 v145, v124, v145, v124
	v_mul_f32_e32 v145, 0x3f4c422a, v145
	v_add_f32_e32 v145, v145, v145
	v_mul_f32_e32 v145, 0xbfb8aa3b, v145
	v_exp_f32_e32 v145, v145
	s_nop 0
	v_add_f32_e32 v145, 1.0, v145
	v_rcp_f32_e32 v162, v145
	v_mul_f32_e32 v145, 0x3d372713, v129
	v_mul_f32_e32 v145, v129, v145
	v_fma_f32 v145, v129, v145, v129
	v_mul_f32_e32 v145, 0x3f4c422a, v145
	v_add_f32_e32 v145, v145, v145
	v_mul_f32_e32 v145, 0xbfb8aa3b, v145
	v_exp_f32_e32 v145, v145
	s_nop 0
	v_add_f32_e32 v145, 1.0, v145
	v_rcp_f32_e32 v153, v145
	v_mul_f32_e32 v145, 0x3d372713, v125
	v_mul_f32_e32 v145, v125, v145
	v_fma_f32 v145, v125, v145, v125
	v_mul_f32_e32 v145, 0x3f4c422a, v145
	v_add_f32_e32 v145, v145, v145
	v_mul_f32_e32 v145, 0xbfb8aa3b, v145
	v_exp_f32_e32 v145, v145
	v_pk_mul_f32 v[128:129], v[128:129], v[152:153]
; template <class Epi>
; DEVI void gemm_phase(LAS unsigned char* lds, const Gemm g, const Epi& E) {
;     ...
;                 for (int mm = 0; mm < 2; ++mm) {
;                     const int m = m0 + mm;
;                     const int r = row0 + ai * HALF + m * 16; float rs = 1.f, part = 0.f;
;                     if constexpr (Epi::RS) rs = rsv[ai * 4 + m];
;                     if constexpr (Epi::PAIR) E.pair8(cur.b, r, cur.pn * HALF + wc * 32 + 8 * fq, acc[ai][0][m][0] * rs, acc[ai][0][m][1] * rs, acc[ai][1][m][0] * rs, acc[ai][1][m][1] * rs);
;                     else
; #pragma unroll
;                     for (int bj = 0; bj < 2; ++bj) {
;                         const int c = col0 + bj * HALF; f32x4 v0 = acc[ai][bj][m][0], v1 = acc[ai][bj][m][1];
;                         if constexpr (Epi::RS) { v0 = v0 * rs; v1 = v1 * rs; }
;                         if constexpr (Epi::PRE) part += E.frag_pre8(cur.b, r, c, v0, v1, pre[mm][bj][0], pre[mm][bj][1]);
;                         else if constexpr (Epi::PERM) E.frag8(cur.b, r, c, v0, v1);
;                         else { E.frag(cur.b, r, c, v0); E.frag(cur.b, r, c + 16, v1); }
;                     }
	v_add_f32_e32 v145, 1.0, v145
	v_rcp_f32_e32 v163, v145
	s_nop 0
	v_pk_mul_f32 v[152:153], v[124:125], v[162:163]
	v_cvt_pk_bf16_f32 v125, v128, v129
	v_ashrrev_i32_e32 v128, 4, v164
	v_ashrrev_i32_e32 v129, 31, v128
	v_cvt_pk_bf16_f32 v124, v126, v127
	v_cvt_pk_bf16_f32 v126, v122, v123
	v_lshlrev_b64 v[122:123], 11, v[128:129]
	v_cvt_pk_bf16_f32 v127, v152, v153
	v_lshl_add_u64 v[152:153], v[142:143], 0, v[122:123]
	global_store_dwordx4 v[152:153], v[124:127], off
	s_nop 1
	v_mul_f32_e32 v125, 0x3d372713, v114
	v_mul_f32_e32 v125, v114, v125
	v_fma_f32 v125, v114, v125, v114
	v_mul_f32_e32 v125, 0x3f4c422a, v125
	v_add_f32_e32 v125, v125, v125
	v_mul_f32_e32 v125, 0xbfb8aa3b, v125
	v_exp_f32_e32 v125, v125
	v_mul_f32_e32 v124, 0x3d372713, v118
	v_mul_f32_e32 v124, v118, v124
	v_fma_f32 v124, v118, v124, v118
	v_add_f32_e32 v125, 1.0, v125
	v_rcp_f32_e32 v126, v125
	v_mul_f32_e32 v125, 0x3d372713, v119
	v_mul_f32_e32 v125, v119, v125
	v_fma_f32 v125, v119, v125, v119
	v_mul_f32_e32 v124, 0x3f4c422a, v124
	v_mul_f32_e32 v125, 0x3f4c422a, v125
	v_add_f32_e32 v124, v124, v124
	v_add_f32_e32 v125, v125, v125
	v_mul_f32_e32 v124, 0xbfb8aa3b, v124
	v_mul_f32_e32 v125, 0xbfb8aa3b, v125
	v_exp_f32_e32 v124, v124
	v_exp_f32_e32 v125, v125
	v_add_f32_e32 v124, 1.0, v124
	v_add_f32_e32 v125, 1.0, v125
	v_rcp_f32_e32 v124, v124
	v_rcp_f32_e32 v125, v125
	s_nop 0
	v_pk_mul_f32 v[118:119], v[118:119], v[124:125]
	v_mul_f32_e32 v124, 0x3d372713, v115
	v_mul_f32_e32 v124, v115, v124
	v_fma_f32 v124, v115, v124, v115
	v_mul_f32_e32 v124, 0x3f4c422a, v124
	v_add_f32_e32 v124, v124, v124
	v_mul_f32_e32 v125, 0x3d372713, v116
	v_mul_f32_e32 v124, 0xbfb8aa3b, v124
	v_mul_f32_e32 v125, v116, v125
	v_exp_f32_e32 v124, v124
	v_fma_f32 v125, v116, v125, v116
	v_mul_f32_e32 v125, 0x3f4c422a, v125
	v_add_f32_e32 v125, v125, v125
	v_mul_f32_e32 v125, 0xbfb8aa3b, v125
	v_add_f32_e32 v124, 1.0, v124
	v_exp_f32_e32 v125, v125
	v_rcp_f32_e32 v127, v124
	v_mul_f32_e32 v124, 0x3d372713, v120
	v_mul_f32_e32 v124, v120, v124
	v_add_f32_e32 v125, 1.0, v125
	v_pk_mul_f32 v[114:115], v[114:115], v[126:127]
	v_rcp_f32_e32 v126, v125
	v_mul_f32_e32 v125, 0x3d372713, v121
	v_mul_f32_e32 v125, v121, v125
	v_fma_f32 v124, v120, v124, v120
	v_fma_f32 v125, v121, v125, v121
	v_mul_f32_e32 v124, 0x3f4c422a, v124
	v_mul_f32_e32 v125, 0x3f4c422a, v125
	v_add_f32_e32 v124, v124, v124
	v_add_f32_e32 v125, v125, v125
	v_mul_f32_e32 v124, 0xbfb8aa3b, v124
	v_mul_f32_e32 v125, 0xbfb8aa3b, v125
	v_exp_f32_e32 v124, v124
	v_exp_f32_e32 v125, v125
	v_add_f32_e32 v124, 1.0, v124
	v_add_f32_e32 v125, 1.0, v125
	v_rcp_f32_e32 v124, v124
	v_rcp_f32_e32 v125, v125
	s_nop 0
	v_pk_mul_f32 v[120:121], v[120:121], v[124:125]
	v_mul_f32_e32 v124, 0x3d372713, v117
	v_mul_f32_e32 v124, v117, v124
	v_fma_f32 v124, v117, v124, v117
	v_mul_f32_e32 v124, 0x3f4c422a, v124
	v_add_f32_e32 v124, v124, v124
	v_mul_f32_e32 v124, 0xbfb8aa3b, v124
	v_exp_f32_e32 v124, v124
	s_nop 0
	v_add_f32_e32 v124, 1.0, v124
	v_rcp_f32_e32 v127, v124
	s_nop 0
	v_pk_mul_f32 v[124:125], v[116:117], v[126:127]
	v_cvt_pk_bf16_f32 v116, v118, v119
	v_cvt_pk_bf16_f32 v118, v114, v115
	v_or_b32_e32 v114, 8, v128
	v_ashrrev_i32_e32 v115, 31, v114
	v_lshlrev_b64 v[114:115], 11, v[114:115]
	v_cvt_pk_bf16_f32 v117, v120, v121
	v_cvt_pk_bf16_f32 v119, v124, v125
	v_lshl_add_u64 v[120:121], v[142:143], 0, v[114:115]
	global_store_dwordx4 v[120:121], v[116:119], off
	s_nop 1
	v_mul_f32_e32 v119, 0x3d372713, v106
	v_mul_f32_e32 v119, v106, v119
	v_fma_f32 v119, v106, v119, v106
	v_mul_f32_e32 v119, 0x3f4c422a, v119
	v_add_f32_e32 v119, v119, v119
	v_mul_f32_e32 v119, 0xbfb8aa3b, v119
	v_exp_f32_e32 v119, v119
	v_mul_f32_e32 v118, 0x3d372713, v110
	v_mul_f32_e32 v118, v110, v118
	v_fma_f32 v118, v110, v118, v110
	v_add_f32_e32 v119, 1.0, v119
	v_rcp_f32_e32 v120, v119
	v_mul_f32_e32 v119, 0x3d372713, v111
	v_mul_f32_e32 v119, v111, v119
	v_fma_f32 v119, v111, v119, v111
	v_mul_f32_e32 v118, 0x3f4c422a, v118
	v_mul_f32_e32 v119, 0x3f4c422a, v119
	v_add_f32_e32 v118, v118, v118
	v_add_f32_e32 v119, v119, v119
	v_mul_f32_e32 v118, 0xbfb8aa3b, v118
	v_mul_f32_e32 v119, 0xbfb8aa3b, v119
	v_exp_f32_e32 v118, v118
	v_exp_f32_e32 v119, v119
	v_or_b32_e32 v116, 16, v144
	v_ashrrev_i32_e32 v117, 31, v116
	v_add_f32_e32 v118, 1.0, v118
	v_add_f32_e32 v119, 1.0, v119
	v_rcp_f32_e32 v118, v118
	v_rcp_f32_e32 v119, v119
	v_lshlrev_b64 v[116:117], 16, v[116:117]
	v_lshl_add_u64 v[116:117], v[146:147], 0, v[116:117]
	v_pk_mul_f32 v[110:111], v[110:111], v[118:119]
	v_mul_f32_e32 v118, 0x3d372713, v107
	v_mul_f32_e32 v118, v107, v118
	v_fma_f32 v118, v107, v118, v107
	v_mul_f32_e32 v118, 0x3f4c422a, v118
	v_add_f32_e32 v118, v118, v118
	v_mul_f32_e32 v118, 0xbfb8aa3b, v118
	v_exp_f32_e32 v118, v118
	s_nop 0
	v_add_f32_e32 v118, 1.0, v118
	v_rcp_f32_e32 v121, v118
	s_nop 0
	v_pk_mul_f32 v[118:119], v[106:107], v[120:121]
	v_mul_f32_e32 v107, 0x3d372713, v108
	v_mul_f32_e32 v107, v108, v107
	v_fma_f32 v107, v108, v107, v108
	v_mul_f32_e32 v107, 0x3f4c422a, v107
	v_add_f32_e32 v107, v107, v107
	v_mul_f32_e32 v107, 0xbfb8aa3b, v107
	v_exp_f32_e32 v107, v107
	v_mul_f32_e32 v106, 0x3d372713, v112
	v_mul_f32_e32 v106, v112, v106
	v_fma_f32 v106, v112, v106, v112
	v_add_f32_e32 v107, 1.0, v107
	v_rcp_f32_e32 v120, v107
	v_mul_f32_e32 v107, 0x3d372713, v113
	v_mul_f32_e32 v107, v113, v107
	v_fma_f32 v107, v113, v107, v113
	v_mul_f32_e32 v106, 0x3f4c422a, v106
	v_mul_f32_e32 v107, 0x3f4c422a, v107
	v_add_f32_e32 v106, v106, v106
	v_add_f32_e32 v107, v107, v107
	v_mul_f32_e32 v106, 0xbfb8aa3b, v106
	v_mul_f32_e32 v107, 0xbfb8aa3b, v107
	v_exp_f32_e32 v106, v106
; template <class Epi>
; DEVI void gemm_phase(LAS unsigned char* lds, const Gemm g, const Epi& E) {
;     ...
;                 for (int mm = 0; mm < 2; ++mm) {
;                     const int m = m0 + mm;
;                     const int r = row0 + ai * HALF + m * 16; float rs = 1.f, part = 0.f;
;                     if constexpr (Epi::RS) rs = rsv[ai * 4 + m];
;                     if constexpr (Epi::PAIR) E.pair8(cur.b, r, cur.pn * HALF + wc * 32 + 8 * fq, acc[ai][0][m][0] * rs, acc[ai][0][m][1] * rs, acc[ai][1][m][0] * rs, acc[ai][1][m][1] * rs);
;                     else
; #pragma unroll
;                     for (int bj = 0; bj < 2; ++bj) {
;                         const int c = col0 + bj * HALF; f32x4 v0 = acc[ai][bj][m][0], v1 = acc[ai][bj][m][1];
;                         if constexpr (Epi::RS) { v0 = v0 * rs; v1 = v1 * rs; }
;                         if constexpr (Epi::PRE) part += E.frag_pre8(cur.b, r, c, v0, v1, pre[mm][bj][0], pre[mm][bj][1]);
;                         else if constexpr (Epi::PERM) E.frag8(cur.b, r, c, v0, v1);
;                         else { E.frag(cur.b, r, c, v0); E.frag(cur.b, r, c + 16, v1); }
;                     }
	v_exp_f32_e32 v107, v107
	v_add_f32_e32 v106, 1.0, v106
	v_add_f32_e32 v107, 1.0, v107
	v_rcp_f32_e32 v106, v106
	v_rcp_f32_e32 v107, v107
	s_nop 0
	v_pk_mul_f32 v[112:113], v[112:113], v[106:107]
	v_mul_f32_e32 v106, 0x3d372713, v109
	v_mul_f32_e32 v106, v109, v106
	v_fma_f32 v106, v109, v106, v109
	v_mul_f32_e32 v106, 0x3f4c422a, v106
	v_add_f32_e32 v106, v106, v106
	v_mul_f32_e32 v106, 0xbfb8aa3b, v106
	v_exp_f32_e32 v106, v106
	v_cvt_pk_bf16_f32 v107, v112, v113
	v_add_f32_e32 v106, 1.0, v106
	v_rcp_f32_e32 v121, v106
	v_cvt_pk_bf16_f32 v106, v110, v111
	v_lshl_add_u64 v[110:111], v[116:117], 0, v[122:123]
	v_pk_mul_f32 v[120:121], v[108:109], v[120:121]
	v_cvt_pk_bf16_f32 v108, v118, v119
	v_cvt_pk_bf16_f32 v109, v120, v121
	global_store_dwordx4 v[110:111], v[106:109], off
	s_nop 1
	v_mul_f32_e32 v107, 0x3d372713, v98
	v_mul_f32_e32 v107, v98, v107
	v_fma_f32 v107, v98, v107, v98
	v_mul_f32_e32 v107, 0x3f4c422a, v107
	v_add_f32_e32 v107, v107, v107
	v_mul_f32_e32 v107, 0xbfb8aa3b, v107
	v_exp_f32_e32 v107, v107
	v_mul_f32_e32 v106, 0x3d372713, v102
	v_mul_f32_e32 v106, v102, v106
	v_fma_f32 v106, v102, v106, v102
	v_add_f32_e32 v107, 1.0, v107
	v_rcp_f32_e32 v108, v107
	v_mul_f32_e32 v107, 0x3d372713, v103
	v_mul_f32_e32 v107, v103, v107
	v_fma_f32 v107, v103, v107, v103
	v_mul_f32_e32 v106, 0x3f4c422a, v106
	v_mul_f32_e32 v107, 0x3f4c422a, v107
	v_add_f32_e32 v106, v106, v106
	v_add_f32_e32 v107, v107, v107
	v_mul_f32_e32 v106, 0xbfb8aa3b, v106
	v_mul_f32_e32 v107, 0xbfb8aa3b, v107
	v_exp_f32_e32 v106, v106
	v_exp_f32_e32 v107, v107
	v_add_f32_e32 v106, 1.0, v106
	v_add_f32_e32 v107, 1.0, v107
	v_rcp_f32_e32 v106, v106
	v_rcp_f32_e32 v107, v107
	s_nop 0
	v_pk_mul_f32 v[102:103], v[102:103], v[106:107]
	v_mul_f32_e32 v106, 0x3d372713, v99
	v_mul_f32_e32 v106, v99, v106
	v_fma_f32 v106, v99, v106, v99
	v_mul_f32_e32 v106, 0x3f4c422a, v106
	v_add_f32_e32 v106, v106, v106
	v_mul_f32_e32 v106, 0xbfb8aa3b, v106
	v_exp_f32_e32 v106, v106
	s_nop 0
	v_add_f32_e32 v106, 1.0, v106
	v_rcp_f32_e32 v109, v106
	s_nop 0
	v_pk_mul_f32 v[106:107], v[98:99], v[108:109]
	v_mul_f32_e32 v99, 0x3d372713, v100
	v_mul_f32_e32 v99, v100, v99
	v_fma_f32 v99, v100, v99, v100
	v_mul_f32_e32 v99, 0x3f4c422a, v99
	v_add_f32_e32 v99, v99, v99
	v_mul_f32_e32 v99, 0xbfb8aa3b, v99
	v_exp_f32_e32 v99, v99
	v_mul_f32_e32 v98, 0x3d372713, v104
	v_mul_f32_e32 v98, v104, v98
	v_fma_f32 v98, v104, v98, v104
	v_add_f32_e32 v99, 1.0, v99
	v_rcp_f32_e32 v108, v99
	v_mul_f32_e32 v99, 0x3d372713, v105
	v_mul_f32_e32 v99, v105, v99
	v_fma_f32 v99, v105, v99, v105
	v_mul_f32_e32 v98, 0x3f4c422a, v98
	v_mul_f32_e32 v99, 0x3f4c422a, v99
	v_add_f32_e32 v98, v98, v98
	v_add_f32_e32 v99, v99, v99
	v_mul_f32_e32 v98, 0xbfb8aa3b, v98
	v_mul_f32_e32 v99, 0xbfb8aa3b, v99
	v_exp_f32_e32 v98, v98
	v_exp_f32_e32 v99, v99
	v_add_f32_e32 v98, 1.0, v98
	v_add_f32_e32 v99, 1.0, v99
	v_rcp_f32_e32 v98, v98
	v_rcp_f32_e32 v99, v99
	s_nop 0
	v_pk_mul_f32 v[104:105], v[104:105], v[98:99]
	v_mul_f32_e32 v98, 0x3d372713, v101
	v_mul_f32_e32 v98, v101, v98
	v_fma_f32 v98, v101, v98, v101
	v_mul_f32_e32 v98, 0x3f4c422a, v98
	v_add_f32_e32 v98, v98, v98
	v_mul_f32_e32 v98, 0xbfb8aa3b, v98
	v_exp_f32_e32 v98, v98
	v_cvt_pk_bf16_f32 v99, v104, v105
	v_add_f32_e32 v98, 1.0, v98
	v_rcp_f32_e32 v109, v98
	v_cvt_pk_bf16_f32 v98, v102, v103
	v_lshl_add_u64 v[102:103], v[116:117], 0, v[114:115]
	v_pk_mul_f32 v[108:109], v[100:101], v[108:109]
	v_cvt_pk_bf16_f32 v100, v106, v107
	v_cvt_pk_bf16_f32 v101, v108, v109
	global_store_dwordx4 v[102:103], v[98:101], off
	s_nop 1
	v_mul_f32_e32 v101, 0x3d372713, v90
	v_mul_f32_e32 v101, v90, v101
	v_fma_f32 v101, v90, v101, v90
	v_mul_f32_e32 v101, 0x3f4c422a, v101
	v_add_f32_e32 v101, v101, v101
	v_mul_f32_e32 v101, 0xbfb8aa3b, v101
	v_exp_f32_e32 v101, v101
	v_mul_f32_e32 v100, 0x3d372713, v94
	v_mul_f32_e32 v100, v94, v100
	v_fma_f32 v100, v94, v100, v94
	v_add_f32_e32 v101, 1.0, v101
	v_rcp_f32_e32 v102, v101
	v_mul_f32_e32 v101, 0x3d372713, v95
	v_mul_f32_e32 v101, v95, v101
	v_fma_f32 v101, v95, v101, v95
	v_mul_f32_e32 v100, 0x3f4c422a, v100
	v_mul_f32_e32 v101, 0x3f4c422a, v101
	v_add_f32_e32 v100, v100, v100
	v_add_f32_e32 v101, v101, v101
	v_mul_f32_e32 v100, 0xbfb8aa3b, v100
	v_mul_f32_e32 v101, 0xbfb8aa3b, v101
	v_exp_f32_e32 v100, v100
	v_exp_f32_e32 v101, v101
	v_or_b32_e32 v98, 32, v144
	v_ashrrev_i32_e32 v99, 31, v98
	v_add_f32_e32 v100, 1.0, v100
	v_add_f32_e32 v101, 1.0, v101
	v_rcp_f32_e32 v100, v100
	v_rcp_f32_e32 v101, v101
	v_lshlrev_b64 v[98:99], 16, v[98:99]
	v_lshl_add_u64 v[98:99], v[146:147], 0, v[98:99]
	v_pk_mul_f32 v[94:95], v[94:95], v[100:101]
	v_mul_f32_e32 v100, 0x3d372713, v91
	v_mul_f32_e32 v100, v91, v100
	v_fma_f32 v100, v91, v100, v91
	v_mul_f32_e32 v100, 0x3f4c422a, v100
	v_add_f32_e32 v100, v100, v100
	v_mul_f32_e32 v100, 0xbfb8aa3b, v100
	v_exp_f32_e32 v100, v100
	s_nop 0
	v_add_f32_e32 v100, 1.0, v100
	v_rcp_f32_e32 v103, v100
	s_nop 0
	v_pk_mul_f32 v[100:101], v[90:91], v[102:103]
	v_mul_f32_e32 v91, 0x3d372713, v92
	v_mul_f32_e32 v91, v92, v91
	v_fma_f32 v91, v92, v91, v92
	v_mul_f32_e32 v91, 0x3f4c422a, v91
	v_add_f32_e32 v91, v91, v91
	v_mul_f32_e32 v91, 0xbfb8aa3b, v91
	v_exp_f32_e32 v91, v91
	v_mul_f32_e32 v90, 0x3d372713, v96
	v_mul_f32_e32 v90, v96, v90
	v_fma_f32 v90, v96, v90, v96
	v_add_f32_e32 v91, 1.0, v91
	v_rcp_f32_e32 v102, v91
	v_mul_f32_e32 v91, 0x3d372713, v97
	v_mul_f32_e32 v91, v97, v91
	v_fma_f32 v91, v97, v91, v97
	v_mul_f32_e32 v90, 0x3f4c422a, v90
	v_mul_f32_e32 v91, 0x3f4c422a, v91
	v_add_f32_e32 v90, v90, v90
	v_add_f32_e32 v91, v91, v91
	v_mul_f32_e32 v90, 0xbfb8aa3b, v90
	v_mul_f32_e32 v91, 0xbfb8aa3b, v91
; template <class Epi>
; DEVI void gemm_phase(LAS unsigned char* lds, const Gemm g, const Epi& E) {
;     ...
;                 for (int mm = 0; mm < 2; ++mm) {
;                     const int m = m0 + mm;
;                     const int r = row0 + ai * HALF + m * 16; float rs = 1.f, part = 0.f;
;                     if constexpr (Epi::RS) rs = rsv[ai * 4 + m];
;                     if constexpr (Epi::PAIR) E.pair8(cur.b, r, cur.pn * HALF + wc * 32 + 8 * fq, acc[ai][0][m][0] * rs, acc[ai][0][m][1] * rs, acc[ai][1][m][0] * rs, acc[ai][1][m][1] * rs);
;                     else
; #pragma unroll
;                     for (int bj = 0; bj < 2; ++bj) {
;                         const int c = col0 + bj * HALF; f32x4 v0 = acc[ai][bj][m][0], v1 = acc[ai][bj][m][1];
;                         if constexpr (Epi::RS) { v0 = v0 * rs; v1 = v1 * rs; }
;                         if constexpr (Epi::PRE) part += E.frag_pre8(cur.b, r, c, v0, v1, pre[mm][bj][0], pre[mm][bj][1]);
;                         else if constexpr (Epi::PERM) E.frag8(cur.b, r, c, v0, v1);
;                         else { E.frag(cur.b, r, c, v0); E.frag(cur.b, r, c + 16, v1); }
;                     }
	v_exp_f32_e32 v90, v90
	v_exp_f32_e32 v91, v91
	v_add_f32_e32 v90, 1.0, v90
	v_add_f32_e32 v91, 1.0, v91
	v_rcp_f32_e32 v90, v90
	v_rcp_f32_e32 v91, v91
	s_nop 0
	v_pk_mul_f32 v[96:97], v[96:97], v[90:91]
	v_mul_f32_e32 v90, 0x3d372713, v93
	v_mul_f32_e32 v90, v93, v90
	v_fma_f32 v90, v93, v90, v93
	v_mul_f32_e32 v90, 0x3f4c422a, v90
	v_add_f32_e32 v90, v90, v90
	v_mul_f32_e32 v90, 0xbfb8aa3b, v90
	v_exp_f32_e32 v90, v90
	v_cvt_pk_bf16_f32 v91, v96, v97
	v_add_f32_e32 v90, 1.0, v90
	v_rcp_f32_e32 v103, v90
	v_cvt_pk_bf16_f32 v90, v94, v95
	v_lshl_add_u64 v[94:95], v[98:99], 0, v[122:123]
	v_pk_mul_f32 v[102:103], v[92:93], v[102:103]
	v_cvt_pk_bf16_f32 v92, v100, v101
	v_cvt_pk_bf16_f32 v93, v102, v103
	global_store_dwordx4 v[94:95], v[90:93], off
	s_nop 1
	v_mul_f32_e32 v91, 0x3d372713, v82
	v_mul_f32_e32 v91, v82, v91
	v_fma_f32 v91, v82, v91, v82
	v_mul_f32_e32 v91, 0x3f4c422a, v91
	v_add_f32_e32 v91, v91, v91
	v_mul_f32_e32 v91, 0xbfb8aa3b, v91
	v_exp_f32_e32 v91, v91
	v_mul_f32_e32 v90, 0x3d372713, v86
	v_mul_f32_e32 v90, v86, v90
	v_fma_f32 v90, v86, v90, v86
	v_add_f32_e32 v91, 1.0, v91
	v_rcp_f32_e32 v92, v91
	v_mul_f32_e32 v91, 0x3d372713, v87
	v_mul_f32_e32 v91, v87, v91
	v_fma_f32 v91, v87, v91, v87
	v_mul_f32_e32 v90, 0x3f4c422a, v90
	v_mul_f32_e32 v91, 0x3f4c422a, v91
	v_add_f32_e32 v90, v90, v90
	v_add_f32_e32 v91, v91, v91
	v_mul_f32_e32 v90, 0xbfb8aa3b, v90
	v_mul_f32_e32 v91, 0xbfb8aa3b, v91
	v_exp_f32_e32 v90, v90
	v_exp_f32_e32 v91, v91
	v_add_f32_e32 v90, 1.0, v90
	v_add_f32_e32 v91, 1.0, v91
	v_rcp_f32_e32 v90, v90
	v_rcp_f32_e32 v91, v91
	s_nop 0
	v_pk_mul_f32 v[86:87], v[86:87], v[90:91]
	v_mul_f32_e32 v90, 0x3d372713, v83
	v_mul_f32_e32 v90, v83, v90
	v_fma_f32 v90, v83, v90, v83
	v_mul_f32_e32 v90, 0x3f4c422a, v90
	v_add_f32_e32 v90, v90, v90
	v_mul_f32_e32 v90, 0xbfb8aa3b, v90
	v_exp_f32_e32 v90, v90
	s_nop 0
	v_add_f32_e32 v90, 1.0, v90
	v_rcp_f32_e32 v93, v90
	s_nop 0
	v_pk_mul_f32 v[90:91], v[82:83], v[92:93]
	v_mul_f32_e32 v83, 0x3d372713, v84
	v_mul_f32_e32 v83, v84, v83
	v_fma_f32 v83, v84, v83, v84
	v_mul_f32_e32 v83, 0x3f4c422a, v83
	v_add_f32_e32 v83, v83, v83
	v_mul_f32_e32 v83, 0xbfb8aa3b, v83
	v_exp_f32_e32 v83, v83
	v_mul_f32_e32 v82, 0x3d372713, v88
	v_mul_f32_e32 v82, v88, v82
	v_fma_f32 v82, v88, v82, v88
	v_add_f32_e32 v83, 1.0, v83
	v_rcp_f32_e32 v92, v83
	v_mul_f32_e32 v83, 0x3d372713, v89
	v_mul_f32_e32 v83, v89, v83
	v_fma_f32 v83, v89, v83, v89
	v_mul_f32_e32 v82, 0x3f4c422a, v82
	v_mul_f32_e32 v83, 0x3f4c422a, v83
	v_add_f32_e32 v82, v82, v82
	v_add_f32_e32 v83, v83, v83
	v_mul_f32_e32 v82, 0xbfb8aa3b, v82
	v_mul_f32_e32 v83, 0xbfb8aa3b, v83
	v_exp_f32_e32 v82, v82
	v_exp_f32_e32 v83, v83
	v_add_f32_e32 v82, 1.0, v82
	v_add_f32_e32 v83, 1.0, v83
	v_rcp_f32_e32 v82, v82
	v_rcp_f32_e32 v83, v83
	s_nop 0
	v_pk_mul_f32 v[88:89], v[88:89], v[82:83]
	v_mul_f32_e32 v82, 0x3d372713, v85
	v_mul_f32_e32 v82, v85, v82
	v_fma_f32 v82, v85, v82, v85
	v_mul_f32_e32 v82, 0x3f4c422a, v82
	v_add_f32_e32 v82, v82, v82
	v_mul_f32_e32 v82, 0xbfb8aa3b, v82
	v_exp_f32_e32 v82, v82
	v_cvt_pk_bf16_f32 v83, v88, v89
	v_add_f32_e32 v82, 1.0, v82
	v_rcp_f32_e32 v93, v82
	v_cvt_pk_bf16_f32 v82, v86, v87
	v_lshl_add_u64 v[86:87], v[98:99], 0, v[114:115]
	v_pk_mul_f32 v[92:93], v[84:85], v[92:93]
	v_cvt_pk_bf16_f32 v84, v90, v91
	v_cvt_pk_bf16_f32 v85, v92, v93
	global_store_dwordx4 v[86:87], v[82:85], off
	s_nop 1
	v_mul_f32_e32 v85, 0x3d372713, v74
	v_mul_f32_e32 v85, v74, v85
	v_fma_f32 v85, v74, v85, v74
	v_mul_f32_e32 v85, 0x3f4c422a, v85
	v_add_f32_e32 v85, v85, v85
	v_mul_f32_e32 v85, 0xbfb8aa3b, v85
	v_exp_f32_e32 v85, v85
	v_mul_f32_e32 v84, 0x3d372713, v78
	v_mul_f32_e32 v84, v78, v84
	v_fma_f32 v84, v78, v84, v78
	v_add_f32_e32 v85, 1.0, v85
	v_rcp_f32_e32 v86, v85
	v_mul_f32_e32 v85, 0x3d372713, v79
	v_mul_f32_e32 v85, v79, v85
	v_fma_f32 v85, v79, v85, v79
	v_mul_f32_e32 v84, 0x3f4c422a, v84
	v_mul_f32_e32 v85, 0x3f4c422a, v85
	v_add_f32_e32 v84, v84, v84
	v_add_f32_e32 v85, v85, v85
	v_mul_f32_e32 v84, 0xbfb8aa3b, v84
	v_mul_f32_e32 v85, 0xbfb8aa3b, v85
	v_exp_f32_e32 v84, v84
	v_exp_f32_e32 v85, v85
	v_or_b32_e32 v82, 48, v144
	v_ashrrev_i32_e32 v83, 31, v82
	v_add_f32_e32 v84, 1.0, v84
	v_add_f32_e32 v85, 1.0, v85
	v_rcp_f32_e32 v84, v84
	v_rcp_f32_e32 v85, v85
	v_lshlrev_b64 v[82:83], 16, v[82:83]
	v_lshl_add_u64 v[82:83], v[146:147], 0, v[82:83]
	v_pk_mul_f32 v[78:79], v[78:79], v[84:85]
	v_mul_f32_e32 v84, 0x3d372713, v75
	v_mul_f32_e32 v84, v75, v84
	v_fma_f32 v84, v75, v84, v75
	v_mul_f32_e32 v84, 0x3f4c422a, v84
	v_add_f32_e32 v84, v84, v84
	v_mul_f32_e32 v84, 0xbfb8aa3b, v84
	v_exp_f32_e32 v84, v84
	s_nop 0
	v_add_f32_e32 v84, 1.0, v84
	v_rcp_f32_e32 v87, v84
	s_nop 0
	v_pk_mul_f32 v[84:85], v[74:75], v[86:87]
	v_mul_f32_e32 v75, 0x3d372713, v76
	v_mul_f32_e32 v75, v76, v75
	v_fma_f32 v75, v76, v75, v76
	v_mul_f32_e32 v75, 0x3f4c422a, v75
	v_add_f32_e32 v75, v75, v75
	v_mul_f32_e32 v75, 0xbfb8aa3b, v75
	v_exp_f32_e32 v75, v75
	v_mul_f32_e32 v74, 0x3d372713, v80
	v_mul_f32_e32 v74, v80, v74
	v_fma_f32 v74, v80, v74, v80
	v_add_f32_e32 v75, 1.0, v75
	v_rcp_f32_e32 v86, v75
	v_mul_f32_e32 v75, 0x3d372713, v81
	v_mul_f32_e32 v75, v81, v75
	v_fma_f32 v75, v81, v75, v81
	v_mul_f32_e32 v74, 0x3f4c422a, v74
	v_mul_f32_e32 v75, 0x3f4c422a, v75
	v_add_f32_e32 v74, v74, v74
	v_add_f32_e32 v75, v75, v75
	v_mul_f32_e32 v74, 0xbfb8aa3b, v74
	v_mul_f32_e32 v75, 0xbfb8aa3b, v75
	v_exp_f32_e32 v74, v74
	v_exp_f32_e32 v75, v75
	v_add_f32_e32 v74, 1.0, v74
	v_add_f32_e32 v75, 1.0, v75
	v_rcp_f32_e32 v74, v74
	v_rcp_f32_e32 v75, v75
	s_nop 0
	v_pk_mul_f32 v[80:81], v[80:81], v[74:75]
	v_mul_f32_e32 v74, 0x3d372713, v77
; template <class Epi>
; DEVI void gemm_phase(LAS unsigned char* lds, const Gemm g, const Epi& E) {
;     ...
;                 for (int mm = 0; mm < 2; ++mm) {
;                     const int m = m0 + mm;
;                     const int r = row0 + ai * HALF + m * 16; float rs = 1.f, part = 0.f;
;                     if constexpr (Epi::RS) rs = rsv[ai * 4 + m];
;                     if constexpr (Epi::PAIR) E.pair8(cur.b, r, cur.pn * HALF + wc * 32 + 8 * fq, acc[ai][0][m][0] * rs, acc[ai][0][m][1] * rs, acc[ai][1][m][0] * rs, acc[ai][1][m][1] * rs);
;                     else
; #pragma unroll
;                     for (int bj = 0; bj < 2; ++bj) {
;                         const int c = col0 + bj * HALF; f32x4 v0 = acc[ai][bj][m][0], v1 = acc[ai][bj][m][1];
;                         if constexpr (Epi::RS) { v0 = v0 * rs; v1 = v1 * rs; }
;                         if constexpr (Epi::PRE) part += E.frag_pre8(cur.b, r, c, v0, v1, pre[mm][bj][0], pre[mm][bj][1]);
;                         else if constexpr (Epi::PERM) E.frag8(cur.b, r, c, v0, v1);
;                         else { E.frag(cur.b, r, c, v0); E.frag(cur.b, r, c + 16, v1); }
;                     }
	v_mul_f32_e32 v74, v77, v74
	v_fma_f32 v74, v77, v74, v77
	v_mul_f32_e32 v74, 0x3f4c422a, v74
	v_add_f32_e32 v74, v74, v74
	v_mul_f32_e32 v74, 0xbfb8aa3b, v74
	v_exp_f32_e32 v74, v74
	v_cvt_pk_bf16_f32 v75, v80, v81
	v_add_f32_e32 v74, 1.0, v74
	v_rcp_f32_e32 v87, v74
	v_cvt_pk_bf16_f32 v74, v78, v79
	v_lshl_add_u64 v[78:79], v[82:83], 0, v[122:123]
	v_pk_mul_f32 v[86:87], v[76:77], v[86:87]
	v_cvt_pk_bf16_f32 v76, v84, v85
	v_cvt_pk_bf16_f32 v77, v86, v87
	global_store_dwordx4 v[78:79], v[74:77], off
	s_nop 1
	v_mul_f32_e32 v75, 0x3d372713, v66
	v_mul_f32_e32 v75, v66, v75
	v_fma_f32 v75, v66, v75, v66
	v_mul_f32_e32 v75, 0x3f4c422a, v75
	v_add_f32_e32 v75, v75, v75
	v_mul_f32_e32 v75, 0xbfb8aa3b, v75
	v_exp_f32_e32 v75, v75
	v_mul_f32_e32 v74, 0x3d372713, v70
	v_mul_f32_e32 v74, v70, v74
	v_fma_f32 v74, v70, v74, v70
	v_add_f32_e32 v75, 1.0, v75
	v_rcp_f32_e32 v76, v75
	v_mul_f32_e32 v75, 0x3d372713, v71
	v_mul_f32_e32 v75, v71, v75
	v_fma_f32 v75, v71, v75, v71
	v_mul_f32_e32 v74, 0x3f4c422a, v74
	v_mul_f32_e32 v75, 0x3f4c422a, v75
	v_add_f32_e32 v74, v74, v74
	v_add_f32_e32 v75, v75, v75
	v_mul_f32_e32 v74, 0xbfb8aa3b, v74
	v_mul_f32_e32 v75, 0xbfb8aa3b, v75
	v_exp_f32_e32 v74, v74
	v_exp_f32_e32 v75, v75
	v_add_f32_e32 v74, 1.0, v74
	v_add_f32_e32 v75, 1.0, v75
	v_rcp_f32_e32 v74, v74
	v_rcp_f32_e32 v75, v75
	s_nop 0
	v_pk_mul_f32 v[70:71], v[70:71], v[74:75]
	v_mul_f32_e32 v74, 0x3d372713, v67
	v_mul_f32_e32 v74, v67, v74
	v_fma_f32 v74, v67, v74, v67
	v_mul_f32_e32 v74, 0x3f4c422a, v74
	v_add_f32_e32 v74, v74, v74
	v_mul_f32_e32 v74, 0xbfb8aa3b, v74
	v_exp_f32_e32 v74, v74
	s_nop 0
	v_add_f32_e32 v74, 1.0, v74
	v_rcp_f32_e32 v77, v74
	s_nop 0
	v_pk_mul_f32 v[74:75], v[66:67], v[76:77]
	v_mul_f32_e32 v67, 0x3d372713, v68
	v_mul_f32_e32 v67, v68, v67
	v_fma_f32 v67, v68, v67, v68
	v_mul_f32_e32 v67, 0x3f4c422a, v67
	v_add_f32_e32 v67, v67, v67
	v_mul_f32_e32 v67, 0xbfb8aa3b, v67
	v_exp_f32_e32 v67, v67
	v_mul_f32_e32 v66, 0x3d372713, v72
	v_mul_f32_e32 v66, v72, v66
	v_fma_f32 v66, v72, v66, v72
	v_add_f32_e32 v67, 1.0, v67
	v_rcp_f32_e32 v76, v67
	v_mul_f32_e32 v67, 0x3d372713, v73
	v_mul_f32_e32 v67, v73, v67
	v_fma_f32 v67, v73, v67, v73
	v_mul_f32_e32 v66, 0x3f4c422a, v66
	v_mul_f32_e32 v67, 0x3f4c422a, v67
	v_add_f32_e32 v66, v66, v66
	v_add_f32_e32 v67, v67, v67
	v_mul_f32_e32 v66, 0xbfb8aa3b, v66
	v_mul_f32_e32 v67, 0xbfb8aa3b, v67
	v_exp_f32_e32 v66, v66
	v_exp_f32_e32 v67, v67
	v_add_f32_e32 v66, 1.0, v66
	v_add_f32_e32 v67, 1.0, v67
	v_rcp_f32_e32 v66, v66
	v_rcp_f32_e32 v67, v67
	s_nop 0
	v_pk_mul_f32 v[72:73], v[72:73], v[66:67]
	v_mul_f32_e32 v66, 0x3d372713, v69
	v_mul_f32_e32 v66, v69, v66
	v_fma_f32 v66, v69, v66, v69
	v_mul_f32_e32 v66, 0x3f4c422a, v66
	v_add_f32_e32 v66, v66, v66
	v_mul_f32_e32 v66, 0xbfb8aa3b, v66
	v_exp_f32_e32 v66, v66
	v_cvt_pk_bf16_f32 v67, v72, v73
	v_add_f32_e32 v66, 1.0, v66
	v_rcp_f32_e32 v77, v66
	v_cvt_pk_bf16_f32 v66, v70, v71
	v_lshl_add_u64 v[70:71], v[82:83], 0, v[114:115]
	v_pk_mul_f32 v[76:77], v[68:69], v[76:77]
	v_cvt_pk_bf16_f32 v68, v74, v75
	v_cvt_pk_bf16_f32 v69, v76, v77
	global_store_dwordx4 v[70:71], v[66:69], off
	s_nop 1
	v_mul_f32_e32 v69, 0x3d372713, v58
	v_mul_f32_e32 v69, v58, v69
	v_fma_f32 v69, v58, v69, v58
	v_mul_f32_e32 v69, 0x3f4c422a, v69
	v_add_f32_e32 v69, v69, v69
	v_mul_f32_e32 v69, 0xbfb8aa3b, v69
	v_exp_f32_e32 v69, v69
	v_mul_f32_e32 v68, 0x3d372713, v62
	v_mul_f32_e32 v68, v62, v68
	v_fma_f32 v68, v62, v68, v62
	v_add_f32_e32 v69, 1.0, v69
	v_rcp_f32_e32 v70, v69
	v_mul_f32_e32 v69, 0x3d372713, v63
	v_mul_f32_e32 v69, v63, v69
	v_fma_f32 v69, v63, v69, v63
	v_mul_f32_e32 v68, 0x3f4c422a, v68
	v_mul_f32_e32 v69, 0x3f4c422a, v69
	v_add_f32_e32 v68, v68, v68
	v_add_f32_e32 v69, v69, v69
	v_mul_f32_e32 v68, 0xbfb8aa3b, v68
	v_mul_f32_e32 v69, 0xbfb8aa3b, v69
	v_exp_f32_e32 v68, v68
	v_exp_f32_e32 v69, v69
	v_lshl_add_u64 v[66:67], v[142:143], 0, s[0:1]
	s_mov_b64 s[0:1], 0x900000
	v_add_f32_e32 v68, 1.0, v68
	v_add_f32_e32 v69, 1.0, v69
	v_rcp_f32_e32 v68, v68
	v_rcp_f32_e32 v69, v69
	s_nop 0
	v_pk_mul_f32 v[62:63], v[62:63], v[68:69]
	v_mul_f32_e32 v68, 0x3d372713, v59
	v_mul_f32_e32 v68, v59, v68
	v_fma_f32 v68, v59, v68, v59
	v_mul_f32_e32 v68, 0x3f4c422a, v68
	v_add_f32_e32 v68, v68, v68
	v_mul_f32_e32 v68, 0xbfb8aa3b, v68
	v_exp_f32_e32 v68, v68
	s_nop 0
	v_add_f32_e32 v68, 1.0, v68
	v_rcp_f32_e32 v71, v68
	s_nop 0
	v_pk_mul_f32 v[68:69], v[58:59], v[70:71]
	v_mul_f32_e32 v59, 0x3d372713, v60
	v_mul_f32_e32 v59, v60, v59
	v_fma_f32 v59, v60, v59, v60
	v_mul_f32_e32 v59, 0x3f4c422a, v59
	v_add_f32_e32 v59, v59, v59
	v_mul_f32_e32 v59, 0xbfb8aa3b, v59
	v_exp_f32_e32 v59, v59
	v_mul_f32_e32 v58, 0x3d372713, v64
	v_mul_f32_e32 v58, v64, v58
	v_fma_f32 v58, v64, v58, v64
	v_add_f32_e32 v59, 1.0, v59
	v_rcp_f32_e32 v70, v59
	v_mul_f32_e32 v59, 0x3d372713, v65
	v_mul_f32_e32 v59, v65, v59
	v_fma_f32 v59, v65, v59, v65
	v_mul_f32_e32 v58, 0x3f4c422a, v58
	v_mul_f32_e32 v59, 0x3f4c422a, v59
	v_add_f32_e32 v58, v58, v58
	v_add_f32_e32 v59, v59, v59
	v_mul_f32_e32 v58, 0xbfb8aa3b, v58
	v_mul_f32_e32 v59, 0xbfb8aa3b, v59
	v_exp_f32_e32 v58, v58
	v_exp_f32_e32 v59, v59
	v_add_f32_e32 v58, 1.0, v58
	v_add_f32_e32 v59, 1.0, v59
	v_rcp_f32_e32 v58, v58
	v_rcp_f32_e32 v59, v59
	s_nop 0
	v_pk_mul_f32 v[64:65], v[64:65], v[58:59]
	v_mul_f32_e32 v58, 0x3d372713, v61
	v_mul_f32_e32 v58, v61, v58
	v_fma_f32 v58, v61, v58, v61
	v_mul_f32_e32 v58, 0x3f4c422a, v58
	v_add_f32_e32 v58, v58, v58
	v_mul_f32_e32 v58, 0xbfb8aa3b, v58
	v_exp_f32_e32 v58, v58
	v_cvt_pk_bf16_f32 v59, v64, v65
	v_add_f32_e32 v58, 1.0, v58
	v_rcp_f32_e32 v71, v58
	v_cvt_pk_bf16_f32 v58, v62, v63
; template <class Epi>
; DEVI void gemm_phase(LAS unsigned char* lds, const Gemm g, const Epi& E) {
;     ...
;                 for (int mm = 0; mm < 2; ++mm) {
;                     const int m = m0 + mm;
;                     const int r = row0 + ai * HALF + m * 16; float rs = 1.f, part = 0.f;
;                     if constexpr (Epi::RS) rs = rsv[ai * 4 + m];
;                     if constexpr (Epi::PAIR) E.pair8(cur.b, r, cur.pn * HALF + wc * 32 + 8 * fq, acc[ai][0][m][0] * rs, acc[ai][0][m][1] * rs, acc[ai][1][m][0] * rs, acc[ai][1][m][1] * rs);
;                     else
; #pragma unroll
;                     for (int bj = 0; bj < 2; ++bj) {
;                         const int c = col0 + bj * HALF; f32x4 v0 = acc[ai][bj][m][0], v1 = acc[ai][bj][m][1];
;                         if constexpr (Epi::RS) { v0 = v0 * rs; v1 = v1 * rs; }
;                         if constexpr (Epi::PRE) part += E.frag_pre8(cur.b, r, c, v0, v1, pre[mm][bj][0], pre[mm][bj][1]);
;                         else if constexpr (Epi::PERM) E.frag8(cur.b, r, c, v0, v1);
;                         else { E.frag(cur.b, r, c, v0); E.frag(cur.b, r, c + 16, v1); }
;                     }
	v_lshl_add_u64 v[62:63], v[66:67], 0, v[122:123]
	v_pk_mul_f32 v[70:71], v[60:61], v[70:71]
	v_cvt_pk_bf16_f32 v60, v68, v69
	v_cvt_pk_bf16_f32 v61, v70, v71
	global_store_dwordx4 v[62:63], v[58:61], off
	s_nop 1
	v_mul_f32_e32 v59, 0x3d372713, v50
	v_mul_f32_e32 v59, v50, v59
	v_fma_f32 v59, v50, v59, v50
	v_mul_f32_e32 v59, 0x3f4c422a, v59
	v_add_f32_e32 v59, v59, v59
	v_mul_f32_e32 v59, 0xbfb8aa3b, v59
	v_exp_f32_e32 v59, v59
	v_mul_f32_e32 v58, 0x3d372713, v54
	v_mul_f32_e32 v58, v54, v58
	v_fma_f32 v58, v54, v58, v54
	v_add_f32_e32 v59, 1.0, v59
	v_rcp_f32_e32 v60, v59
	v_mul_f32_e32 v59, 0x3d372713, v55
	v_mul_f32_e32 v59, v55, v59
	v_fma_f32 v59, v55, v59, v55
	v_mul_f32_e32 v58, 0x3f4c422a, v58
	v_mul_f32_e32 v59, 0x3f4c422a, v59
	v_add_f32_e32 v58, v58, v58
	v_add_f32_e32 v59, v59, v59
	v_mul_f32_e32 v58, 0xbfb8aa3b, v58
	v_mul_f32_e32 v59, 0xbfb8aa3b, v59
	v_exp_f32_e32 v58, v58
	v_exp_f32_e32 v59, v59
	v_add_f32_e32 v58, 1.0, v58
	v_add_f32_e32 v59, 1.0, v59
	v_rcp_f32_e32 v58, v58
	v_rcp_f32_e32 v59, v59
	s_nop 0
	v_pk_mul_f32 v[54:55], v[54:55], v[58:59]
	v_mul_f32_e32 v58, 0x3d372713, v51
	v_mul_f32_e32 v58, v51, v58
	v_fma_f32 v58, v51, v58, v51
	v_mul_f32_e32 v58, 0x3f4c422a, v58
	v_add_f32_e32 v58, v58, v58
	v_mul_f32_e32 v58, 0xbfb8aa3b, v58
	v_exp_f32_e32 v58, v58
	s_nop 0
	v_add_f32_e32 v58, 1.0, v58
	v_rcp_f32_e32 v61, v58
	s_nop 0
	v_pk_mul_f32 v[58:59], v[50:51], v[60:61]
	v_mul_f32_e32 v51, 0x3d372713, v52
	v_mul_f32_e32 v51, v52, v51
	v_fma_f32 v51, v52, v51, v52
	v_mul_f32_e32 v51, 0x3f4c422a, v51
	v_add_f32_e32 v51, v51, v51
	v_mul_f32_e32 v51, 0xbfb8aa3b, v51
	v_exp_f32_e32 v51, v51
	v_mul_f32_e32 v50, 0x3d372713, v56
	v_mul_f32_e32 v50, v56, v50
	v_fma_f32 v50, v56, v50, v56
	v_add_f32_e32 v51, 1.0, v51
	v_rcp_f32_e32 v60, v51
	v_mul_f32_e32 v51, 0x3d372713, v57
	v_mul_f32_e32 v51, v57, v51
	v_fma_f32 v51, v57, v51, v57
	v_mul_f32_e32 v50, 0x3f4c422a, v50
	v_mul_f32_e32 v51, 0x3f4c422a, v51
	v_add_f32_e32 v50, v50, v50
	v_add_f32_e32 v51, v51, v51
	v_mul_f32_e32 v50, 0xbfb8aa3b, v50
	v_mul_f32_e32 v51, 0xbfb8aa3b, v51
	v_exp_f32_e32 v50, v50
	v_exp_f32_e32 v51, v51
	v_add_f32_e32 v50, 1.0, v50
	v_add_f32_e32 v51, 1.0, v51
	v_rcp_f32_e32 v50, v50
	v_rcp_f32_e32 v51, v51
	s_nop 0
	v_pk_mul_f32 v[56:57], v[56:57], v[50:51]
	v_mul_f32_e32 v50, 0x3d372713, v53
	v_mul_f32_e32 v50, v53, v50
	v_fma_f32 v50, v53, v50, v53
	v_mul_f32_e32 v50, 0x3f4c422a, v50
	v_add_f32_e32 v50, v50, v50
	v_mul_f32_e32 v50, 0xbfb8aa3b, v50
	v_exp_f32_e32 v50, v50
	v_cvt_pk_bf16_f32 v51, v56, v57
	v_add_f32_e32 v50, 1.0, v50
	v_rcp_f32_e32 v61, v50
	v_cvt_pk_bf16_f32 v50, v54, v55
	v_lshl_add_u64 v[54:55], v[66:67], 0, v[114:115]
	v_pk_mul_f32 v[60:61], v[52:53], v[60:61]
	v_cvt_pk_bf16_f32 v52, v58, v59
	v_cvt_pk_bf16_f32 v53, v60, v61
	global_store_dwordx4 v[54:55], v[50:53], off
	s_nop 1
	v_mul_f32_e32 v53, 0x3d372713, v42
	v_mul_f32_e32 v53, v42, v53
	v_fma_f32 v53, v42, v53, v42
	v_mul_f32_e32 v53, 0x3f4c422a, v53
	v_add_f32_e32 v53, v53, v53
	v_mul_f32_e32 v53, 0xbfb8aa3b, v53
	v_exp_f32_e32 v53, v53
	v_mul_f32_e32 v52, 0x3d372713, v46
	v_mul_f32_e32 v52, v46, v52
	v_fma_f32 v52, v46, v52, v46
	v_add_f32_e32 v53, 1.0, v53
	v_rcp_f32_e32 v54, v53
	v_mul_f32_e32 v53, 0x3d372713, v47
	v_mul_f32_e32 v53, v47, v53
	v_fma_f32 v53, v47, v53, v47
	v_mul_f32_e32 v52, 0x3f4c422a, v52
	v_mul_f32_e32 v53, 0x3f4c422a, v53
	v_add_f32_e32 v52, v52, v52
	v_add_f32_e32 v53, v53, v53
	v_mul_f32_e32 v52, 0xbfb8aa3b, v52
	v_mul_f32_e32 v53, 0xbfb8aa3b, v53
	v_exp_f32_e32 v52, v52
	v_exp_f32_e32 v53, v53
	v_lshl_add_u64 v[50:51], v[142:143], 0, s[0:1]
	s_mov_b64 s[0:1], 0xa00000
	v_add_f32_e32 v52, 1.0, v52
	v_add_f32_e32 v53, 1.0, v53
	v_rcp_f32_e32 v52, v52
	v_rcp_f32_e32 v53, v53
	s_nop 0
	v_pk_mul_f32 v[46:47], v[46:47], v[52:53]
	v_mul_f32_e32 v52, 0x3d372713, v43
	v_mul_f32_e32 v52, v43, v52
	v_fma_f32 v52, v43, v52, v43
	v_mul_f32_e32 v52, 0x3f4c422a, v52
	v_add_f32_e32 v52, v52, v52
	v_mul_f32_e32 v52, 0xbfb8aa3b, v52
	v_exp_f32_e32 v52, v52
	s_nop 0
	v_add_f32_e32 v52, 1.0, v52
	v_rcp_f32_e32 v55, v52
	s_nop 0
	v_pk_mul_f32 v[52:53], v[42:43], v[54:55]
	v_mul_f32_e32 v43, 0x3d372713, v44
	v_mul_f32_e32 v43, v44, v43
	v_fma_f32 v43, v44, v43, v44
	v_mul_f32_e32 v43, 0x3f4c422a, v43
	v_add_f32_e32 v43, v43, v43
	v_mul_f32_e32 v43, 0xbfb8aa3b, v43
	v_exp_f32_e32 v43, v43
	v_mul_f32_e32 v42, 0x3d372713, v48
	v_mul_f32_e32 v42, v48, v42
	v_fma_f32 v42, v48, v42, v48
	v_add_f32_e32 v43, 1.0, v43
	v_rcp_f32_e32 v54, v43
	v_mul_f32_e32 v43, 0x3d372713, v49
	v_mul_f32_e32 v43, v49, v43
	v_fma_f32 v43, v49, v43, v49
	v_mul_f32_e32 v42, 0x3f4c422a, v42
	v_mul_f32_e32 v43, 0x3f4c422a, v43
	v_add_f32_e32 v42, v42, v42
	v_add_f32_e32 v43, v43, v43
	v_mul_f32_e32 v42, 0xbfb8aa3b, v42
	v_mul_f32_e32 v43, 0xbfb8aa3b, v43
	v_exp_f32_e32 v42, v42
	v_exp_f32_e32 v43, v43
	v_add_f32_e32 v42, 1.0, v42
	v_add_f32_e32 v43, 1.0, v43
	v_rcp_f32_e32 v42, v42
	v_rcp_f32_e32 v43, v43
	s_nop 0
	v_pk_mul_f32 v[48:49], v[48:49], v[42:43]
	v_mul_f32_e32 v42, 0x3d372713, v45
	v_mul_f32_e32 v42, v45, v42
	v_fma_f32 v42, v45, v42, v45
	v_mul_f32_e32 v42, 0x3f4c422a, v42
	v_add_f32_e32 v42, v42, v42
	v_mul_f32_e32 v42, 0xbfb8aa3b, v42
	v_exp_f32_e32 v42, v42
	v_cvt_pk_bf16_f32 v43, v48, v49
	v_add_f32_e32 v42, 1.0, v42
	v_rcp_f32_e32 v55, v42
	v_cvt_pk_bf16_f32 v42, v46, v47
	v_lshl_add_u64 v[46:47], v[50:51], 0, v[122:123]
	v_pk_mul_f32 v[54:55], v[44:45], v[54:55]
	v_cvt_pk_bf16_f32 v44, v52, v53
	v_cvt_pk_bf16_f32 v45, v54, v55
	global_store_dwordx4 v[46:47], v[42:45], off
	s_nop 1
	v_mul_f32_e32 v43, 0x3d372713, v34
	v_mul_f32_e32 v43, v34, v43
	v_fma_f32 v43, v34, v43, v34
; template <class Epi>
; DEVI void gemm_phase(LAS unsigned char* lds, const Gemm g, const Epi& E) {
;     ...
;                 for (int mm = 0; mm < 2; ++mm) {
;                     const int m = m0 + mm;
;                     const int r = row0 + ai * HALF + m * 16; float rs = 1.f, part = 0.f;
;                     if constexpr (Epi::RS) rs = rsv[ai * 4 + m];
;                     if constexpr (Epi::PAIR) E.pair8(cur.b, r, cur.pn * HALF + wc * 32 + 8 * fq, acc[ai][0][m][0] * rs, acc[ai][0][m][1] * rs, acc[ai][1][m][0] * rs, acc[ai][1][m][1] * rs);
;                     else
; #pragma unroll
;                     for (int bj = 0; bj < 2; ++bj) {
;                         const int c = col0 + bj * HALF; f32x4 v0 = acc[ai][bj][m][0], v1 = acc[ai][bj][m][1];
;                         if constexpr (Epi::RS) { v0 = v0 * rs; v1 = v1 * rs; }
;                         if constexpr (Epi::PRE) part += E.frag_pre8(cur.b, r, c, v0, v1, pre[mm][bj][0], pre[mm][bj][1]);
;                         else if constexpr (Epi::PERM) E.frag8(cur.b, r, c, v0, v1);
;                         else { E.frag(cur.b, r, c, v0); E.frag(cur.b, r, c + 16, v1); }
;                     }
	v_mul_f32_e32 v43, 0x3f4c422a, v43
	v_add_f32_e32 v43, v43, v43
	v_mul_f32_e32 v43, 0xbfb8aa3b, v43
	v_exp_f32_e32 v43, v43
	v_mul_f32_e32 v42, 0x3d372713, v38
	v_mul_f32_e32 v42, v38, v42
	v_fma_f32 v42, v38, v42, v38
	v_add_f32_e32 v43, 1.0, v43
	v_rcp_f32_e32 v44, v43
	v_mul_f32_e32 v43, 0x3d372713, v39
	v_mul_f32_e32 v43, v39, v43
	v_fma_f32 v43, v39, v43, v39
	v_mul_f32_e32 v42, 0x3f4c422a, v42
	v_mul_f32_e32 v43, 0x3f4c422a, v43
	v_add_f32_e32 v42, v42, v42
	v_add_f32_e32 v43, v43, v43
	v_mul_f32_e32 v42, 0xbfb8aa3b, v42
	v_mul_f32_e32 v43, 0xbfb8aa3b, v43
	v_exp_f32_e32 v42, v42
	v_exp_f32_e32 v43, v43
	v_add_f32_e32 v42, 1.0, v42
	v_add_f32_e32 v43, 1.0, v43
	v_rcp_f32_e32 v42, v42
	v_rcp_f32_e32 v43, v43
	s_nop 0
	v_pk_mul_f32 v[38:39], v[38:39], v[42:43]
	v_mul_f32_e32 v42, 0x3d372713, v35
	v_mul_f32_e32 v42, v35, v42
	v_fma_f32 v42, v35, v42, v35
	v_mul_f32_e32 v42, 0x3f4c422a, v42
	v_add_f32_e32 v42, v42, v42
	v_mul_f32_e32 v42, 0xbfb8aa3b, v42
	v_exp_f32_e32 v42, v42
	s_nop 0
	v_add_f32_e32 v42, 1.0, v42
	v_rcp_f32_e32 v45, v42
	s_nop 0
	v_pk_mul_f32 v[42:43], v[34:35], v[44:45]
	v_mul_f32_e32 v35, 0x3d372713, v36
	v_mul_f32_e32 v35, v36, v35
	v_fma_f32 v35, v36, v35, v36
	v_mul_f32_e32 v35, 0x3f4c422a, v35
	v_add_f32_e32 v35, v35, v35
	v_mul_f32_e32 v35, 0xbfb8aa3b, v35
	v_exp_f32_e32 v35, v35
	v_mul_f32_e32 v34, 0x3d372713, v40
	v_mul_f32_e32 v34, v40, v34
	v_fma_f32 v34, v40, v34, v40
	v_add_f32_e32 v35, 1.0, v35
	v_rcp_f32_e32 v44, v35
	v_mul_f32_e32 v35, 0x3d372713, v41
	v_mul_f32_e32 v35, v41, v35
	v_fma_f32 v35, v41, v35, v41
	v_mul_f32_e32 v34, 0x3f4c422a, v34
	v_mul_f32_e32 v35, 0x3f4c422a, v35
	v_add_f32_e32 v34, v34, v34
	v_add_f32_e32 v35, v35, v35
	v_mul_f32_e32 v34, 0xbfb8aa3b, v34
	v_mul_f32_e32 v35, 0xbfb8aa3b, v35
	v_exp_f32_e32 v34, v34
	v_exp_f32_e32 v35, v35
	v_add_f32_e32 v34, 1.0, v34
	v_add_f32_e32 v35, 1.0, v35
	v_rcp_f32_e32 v34, v34
	v_rcp_f32_e32 v35, v35
	s_nop 0
	v_pk_mul_f32 v[40:41], v[40:41], v[34:35]
	v_mul_f32_e32 v34, 0x3d372713, v37
	v_mul_f32_e32 v34, v37, v34
	v_fma_f32 v34, v37, v34, v37
	v_mul_f32_e32 v34, 0x3f4c422a, v34
	v_add_f32_e32 v34, v34, v34
	v_mul_f32_e32 v34, 0xbfb8aa3b, v34
	v_exp_f32_e32 v34, v34
	v_cvt_pk_bf16_f32 v35, v40, v41
	v_add_f32_e32 v34, 1.0, v34
	v_rcp_f32_e32 v45, v34
	v_cvt_pk_bf16_f32 v34, v38, v39
	v_lshl_add_u64 v[38:39], v[50:51], 0, v[114:115]
	v_pk_mul_f32 v[44:45], v[36:37], v[44:45]
	v_cvt_pk_bf16_f32 v36, v42, v43
	v_cvt_pk_bf16_f32 v37, v44, v45
	global_store_dwordx4 v[38:39], v[34:37], off
	s_nop 1
	v_mul_f32_e32 v37, 0x3d372713, v26
	v_mul_f32_e32 v37, v26, v37
	v_fma_f32 v37, v26, v37, v26
	v_mul_f32_e32 v37, 0x3f4c422a, v37
	v_add_f32_e32 v37, v37, v37
	v_mul_f32_e32 v37, 0xbfb8aa3b, v37
	v_exp_f32_e32 v37, v37
	v_mul_f32_e32 v36, 0x3d372713, v30
	v_mul_f32_e32 v36, v30, v36
	v_fma_f32 v36, v30, v36, v30
	v_add_f32_e32 v37, 1.0, v37
	v_rcp_f32_e32 v38, v37
	v_mul_f32_e32 v37, 0x3d372713, v31
	v_mul_f32_e32 v37, v31, v37
	v_fma_f32 v37, v31, v37, v31
	v_mul_f32_e32 v36, 0x3f4c422a, v36
	v_mul_f32_e32 v37, 0x3f4c422a, v37
	v_add_f32_e32 v36, v36, v36
	v_add_f32_e32 v37, v37, v37
	v_mul_f32_e32 v36, 0xbfb8aa3b, v36
	v_mul_f32_e32 v37, 0xbfb8aa3b, v37
	v_exp_f32_e32 v36, v36
	v_exp_f32_e32 v37, v37
	v_lshl_add_u64 v[34:35], v[142:143], 0, s[0:1]
	s_mov_b64 s[0:1], 0xb00000
	v_add_f32_e32 v36, 1.0, v36
	v_add_f32_e32 v37, 1.0, v37
	v_rcp_f32_e32 v36, v36
	v_rcp_f32_e32 v37, v37
	s_nop 0
	v_pk_mul_f32 v[30:31], v[30:31], v[36:37]
	v_mul_f32_e32 v36, 0x3d372713, v27
	v_mul_f32_e32 v36, v27, v36
	v_fma_f32 v36, v27, v36, v27
	v_mul_f32_e32 v36, 0x3f4c422a, v36
	v_add_f32_e32 v36, v36, v36
	v_mul_f32_e32 v36, 0xbfb8aa3b, v36
	v_exp_f32_e32 v36, v36
	s_nop 0
	v_add_f32_e32 v36, 1.0, v36
	v_rcp_f32_e32 v39, v36
	s_nop 0
	v_pk_mul_f32 v[36:37], v[26:27], v[38:39]
	v_mul_f32_e32 v27, 0x3d372713, v28
	v_mul_f32_e32 v27, v28, v27
	v_fma_f32 v27, v28, v27, v28
	v_mul_f32_e32 v27, 0x3f4c422a, v27
	v_add_f32_e32 v27, v27, v27
	v_mul_f32_e32 v27, 0xbfb8aa3b, v27
	v_exp_f32_e32 v27, v27
	v_mul_f32_e32 v26, 0x3d372713, v32
	v_mul_f32_e32 v26, v32, v26
	v_fma_f32 v26, v32, v26, v32
	v_add_f32_e32 v27, 1.0, v27
	v_rcp_f32_e32 v38, v27
	v_mul_f32_e32 v27, 0x3d372713, v33
	v_mul_f32_e32 v27, v33, v27
	v_fma_f32 v27, v33, v27, v33
	v_mul_f32_e32 v26, 0x3f4c422a, v26
	v_mul_f32_e32 v27, 0x3f4c422a, v27
	v_add_f32_e32 v26, v26, v26
	v_add_f32_e32 v27, v27, v27
	v_mul_f32_e32 v26, 0xbfb8aa3b, v26
	v_mul_f32_e32 v27, 0xbfb8aa3b, v27
	v_exp_f32_e32 v26, v26
	v_exp_f32_e32 v27, v27
	v_add_f32_e32 v26, 1.0, v26
	v_add_f32_e32 v27, 1.0, v27
	v_rcp_f32_e32 v26, v26
	v_rcp_f32_e32 v27, v27
	s_nop 0
	v_pk_mul_f32 v[32:33], v[32:33], v[26:27]
	v_mul_f32_e32 v26, 0x3d372713, v29
	v_mul_f32_e32 v26, v29, v26
	v_fma_f32 v26, v29, v26, v29
	v_mul_f32_e32 v26, 0x3f4c422a, v26
	v_add_f32_e32 v26, v26, v26
	v_mul_f32_e32 v26, 0xbfb8aa3b, v26
	v_exp_f32_e32 v26, v26
	v_cvt_pk_bf16_f32 v27, v32, v33
	v_add_f32_e32 v26, 1.0, v26
	v_rcp_f32_e32 v39, v26
	v_cvt_pk_bf16_f32 v26, v30, v31
	v_lshl_add_u64 v[30:31], v[34:35], 0, v[122:123]
	v_pk_mul_f32 v[38:39], v[28:29], v[38:39]
	v_cvt_pk_bf16_f32 v28, v36, v37
	v_cvt_pk_bf16_f32 v29, v38, v39
	global_store_dwordx4 v[30:31], v[26:29], off
	s_nop 1
	v_mul_f32_e32 v27, 0x3d372713, v18
	v_mul_f32_e32 v27, v18, v27
	v_fma_f32 v27, v18, v27, v18
	v_mul_f32_e32 v27, 0x3f4c422a, v27
	v_add_f32_e32 v27, v27, v27
	v_mul_f32_e32 v27, 0xbfb8aa3b, v27
	v_exp_f32_e32 v27, v27
	v_mul_f32_e32 v26, 0x3d372713, v22
	v_mul_f32_e32 v26, v22, v26
	v_fma_f32 v26, v22, v26, v22
	v_add_f32_e32 v27, 1.0, v27
	v_rcp_f32_e32 v28, v27
	v_mul_f32_e32 v27, 0x3d372713, v23
; template <class Epi>
; DEVI void gemm_phase(LAS unsigned char* lds, const Gemm g, const Epi& E) {
;     ...
;                 for (int mm = 0; mm < 2; ++mm) {
;                     const int m = m0 + mm;
;                     const int r = row0 + ai * HALF + m * 16; float rs = 1.f, part = 0.f;
;                     if constexpr (Epi::RS) rs = rsv[ai * 4 + m];
;                     if constexpr (Epi::PAIR) E.pair8(cur.b, r, cur.pn * HALF + wc * 32 + 8 * fq, acc[ai][0][m][0] * rs, acc[ai][0][m][1] * rs, acc[ai][1][m][0] * rs, acc[ai][1][m][1] * rs);
;                     else
; #pragma unroll
;                     for (int bj = 0; bj < 2; ++bj) {
;                         const int c = col0 + bj * HALF; f32x4 v0 = acc[ai][bj][m][0], v1 = acc[ai][bj][m][1];
;                         if constexpr (Epi::RS) { v0 = v0 * rs; v1 = v1 * rs; }
;                         if constexpr (Epi::PRE) part += E.frag_pre8(cur.b, r, c, v0, v1, pre[mm][bj][0], pre[mm][bj][1]);
;                         else if constexpr (Epi::PERM) E.frag8(cur.b, r, c, v0, v1);
;                         else { E.frag(cur.b, r, c, v0); E.frag(cur.b, r, c + 16, v1); }
;                     }
	v_mul_f32_e32 v27, v23, v27
	v_fma_f32 v27, v23, v27, v23
	v_mul_f32_e32 v26, 0x3f4c422a, v26
	v_mul_f32_e32 v27, 0x3f4c422a, v27
	v_add_f32_e32 v26, v26, v26
	v_add_f32_e32 v27, v27, v27
	v_mul_f32_e32 v26, 0xbfb8aa3b, v26
	v_mul_f32_e32 v27, 0xbfb8aa3b, v27
	v_exp_f32_e32 v26, v26
	v_exp_f32_e32 v27, v27
	v_add_f32_e32 v26, 1.0, v26
	v_add_f32_e32 v27, 1.0, v27
	v_rcp_f32_e32 v26, v26
	v_rcp_f32_e32 v27, v27
	s_nop 0
	v_pk_mul_f32 v[22:23], v[22:23], v[26:27]
	v_mul_f32_e32 v26, 0x3d372713, v19
	v_mul_f32_e32 v26, v19, v26
	v_fma_f32 v26, v19, v26, v19
	v_mul_f32_e32 v26, 0x3f4c422a, v26
	v_add_f32_e32 v26, v26, v26
	v_mul_f32_e32 v26, 0xbfb8aa3b, v26
	v_exp_f32_e32 v26, v26
	s_nop 0
	v_add_f32_e32 v26, 1.0, v26
	v_rcp_f32_e32 v29, v26
	s_nop 0
	v_pk_mul_f32 v[26:27], v[18:19], v[28:29]
	v_mul_f32_e32 v19, 0x3d372713, v20
	v_mul_f32_e32 v19, v20, v19
	v_fma_f32 v19, v20, v19, v20
	v_mul_f32_e32 v19, 0x3f4c422a, v19
	v_add_f32_e32 v19, v19, v19
	v_mul_f32_e32 v19, 0xbfb8aa3b, v19
	v_exp_f32_e32 v19, v19
	v_mul_f32_e32 v18, 0x3d372713, v24
	v_mul_f32_e32 v18, v24, v18
	v_fma_f32 v18, v24, v18, v24
	v_add_f32_e32 v19, 1.0, v19
	v_rcp_f32_e32 v28, v19
	v_mul_f32_e32 v19, 0x3d372713, v25
	v_mul_f32_e32 v19, v25, v19
	v_fma_f32 v19, v25, v19, v25
	v_mul_f32_e32 v18, 0x3f4c422a, v18
	v_mul_f32_e32 v19, 0x3f4c422a, v19
	v_add_f32_e32 v18, v18, v18
	v_add_f32_e32 v19, v19, v19
	v_mul_f32_e32 v18, 0xbfb8aa3b, v18
	v_mul_f32_e32 v19, 0xbfb8aa3b, v19
	v_exp_f32_e32 v18, v18
	v_exp_f32_e32 v19, v19
	v_add_f32_e32 v18, 1.0, v18
	v_add_f32_e32 v19, 1.0, v19
	v_rcp_f32_e32 v18, v18
	v_rcp_f32_e32 v19, v19
	s_nop 0
	v_pk_mul_f32 v[24:25], v[24:25], v[18:19]
	v_mul_f32_e32 v18, 0x3d372713, v21
	v_mul_f32_e32 v18, v21, v18
	v_fma_f32 v18, v21, v18, v21
	v_mul_f32_e32 v18, 0x3f4c422a, v18
	v_add_f32_e32 v18, v18, v18
	v_mul_f32_e32 v18, 0xbfb8aa3b, v18
	v_exp_f32_e32 v18, v18
	v_cvt_pk_bf16_f32 v19, v24, v25
	v_add_f32_e32 v18, 1.0, v18
	v_rcp_f32_e32 v29, v18
	v_cvt_pk_bf16_f32 v18, v22, v23
	v_lshl_add_u64 v[22:23], v[34:35], 0, v[114:115]
	v_pk_mul_f32 v[28:29], v[20:21], v[28:29]
	v_cvt_pk_bf16_f32 v20, v26, v27
	v_cvt_pk_bf16_f32 v21, v28, v29
	global_store_dwordx4 v[22:23], v[18:21], off
	s_nop 1
	v_mul_f32_e32 v21, 0x3d372713, v10
	v_mul_f32_e32 v21, v10, v21
	v_fma_f32 v21, v10, v21, v10
	v_mul_f32_e32 v21, 0x3f4c422a, v21
	v_add_f32_e32 v21, v21, v21
	v_mul_f32_e32 v21, 0xbfb8aa3b, v21
	v_exp_f32_e32 v21, v21
	v_mul_f32_e32 v20, 0x3d372713, v14
	v_mul_f32_e32 v20, v14, v20
	v_fma_f32 v20, v14, v20, v14
	v_add_f32_e32 v21, 1.0, v21
	v_rcp_f32_e32 v22, v21
	v_mul_f32_e32 v21, 0x3d372713, v15
	v_mul_f32_e32 v21, v15, v21
	v_fma_f32 v21, v15, v21, v15
	v_mul_f32_e32 v20, 0x3f4c422a, v20
	v_mul_f32_e32 v21, 0x3f4c422a, v21
	v_add_f32_e32 v20, v20, v20
	v_add_f32_e32 v21, v21, v21
	v_mul_f32_e32 v20, 0xbfb8aa3b, v20
	v_mul_f32_e32 v21, 0xbfb8aa3b, v21
	v_exp_f32_e32 v20, v20
	v_exp_f32_e32 v21, v21
	v_lshl_add_u64 v[18:19], v[142:143], 0, s[0:1]
	s_mov_b32 s0, s8
	v_add_f32_e32 v20, 1.0, v20
	v_add_f32_e32 v21, 1.0, v21
	v_rcp_f32_e32 v20, v20
	v_rcp_f32_e32 v21, v21
	s_mov_b32 s1, s9
	v_pk_mul_f32 v[14:15], v[14:15], v[20:21]
	v_mul_f32_e32 v20, 0x3d372713, v11
	v_mul_f32_e32 v20, v11, v20
	v_fma_f32 v20, v11, v20, v11
	v_mul_f32_e32 v20, 0x3f4c422a, v20
	v_add_f32_e32 v20, v20, v20
	v_mul_f32_e32 v20, 0xbfb8aa3b, v20
	v_exp_f32_e32 v20, v20
	s_nop 0
	v_add_f32_e32 v20, 1.0, v20
	v_rcp_f32_e32 v23, v20
	s_nop 0
	v_pk_mul_f32 v[20:21], v[10:11], v[22:23]
	v_mul_f32_e32 v11, 0x3d372713, v12
	v_mul_f32_e32 v11, v12, v11
	v_fma_f32 v11, v12, v11, v12
	v_mul_f32_e32 v11, 0x3f4c422a, v11
	v_add_f32_e32 v11, v11, v11
	v_mul_f32_e32 v11, 0xbfb8aa3b, v11
	v_exp_f32_e32 v11, v11
	v_mul_f32_e32 v10, 0x3d372713, v16
; #define PG8_WAIT_V(n) asm volatile("s_waitcnt vmcnt(" #n ")" ::: "memory")
; #define PG8_BAR __builtin_amdgcn_s_barrier()
; template <class Epi>
; DEVI void gemm_phase(LAS unsigned char* lds, const Gemm g, const Epi& E) {
;     ...
;         if (!has_next) break;
; #pragma unroll
;         for (int a = 0; a < 2; ++a)
; #pragma unroll
;             for (int b = 0; b < 2; ++b)
; #pragma unroll
;                 for (int m = 0; m < 4; ++m)
; #pragma unroll
;                     for (int n = 0; n < 2; ++n) acc[a][b][m][n] = (f32x4){0.f, 0.f, 0.f, 0.f};
;         cur = nxt; cA = nA; cB = nB; ++ui;
;     }
;     PG8_WAIT_V(0);
;     if (wr == 0) PG8_BAR;
;     PG8_BAR;
	v_mul_f32_e32 v10, v16, v10
	v_fma_f32 v10, v16, v10, v16
	v_add_f32_e32 v11, 1.0, v11
	v_rcp_f32_e32 v22, v11
	v_mul_f32_e32 v11, 0x3d372713, v17
	v_mul_f32_e32 v11, v17, v11
	v_fma_f32 v11, v17, v11, v17
	v_mul_f32_e32 v10, 0x3f4c422a, v10
	v_mul_f32_e32 v11, 0x3f4c422a, v11
	v_add_f32_e32 v10, v10, v10
	v_add_f32_e32 v11, v11, v11
	v_mul_f32_e32 v10, 0xbfb8aa3b, v10
	v_mul_f32_e32 v11, 0xbfb8aa3b, v11
	v_exp_f32_e32 v10, v10
	v_exp_f32_e32 v11, v11
	v_add_f32_e32 v10, 1.0, v10
	v_add_f32_e32 v11, 1.0, v11
	v_rcp_f32_e32 v10, v10
	v_rcp_f32_e32 v11, v11
	s_nop 0
	v_pk_mul_f32 v[16:17], v[16:17], v[10:11]
	v_mul_f32_e32 v10, 0x3d372713, v13
	v_mul_f32_e32 v10, v13, v10
	v_fma_f32 v10, v13, v10, v13
	v_mul_f32_e32 v10, 0x3f4c422a, v10
	v_add_f32_e32 v10, v10, v10
	v_mul_f32_e32 v10, 0xbfb8aa3b, v10
	v_exp_f32_e32 v10, v10
	v_cvt_pk_bf16_f32 v11, v16, v17
	v_add_f32_e32 v10, 1.0, v10
	v_rcp_f32_e32 v23, v10
	v_cvt_pk_bf16_f32 v10, v14, v15
	v_lshl_add_u64 v[14:15], v[18:19], 0, v[122:123]
	v_pk_mul_f32 v[22:23], v[12:13], v[22:23]
	v_cvt_pk_bf16_f32 v12, v20, v21
	v_cvt_pk_bf16_f32 v13, v22, v23
	global_store_dwordx4 v[14:15], v[10:13], off
	s_nop 1
	v_mul_f32_e32 v11, 0x3d372713, v0
	v_mul_f32_e32 v11, v0, v11
	v_fma_f32 v11, v0, v11, v0
	v_mul_f32_e32 v11, 0x3f4c422a, v11
	v_add_f32_e32 v11, v11, v11
	v_mul_f32_e32 v11, 0xbfb8aa3b, v11
	v_exp_f32_e32 v11, v11
	v_mul_f32_e32 v10, 0x3d372713, v4
	v_mul_f32_e32 v10, v4, v10
	v_fma_f32 v10, v4, v10, v4
	v_add_f32_e32 v11, 1.0, v11
	v_rcp_f32_e32 v12, v11
	v_mul_f32_e32 v11, 0x3d372713, v5
	v_mul_f32_e32 v11, v5, v11
	v_fma_f32 v11, v5, v11, v5
	v_mul_f32_e32 v10, 0x3f4c422a, v10
	v_mul_f32_e32 v11, 0x3f4c422a, v11
	v_add_f32_e32 v10, v10, v10
	v_add_f32_e32 v11, v11, v11
	v_mul_f32_e32 v10, 0xbfb8aa3b, v10
	v_mul_f32_e32 v11, 0xbfb8aa3b, v11
	v_exp_f32_e32 v10, v10
	v_exp_f32_e32 v11, v11
	v_add_f32_e32 v10, 1.0, v10
	v_add_f32_e32 v11, 1.0, v11
	v_rcp_f32_e32 v10, v10
	v_rcp_f32_e32 v11, v11
	s_nop 0
	v_pk_mul_f32 v[4:5], v[4:5], v[10:11]
	v_mul_f32_e32 v10, 0x3d372713, v1
	v_mul_f32_e32 v10, v1, v10
	v_fma_f32 v10, v1, v10, v1
	v_mul_f32_e32 v10, 0x3f4c422a, v10
	v_add_f32_e32 v10, v10, v10
	v_mul_f32_e32 v10, 0xbfb8aa3b, v10
	v_exp_f32_e32 v10, v10
	s_nop 0
	v_add_f32_e32 v10, 1.0, v10
	v_rcp_f32_e32 v13, v10
	s_nop 0
	v_pk_mul_f32 v[10:11], v[0:1], v[12:13]
	v_mul_f32_e32 v1, 0x3d372713, v2
	v_mul_f32_e32 v1, v2, v1
	v_fma_f32 v1, v2, v1, v2
	v_mul_f32_e32 v1, 0x3f4c422a, v1
	v_add_f32_e32 v1, v1, v1
	v_mul_f32_e32 v1, 0xbfb8aa3b, v1
	v_exp_f32_e32 v1, v1
	v_mul_f32_e32 v0, 0x3d372713, v6
	v_mul_f32_e32 v0, v6, v0
	v_fma_f32 v0, v6, v0, v6
	v_add_f32_e32 v1, 1.0, v1
	v_rcp_f32_e32 v12, v1
	v_mul_f32_e32 v1, 0x3d372713, v7
	v_mul_f32_e32 v1, v7, v1
	v_fma_f32 v1, v7, v1, v7
	v_mul_f32_e32 v0, 0x3f4c422a, v0
	v_mul_f32_e32 v1, 0x3f4c422a, v1
	v_add_f32_e32 v0, v0, v0
	v_add_f32_e32 v1, v1, v1
	v_mul_f32_e32 v0, 0xbfb8aa3b, v0
	v_mul_f32_e32 v1, 0xbfb8aa3b, v1
	v_exp_f32_e32 v0, v0
	v_exp_f32_e32 v1, v1
	v_add_f32_e32 v0, 1.0, v0
	v_add_f32_e32 v1, 1.0, v1
	v_rcp_f32_e32 v0, v0
	v_rcp_f32_e32 v1, v1
	s_nop 0
	v_pk_mul_f32 v[6:7], v[6:7], v[0:1]
	v_mul_f32_e32 v0, 0x3d372713, v3
	v_mul_f32_e32 v0, v3, v0
	v_fma_f32 v0, v3, v0, v3
	v_mul_f32_e32 v0, 0x3f4c422a, v0
	v_add_f32_e32 v0, v0, v0
	v_mul_f32_e32 v0, 0xbfb8aa3b, v0
	v_exp_f32_e32 v0, v0
	v_cvt_pk_bf16_f32 v1, v6, v7
	v_add_f32_e32 v0, 1.0, v0
	v_rcp_f32_e32 v13, v0
	v_cvt_pk_bf16_f32 v0, v4, v5
	v_lshl_add_u64 v[4:5], v[18:19], 0, v[114:115]
	v_pk_mul_f32 v[12:13], v[2:3], v[12:13]
	v_cvt_pk_bf16_f32 v2, v10, v11
	v_cvt_pk_bf16_f32 v3, v12, v13
	global_store_dwordx4 v[4:5], v[0:3], off
	s_cbranch_vccz .LBB0_1271
	s_waitcnt vmcnt(0)
	s_cmpk_gt_u32 s36, 0xff
	s_cbranch_scc1 .LBB0_1282
	s_barrier

; #define PG8_STAGE(bufoff, gbase, voff) do { _Pragma("unroll") for (int _i = 0; _i < 2; ++_i) \
;         __builtin_amdgcn_global_load_lds((const unsigned*)((const char*)(gbase) + (voff)[_i]), (LAS unsigned*)(lds + (bufoff) + ldsw + _i * 8192), 16, 0, 0); } while (0)
; #define PG8_LDA(dst, b, h) do { _Pragma("unroll") for (int m = 0; m < 4; ++m) _Pragma("unroll") for (int k = 0; k < 2; ++k) dst[m][k] = *(const LAS bf16x8*)(lds + PG8_SA(b, h) + aoff + m * 2048 + k * 1024); } while (0)
; #define PG8_LDB(dst, b, h) do { _Pragma("unroll") for (int n = 0; n < 2; ++n) _Pragma("unroll") for (int k = 0; k < 2; ++k) dst[n][k] = *(const LAS bf16x8*)(lds + PG8_SB(b, h) + boff + n * 2048 + k * 1024); } while (0)
; #define PG8_WAIT_V(n) asm volatile("s_waitcnt vmcnt(" #n ")" ::: "memory")
; #define PG8_WAIT_L(n) asm volatile("s_waitcnt lgkmcnt(" #n ")" ::: "memory")
; #define PG8_BAR __builtin_amdgcn_s_barrier()
; #define PG8_SCHED __builtin_amdgcn_sched_barrier(0)
; template <class Epi>
; DEVI void gemm_phase(LAS unsigned char* lds, const Gemm g, const Epi& E) {
;     ...
;         for (int t = 0; t < nt; t += 2) {
;             const bool last = (t == nt - 2);
;             const char* a1 = cA + (size_t)(t + 1) * kstep;
;             const char* a2 = last ? nA : cA + (size_t)(t + 2) * kstep; const char* b2 = last ? nB : cB + (size_t)(t + 2) * kstep;
;             const char* a3 = a2 + kstep; const char* b3 = b2 + kstep;
;             PG8_LDB(B0, 0, 0); PG8_SCHED; PG8_LDA(At, 0, 0); PG8_STAGE(PG8_SA(1, 1), a1 + hstepA, voffA);
;             PG8_WAIT_L(8); PG8_BAR; PG8_WAIT_L(0); PG8_MMA(0, 0, At, B0); PG8_BAR; PG8_SCHED;
;             PG8_LDB(B1, 0, 1); PG8_STAGE(PG8_SB(0, 0), b2, voffB);
;             PG8_BAR; PG8_WAIT_L(0); PG8_MMA(0, 1, At, B1); PG8_BAR;
;             PG8_LDA(At, 0, 1); PG8_STAGE(PG8_SA(0, 0), a2, voffA);
;             PG8_BAR; PG8_WAIT_L(0); PG8_MMA(1, 0, At, B0); PG8_BAR; PG8_SCHED;
;             PG8_STAGE(PG8_SB(0, 1), b2 + hstepB, voffB);
;             PG8_WAIT_V(6); PG8_BAR; PG8_MMA(1, 1, At, B1); PG8_BAR;
;             PG8_LDB(B0, 1, 0); PG8_SCHED; PG8_LDA(At, 1, 0); PG8_STAGE(PG8_SA(0, 1), a2 + hstepA, voffA);
;             PG8_WAIT_L(8); PG8_BAR; PG8_WAIT_L(0); PG8_MMA(0, 0, At, B0); PG8_BAR; PG8_SCHED;
;             PG8_LDB(B1, 1, 1); PG8_STAGE(PG8_SB(1, 0), b3, voffB);
;             PG8_BAR; PG8_WAIT_L(0); PG8_MMA(0, 1, At, B1); PG8_BAR;
.LBB0_1346:
	s_add_u32 s14, s12, 0xfffc0080
	s_addc_u32 s15, s13, -1
	s_add_i32 s38, 0, 0x10000
	v_add_u32_e32 v152, s38, v185
	ds_read_b128 v[114:117], v152
	ds_read_b128 v[126:129], v152 offset:1024
	ds_read_b128 v[130:133], v152 offset:2048
	ds_read_b128 v[176:179], v152 offset:3072
	s_cmp_eq_u32 s27, 12
	s_cselect_b32 s17, s1, s15
	s_cselect_b32 s16, s3, s14
	s_cselect_b32 s15, s5, s26
	s_cselect_b32 s14, s18, s19
	v_lshl_add_u64 v[152:153], s[12:13], 0, v[148:149]
	s_add_i32 m0, s11, 0xc000
	ds_read_b128 v[180:183], v187
	ds_read_b128 v[188:191], v187 offset:1024
	ds_read_b128 v[192:195], v187 offset:2048
	ds_read_b128 v[196:199], v187 offset:3072
	ds_read_b128 v[200:203], v187 offset:4096
	ds_read_b128 v[204:207], v187 offset:5120
	ds_read_b128 v[214:217], v187 offset:6144
	ds_read_b128 v[218:221], v187 offset:7168
	global_load_lds_dwordx4 v[152:153], off
	s_add_i32 m0, s11, 0xe000
	v_lshl_add_u64 v[152:153], s[12:13], 0, v[150:151]
	global_load_lds_dwordx4 v[152:153], off
	s_waitcnt lgkmcnt(8)
	s_barrier
	s_waitcnt lgkmcnt(0)
	v_mfma_f32_16x16x32_bf16 v[138:141], v[114:117], v[180:183], v[138:141]
	v_mfma_f32_16x16x32_bf16 v[134:137], v[130:133], v[180:183], v[134:137]
	v_mfma_f32_16x16x32_bf16 v[110:113], v[114:117], v[192:195], v[110:113]
	v_mfma_f32_16x16x32_bf16 v[106:109], v[130:133], v[192:195], v[106:109]
	v_mfma_f32_16x16x32_bf16 v[94:97], v[114:117], v[200:203], v[94:97]
	v_mfma_f32_16x16x32_bf16 v[90:93], v[130:133], v[200:203], v[90:93]
	v_mfma_f32_16x16x32_bf16 v[78:81], v[114:117], v[214:217], v[78:81]
	v_mfma_f32_16x16x32_bf16 v[74:77], v[130:133], v[214:217], v[74:77]
	v_mfma_f32_16x16x32_bf16 v[138:141], v[126:129], v[188:191], v[138:141]
	v_mfma_f32_16x16x32_bf16 v[134:137], v[176:179], v[188:191], v[134:137]
	v_mfma_f32_16x16x32_bf16 v[110:113], v[126:129], v[196:199], v[110:113]
	v_mfma_f32_16x16x32_bf16 v[106:109], v[176:179], v[196:199], v[106:109]
	v_mfma_f32_16x16x32_bf16 v[94:97], v[126:129], v[204:207], v[94:97]
	v_mfma_f32_16x16x32_bf16 v[90:93], v[176:179], v[204:207], v[90:93]
	v_mfma_f32_16x16x32_bf16 v[78:81], v[126:129], v[218:221], v[78:81]
	v_mfma_f32_16x16x32_bf16 v[74:77], v[176:179], v[218:221], v[74:77]
	s_barrier
	s_add_i32 s40, 0, 0x14000
	v_add_u32_e32 v152, s40, v185
	s_add_i32 s38, s38, s47
	ds_read_b128 v[222:225], v152
	ds_read_b128 v[226:229], v152 offset:1024
	ds_read_b128 v[230:233], v152 offset:2048
	ds_read_b128 v[234:237], v152 offset:3072
	v_lshl_add_u64 v[152:153], s[14:15], 0, v[8:9]
	s_mov_b32 m0, s38
	v_lshl_add_u64 v[162:163], s[14:15], 0, v[146:147]
	global_load_lds_dwordx4 v[152:153], off
	s_add_i32 m0, s38, 0x2000
	s_nop 0
	global_load_lds_dwordx4 v[162:163], off
	s_barrier
	s_waitcnt lgkmcnt(0)
	v_mfma_f32_16x16x32_bf16 v[122:125], v[222:225], v[180:183], v[122:125]
	v_mfma_f32_16x16x32_bf16 v[118:121], v[230:233], v[180:183], v[118:121]
	v_mfma_f32_16x16x32_bf16 v[102:105], v[222:225], v[192:195], v[102:105]
	v_mfma_f32_16x16x32_bf16 v[98:101], v[230:233], v[192:195], v[98:101]
	v_mfma_f32_16x16x32_bf16 v[86:89], v[222:225], v[200:203], v[86:89]
	v_mfma_f32_16x16x32_bf16 v[82:85], v[230:233], v[200:203], v[82:85]
	v_mfma_f32_16x16x32_bf16 v[70:73], v[222:225], v[214:217], v[70:73]
	v_mfma_f32_16x16x32_bf16 v[66:69], v[230:233], v[214:217], v[66:69]
	v_mfma_f32_16x16x32_bf16 v[122:125], v[226:229], v[188:191], v[122:125]
	v_mfma_f32_16x16x32_bf16 v[118:121], v[234:237], v[188:191], v[118:121]
	v_mfma_f32_16x16x32_bf16 v[102:105], v[226:229], v[196:199], v[102:105]
	v_mfma_f32_16x16x32_bf16 v[98:101], v[234:237], v[196:199], v[98:101]
	v_mfma_f32_16x16x32_bf16 v[86:89], v[226:229], v[204:207], v[86:89]
	v_mfma_f32_16x16x32_bf16 v[82:85], v[234:237], v[204:207], v[82:85]
	v_mfma_f32_16x16x32_bf16 v[70:73], v[226:229], v[218:221], v[70:73]
	v_mfma_f32_16x16x32_bf16 v[66:69], v[234:237], v[218:221], v[66:69]
	s_mov_b32 m0, s11
	v_lshl_add_u64 v[164:165], s[16:17], 0, v[142:143]
	s_barrier
	ds_read_b128 v[180:183], v187 offset:16384
	ds_read_b128 v[188:191], v187 offset:17408
	ds_read_b128 v[192:195], v187 offset:18432
	ds_read_b128 v[196:199], v187 offset:19456
	ds_read_b128 v[200:203], v187 offset:20480
	ds_read_b128 v[204:207], v187 offset:21504
	ds_read_b128 v[214:217], v187 offset:22528
	ds_read_b128 v[218:221], v187 offset:23552
	global_load_lds_dwordx4 v[164:165], off
	s_mov_b32 m0, s66
	v_lshl_add_u64 v[208:209], s[16:17], 0, v[144:145]
	global_load_lds_dwordx4 v[208:209], off
	s_barrier
	s_waitcnt lgkmcnt(0)
	v_mfma_f32_16x16x32_bf16 v[62:65], v[114:117], v[180:183], v[62:65]
	v_mfma_f32_16x16x32_bf16 v[58:61], v[130:133], v[180:183], v[58:61]
	v_mfma_f32_16x16x32_bf16 v[46:49], v[114:117], v[192:195], v[46:49]
	v_mfma_f32_16x16x32_bf16 v[42:45], v[130:133], v[192:195], v[42:45]
	v_mfma_f32_16x16x32_bf16 v[30:33], v[114:117], v[200:203], v[30:33]
	v_mfma_f32_16x16x32_bf16 v[26:29], v[130:133], v[200:203], v[26:29]
	v_mfma_f32_16x16x32_bf16 v[14:17], v[114:117], v[214:217], v[14:17]
	v_mfma_f32_16x16x32_bf16 v[10:13], v[130:133], v[214:217], v[10:13]
	v_mfma_f32_16x16x32_bf16 v[62:65], v[126:129], v[188:191], v[62:65]
	v_mfma_f32_16x16x32_bf16 v[58:61], v[176:179], v[188:191], v[58:61]
	v_mfma_f32_16x16x32_bf16 v[46:49], v[126:129], v[196:199], v[46:49]
	v_mfma_f32_16x16x32_bf16 v[42:45], v[176:179], v[196:199], v[42:45]
	v_mfma_f32_16x16x32_bf16 v[30:33], v[126:129], v[204:207], v[30:33]
	v_mfma_f32_16x16x32_bf16 v[26:29], v[176:179], v[204:207], v[26:29]
	v_mfma_f32_16x16x32_bf16 v[14:17], v[126:129], v[218:221], v[14:17]
	v_mfma_f32_16x16x32_bf16 v[10:13], v[176:179], v[218:221], v[10:13]
	s_barrier
; #define PG8_STAGE(bufoff, gbase, voff) do { _Pragma("unroll") for (int _i = 0; _i < 2; ++_i) \
;         __builtin_amdgcn_global_load_lds((const unsigned*)((const char*)(gbase) + (voff)[_i]), (LAS unsigned*)(lds + (bufoff) + ldsw + _i * 8192), 16, 0, 0); } while (0)
; #define PG8_LDA(dst, b, h) do { _Pragma("unroll") for (int m = 0; m < 4; ++m) _Pragma("unroll") for (int k = 0; k < 2; ++k) dst[m][k] = *(const LAS bf16x8*)(lds + PG8_SA(b, h) + aoff + m * 2048 + k * 1024); } while (0)
; #define PG8_LDB(dst, b, h) do { _Pragma("unroll") for (int n = 0; n < 2; ++n) _Pragma("unroll") for (int k = 0; k < 2; ++k) dst[n][k] = *(const LAS bf16x8*)(lds + PG8_SB(b, h) + boff + n * 2048 + k * 1024); } while (0)
; #define PG8_MMA(ai, bj, At, Bt) do { __builtin_amdgcn_s_setprio(1); _Pragma("unroll") for (int m = 0; m < 4; ++m) _Pragma("unroll") for (int n = 0; n < 2; ++n) _Pragma("unroll") for (int k = 0; k < 2; ++k) \
;         acc[ai][bj][m][n] = __builtin_amdgcn_mfma_f32_16x16x32_bf16(Bt[n][k], At[m][k], acc[ai][bj][m][n], 0, 0, 0); __builtin_amdgcn_s_setprio(0); } while (0)
; #define PG8_WAIT_V(n) asm volatile("s_waitcnt vmcnt(" #n ")" ::: "memory")
; #define PG8_WAIT_L(n) asm volatile("s_waitcnt lgkmcnt(" #n ")" ::: "memory")
; #define PG8_BAR __builtin_amdgcn_s_barrier()
; #define PG8_SCHED __builtin_amdgcn_sched_barrier(0)
; template <class Epi>
; DEVI void gemm_phase(LAS unsigned char* lds, const Gemm g, const Epi& E) {
;     ...
;             PG8_STAGE(PG8_SB(0, 1), b2 + hstepB, voffB);
;             PG8_WAIT_V(6); PG8_BAR; PG8_MMA(1, 1, At, B1); PG8_BAR;
;             PG8_LDB(B0, 1, 0); PG8_SCHED; PG8_LDA(At, 1, 0); PG8_STAGE(PG8_SA(0, 1), a2 + hstepA, voffA);
;             PG8_WAIT_L(8); PG8_BAR; PG8_WAIT_L(0); PG8_MMA(0, 0, At, B0); PG8_BAR; PG8_SCHED;
;             PG8_LDB(B1, 1, 1); PG8_STAGE(PG8_SB(1, 0), b3, voffB);
;             PG8_BAR; PG8_WAIT_L(0); PG8_MMA(0, 1, At, B1); PG8_BAR;
;             PG8_LDA(At, 1, 1); PG8_STAGE(PG8_SA(1, 0), a3, voffA);
;             PG8_BAR; PG8_WAIT_L(0); PG8_MMA(1, 0, At, B0); PG8_BAR; PG8_SCHED;
	s_add_u32 s38, s14, 0x40000
	s_addc_u32 s39, s15, 0
	s_add_i32 s40, s40, s47
	s_mov_b32 m0, s40
	v_lshl_add_u64 v[114:115], s[38:39], 0, v[8:9]
	global_load_lds_dwordx4 v[114:115], off
	s_add_i32 m0, s40, 0x2000
	v_lshl_add_u64 v[114:115], s[38:39], 0, v[146:147]
	global_load_lds_dwordx4 v[114:115], off
	s_waitcnt vmcnt(6)
	s_barrier
	v_mfma_f32_16x16x32_bf16 v[54:57], v[222:225], v[180:183], v[54:57]
	v_mfma_f32_16x16x32_bf16 v[50:53], v[230:233], v[180:183], v[50:53]
	v_mfma_f32_16x16x32_bf16 v[38:41], v[222:225], v[192:195], v[38:41]
	v_mfma_f32_16x16x32_bf16 v[34:37], v[230:233], v[192:195], v[34:37]
	v_mfma_f32_16x16x32_bf16 v[22:25], v[222:225], v[200:203], v[22:25]
	v_mfma_f32_16x16x32_bf16 v[18:21], v[230:233], v[200:203], v[18:21]
	v_mfma_f32_16x16x32_bf16 v[4:7], v[222:225], v[214:217], v[4:7]
	v_mfma_f32_16x16x32_bf16 v[0:3], v[230:233], v[214:217], v[0:3]
	v_mfma_f32_16x16x32_bf16 v[54:57], v[226:229], v[188:191], v[54:57]
	v_mfma_f32_16x16x32_bf16 v[50:53], v[234:237], v[188:191], v[50:53]
	v_mfma_f32_16x16x32_bf16 v[38:41], v[226:229], v[196:199], v[38:41]
	v_mfma_f32_16x16x32_bf16 v[34:37], v[234:237], v[196:199], v[34:37]
	v_mfma_f32_16x16x32_bf16 v[22:25], v[226:229], v[204:207], v[22:25]
	v_mfma_f32_16x16x32_bf16 v[18:21], v[234:237], v[204:207], v[18:21]
	v_mfma_f32_16x16x32_bf16 v[4:7], v[226:229], v[218:221], v[4:7]
	v_mfma_f32_16x16x32_bf16 v[0:3], v[234:237], v[218:221], v[0:3]
	s_add_i32 s38, 0, 0x18000
	v_add_u32_e32 v176, s38, v185
	s_barrier
	ds_read_b128 v[114:117], v176
	ds_read_b128 v[126:129], v176 offset:1024
	ds_read_b128 v[130:133], v176 offset:2048
	ds_read_b128 v[176:179], v176 offset:3072
	s_add_u32 s16, s16, 0x40000
	s_addc_u32 s17, s17, 0
	s_mov_b32 m0, s68
	v_lshl_add_u64 v[222:223], s[16:17], 0, v[142:143]
	ds_read_b128 v[180:183], v187 offset:32768
	ds_read_b128 v[188:191], v187 offset:33792
	ds_read_b128 v[192:195], v187 offset:34816
	ds_read_b128 v[196:199], v187 offset:35840
	ds_read_b128 v[200:203], v187 offset:36864
	ds_read_b128 v[204:207], v187 offset:37888
	ds_read_b128 v[214:217], v187 offset:38912
	ds_read_b128 v[218:221], v187 offset:39936
	global_load_lds_dwordx4 v[222:223], off
	s_mov_b32 m0, s69
	v_lshl_add_u64 v[222:223], s[16:17], 0, v[144:145]
	global_load_lds_dwordx4 v[222:223], off
	s_waitcnt lgkmcnt(8)
	s_barrier
	s_waitcnt lgkmcnt(0)
	v_mfma_f32_16x16x32_bf16 v[138:141], v[114:117], v[180:183], v[138:141]
	v_mfma_f32_16x16x32_bf16 v[134:137], v[130:133], v[180:183], v[134:137]
	v_mfma_f32_16x16x32_bf16 v[110:113], v[114:117], v[192:195], v[110:113]
	v_mfma_f32_16x16x32_bf16 v[106:109], v[130:133], v[192:195], v[106:109]
	v_mfma_f32_16x16x32_bf16 v[94:97], v[114:117], v[200:203], v[94:97]
	v_mfma_f32_16x16x32_bf16 v[90:93], v[130:133], v[200:203], v[90:93]
	v_mfma_f32_16x16x32_bf16 v[78:81], v[114:117], v[214:217], v[78:81]
	v_mfma_f32_16x16x32_bf16 v[74:77], v[130:133], v[214:217], v[74:77]
	v_mfma_f32_16x16x32_bf16 v[138:141], v[126:129], v[188:191], v[138:141]
	v_mfma_f32_16x16x32_bf16 v[134:137], v[176:179], v[188:191], v[134:137]
	v_mfma_f32_16x16x32_bf16 v[110:113], v[126:129], v[196:199], v[110:113]
	v_mfma_f32_16x16x32_bf16 v[106:109], v[176:179], v[196:199], v[106:109]
	v_mfma_f32_16x16x32_bf16 v[94:97], v[126:129], v[204:207], v[94:97]
	v_mfma_f32_16x16x32_bf16 v[90:93], v[176:179], v[204:207], v[90:93]
	v_mfma_f32_16x16x32_bf16 v[78:81], v[126:129], v[218:221], v[78:81]
	v_mfma_f32_16x16x32_bf16 v[74:77], v[176:179], v[218:221], v[74:77]
	s_barrier
	s_add_i32 s16, 0, 0x1c000
	s_add_i32 s17, s38, s47
	v_add_u32_e32 v213, s16, v185
	v_lshl_add_u64 v[152:153], v[152:153], 0, s[70:71]
	s_mov_b32 m0, s17
	ds_read_b128 v[222:225], v213
	ds_read_b128 v[226:229], v213 offset:1024
	ds_read_b128 v[230:233], v213 offset:2048
	ds_read_b128 v[234:237], v213 offset:3072
	global_load_lds_dwordx4 v[152:153], off
	s_add_i32 m0, s17, 0x2000
	v_lshl_add_u64 v[152:153], v[162:163], 0, s[70:71]
	global_load_lds_dwordx4 v[152:153], off
	s_barrier
	s_waitcnt lgkmcnt(0)
	v_mfma_f32_16x16x32_bf16 v[122:125], v[222:225], v[180:183], v[122:125]
	v_mfma_f32_16x16x32_bf16 v[118:121], v[230:233], v[180:183], v[118:121]
	v_mfma_f32_16x16x32_bf16 v[102:105], v[222:225], v[192:195], v[102:105]
	v_mfma_f32_16x16x32_bf16 v[98:101], v[230:233], v[192:195], v[98:101]
	v_mfma_f32_16x16x32_bf16 v[86:89], v[222:225], v[200:203], v[86:89]
	v_mfma_f32_16x16x32_bf16 v[82:85], v[230:233], v[200:203], v[82:85]
	v_mfma_f32_16x16x32_bf16 v[70:73], v[222:225], v[214:217], v[70:73]
	v_mfma_f32_16x16x32_bf16 v[66:69], v[230:233], v[214:217], v[66:69]
	v_mfma_f32_16x16x32_bf16 v[122:125], v[226:229], v[188:191], v[122:125]
	v_mfma_f32_16x16x32_bf16 v[118:121], v[234:237], v[188:191], v[118:121]
	v_mfma_f32_16x16x32_bf16 v[102:105], v[226:229], v[196:199], v[102:105]
	v_mfma_f32_16x16x32_bf16 v[98:101], v[234:237], v[196:199], v[98:101]
	v_mfma_f32_16x16x32_bf16 v[86:89], v[226:229], v[204:207], v[86:89]
	v_mfma_f32_16x16x32_bf16 v[82:85], v[234:237], v[204:207], v[82:85]
	v_mfma_f32_16x16x32_bf16 v[70:73], v[226:229], v[218:221], v[70:73]
	v_mfma_f32_16x16x32_bf16 v[66:69], v[234:237], v[218:221], v[66:69]
	s_mov_b32 m0, s80
	v_lshl_add_u64 v[152:153], v[164:165], 0, s[70:71]
	s_barrier
	ds_read_b128 v[180:183], v187 offset:49152
	ds_read_b128 v[188:191], v187 offset:50176
	ds_read_b128 v[192:195], v187 offset:51200
	ds_read_b128 v[196:199], v187 offset:52224
	ds_read_b128 v[200:203], v187 offset:53248
	ds_read_b128 v[204:207], v187 offset:54272
	ds_read_b128 v[214:217], v187 offset:55296
	ds_read_b128 v[218:221], v187 offset:56320
	global_load_lds_dwordx4 v[152:153], off
	s_mov_b32 m0, s81
	v_lshl_add_u64 v[152:153], v[208:209], 0, s[70:71]
	global_load_lds_dwordx4 v[152:153], off
	s_barrier
; #define PG8_STAGE(bufoff, gbase, voff) do { _Pragma("unroll") for (int _i = 0; _i < 2; ++_i) \
;         __builtin_amdgcn_global_load_lds((const unsigned*)((const char*)(gbase) + (voff)[_i]), (LAS unsigned*)(lds + (bufoff) + ldsw + _i * 8192), 16, 0, 0); } while (0)
; #define PG8_MMA(ai, bj, At, Bt) do { __builtin_amdgcn_s_setprio(1); _Pragma("unroll") for (int m = 0; m < 4; ++m) _Pragma("unroll") for (int n = 0; n < 2; ++n) _Pragma("unroll") for (int k = 0; k < 2; ++k) \
;         acc[ai][bj][m][n] = __builtin_amdgcn_mfma_f32_16x16x32_bf16(Bt[n][k], At[m][k], acc[ai][bj][m][n], 0, 0, 0); __builtin_amdgcn_s_setprio(0); } while (0)
; #define PG8_WAIT_V(n) asm volatile("s_waitcnt vmcnt(" #n ")" ::: "memory")
; #define PG8_BAR __builtin_amdgcn_s_barrier()
;     DEVI f32x4 load(int r, int c) const { const bf16x4 y = *(const bf16x4*)(Y + (size_t)r * DM + c); return (f32x4){bf2f((u16)y[0]), bf2f((u16)y[1]), bf2f((u16)y[2]), bf2f((u16)y[3])}; }
; template <class Epi>
; DEVI void gemm_phase(LAS unsigned char* lds, const Gemm g, const Epi& E) {
;     ...
;             PG8_STAGE(PG8_SB(1, 1), b3 + hstepB, voffB);
;             PG8_WAIT_V(6); PG8_BAR; PG8_MMA(1, 1, At, B1); PG8_BAR;
;     ...
;                 if constexpr (Epi::PRE) {
; #pragma unroll
;                     for (int m = 0; m < 2; ++m)
; #pragma unroll
;                         for (int bj = 0; bj < 2; ++bj)
; #pragma unroll
;                             for (int n = 0; n < 2; ++n) pre[m][bj][n] = E.load(row0 + ai * HALF + (m0 + m) * 16, col0 + bj * HALF + n * NST);
	s_waitcnt lgkmcnt(0)
	v_mfma_f32_16x16x32_bf16 v[62:65], v[114:117], v[180:183], v[62:65]
	v_mfma_f32_16x16x32_bf16 v[58:61], v[130:133], v[180:183], v[58:61]
	v_mfma_f32_16x16x32_bf16 v[46:49], v[114:117], v[192:195], v[46:49]
	v_mfma_f32_16x16x32_bf16 v[42:45], v[130:133], v[192:195], v[42:45]
	v_mfma_f32_16x16x32_bf16 v[30:33], v[114:117], v[200:203], v[30:33]
	v_mfma_f32_16x16x32_bf16 v[26:29], v[130:133], v[200:203], v[26:29]
	v_mfma_f32_16x16x32_bf16 v[14:17], v[114:117], v[214:217], v[14:17]
	v_mfma_f32_16x16x32_bf16 v[10:13], v[130:133], v[214:217], v[10:13]
	v_mfma_f32_16x16x32_bf16 v[62:65], v[126:129], v[188:191], v[62:65]
	v_mfma_f32_16x16x32_bf16 v[58:61], v[176:179], v[188:191], v[58:61]
	v_mfma_f32_16x16x32_bf16 v[46:49], v[126:129], v[196:199], v[46:49]
	v_mfma_f32_16x16x32_bf16 v[42:45], v[176:179], v[196:199], v[42:45]
	v_mfma_f32_16x16x32_bf16 v[30:33], v[126:129], v[204:207], v[30:33]
	v_mfma_f32_16x16x32_bf16 v[26:29], v[176:179], v[204:207], v[26:29]
	v_mfma_f32_16x16x32_bf16 v[14:17], v[126:129], v[218:221], v[14:17]
	v_mfma_f32_16x16x32_bf16 v[10:13], v[176:179], v[218:221], v[10:13]
	s_barrier
	s_add_u32 s14, s14, 0x40080
	s_addc_u32 s15, s15, 0
	s_add_i32 s16, s16, s47
	s_mov_b32 m0, s16
	v_lshl_add_u64 v[114:115], s[14:15], 0, v[8:9]
	global_load_lds_dwordx4 v[114:115], off
	s_add_i32 m0, s16, 0x2000
	v_lshl_add_u64 v[114:115], s[14:15], 0, v[146:147]
	global_load_lds_dwordx4 v[114:115], off
	s_waitcnt vmcnt(6)
	s_barrier
	v_mfma_f32_16x16x32_bf16 v[54:57], v[222:225], v[180:183], v[54:57]
	v_mfma_f32_16x16x32_bf16 v[50:53], v[230:233], v[180:183], v[50:53]
	v_mfma_f32_16x16x32_bf16 v[38:41], v[222:225], v[192:195], v[38:41]
	v_mfma_f32_16x16x32_bf16 v[34:37], v[230:233], v[192:195], v[34:37]
	v_mfma_f32_16x16x32_bf16 v[22:25], v[222:225], v[200:203], v[22:25]
	v_mfma_f32_16x16x32_bf16 v[18:21], v[230:233], v[200:203], v[18:21]
	v_mfma_f32_16x16x32_bf16 v[4:7], v[222:225], v[214:217], v[4:7]
	v_mfma_f32_16x16x32_bf16 v[0:3], v[230:233], v[214:217], v[0:3]
	v_mfma_f32_16x16x32_bf16 v[54:57], v[226:229], v[188:191], v[54:57]
	v_mfma_f32_16x16x32_bf16 v[50:53], v[234:237], v[188:191], v[50:53]
	v_mfma_f32_16x16x32_bf16 v[38:41], v[226:229], v[196:199], v[38:41]
	v_mfma_f32_16x16x32_bf16 v[34:37], v[234:237], v[196:199], v[34:37]
	v_mfma_f32_16x16x32_bf16 v[22:25], v[226:229], v[204:207], v[22:25]
	v_mfma_f32_16x16x32_bf16 v[18:21], v[234:237], v[204:207], v[18:21]
	v_mfma_f32_16x16x32_bf16 v[4:7], v[226:229], v[218:221], v[4:7]
	v_mfma_f32_16x16x32_bf16 v[0:3], v[234:237], v[218:221], v[0:3]
	s_add_i32 s27, s27, 2
	s_add_u32 s12, s12, 0x100
	s_addc_u32 s13, s13, 0
	s_add_u32 s19, s19, 0x100
	s_addc_u32 s26, s26, 0
	s_cmp_gt_u32 s27, 13
	s_barrier
	s_cbranch_scc0 .LBB0_1346
	s_setprio 0
	v_lshl_add_u32 v180, s10, 8, v184
	v_lshl_or_b32 v152, s0, 8, v186
	v_ashrrev_i32_e32 v181, 31, v180
	v_lshlrev_b64 v[178:179], 11, v[180:181]
	v_ashrrev_i32_e32 v153, 31, v152
	v_lshl_add_u64 v[114:115], s[24:25], 0, v[178:179]
	v_lshlrev_b64 v[176:177], 1, v[152:153]
	v_lshl_add_u64 v[114:115], v[114:115], 0, v[176:177]
	global_load_dwordx4 v[188:191], v[114:115], off
	global_load_dwordx4 v[130:133], v[114:115], off offset:256
	v_or_b32_e32 v114, 16, v180
	v_ashrrev_i32_e32 v115, 31, v114
	v_lshlrev_b64 v[182:183], 11, v[114:115]
	v_readlane_b32 s48, v251, 40
	v_lshl_add_u64 v[114:115], s[24:25], 0, v[182:183]
	v_readlane_b32 s54, v251, 46
	v_readlane_b32 s55, v251, 47
	v_lshl_add_u64 v[114:115], v[114:115], 0, v[176:177]
	global_load_dwordx4 v[126:129], v[114:115], off
	s_nop 0
	global_load_dwordx4 v[114:117], v[114:115], off offset:256
	v_lshl_add_u64 v[152:153], v[152:153], 2, s[54:55]
	global_load_dwordx4 v[214:217], v[152:153], off
	global_load_dwordx4 v[218:221], v[152:153], off offset:16
	global_load_dwordx4 v[222:225], v[152:153], off offset:512
	global_load_dwordx4 v[226:229], v[152:153], off offset:528
	s_mov_b64 s[0:1], 0x40000
	v_readlane_b32 s52, v251, 44
	v_readlane_b32 s56, v251, 48
	v_readlane_b32 s57, v251, 49
	v_readlane_b32 s58, v251, 50
	v_readlane_b32 s59, v251, 51
	v_readlane_b32 s60, v251, 52
	v_readlane_b32 s61, v251, 53
	v_readlane_b32 s62, v251, 54
	v_readlane_b32 s63, v251, 55
	s_and_b64 vcc, exec, s[36:37]
	s_mov_b32 s10, s2
	s_mov_b64 s[14:15], s[8:9]
	s_mov_b64 s[12:13], s[6:7]
	s_mov_b64 s[56:57], s[42:43]
	s_mov_b64 s[58:59], s[44:45]
	s_mov_b32 s60, s41
	s_mov_b32 s61, s83
	s_mov_b32 s62, s84
	s_mov_b32 s63, s85
	v_readlane_b32 s55, v254, 0
	s_movk_i32 s52, 0x110
	v_readlane_b32 s49, v251, 41
	v_readlane_b32 s50, v251, 42
	v_readlane_b32 s51, v251, 43
	v_readlane_b32 s53, v251, 45
	v_readlane_b32 s40, v254, 1
	s_waitcnt vmcnt(0)
; template <class Epi>
; DEVI void gemm_phase(LAS unsigned char* lds, const Gemm g, const Epi& E) {
;     ...
;                 for (int mm = 0; mm < 2; ++mm) {
;                     const int m = m0 + mm;
;                     const int r = row0 + ai * HALF + m * 16; float rs = 1.f, part = 0.f;
;                     if constexpr (Epi::RS) rs = rsv[ai * 4 + m];
;                     if constexpr (Epi::PAIR) E.pair8(cur.b, r, cur.pn * HALF + wc * 32 + 8 * fq, acc[ai][0][m][0] * rs, acc[ai][0][m][1] * rs, acc[ai][1][m][0] * rs, acc[ai][1][m][1] * rs);
;                     else
; #pragma unroll
;                     for (int bj = 0; bj < 2; ++bj) {
;                         const int c = col0 + bj * HALF; f32x4 v0 = acc[ai][bj][m][0], v1 = acc[ai][bj][m][1];
;                         if constexpr (Epi::RS) { v0 = v0 * rs; v1 = v1 * rs; }
;                         if constexpr (Epi::PRE) part += E.frag_pre8(cur.b, r, c, v0, v1, pre[mm][bj][0], pre[mm][bj][1]);
;                         else if constexpr (Epi::PERM) E.frag8(cur.b, r, c, v0, v1);
;                         else { E.frag(cur.b, r, c, v0); E.frag(cur.b, r, c + 16, v1); }
;                     }
	v_and_b32_e32 v163, 0xffff0000, v188
	v_lshlrev_b32_e32 v162, 16, v188
	v_add_f32_e32 v134, v134, v218
	v_add_f32_e32 v138, v138, v214
	v_add_f32_e32 v139, v139, v215
	v_mul_f32_e32 v138, 0xbfb8aa3b, v138
	v_mul_f32_e32 v139, 0xbfb8aa3b, v139
	v_add_f32_e32 v135, v135, v219
	v_exp_f32_e32 v138, v138
	v_mul_f32_e32 v134, 0xbfb8aa3b, v134
	v_exp_f32_e32 v139, v139
	v_mul_f32_e32 v135, 0xbfb8aa3b, v135
	v_exp_f32_e32 v134, v134
	v_exp_f32_e32 v135, v135
	v_add_f32_e32 v138, 1.0, v138
	v_add_f32_e32 v139, 1.0, v139
	v_rcp_f32_e32 v138, v138
	v_add_f32_e32 v134, 1.0, v134
	v_rcp_f32_e32 v139, v139
	v_add_f32_e32 v135, 1.0, v135
	v_rcp_f32_e32 v134, v134
	v_rcp_f32_e32 v135, v135
	v_pk_mul_f32 v[138:139], v[138:139], v[162:163]
	v_and_b32_e32 v163, 0xffff0000, v190
	v_lshlrev_b32_e32 v162, 16, v190
	v_pk_mul_f32 v[162:163], v[134:135], v[162:163]
	v_add_f32_e32 v135, v136, v220
	v_mul_f32_e32 v135, 0xbfb8aa3b, v135
	v_exp_f32_e32 v135, v135
	v_add_f32_e32 v134, v140, v216
	v_mul_f32_e32 v134, 0xbfb8aa3b, v134
	v_exp_f32_e32 v134, v134
	v_add_f32_e32 v135, 1.0, v135
	v_rcp_f32_e32 v136, v135
	v_add_f32_e32 v135, v141, v217
	v_mul_f32_e32 v135, 0xbfb8aa3b, v135
	v_exp_f32_e32 v135, v135
	v_add_f32_e32 v134, 1.0, v134
	v_rcp_f32_e32 v134, v134
	v_and_b32_e32 v141, 0xffff0000, v189
	v_add_f32_e32 v135, 1.0, v135
	v_rcp_f32_e32 v135, v135
	v_lshlrev_b32_e32 v140, 16, v189
	v_pk_mul_f32 v[140:141], v[134:135], v[140:141]
	v_add_f32_e32 v134, v137, v221
	v_mul_f32_e32 v134, 0xbfb8aa3b, v134
	v_exp_f32_e32 v134, v134
	v_and_b32_e32 v135, 0xffff0000, v191
	v_add_f32_e32 v134, 1.0, v134
	v_rcp_f32_e32 v137, v134
	v_lshlrev_b32_e32 v134, 16, v191
	v_pk_mul_f32 v[164:165], v[136:137], v[134:135]
	v_cvt_pk_bf16_f32 v134, v138, v139
	v_lshl_add_u64 v[138:139], s[64:65], 0, v[178:179]
	v_cvt_pk_bf16_f32 v135, v140, v141
	v_cvt_pk_bf16_f32 v136, v162, v163
	v_cvt_pk_bf16_f32 v137, v164, v165
	v_lshl_add_u64 v[138:139], v[138:139], 0, v[176:177]
	global_store_dwordx4 v[138:139], v[134:137], off
	s_nop 0
	v_and_b32_e32 v141, 0xffff0000, v130
	v_lshlrev_b32_e32 v140, 16, v130
	v_lshlrev_b32_e32 v130, 16, v133
	v_add_f32_e32 v118, v118, v226
	v_add_f32_e32 v119, v119, v227
	v_add_f32_e32 v122, v122, v222
	v_mul_f32_e32 v118, 0xbfb8aa3b, v118
	v_add_f32_e32 v123, v123, v223
	v_mul_f32_e32 v119, 0xbfb8aa3b, v119
	v_add_f32_e32 v124, v124, v224
	v_add_f32_e32 v120, v120, v228
	v_add_f32_e32 v125, v125, v225
	v_add_f32_e32 v121, v121, v229
	v_mul_f32_e32 v122, 0xbfb8aa3b, v122
	v_exp_f32_e32 v118, v118
	v_mul_f32_e32 v123, 0xbfb8aa3b, v123
	v_exp_f32_e32 v119, v119
	v_mul_f32_e32 v124, 0xbfb8aa3b, v124
	v_mul_f32_e32 v120, 0xbfb8aa3b, v120
	v_mul_f32_e32 v125, 0xbfb8aa3b, v125
	v_mul_f32_e32 v121, 0xbfb8aa3b, v121
	v_exp_f32_e32 v122, v122
	v_exp_f32_e32 v123, v123
	v_exp_f32_e32 v124, v124
	v_exp_f32_e32 v120, v120
	v_exp_f32_e32 v125, v125
	v_exp_f32_e32 v121, v121
	v_add_f32_e32 v118, 1.0, v118
	v_add_f32_e32 v119, 1.0, v119
	v_add_f32_e32 v122, 1.0, v122
	v_rcp_f32_e32 v118, v118
	v_add_f32_e32 v123, 1.0, v123
	v_rcp_f32_e32 v119, v119
	v_add_f32_e32 v124, 1.0, v124
	v_add_f32_e32 v120, 1.0, v120
	v_add_f32_e32 v125, 1.0, v125
	v_add_f32_e32 v121, 1.0, v121
	v_rcp_f32_e32 v122, v122
	v_rcp_f32_e32 v123, v123
	v_rcp_f32_e32 v124, v124
	v_rcp_f32_e32 v120, v120
	v_rcp_f32_e32 v125, v125
	v_rcp_f32_e32 v121, v121
	v_and_b32_e32 v135, 0xffff0000, v132
	v_lshlrev_b32_e32 v134, 16, v132
	v_pk_mul_f32 v[118:119], v[118:119], v[134:135]
	v_and_b32_e32 v135, 0xffff0000, v131
	v_lshlrev_b32_e32 v134, 16, v131
	v_and_b32_e32 v131, 0xffff0000, v133
	v_pk_mul_f32 v[122:123], v[122:123], v[140:141]
	v_pk_mul_f32 v[124:125], v[124:125], v[134:135]
	v_pk_mul_f32 v[130:131], v[120:121], v[130:131]
	v_cvt_pk_bf16_f32 v120, v122, v123
	v_cvt_pk_bf16_f32 v121, v124, v125
	v_cvt_pk_bf16_f32 v122, v118, v119
	v_cvt_pk_bf16_f32 v123, v130, v131
	global_store_dwordx4 v[138:139], v[120:123], off offset:256
	s_nop 0
	v_add_f32_e32 v106, v106, v218
	v_add_f32_e32 v107, v107, v219
	v_mul_f32_e32 v106, 0xbfb8aa3b, v106
	v_mul_f32_e32 v107, 0xbfb8aa3b, v107
	v_exp_f32_e32 v106, v106
	v_exp_f32_e32 v107, v107
	v_and_b32_e32 v119, 0xffff0000, v128
	v_lshlrev_b32_e32 v118, 16, v128
	v_add_f32_e32 v106, 1.0, v106
	v_add_f32_e32 v107, 1.0, v107
	v_rcp_f32_e32 v106, v106
	v_rcp_f32_e32 v107, v107
	v_add_f32_e32 v110, v110, v214
	v_add_f32_e32 v111, v111, v215
	v_mul_f32_e32 v110, 0xbfb8aa3b, v110
	v_pk_mul_f32 v[118:119], v[106:107], v[118:119]
	v_add_f32_e32 v107, v108, v220
	v_mul_f32_e32 v107, 0xbfb8aa3b, v107
	v_exp_f32_e32 v107, v107
	v_add_f32_e32 v106, v112, v216
	v_mul_f32_e32 v106, 0xbfb8aa3b, v106
	v_exp_f32_e32 v106, v106
	v_add_f32_e32 v107, 1.0, v107
	v_rcp_f32_e32 v108, v107
	v_add_f32_e32 v107, v113, v217
	v_mul_f32_e32 v107, 0xbfb8aa3b, v107
	v_exp_f32_e32 v107, v107
	v_add_f32_e32 v106, 1.0, v106
	v_rcp_f32_e32 v106, v106
	v_and_b32_e32 v113, 0xffff0000, v127
	v_add_f32_e32 v107, 1.0, v107
	v_rcp_f32_e32 v107, v107
	v_lshlrev_b32_e32 v112, 16, v127
	v_mul_f32_e32 v111, 0xbfb8aa3b, v111
	v_exp_f32_e32 v110, v110
	v_pk_mul_f32 v[112:113], v[106:107], v[112:113]
	v_add_f32_e32 v106, v109, v221
	v_exp_f32_e32 v111, v111
	v_mul_f32_e32 v106, 0xbfb8aa3b, v106
	v_exp_f32_e32 v106, v106
	v_add_f32_e32 v110, 1.0, v110
	v_add_f32_e32 v111, 1.0, v111
	v_rcp_f32_e32 v110, v110
	v_rcp_f32_e32 v111, v111
	v_add_f32_e32 v106, 1.0, v106
	v_rcp_f32_e32 v109, v106
	v_and_b32_e32 v123, 0xffff0000, v126
	v_lshlrev_b32_e32 v122, 16, v126
	v_pk_mul_f32 v[110:111], v[110:111], v[122:123]
	v_and_b32_e32 v107, 0xffff0000, v129
	v_lshlrev_b32_e32 v106, 16, v129
	v_pk_mul_f32 v[120:121], v[108:109], v[106:107]
;     DEVI f32x4 load(int r, int c) const { const bf16x4 y = *(const bf16x4*)(Y + (size_t)r * DM + c); return (f32x4){bf2f((u16)y[0]), bf2f((u16)y[1]), bf2f((u16)y[2]), bf2f((u16)y[3])}; }
; template <class Epi>
; DEVI void gemm_phase(LAS unsigned char* lds, const Gemm g, const Epi& E) {
;     ...
;                 if constexpr (Epi::PRE) {
; #pragma unroll
;                     for (int m = 0; m < 2; ++m)
; #pragma unroll
;                         for (int bj = 0; bj < 2; ++bj)
; #pragma unroll
;                             for (int n = 0; n < 2; ++n) pre[m][bj][n] = E.load(row0 + ai * HALF + (m0 + m) * 16, col0 + bj * HALF + n * NST);
	v_cvt_pk_bf16_f32 v106, v110, v111
	v_lshl_add_u64 v[110:111], s[64:65], 0, v[182:183]
	v_cvt_pk_bf16_f32 v107, v112, v113
	v_cvt_pk_bf16_f32 v108, v118, v119
	v_cvt_pk_bf16_f32 v109, v120, v121
	v_lshl_add_u64 v[110:111], v[110:111], 0, v[176:177]
	global_store_dwordx4 v[110:111], v[106:109], off
	s_nop 0
	v_and_b32_e32 v113, 0xffff0000, v114
	v_lshlrev_b32_e32 v112, 16, v114
	v_add_f32_e32 v98, v98, v226
	v_add_f32_e32 v99, v99, v227
	v_mul_f32_e32 v98, 0xbfb8aa3b, v98
	v_mul_f32_e32 v99, 0xbfb8aa3b, v99
	v_exp_f32_e32 v98, v98
	v_exp_f32_e32 v99, v99
	v_and_b32_e32 v107, 0xffff0000, v116
	v_lshlrev_b32_e32 v106, 16, v116
	v_add_f32_e32 v98, 1.0, v98
	v_add_f32_e32 v99, 1.0, v99
	v_rcp_f32_e32 v98, v98
	v_rcp_f32_e32 v99, v99
	v_add_f32_e32 v102, v102, v222
	v_add_f32_e32 v103, v103, v223
	v_mul_f32_e32 v102, 0xbfb8aa3b, v102
	v_pk_mul_f32 v[106:107], v[98:99], v[106:107]
	v_add_f32_e32 v99, v100, v228
	v_mul_f32_e32 v99, 0xbfb8aa3b, v99
	v_exp_f32_e32 v99, v99
	v_add_f32_e32 v98, v104, v224
	v_mul_f32_e32 v98, 0xbfb8aa3b, v98
	v_exp_f32_e32 v98, v98
	v_add_f32_e32 v99, 1.0, v99
	v_rcp_f32_e32 v100, v99
	v_add_f32_e32 v99, v105, v225
	v_mul_f32_e32 v99, 0xbfb8aa3b, v99
	v_exp_f32_e32 v99, v99
	v_add_f32_e32 v98, 1.0, v98
	v_rcp_f32_e32 v98, v98
	v_and_b32_e32 v105, 0xffff0000, v115
	v_add_f32_e32 v99, 1.0, v99
	v_rcp_f32_e32 v99, v99
	v_lshlrev_b32_e32 v104, 16, v115
	v_mul_f32_e32 v103, 0xbfb8aa3b, v103
	v_exp_f32_e32 v102, v102
	v_pk_mul_f32 v[104:105], v[98:99], v[104:105]
	v_add_f32_e32 v98, v101, v229
	v_mul_f32_e32 v98, 0xbfb8aa3b, v98
	v_exp_f32_e32 v103, v103
	v_exp_f32_e32 v98, v98
	v_add_f32_e32 v102, 1.0, v102
	v_rcp_f32_e32 v102, v102
	v_add_f32_e32 v103, 1.0, v103
	v_add_f32_e32 v98, 1.0, v98
	v_rcp_f32_e32 v103, v103
	v_rcp_f32_e32 v101, v98
	v_and_b32_e32 v99, 0xffff0000, v117
	v_lshlrev_b32_e32 v98, 16, v117
	v_pk_mul_f32 v[102:103], v[102:103], v[112:113]
	v_pk_mul_f32 v[108:109], v[100:101], v[98:99]
	v_cvt_pk_bf16_f32 v98, v102, v103
	v_cvt_pk_bf16_f32 v99, v104, v105
	v_cvt_pk_bf16_f32 v100, v106, v107
	v_cvt_pk_bf16_f32 v101, v108, v109
	global_store_dwordx4 v[110:111], v[98:101], off offset:256
	s_nop 1
	v_or_b32_e32 v98, 32, v180
	v_ashrrev_i32_e32 v99, 31, v98
	v_lshlrev_b64 v[120:121], 11, v[98:99]
	v_lshl_add_u64 v[98:99], s[24:25], 0, v[120:121]
	v_lshl_add_u64 v[98:99], v[98:99], 0, v[176:177]
	global_load_dwordx4 v[110:113], v[98:99], off
	global_load_dwordx4 v[106:109], v[98:99], off offset:256
	v_or_b32_e32 v98, 48, v180
	v_ashrrev_i32_e32 v99, 31, v98
	v_lshlrev_b64 v[118:119], 11, v[98:99]
	v_lshl_add_u64 v[98:99], s[24:25], 0, v[118:119]
	v_lshl_add_u64 v[98:99], v[98:99], 0, v[176:177]
	global_load_dwordx4 v[102:105], v[98:99], off
	s_nop 0
	global_load_dwordx4 v[98:101], v[98:99], off offset:256
	s_nop 0
	s_waitcnt vmcnt(0)
	v_add_f32_e32 v90, v90, v218
	v_add_f32_e32 v91, v91, v219
	v_mul_f32_e32 v90, 0xbfb8aa3b, v90
	v_mul_f32_e32 v91, 0xbfb8aa3b, v91
	v_exp_f32_e32 v90, v90
	v_exp_f32_e32 v91, v91
	v_and_b32_e32 v115, 0xffff0000, v112
	v_lshlrev_b32_e32 v114, 16, v112
	v_add_f32_e32 v90, 1.0, v90
	v_add_f32_e32 v91, 1.0, v91
	v_rcp_f32_e32 v90, v90
	v_rcp_f32_e32 v91, v91
	v_add_f32_e32 v94, v94, v214
	v_add_f32_e32 v95, v95, v215
	v_mul_f32_e32 v94, 0xbfb8aa3b, v94
	v_pk_mul_f32 v[114:115], v[90:91], v[114:115]
	v_add_f32_e32 v91, v92, v220
	v_mul_f32_e32 v91, 0xbfb8aa3b, v91
	v_exp_f32_e32 v91, v91
	v_add_f32_e32 v90, v96, v216
	v_mul_f32_e32 v90, 0xbfb8aa3b, v90
	v_exp_f32_e32 v90, v90
	v_add_f32_e32 v91, 1.0, v91
	v_rcp_f32_e32 v92, v91
	v_add_f32_e32 v91, v97, v217
	v_mul_f32_e32 v91, 0xbfb8aa3b, v91
	v_exp_f32_e32 v91, v91
	v_add_f32_e32 v90, 1.0, v90
	v_rcp_f32_e32 v90, v90
	v_and_b32_e32 v97, 0xffff0000, v111
	v_add_f32_e32 v91, 1.0, v91
	v_rcp_f32_e32 v91, v91
	v_lshlrev_b32_e32 v96, 16, v111
	v_mul_f32_e32 v95, 0xbfb8aa3b, v95
	v_exp_f32_e32 v94, v94
	v_pk_mul_f32 v[96:97], v[90:91], v[96:97]
	v_add_f32_e32 v90, v93, v221
	v_exp_f32_e32 v95, v95
	v_mul_f32_e32 v90, 0xbfb8aa3b, v90
	v_exp_f32_e32 v90, v90
	v_add_f32_e32 v94, 1.0, v94
	v_add_f32_e32 v95, 1.0, v95
	v_rcp_f32_e32 v94, v94
	v_rcp_f32_e32 v95, v95
	v_add_f32_e32 v90, 1.0, v90
	v_rcp_f32_e32 v93, v90
	v_and_b32_e32 v123, 0xffff0000, v110
	v_lshlrev_b32_e32 v122, 16, v110
	v_pk_mul_f32 v[94:95], v[94:95], v[122:123]
	v_and_b32_e32 v91, 0xffff0000, v113
	v_lshlrev_b32_e32 v90, 16, v113
	v_pk_mul_f32 v[110:111], v[92:93], v[90:91]
	v_cvt_pk_bf16_f32 v90, v94, v95
	v_lshl_add_u64 v[94:95], s[64:65], 0, v[120:121]
	v_cvt_pk_bf16_f32 v91, v96, v97
	v_cvt_pk_bf16_f32 v92, v114, v115
	v_cvt_pk_bf16_f32 v93, v110, v111
	v_lshl_add_u64 v[94:95], v[94:95], 0, v[176:177]
	global_store_dwordx4 v[94:95], v[90:93], off
	s_nop 0
	v_and_b32_e32 v97, 0xffff0000, v106
	v_lshlrev_b32_e32 v96, 16, v106
	v_add_f32_e32 v82, v82, v226
	v_add_f32_e32 v83, v83, v227
	v_mul_f32_e32 v82, 0xbfb8aa3b, v82
	v_mul_f32_e32 v83, 0xbfb8aa3b, v83
	v_add_f32_e32 v88, v88, v224
	v_add_f32_e32 v89, v89, v225
	v_add_f32_e32 v86, v86, v222
	v_exp_f32_e32 v82, v82
	v_add_f32_e32 v87, v87, v223
	v_exp_f32_e32 v83, v83
	v_mul_f32_e32 v88, 0xbfb8aa3b, v88
	v_add_f32_e32 v84, v84, v228
	v_mul_f32_e32 v89, 0xbfb8aa3b, v89
	v_add_f32_e32 v85, v85, v229
	v_mul_f32_e32 v86, 0xbfb8aa3b, v86
	v_mul_f32_e32 v87, 0xbfb8aa3b, v87
	v_exp_f32_e32 v88, v88
	v_mul_f32_e32 v84, 0xbfb8aa3b, v84
	v_exp_f32_e32 v89, v89
	v_mul_f32_e32 v85, 0xbfb8aa3b, v85
	v_exp_f32_e32 v86, v86
	v_exp_f32_e32 v87, v87
	v_exp_f32_e32 v84, v84
	v_exp_f32_e32 v85, v85
	v_add_f32_e32 v82, 1.0, v82
	v_add_f32_e32 v83, 1.0, v83
	v_rcp_f32_e32 v82, v82
	v_rcp_f32_e32 v83, v83
	v_add_f32_e32 v88, 1.0, v88
;     DEVI f32x4 load(int r, int c) const { const bf16x4 y = *(const bf16x4*)(Y + (size_t)r * DM + c); return (f32x4){bf2f((u16)y[0]), bf2f((u16)y[1]), bf2f((u16)y[2]), bf2f((u16)y[3])}; }
; template <class Epi>
; DEVI void gemm_phase(LAS unsigned char* lds, const Gemm g, const Epi& E) {
;     ...
;                 if constexpr (Epi::PRE) {
; #pragma unroll
;                     for (int m = 0; m < 2; ++m)
; #pragma unroll
;                         for (int bj = 0; bj < 2; ++bj)
; #pragma unroll
;                             for (int n = 0; n < 2; ++n) pre[m][bj][n] = E.load(row0 + ai * HALF + (m0 + m) * 16, col0 + bj * HALF + n * NST);
	v_add_f32_e32 v89, 1.0, v89
	v_add_f32_e32 v86, 1.0, v86
	v_add_f32_e32 v87, 1.0, v87
	v_rcp_f32_e32 v88, v88
	v_add_f32_e32 v84, 1.0, v84
	v_rcp_f32_e32 v89, v89
	v_add_f32_e32 v85, 1.0, v85
	v_rcp_f32_e32 v86, v86
	v_rcp_f32_e32 v87, v87
	v_rcp_f32_e32 v84, v84
	v_rcp_f32_e32 v85, v85
	v_and_b32_e32 v91, 0xffff0000, v108
	v_lshlrev_b32_e32 v90, 16, v108
	v_pk_mul_f32 v[82:83], v[82:83], v[90:91]
	v_and_b32_e32 v91, 0xffff0000, v107
	v_lshlrev_b32_e32 v90, 16, v107
	v_pk_mul_f32 v[88:89], v[88:89], v[90:91]
	v_and_b32_e32 v91, 0xffff0000, v109
	v_lshlrev_b32_e32 v90, 16, v109
	v_pk_mul_f32 v[86:87], v[86:87], v[96:97]
	v_pk_mul_f32 v[90:91], v[84:85], v[90:91]
	v_cvt_pk_bf16_f32 v84, v86, v87
	v_cvt_pk_bf16_f32 v85, v88, v89
	v_cvt_pk_bf16_f32 v86, v82, v83
	v_cvt_pk_bf16_f32 v87, v90, v91
	global_store_dwordx4 v[94:95], v[84:87], off offset:256
	s_nop 0
	v_add_f32_e32 v74, v74, v218
	v_add_f32_e32 v75, v75, v219
	v_mul_f32_e32 v74, 0xbfb8aa3b, v74
	v_mul_f32_e32 v75, 0xbfb8aa3b, v75
	v_exp_f32_e32 v74, v74
	v_exp_f32_e32 v75, v75
	v_and_b32_e32 v83, 0xffff0000, v104
	v_lshlrev_b32_e32 v82, 16, v104
	v_add_f32_e32 v74, 1.0, v74
	v_add_f32_e32 v75, 1.0, v75
	v_rcp_f32_e32 v74, v74
	v_rcp_f32_e32 v75, v75
	v_add_f32_e32 v78, v78, v214
	v_add_f32_e32 v79, v79, v215
	v_mul_f32_e32 v78, 0xbfb8aa3b, v78
	v_pk_mul_f32 v[82:83], v[74:75], v[82:83]
	v_add_f32_e32 v75, v76, v220
	v_mul_f32_e32 v75, 0xbfb8aa3b, v75
	v_exp_f32_e32 v75, v75
	v_add_f32_e32 v74, v80, v216
	v_mul_f32_e32 v74, 0xbfb8aa3b, v74
	v_exp_f32_e32 v74, v74
	v_add_f32_e32 v75, 1.0, v75
	v_rcp_f32_e32 v76, v75
	v_add_f32_e32 v75, v81, v217
	v_mul_f32_e32 v75, 0xbfb8aa3b, v75
	v_exp_f32_e32 v75, v75
	v_add_f32_e32 v74, 1.0, v74
	v_rcp_f32_e32 v74, v74
	v_and_b32_e32 v81, 0xffff0000, v103
	v_add_f32_e32 v75, 1.0, v75
	v_rcp_f32_e32 v75, v75
	v_lshlrev_b32_e32 v80, 16, v103
	v_mul_f32_e32 v79, 0xbfb8aa3b, v79
	v_exp_f32_e32 v78, v78
	v_pk_mul_f32 v[80:81], v[74:75], v[80:81]
	v_add_f32_e32 v74, v77, v221
	v_exp_f32_e32 v79, v79
	v_mul_f32_e32 v74, 0xbfb8aa3b, v74
	v_exp_f32_e32 v74, v74
	v_add_f32_e32 v78, 1.0, v78
	v_add_f32_e32 v79, 1.0, v79
	v_rcp_f32_e32 v78, v78
	v_rcp_f32_e32 v79, v79
	v_add_f32_e32 v74, 1.0, v74
	v_rcp_f32_e32 v77, v74
	v_and_b32_e32 v87, 0xffff0000, v102
	v_lshlrev_b32_e32 v86, 16, v102
	v_pk_mul_f32 v[78:79], v[78:79], v[86:87]
	v_and_b32_e32 v75, 0xffff0000, v105
	v_lshlrev_b32_e32 v74, 16, v105
	v_pk_mul_f32 v[84:85], v[76:77], v[74:75]
	v_cvt_pk_bf16_f32 v74, v78, v79
	v_lshl_add_u64 v[78:79], s[64:65], 0, v[118:119]
	v_cvt_pk_bf16_f32 v75, v80, v81
	v_cvt_pk_bf16_f32 v76, v82, v83
	v_cvt_pk_bf16_f32 v77, v84, v85
	v_lshl_add_u64 v[78:79], v[78:79], 0, v[176:177]
	global_store_dwordx4 v[78:79], v[74:77], off
	s_nop 0
	v_lshl_add_u64 v[88:89], v[178:179], 0, s[0:1]
	s_mov_b64 s[0:1], 0x48000
	v_lshl_add_u64 v[86:87], v[178:179], 0, s[0:1]
	s_mov_b64 s[0:1], 0x50000
	v_add_f32_e32 v66, v66, v226
	v_add_f32_e32 v67, v67, v227
	v_mul_f32_e32 v66, 0xbfb8aa3b, v66
	v_mul_f32_e32 v67, 0xbfb8aa3b, v67
	v_exp_f32_e32 v66, v66
	v_exp_f32_e32 v67, v67
	v_and_b32_e32 v75, 0xffff0000, v100
	v_lshlrev_b32_e32 v74, 16, v100
	v_add_f32_e32 v66, 1.0, v66
	v_add_f32_e32 v67, 1.0, v67
	v_rcp_f32_e32 v66, v66
	v_rcp_f32_e32 v67, v67
	v_add_f32_e32 v70, v70, v222
	v_add_f32_e32 v71, v71, v223
	v_mul_f32_e32 v70, 0xbfb8aa3b, v70
	v_pk_mul_f32 v[74:75], v[66:67], v[74:75]
	v_add_f32_e32 v67, v68, v228
	v_mul_f32_e32 v67, 0xbfb8aa3b, v67
	v_exp_f32_e32 v67, v67
	v_add_f32_e32 v66, v72, v224
	v_mul_f32_e32 v66, 0xbfb8aa3b, v66
	v_exp_f32_e32 v66, v66
	v_add_f32_e32 v67, 1.0, v67
	v_rcp_f32_e32 v68, v67
	v_add_f32_e32 v67, v73, v225
	v_mul_f32_e32 v67, 0xbfb8aa3b, v67
	v_exp_f32_e32 v67, v67
	v_add_f32_e32 v66, 1.0, v66
	v_rcp_f32_e32 v66, v66
	v_and_b32_e32 v73, 0xffff0000, v99
	v_add_f32_e32 v67, 1.0, v67
	v_rcp_f32_e32 v67, v67
	v_lshlrev_b32_e32 v72, 16, v99
	v_mul_f32_e32 v71, 0xbfb8aa3b, v71
	v_exp_f32_e32 v70, v70
	v_pk_mul_f32 v[72:73], v[66:67], v[72:73]
	v_add_f32_e32 v66, v69, v229
	v_mul_f32_e32 v66, 0xbfb8aa3b, v66
	v_exp_f32_e32 v71, v71
	v_exp_f32_e32 v66, v66
	v_add_f32_e32 v70, 1.0, v70
	v_rcp_f32_e32 v70, v70
	v_add_f32_e32 v71, 1.0, v71
	v_add_f32_e32 v66, 1.0, v66
	v_rcp_f32_e32 v71, v71
	v_rcp_f32_e32 v69, v66
	v_and_b32_e32 v81, 0xffff0000, v98
	v_lshlrev_b32_e32 v80, 16, v98
	v_and_b32_e32 v67, 0xffff0000, v101
	v_lshlrev_b32_e32 v66, 16, v101
	v_pk_mul_f32 v[70:71], v[70:71], v[80:81]
	v_pk_mul_f32 v[76:77], v[68:69], v[66:67]
	v_cvt_pk_bf16_f32 v66, v70, v71
	v_cvt_pk_bf16_f32 v67, v72, v73
	v_cvt_pk_bf16_f32 v68, v74, v75
	v_cvt_pk_bf16_f32 v69, v76, v77
	global_store_dwordx4 v[78:79], v[66:69], off offset:256
	s_nop 1
	v_lshl_add_u64 v[66:67], s[24:25], 0, v[88:89]
	v_lshl_add_u64 v[66:67], v[66:67], 0, v[176:177]
	global_load_dwordx4 v[78:81], v[66:67], off
	global_load_dwordx4 v[74:77], v[66:67], off offset:256
	v_lshl_add_u64 v[66:67], s[24:25], 0, v[86:87]
	v_lshl_add_u64 v[66:67], v[66:67], 0, v[176:177]
	global_load_dwordx4 v[70:73], v[66:67], off
	s_nop 0
	global_load_dwordx4 v[66:69], v[66:67], off offset:256
	s_nop 0
	s_waitcnt vmcnt(0)
; template <class Epi>
; DEVI void gemm_phase(LAS unsigned char* lds, const Gemm g, const Epi& E) {
;     ...
;                 for (int mm = 0; mm < 2; ++mm) {
;                     const int m = m0 + mm;
;                     const int r = row0 + ai * HALF + m * 16; float rs = 1.f, part = 0.f;
;                     if constexpr (Epi::RS) rs = rsv[ai * 4 + m];
;                     if constexpr (Epi::PAIR) E.pair8(cur.b, r, cur.pn * HALF + wc * 32 + 8 * fq, acc[ai][0][m][0] * rs, acc[ai][0][m][1] * rs, acc[ai][1][m][0] * rs, acc[ai][1][m][1] * rs);
;                     else
; #pragma unroll
;                     for (int bj = 0; bj < 2; ++bj) {
;                         const int c = col0 + bj * HALF; f32x4 v0 = acc[ai][bj][m][0], v1 = acc[ai][bj][m][1];
;                         if constexpr (Epi::RS) { v0 = v0 * rs; v1 = v1 * rs; }
;                         if constexpr (Epi::PRE) part += E.frag_pre8(cur.b, r, c, v0, v1, pre[mm][bj][0], pre[mm][bj][1]);
;                         else if constexpr (Epi::PERM) E.frag8(cur.b, r, c, v0, v1);
;                         else { E.frag(cur.b, r, c, v0); E.frag(cur.b, r, c + 16, v1); }
;                     }
	v_add_f32_e32 v58, v58, v218
	v_add_f32_e32 v59, v59, v219
	v_mul_f32_e32 v58, 0xbfb8aa3b, v58
	v_mul_f32_e32 v59, 0xbfb8aa3b, v59
	v_exp_f32_e32 v58, v58
	v_exp_f32_e32 v59, v59
	v_and_b32_e32 v83, 0xffff0000, v80
	v_lshlrev_b32_e32 v82, 16, v80
	v_add_f32_e32 v58, 1.0, v58
	v_add_f32_e32 v59, 1.0, v59
	v_rcp_f32_e32 v58, v58
	v_rcp_f32_e32 v59, v59
	v_add_f32_e32 v62, v62, v214
	v_add_f32_e32 v63, v63, v215
	v_mul_f32_e32 v62, 0xbfb8aa3b, v62
	v_pk_mul_f32 v[82:83], v[58:59], v[82:83]
	v_add_f32_e32 v59, v60, v220
	v_mul_f32_e32 v59, 0xbfb8aa3b, v59
	v_exp_f32_e32 v59, v59
	v_add_f32_e32 v58, v64, v216
	v_mul_f32_e32 v58, 0xbfb8aa3b, v58
	v_exp_f32_e32 v58, v58
	v_add_f32_e32 v59, 1.0, v59
	v_rcp_f32_e32 v60, v59
	v_add_f32_e32 v59, v65, v217
	v_mul_f32_e32 v59, 0xbfb8aa3b, v59
	v_exp_f32_e32 v59, v59
	v_add_f32_e32 v58, 1.0, v58
	v_rcp_f32_e32 v58, v58
	v_and_b32_e32 v65, 0xffff0000, v79
	v_add_f32_e32 v59, 1.0, v59
	v_rcp_f32_e32 v59, v59
	v_lshlrev_b32_e32 v64, 16, v79
	v_mul_f32_e32 v63, 0xbfb8aa3b, v63
	v_exp_f32_e32 v62, v62
	v_pk_mul_f32 v[64:65], v[58:59], v[64:65]
	v_add_f32_e32 v58, v61, v221
	v_exp_f32_e32 v63, v63
	v_mul_f32_e32 v58, 0xbfb8aa3b, v58
	v_exp_f32_e32 v58, v58
	v_add_f32_e32 v62, 1.0, v62
	v_add_f32_e32 v63, 1.0, v63
	v_rcp_f32_e32 v62, v62
	v_rcp_f32_e32 v63, v63
	v_add_f32_e32 v58, 1.0, v58
	v_rcp_f32_e32 v61, v58
	v_and_b32_e32 v91, 0xffff0000, v78
	v_lshlrev_b32_e32 v90, 16, v78
	v_pk_mul_f32 v[62:63], v[62:63], v[90:91]
	v_and_b32_e32 v59, 0xffff0000, v81
	v_lshlrev_b32_e32 v58, 16, v81
	v_pk_mul_f32 v[78:79], v[60:61], v[58:59]
	v_cvt_pk_bf16_f32 v58, v62, v63
	v_lshl_add_u64 v[62:63], s[64:65], 0, v[88:89]
	v_cvt_pk_bf16_f32 v59, v64, v65
	v_cvt_pk_bf16_f32 v60, v82, v83
	v_cvt_pk_bf16_f32 v61, v78, v79
	v_lshl_add_u64 v[62:63], v[62:63], 0, v[176:177]
	global_store_dwordx4 v[62:63], v[58:61], off
	s_nop 0
	v_and_b32_e32 v65, 0xffff0000, v74
	v_lshlrev_b32_e32 v64, 16, v74
	v_add_f32_e32 v50, v50, v226
	v_add_f32_e32 v51, v51, v227
	v_mul_f32_e32 v50, 0xbfb8aa3b, v50
	v_mul_f32_e32 v51, 0xbfb8aa3b, v51
	v_add_f32_e32 v56, v56, v224
	v_add_f32_e32 v57, v57, v225
	v_add_f32_e32 v54, v54, v222
	v_exp_f32_e32 v50, v50
	v_add_f32_e32 v55, v55, v223
	v_exp_f32_e32 v51, v51
	v_mul_f32_e32 v56, 0xbfb8aa3b, v56
	v_add_f32_e32 v52, v52, v228
	v_mul_f32_e32 v57, 0xbfb8aa3b, v57
	v_add_f32_e32 v53, v53, v229
	v_mul_f32_e32 v54, 0xbfb8aa3b, v54
	v_mul_f32_e32 v55, 0xbfb8aa3b, v55
	v_exp_f32_e32 v56, v56
	v_mul_f32_e32 v52, 0xbfb8aa3b, v52
	v_exp_f32_e32 v57, v57
	v_mul_f32_e32 v53, 0xbfb8aa3b, v53
	v_exp_f32_e32 v54, v54
	v_exp_f32_e32 v55, v55
	v_exp_f32_e32 v52, v52
	v_exp_f32_e32 v53, v53
	v_add_f32_e32 v50, 1.0, v50
	v_add_f32_e32 v51, 1.0, v51
	v_rcp_f32_e32 v50, v50
	v_rcp_f32_e32 v51, v51
	v_add_f32_e32 v56, 1.0, v56
	v_add_f32_e32 v57, 1.0, v57
	v_add_f32_e32 v54, 1.0, v54
	v_add_f32_e32 v55, 1.0, v55
	v_rcp_f32_e32 v56, v56
	v_add_f32_e32 v52, 1.0, v52
	v_rcp_f32_e32 v57, v57
	v_add_f32_e32 v53, 1.0, v53
	v_rcp_f32_e32 v54, v54
	v_rcp_f32_e32 v55, v55
	v_rcp_f32_e32 v52, v52
	v_rcp_f32_e32 v53, v53
	v_and_b32_e32 v59, 0xffff0000, v76
	v_lshlrev_b32_e32 v58, 16, v76
	v_pk_mul_f32 v[50:51], v[50:51], v[58:59]
	v_and_b32_e32 v59, 0xffff0000, v75
	v_lshlrev_b32_e32 v58, 16, v75
	v_pk_mul_f32 v[56:57], v[56:57], v[58:59]
	v_and_b32_e32 v59, 0xffff0000, v77
	v_lshlrev_b32_e32 v58, 16, v77
	v_pk_mul_f32 v[54:55], v[54:55], v[64:65]
	v_pk_mul_f32 v[58:59], v[52:53], v[58:59]
	v_cvt_pk_bf16_f32 v52, v54, v55
	v_cvt_pk_bf16_f32 v53, v56, v57
	v_cvt_pk_bf16_f32 v54, v50, v51
	v_cvt_pk_bf16_f32 v55, v58, v59
	global_store_dwordx4 v[62:63], v[52:55], off offset:256
	s_nop 0
	v_add_f32_e32 v42, v42, v218
	v_add_f32_e32 v43, v43, v219
	v_mul_f32_e32 v42, 0xbfb8aa3b, v42
	v_mul_f32_e32 v43, 0xbfb8aa3b, v43
	v_exp_f32_e32 v42, v42
	v_exp_f32_e32 v43, v43
	v_and_b32_e32 v51, 0xffff0000, v72
	v_lshlrev_b32_e32 v50, 16, v72
	v_add_f32_e32 v42, 1.0, v42
	v_add_f32_e32 v43, 1.0, v43
	v_rcp_f32_e32 v42, v42
	v_rcp_f32_e32 v43, v43
	v_add_f32_e32 v46, v46, v214
	v_add_f32_e32 v47, v47, v215
	v_mul_f32_e32 v46, 0xbfb8aa3b, v46
	v_pk_mul_f32 v[50:51], v[42:43], v[50:51]
	v_add_f32_e32 v43, v44, v220
	v_mul_f32_e32 v43, 0xbfb8aa3b, v43
	v_exp_f32_e32 v43, v43
	v_add_f32_e32 v42, v48, v216
	v_mul_f32_e32 v42, 0xbfb8aa3b, v42
	v_exp_f32_e32 v42, v42
	v_add_f32_e32 v43, 1.0, v43
	v_rcp_f32_e32 v44, v43
	v_add_f32_e32 v43, v49, v217
	v_mul_f32_e32 v43, 0xbfb8aa3b, v43
	v_exp_f32_e32 v43, v43
	v_add_f32_e32 v42, 1.0, v42
	v_rcp_f32_e32 v42, v42
	v_and_b32_e32 v49, 0xffff0000, v71
	v_add_f32_e32 v43, 1.0, v43
	v_rcp_f32_e32 v43, v43
	v_lshlrev_b32_e32 v48, 16, v71
	v_mul_f32_e32 v47, 0xbfb8aa3b, v47
	v_exp_f32_e32 v46, v46
	v_pk_mul_f32 v[48:49], v[42:43], v[48:49]
	v_add_f32_e32 v42, v45, v221
	v_exp_f32_e32 v47, v47
	v_mul_f32_e32 v42, 0xbfb8aa3b, v42
	v_exp_f32_e32 v42, v42
	v_add_f32_e32 v46, 1.0, v46
	v_add_f32_e32 v47, 1.0, v47
	v_rcp_f32_e32 v46, v46
	v_rcp_f32_e32 v47, v47
	v_add_f32_e32 v42, 1.0, v42
	v_rcp_f32_e32 v45, v42
	v_and_b32_e32 v55, 0xffff0000, v70
	v_lshlrev_b32_e32 v54, 16, v70
	v_pk_mul_f32 v[46:47], v[46:47], v[54:55]
	v_and_b32_e32 v43, 0xffff0000, v73
	v_lshlrev_b32_e32 v42, 16, v73
	v_pk_mul_f32 v[52:53], v[44:45], v[42:43]
	v_cvt_pk_bf16_f32 v42, v46, v47
	v_lshl_add_u64 v[46:47], s[64:65], 0, v[86:87]
	v_cvt_pk_bf16_f32 v43, v48, v49
	v_cvt_pk_bf16_f32 v44, v50, v51
	v_cvt_pk_bf16_f32 v45, v52, v53
	v_lshl_add_u64 v[46:47], v[46:47], 0, v[176:177]
	global_store_dwordx4 v[46:47], v[42:45], off
	s_nop 0
	v_lshl_add_u64 v[56:57], v[178:179], 0, s[0:1]
	s_mov_b64 s[0:1], 0x58000
	v_lshl_add_u64 v[54:55], v[178:179], 0, s[0:1]
;     DEVI f32x4 load(int r, int c) const { const bf16x4 y = *(const bf16x4*)(Y + (size_t)r * DM + c); return (f32x4){bf2f((u16)y[0]), bf2f((u16)y[1]), bf2f((u16)y[2]), bf2f((u16)y[3])}; }
; template <class Epi>
; DEVI void gemm_phase(LAS unsigned char* lds, const Gemm g, const Epi& E) {
;     ...
;                 if constexpr (Epi::PRE) {
; #pragma unroll
;                     for (int m = 0; m < 2; ++m)
; #pragma unroll
;                         for (int bj = 0; bj < 2; ++bj)
; #pragma unroll
;                             for (int n = 0; n < 2; ++n) pre[m][bj][n] = E.load(row0 + ai * HALF + (m0 + m) * 16, col0 + bj * HALF + n * NST);
	s_mov_b32 s0, s4
	v_add_f32_e32 v34, v34, v226
	v_add_f32_e32 v35, v35, v227
	v_mul_f32_e32 v34, 0xbfb8aa3b, v34
	v_mul_f32_e32 v35, 0xbfb8aa3b, v35
	v_exp_f32_e32 v34, v34
	v_exp_f32_e32 v35, v35
	v_and_b32_e32 v43, 0xffff0000, v68
	v_lshlrev_b32_e32 v42, 16, v68
	v_add_f32_e32 v34, 1.0, v34
	v_add_f32_e32 v35, 1.0, v35
	v_rcp_f32_e32 v34, v34
	v_rcp_f32_e32 v35, v35
	v_add_f32_e32 v38, v38, v222
	v_add_f32_e32 v39, v39, v223
	v_mul_f32_e32 v38, 0xbfb8aa3b, v38
	v_pk_mul_f32 v[42:43], v[34:35], v[42:43]
	v_add_f32_e32 v35, v36, v228
	v_mul_f32_e32 v35, 0xbfb8aa3b, v35
	v_exp_f32_e32 v35, v35
	v_add_f32_e32 v34, v40, v224
	v_mul_f32_e32 v34, 0xbfb8aa3b, v34
	v_exp_f32_e32 v34, v34
	v_add_f32_e32 v35, 1.0, v35
	v_rcp_f32_e32 v36, v35
	v_add_f32_e32 v35, v41, v225
	v_mul_f32_e32 v35, 0xbfb8aa3b, v35
	v_exp_f32_e32 v35, v35
	v_add_f32_e32 v34, 1.0, v34
	v_rcp_f32_e32 v34, v34
	v_and_b32_e32 v41, 0xffff0000, v67
	v_add_f32_e32 v35, 1.0, v35
	v_rcp_f32_e32 v35, v35
	v_lshlrev_b32_e32 v40, 16, v67
	v_mul_f32_e32 v39, 0xbfb8aa3b, v39
	v_exp_f32_e32 v38, v38
	v_pk_mul_f32 v[40:41], v[34:35], v[40:41]
	v_add_f32_e32 v34, v37, v229
	v_mul_f32_e32 v34, 0xbfb8aa3b, v34
	v_exp_f32_e32 v39, v39
	v_exp_f32_e32 v34, v34
	v_add_f32_e32 v38, 1.0, v38
	v_rcp_f32_e32 v38, v38
	v_add_f32_e32 v39, 1.0, v39
	v_add_f32_e32 v34, 1.0, v34
	v_rcp_f32_e32 v39, v39
	v_rcp_f32_e32 v37, v34
	v_and_b32_e32 v49, 0xffff0000, v66
	v_lshlrev_b32_e32 v48, 16, v66
	v_and_b32_e32 v35, 0xffff0000, v69
	v_lshlrev_b32_e32 v34, 16, v69
	v_pk_mul_f32 v[38:39], v[38:39], v[48:49]
	v_pk_mul_f32 v[44:45], v[36:37], v[34:35]
	v_cvt_pk_bf16_f32 v34, v38, v39
	v_cvt_pk_bf16_f32 v35, v40, v41
	v_cvt_pk_bf16_f32 v36, v42, v43
	v_cvt_pk_bf16_f32 v37, v44, v45
	global_store_dwordx4 v[46:47], v[34:37], off offset:256
	s_nop 1
	v_lshl_add_u64 v[34:35], s[24:25], 0, v[56:57]
	v_lshl_add_u64 v[34:35], v[34:35], 0, v[176:177]
	global_load_dwordx4 v[46:49], v[34:35], off
	global_load_dwordx4 v[42:45], v[34:35], off offset:256
	v_lshl_add_u64 v[34:35], s[24:25], 0, v[54:55]
	v_lshl_add_u64 v[34:35], v[34:35], 0, v[176:177]
	global_load_dwordx4 v[38:41], v[34:35], off
	s_nop 0
	global_load_dwordx4 v[34:37], v[34:35], off offset:256
	s_nop 0
	s_waitcnt vmcnt(0)
	v_add_f32_e32 v26, v26, v218
	v_add_f32_e32 v27, v27, v219
	v_mul_f32_e32 v26, 0xbfb8aa3b, v26
	v_mul_f32_e32 v27, 0xbfb8aa3b, v27
	v_exp_f32_e32 v26, v26
	v_exp_f32_e32 v27, v27
	v_and_b32_e32 v51, 0xffff0000, v48
	v_lshlrev_b32_e32 v50, 16, v48
	v_add_f32_e32 v26, 1.0, v26
	v_add_f32_e32 v27, 1.0, v27
	v_rcp_f32_e32 v26, v26
	v_rcp_f32_e32 v27, v27
	v_add_f32_e32 v30, v30, v214
	v_add_f32_e32 v31, v31, v215
	v_mul_f32_e32 v30, 0xbfb8aa3b, v30
	v_pk_mul_f32 v[50:51], v[26:27], v[50:51]
	v_add_f32_e32 v27, v28, v220
	v_mul_f32_e32 v27, 0xbfb8aa3b, v27
	v_exp_f32_e32 v27, v27
	v_add_f32_e32 v26, v32, v216
	v_mul_f32_e32 v26, 0xbfb8aa3b, v26
	v_exp_f32_e32 v26, v26
	v_add_f32_e32 v27, 1.0, v27
	v_rcp_f32_e32 v28, v27
	v_add_f32_e32 v27, v33, v217
	v_mul_f32_e32 v27, 0xbfb8aa3b, v27
	v_exp_f32_e32 v27, v27
	v_add_f32_e32 v26, 1.0, v26
	v_rcp_f32_e32 v26, v26
	v_and_b32_e32 v33, 0xffff0000, v47
	v_add_f32_e32 v27, 1.0, v27
	v_rcp_f32_e32 v27, v27
	v_lshlrev_b32_e32 v32, 16, v47
	v_mul_f32_e32 v31, 0xbfb8aa3b, v31
	v_exp_f32_e32 v30, v30
	v_pk_mul_f32 v[32:33], v[26:27], v[32:33]
	v_add_f32_e32 v26, v29, v221
	v_exp_f32_e32 v31, v31
	v_mul_f32_e32 v26, 0xbfb8aa3b, v26
	v_exp_f32_e32 v26, v26
	v_add_f32_e32 v30, 1.0, v30
	v_add_f32_e32 v31, 1.0, v31
	v_rcp_f32_e32 v30, v30
	v_rcp_f32_e32 v31, v31
	v_add_f32_e32 v26, 1.0, v26
	v_rcp_f32_e32 v29, v26
	v_and_b32_e32 v59, 0xffff0000, v46
	v_lshlrev_b32_e32 v58, 16, v46
	v_pk_mul_f32 v[30:31], v[30:31], v[58:59]
	v_and_b32_e32 v27, 0xffff0000, v49
	v_lshlrev_b32_e32 v26, 16, v49
	v_pk_mul_f32 v[46:47], v[28:29], v[26:27]
	v_cvt_pk_bf16_f32 v26, v30, v31
	v_lshl_add_u64 v[30:31], s[64:65], 0, v[56:57]
	v_cvt_pk_bf16_f32 v27, v32, v33
	v_cvt_pk_bf16_f32 v28, v50, v51
	v_cvt_pk_bf16_f32 v29, v46, v47
	v_lshl_add_u64 v[30:31], v[30:31], 0, v[176:177]
	global_store_dwordx4 v[30:31], v[26:29], off
	s_nop 0
	v_and_b32_e32 v33, 0xffff0000, v42
	v_lshlrev_b32_e32 v32, 16, v42
	v_add_f32_e32 v18, v18, v226
	v_add_f32_e32 v19, v19, v227
	v_mul_f32_e32 v18, 0xbfb8aa3b, v18
	v_mul_f32_e32 v19, 0xbfb8aa3b, v19
	v_add_f32_e32 v24, v24, v224
	v_add_f32_e32 v25, v25, v225
	v_add_f32_e32 v22, v22, v222
	v_exp_f32_e32 v18, v18
	v_add_f32_e32 v23, v23, v223
	v_exp_f32_e32 v19, v19
	v_mul_f32_e32 v24, 0xbfb8aa3b, v24
	v_add_f32_e32 v20, v20, v228
	v_mul_f32_e32 v25, 0xbfb8aa3b, v25
	v_add_f32_e32 v21, v21, v229
	v_mul_f32_e32 v22, 0xbfb8aa3b, v22
	v_mul_f32_e32 v23, 0xbfb8aa3b, v23
	v_exp_f32_e32 v24, v24
	v_mul_f32_e32 v20, 0xbfb8aa3b, v20
	v_exp_f32_e32 v25, v25
; #define PG8_WAIT_V(n) asm volatile("s_waitcnt vmcnt(" #n ")" ::: "memory")
; #define PG8_BAR __builtin_amdgcn_s_barrier()
; template <class Epi>
; DEVI void gemm_phase(LAS unsigned char* lds, const Gemm g, const Epi& E) {
;     ...
;         if (!has_next) break;
; #pragma unroll
;         for (int a = 0; a < 2; ++a)
; #pragma unroll
;             for (int b = 0; b < 2; ++b)
; #pragma unroll
;                 for (int m = 0; m < 4; ++m)
; #pragma unroll
;                     for (int n = 0; n < 2; ++n) acc[a][b][m][n] = (f32x4){0.f, 0.f, 0.f, 0.f};
;         cur = nxt; cA = nA; cB = nB; ++ui;
;     }
;     PG8_WAIT_V(0);
;     if (wr == 0) PG8_BAR;
;     PG8_BAR;
	v_mul_f32_e32 v21, 0xbfb8aa3b, v21
	v_exp_f32_e32 v22, v22
	v_exp_f32_e32 v23, v23
	v_exp_f32_e32 v20, v20
	v_exp_f32_e32 v21, v21
	v_add_f32_e32 v18, 1.0, v18
	v_add_f32_e32 v19, 1.0, v19
	v_rcp_f32_e32 v18, v18
	v_rcp_f32_e32 v19, v19
	v_add_f32_e32 v24, 1.0, v24
	v_add_f32_e32 v25, 1.0, v25
	v_add_f32_e32 v22, 1.0, v22
	v_add_f32_e32 v23, 1.0, v23
	v_rcp_f32_e32 v24, v24
	v_add_f32_e32 v20, 1.0, v20
	v_rcp_f32_e32 v25, v25
	v_add_f32_e32 v21, 1.0, v21
	v_rcp_f32_e32 v22, v22
	v_rcp_f32_e32 v23, v23
	v_rcp_f32_e32 v20, v20
	v_rcp_f32_e32 v21, v21
	v_and_b32_e32 v27, 0xffff0000, v44
	v_lshlrev_b32_e32 v26, 16, v44
	v_pk_mul_f32 v[18:19], v[18:19], v[26:27]
	v_and_b32_e32 v27, 0xffff0000, v43
	v_lshlrev_b32_e32 v26, 16, v43
	v_pk_mul_f32 v[24:25], v[24:25], v[26:27]
	v_and_b32_e32 v27, 0xffff0000, v45
	v_lshlrev_b32_e32 v26, 16, v45
	v_pk_mul_f32 v[22:23], v[22:23], v[32:33]
	v_pk_mul_f32 v[26:27], v[20:21], v[26:27]
	v_cvt_pk_bf16_f32 v20, v22, v23
	v_cvt_pk_bf16_f32 v21, v24, v25
	v_cvt_pk_bf16_f32 v22, v18, v19
	v_cvt_pk_bf16_f32 v23, v26, v27
	global_store_dwordx4 v[30:31], v[20:23], off offset:256
	s_nop 0
	v_add_f32_e32 v10, v10, v218
	v_add_f32_e32 v11, v11, v219
	v_mul_f32_e32 v10, 0xbfb8aa3b, v10
	v_mul_f32_e32 v11, 0xbfb8aa3b, v11
	v_exp_f32_e32 v10, v10
	v_exp_f32_e32 v11, v11
	v_and_b32_e32 v19, 0xffff0000, v40
	v_lshlrev_b32_e32 v18, 16, v40
	v_add_f32_e32 v10, 1.0, v10
	v_add_f32_e32 v11, 1.0, v11
	v_rcp_f32_e32 v10, v10
	v_rcp_f32_e32 v11, v11
	v_add_f32_e32 v14, v14, v214
	v_add_f32_e32 v15, v15, v215
	v_mul_f32_e32 v14, 0xbfb8aa3b, v14
	v_pk_mul_f32 v[18:19], v[10:11], v[18:19]
	v_add_f32_e32 v11, v12, v220
	v_mul_f32_e32 v11, 0xbfb8aa3b, v11
	v_exp_f32_e32 v11, v11
	v_add_f32_e32 v10, v16, v216
	v_mul_f32_e32 v10, 0xbfb8aa3b, v10
	v_exp_f32_e32 v10, v10
	v_add_f32_e32 v11, 1.0, v11
	v_rcp_f32_e32 v12, v11
	v_add_f32_e32 v11, v17, v217
	v_mul_f32_e32 v11, 0xbfb8aa3b, v11
	v_exp_f32_e32 v11, v11
	v_add_f32_e32 v10, 1.0, v10
	v_rcp_f32_e32 v10, v10
	v_and_b32_e32 v17, 0xffff0000, v39
	v_add_f32_e32 v11, 1.0, v11
	v_rcp_f32_e32 v11, v11
	v_lshlrev_b32_e32 v16, 16, v39
	v_mul_f32_e32 v15, 0xbfb8aa3b, v15
	v_exp_f32_e32 v14, v14
	v_pk_mul_f32 v[16:17], v[10:11], v[16:17]
	v_add_f32_e32 v10, v13, v221
	v_exp_f32_e32 v15, v15
	v_mul_f32_e32 v10, 0xbfb8aa3b, v10
	v_exp_f32_e32 v10, v10
	v_add_f32_e32 v14, 1.0, v14
	v_add_f32_e32 v15, 1.0, v15
	v_rcp_f32_e32 v14, v14
	v_rcp_f32_e32 v15, v15
	v_add_f32_e32 v10, 1.0, v10
	v_rcp_f32_e32 v13, v10
	v_and_b32_e32 v23, 0xffff0000, v38
	v_lshlrev_b32_e32 v22, 16, v38
	v_pk_mul_f32 v[14:15], v[14:15], v[22:23]
	v_and_b32_e32 v11, 0xffff0000, v41
	v_lshlrev_b32_e32 v10, 16, v41
	v_pk_mul_f32 v[20:21], v[12:13], v[10:11]
	v_cvt_pk_bf16_f32 v10, v14, v15
	v_lshl_add_u64 v[14:15], s[64:65], 0, v[54:55]
	v_cvt_pk_bf16_f32 v11, v16, v17
	v_cvt_pk_bf16_f32 v12, v18, v19
	v_cvt_pk_bf16_f32 v13, v20, v21
	v_lshl_add_u64 v[14:15], v[14:15], 0, v[176:177]
	global_store_dwordx4 v[14:15], v[10:13], off
	s_nop 0
	v_add_f32_e32 v0, v0, v226
	v_add_f32_e32 v1, v1, v227
	v_mul_f32_e32 v0, 0xbfb8aa3b, v0
	v_mul_f32_e32 v1, 0xbfb8aa3b, v1
	v_exp_f32_e32 v0, v0
	v_exp_f32_e32 v1, v1
	v_and_b32_e32 v11, 0xffff0000, v36
	v_lshlrev_b32_e32 v10, 16, v36
	v_add_f32_e32 v0, 1.0, v0
	v_add_f32_e32 v1, 1.0, v1
	v_rcp_f32_e32 v0, v0
	v_rcp_f32_e32 v1, v1
	v_add_f32_e32 v4, v4, v222
	v_add_f32_e32 v5, v5, v223
	v_mul_f32_e32 v4, 0xbfb8aa3b, v4
	v_pk_mul_f32 v[10:11], v[0:1], v[10:11]
	v_add_f32_e32 v1, v2, v228
	v_mul_f32_e32 v1, 0xbfb8aa3b, v1
	v_exp_f32_e32 v1, v1
	v_add_f32_e32 v0, v6, v224
	v_mul_f32_e32 v0, 0xbfb8aa3b, v0
	v_exp_f32_e32 v0, v0
	v_add_f32_e32 v1, 1.0, v1
	v_rcp_f32_e32 v2, v1
	v_add_f32_e32 v1, v7, v225
	v_mul_f32_e32 v1, 0xbfb8aa3b, v1
	v_exp_f32_e32 v1, v1
	v_add_f32_e32 v0, 1.0, v0
	v_rcp_f32_e32 v0, v0
	v_and_b32_e32 v7, 0xffff0000, v35
	v_add_f32_e32 v1, 1.0, v1
	v_rcp_f32_e32 v1, v1
	v_lshlrev_b32_e32 v6, 16, v35
	v_mul_f32_e32 v5, 0xbfb8aa3b, v5
	v_exp_f32_e32 v4, v4
	v_pk_mul_f32 v[6:7], v[0:1], v[6:7]
	v_add_f32_e32 v0, v3, v229
	v_mul_f32_e32 v0, 0xbfb8aa3b, v0
	v_exp_f32_e32 v5, v5
	v_exp_f32_e32 v0, v0
	v_add_f32_e32 v4, 1.0, v4
	v_rcp_f32_e32 v4, v4
	v_add_f32_e32 v5, 1.0, v5
	v_add_f32_e32 v0, 1.0, v0
	v_rcp_f32_e32 v5, v5
	v_rcp_f32_e32 v3, v0
	v_and_b32_e32 v17, 0xffff0000, v34
	v_lshlrev_b32_e32 v16, 16, v34
	v_and_b32_e32 v1, 0xffff0000, v37
	v_lshlrev_b32_e32 v0, 16, v37
	v_pk_mul_f32 v[4:5], v[4:5], v[16:17]
	v_pk_mul_f32 v[12:13], v[2:3], v[0:1]
	v_cvt_pk_bf16_f32 v0, v4, v5
	v_cvt_pk_bf16_f32 v1, v6, v7
	v_cvt_pk_bf16_f32 v2, v10, v11
	v_cvt_pk_bf16_f32 v3, v12, v13
	global_store_dwordx4 v[14:15], v[0:3], off offset:256
	s_cbranch_vccz .LBB0_1339
	s_waitcnt vmcnt(0)
	s_cmpk_gt_u32 s46, 0xff
	s_cbranch_scc1 .LBB0_1350
	s_barrier

; #define PG8_STAGE(bufoff, gbase, voff) do { _Pragma("unroll") for (int _i = 0; _i < 2; ++_i) \
;         __builtin_amdgcn_global_load_lds((const unsigned*)((const char*)(gbase) + (voff)[_i]), (LAS unsigned*)(lds + (bufoff) + ldsw + _i * 8192), 16, 0, 0); } while (0)
; #define PG8_LDA(dst, b, h) do { _Pragma("unroll") for (int m = 0; m < 4; ++m) _Pragma("unroll") for (int k = 0; k < 2; ++k) dst[m][k] = *(const LAS bf16x8*)(lds + PG8_SA(b, h) + aoff + m * 2048 + k * 1024); } while (0)
; #define PG8_LDB(dst, b, h) do { _Pragma("unroll") for (int n = 0; n < 2; ++n) _Pragma("unroll") for (int k = 0; k < 2; ++k) dst[n][k] = *(const LAS bf16x8*)(lds + PG8_SB(b, h) + boff + n * 2048 + k * 1024); } while (0)
; #define PG8_MMA(ai, bj, At, Bt) do { __builtin_amdgcn_s_setprio(1); _Pragma("unroll") for (int m = 0; m < 4; ++m) _Pragma("unroll") for (int n = 0; n < 2; ++n) _Pragma("unroll") for (int k = 0; k < 2; ++k) \
;         acc[ai][bj][m][n] = __builtin_amdgcn_mfma_f32_16x16x32_bf16(Bt[n][k], At[m][k], acc[ai][bj][m][n], 0, 0, 0); __builtin_amdgcn_s_setprio(0); } while (0)
; #define PG8_WAIT_L(n) asm volatile("s_waitcnt lgkmcnt(" #n ")" ::: "memory")
; #define PG8_BAR __builtin_amdgcn_s_barrier()
; #define PG8_SCHED __builtin_amdgcn_sched_barrier(0)
; template <class Epi>
; DEVI void gemm_phase(LAS unsigned char* lds, const Gemm g, const Epi& E) {
;     ...
;             const char* a1 = cA + (size_t)(t + 1) * kstep;
;             const char* a2 = last ? nA : cA + (size_t)(t + 2) * kstep; const char* b2 = last ? nB : cB + (size_t)(t + 2) * kstep;
;             const char* a3 = a2 + kstep; const char* b3 = b2 + kstep;
;             PG8_LDB(B0, 0, 0); PG8_SCHED; PG8_LDA(At, 0, 0); PG8_STAGE(PG8_SA(1, 1), a1 + hstepA, voffA);
;             PG8_WAIT_L(8); PG8_BAR; PG8_WAIT_L(0); PG8_MMA(0, 0, At, B0); PG8_BAR; PG8_SCHED;
;             PG8_LDB(B1, 0, 1); PG8_STAGE(PG8_SB(0, 0), b2, voffB);
;             PG8_BAR; PG8_WAIT_L(0); PG8_MMA(0, 1, At, B1); PG8_BAR;
;             PG8_LDA(At, 0, 1); PG8_STAGE(PG8_SA(0, 0), a2, voffA);
;             PG8_BAR; PG8_WAIT_L(0); PG8_MMA(1, 0, At, B0); PG8_BAR; PG8_SCHED;
.LBB0_1507:
	s_add_u32 s19, s6, 0xfffc0080
	s_addc_u32 s26, s7, -1
	s_add_i32 s27, 0, 0x10000
	v_add_u32_e32 v142, s27, v199
	ds_read_b128 v[130:133], v142
	ds_read_b128 v[134:137], v142 offset:1024
	ds_read_b128 v[138:141], v142 offset:2048
	ds_read_b128 v[142:145], v142 offset:3072
	s_cmp_eq_u32 s18, 12
	s_cselect_b32 s79, s0, s26
	s_cselect_b32 s78, s1, s19
	s_cselect_b32 s69, s15, s13
	s_cselect_b32 s68, s14, s11
	v_lshl_add_u64 v[162:163], s[6:7], 0, v[182:183]
	s_add_i32 m0, s37, 0xc000
	ds_read_b128 v[146:149], v202
	ds_read_b128 v[150:153], v202 offset:1024
	ds_read_b128 v[186:189], v202 offset:2048
	ds_read_b128 v[190:193], v202 offset:3072
	ds_read_b128 v[194:197], v202 offset:4096
	ds_read_b128 v[204:207], v202 offset:5120
	ds_read_b128 v[214:217], v202 offset:6144
	ds_read_b128 v[218:221], v202 offset:7168
	global_load_lds_dwordx4 v[162:163], off
	s_add_i32 m0, s37, 0xe000
	v_lshl_add_u64 v[162:163], s[6:7], 0, v[184:185]
	global_load_lds_dwordx4 v[162:163], off
	s_waitcnt lgkmcnt(8)
	s_barrier
	s_waitcnt lgkmcnt(0)
	v_mfma_f32_16x16x32_bf16 v[126:129], v[130:133], v[146:149], v[126:129]
	v_mfma_f32_16x16x32_bf16 v[122:125], v[138:141], v[146:149], v[122:125]
	v_mfma_f32_16x16x32_bf16 v[110:113], v[130:133], v[186:189], v[110:113]
	v_mfma_f32_16x16x32_bf16 v[106:109], v[138:141], v[186:189], v[106:109]
	v_mfma_f32_16x16x32_bf16 v[94:97], v[130:133], v[194:197], v[94:97]
	v_mfma_f32_16x16x32_bf16 v[90:93], v[138:141], v[194:197], v[90:93]
	v_mfma_f32_16x16x32_bf16 v[78:81], v[130:133], v[214:217], v[78:81]
	v_mfma_f32_16x16x32_bf16 v[74:77], v[138:141], v[214:217], v[74:77]
	v_mfma_f32_16x16x32_bf16 v[126:129], v[134:137], v[150:153], v[126:129]
	v_mfma_f32_16x16x32_bf16 v[122:125], v[142:145], v[150:153], v[122:125]
	v_mfma_f32_16x16x32_bf16 v[110:113], v[134:137], v[190:193], v[110:113]
	v_mfma_f32_16x16x32_bf16 v[106:109], v[142:145], v[190:193], v[106:109]
	v_mfma_f32_16x16x32_bf16 v[94:97], v[134:137], v[204:207], v[94:97]
	v_mfma_f32_16x16x32_bf16 v[90:93], v[142:145], v[204:207], v[90:93]
	v_mfma_f32_16x16x32_bf16 v[78:81], v[134:137], v[218:221], v[78:81]
	v_mfma_f32_16x16x32_bf16 v[74:77], v[142:145], v[218:221], v[74:77]
	s_barrier
	s_add_i32 s19, 0, 0x14000
	v_add_u32_e32 v162, s19, v199
	s_add_i32 s26, s27, s80
	ds_read_b128 v[222:225], v162
	ds_read_b128 v[226:229], v162 offset:1024
	ds_read_b128 v[230:233], v162 offset:2048
	ds_read_b128 v[234:237], v162 offset:3072
	v_lshl_add_u64 v[162:163], s[68:69], 0, v[8:9]
	s_mov_b32 m0, s26
	v_lshl_add_u64 v[164:165], s[68:69], 0, v[180:181]
	global_load_lds_dwordx4 v[162:163], off
	s_add_i32 m0, s26, 0x2000
	s_nop 0
	global_load_lds_dwordx4 v[164:165], off
	s_barrier
	s_waitcnt lgkmcnt(0)
	v_mfma_f32_16x16x32_bf16 v[118:121], v[222:225], v[146:149], v[118:121]
	v_mfma_f32_16x16x32_bf16 v[114:117], v[230:233], v[146:149], v[114:117]
	v_mfma_f32_16x16x32_bf16 v[102:105], v[222:225], v[186:189], v[102:105]
	v_mfma_f32_16x16x32_bf16 v[98:101], v[230:233], v[186:189], v[98:101]
	v_mfma_f32_16x16x32_bf16 v[86:89], v[222:225], v[194:197], v[86:89]
	v_mfma_f32_16x16x32_bf16 v[82:85], v[230:233], v[194:197], v[82:85]
	v_mfma_f32_16x16x32_bf16 v[70:73], v[222:225], v[214:217], v[70:73]
	v_mfma_f32_16x16x32_bf16 v[62:65], v[230:233], v[214:217], v[62:65]
	v_mfma_f32_16x16x32_bf16 v[118:121], v[226:229], v[150:153], v[118:121]
	v_mfma_f32_16x16x32_bf16 v[114:117], v[234:237], v[150:153], v[114:117]
	v_mfma_f32_16x16x32_bf16 v[102:105], v[226:229], v[190:193], v[102:105]
	v_mfma_f32_16x16x32_bf16 v[98:101], v[234:237], v[190:193], v[98:101]
	v_mfma_f32_16x16x32_bf16 v[86:89], v[226:229], v[204:207], v[86:89]
	v_mfma_f32_16x16x32_bf16 v[82:85], v[234:237], v[204:207], v[82:85]
	v_mfma_f32_16x16x32_bf16 v[70:73], v[226:229], v[218:221], v[70:73]
	v_mfma_f32_16x16x32_bf16 v[62:65], v[234:237], v[218:221], v[62:65]
	s_mov_b32 m0, s37
	v_lshl_add_u64 v[208:209], s[78:79], 0, v[176:177]
	s_barrier
	ds_read_b128 v[146:149], v202 offset:16384
	ds_read_b128 v[150:153], v202 offset:17408
	ds_read_b128 v[186:189], v202 offset:18432
	ds_read_b128 v[190:193], v202 offset:19456
	ds_read_b128 v[194:197], v202 offset:20480
	ds_read_b128 v[204:207], v202 offset:21504
	ds_read_b128 v[214:217], v202 offset:22528
	ds_read_b128 v[218:221], v202 offset:23552
	global_load_lds_dwordx4 v[208:209], off
	s_mov_b32 m0, s47
	v_lshl_add_u64 v[238:239], s[78:79], 0, v[178:179]
	global_load_lds_dwordx4 v[238:239], off
	s_barrier
	s_waitcnt lgkmcnt(0)
	v_mfma_f32_16x16x32_bf16 v[66:69], v[130:133], v[146:149], v[66:69]
	v_mfma_f32_16x16x32_bf16 v[54:57], v[138:141], v[146:149], v[54:57]
	v_mfma_f32_16x16x32_bf16 v[46:49], v[130:133], v[186:189], v[46:49]
	v_mfma_f32_16x16x32_bf16 v[38:41], v[138:141], v[186:189], v[38:41]
	v_mfma_f32_16x16x32_bf16 v[30:33], v[130:133], v[194:197], v[30:33]
	v_mfma_f32_16x16x32_bf16 v[22:25], v[138:141], v[194:197], v[22:25]
	v_mfma_f32_16x16x32_bf16 v[14:17], v[130:133], v[214:217], v[14:17]
	v_mfma_f32_16x16x32_bf16 v[4:7], v[138:141], v[214:217], v[4:7]
	v_mfma_f32_16x16x32_bf16 v[66:69], v[134:137], v[150:153], v[66:69]
	v_mfma_f32_16x16x32_bf16 v[54:57], v[142:145], v[150:153], v[54:57]
	v_mfma_f32_16x16x32_bf16 v[46:49], v[134:137], v[190:193], v[46:49]
	v_mfma_f32_16x16x32_bf16 v[38:41], v[142:145], v[190:193], v[38:41]
	v_mfma_f32_16x16x32_bf16 v[30:33], v[134:137], v[204:207], v[30:33]
	v_mfma_f32_16x16x32_bf16 v[22:25], v[142:145], v[204:207], v[22:25]
	v_mfma_f32_16x16x32_bf16 v[14:17], v[134:137], v[218:221], v[14:17]
	v_mfma_f32_16x16x32_bf16 v[4:7], v[142:145], v[218:221], v[4:7]
	s_barrier
; #define PG8_STAGE(bufoff, gbase, voff) do { _Pragma("unroll") for (int _i = 0; _i < 2; ++_i) \
;         __builtin_amdgcn_global_load_lds((const unsigned*)((const char*)(gbase) + (voff)[_i]), (LAS unsigned*)(lds + (bufoff) + ldsw + _i * 8192), 16, 0, 0); } while (0)
; #define PG8_LDA(dst, b, h) do { _Pragma("unroll") for (int m = 0; m < 4; ++m) _Pragma("unroll") for (int k = 0; k < 2; ++k) dst[m][k] = *(const LAS bf16x8*)(lds + PG8_SA(b, h) + aoff + m * 2048 + k * 1024); } while (0)
; #define PG8_LDB(dst, b, h) do { _Pragma("unroll") for (int n = 0; n < 2; ++n) _Pragma("unroll") for (int k = 0; k < 2; ++k) dst[n][k] = *(const LAS bf16x8*)(lds + PG8_SB(b, h) + boff + n * 2048 + k * 1024); } while (0)
; #define PG8_MMA(ai, bj, At, Bt) do { __builtin_amdgcn_s_setprio(1); _Pragma("unroll") for (int m = 0; m < 4; ++m) _Pragma("unroll") for (int n = 0; n < 2; ++n) _Pragma("unroll") for (int k = 0; k < 2; ++k) \
;         acc[ai][bj][m][n] = __builtin_amdgcn_mfma_f32_16x16x32_bf16(Bt[n][k], At[m][k], acc[ai][bj][m][n], 0, 0, 0); __builtin_amdgcn_s_setprio(0); } while (0)
; #define PG8_WAIT_V(n) asm volatile("s_waitcnt vmcnt(" #n ")" ::: "memory")
; #define PG8_WAIT_L(n) asm volatile("s_waitcnt lgkmcnt(" #n ")" ::: "memory")
; #define PG8_BAR __builtin_amdgcn_s_barrier()
; #define PG8_SCHED __builtin_amdgcn_sched_barrier(0)
; template <class Epi>
; DEVI void gemm_phase(LAS unsigned char* lds, const Gemm g, const Epi& E) {
;     ...
;             PG8_STAGE(PG8_SB(0, 1), b2 + hstepB, voffB);
;             PG8_WAIT_V(6); PG8_BAR; PG8_MMA(1, 1, At, B1); PG8_BAR;
;             PG8_LDB(B0, 1, 0); PG8_SCHED; PG8_LDA(At, 1, 0); PG8_STAGE(PG8_SA(0, 1), a2 + hstepA, voffA);
;             PG8_WAIT_L(8); PG8_BAR; PG8_WAIT_L(0); PG8_MMA(0, 0, At, B0); PG8_BAR; PG8_SCHED;
;             PG8_LDB(B1, 1, 1); PG8_STAGE(PG8_SB(1, 0), b3, voffB);
;             PG8_BAR; PG8_WAIT_L(0); PG8_MMA(0, 1, At, B1); PG8_BAR;
;             PG8_LDA(At, 1, 1); PG8_STAGE(PG8_SA(1, 0), a3, voffA);
	s_add_u32 s26, s68, 0x40000
	s_addc_u32 s27, s69, 0
	s_add_i32 s19, s19, s80
	s_mov_b32 m0, s19
	v_lshl_add_u64 v[130:131], s[26:27], 0, v[8:9]
	global_load_lds_dwordx4 v[130:131], off
	s_add_i32 m0, s19, 0x2000
	v_lshl_add_u64 v[130:131], s[26:27], 0, v[180:181]
	global_load_lds_dwordx4 v[130:131], off
	s_waitcnt vmcnt(6)
	s_barrier
	v_mfma_f32_16x16x32_bf16 v[58:61], v[222:225], v[146:149], v[58:61]
	v_mfma_f32_16x16x32_bf16 v[50:53], v[230:233], v[146:149], v[50:53]
	v_mfma_f32_16x16x32_bf16 v[42:45], v[222:225], v[186:189], v[42:45]
	v_mfma_f32_16x16x32_bf16 v[34:37], v[230:233], v[186:189], v[34:37]
	v_mfma_f32_16x16x32_bf16 v[26:29], v[222:225], v[194:197], v[26:29]
	v_mfma_f32_16x16x32_bf16 v[18:21], v[230:233], v[194:197], v[18:21]
	v_mfma_f32_16x16x32_bf16 v[10:13], v[222:225], v[214:217], v[10:13]
	v_mfma_f32_16x16x32_bf16 v[0:3], v[230:233], v[214:217], v[0:3]
	v_mfma_f32_16x16x32_bf16 v[58:61], v[226:229], v[150:153], v[58:61]
	v_mfma_f32_16x16x32_bf16 v[50:53], v[234:237], v[150:153], v[50:53]
	v_mfma_f32_16x16x32_bf16 v[42:45], v[226:229], v[190:193], v[42:45]
	v_mfma_f32_16x16x32_bf16 v[34:37], v[234:237], v[190:193], v[34:37]
	v_mfma_f32_16x16x32_bf16 v[26:29], v[226:229], v[204:207], v[26:29]
	v_mfma_f32_16x16x32_bf16 v[18:21], v[234:237], v[204:207], v[18:21]
	v_mfma_f32_16x16x32_bf16 v[10:13], v[226:229], v[218:221], v[10:13]
	v_mfma_f32_16x16x32_bf16 v[0:3], v[234:237], v[218:221], v[0:3]
	s_add_i32 s19, 0, 0x18000
	v_add_u32_e32 v142, s19, v199
	s_barrier
	ds_read_b128 v[130:133], v142
	ds_read_b128 v[134:137], v142 offset:1024
	ds_read_b128 v[138:141], v142 offset:2048
	ds_read_b128 v[142:145], v142 offset:3072
	s_add_u32 s26, s78, 0x40000
	s_addc_u32 s27, s79, 0
	s_mov_b32 m0, s81
	v_lshl_add_u64 v[222:223], s[26:27], 0, v[176:177]
	ds_read_b128 v[146:149], v202 offset:32768
	ds_read_b128 v[150:153], v202 offset:33792
	ds_read_b128 v[186:189], v202 offset:34816
	ds_read_b128 v[190:193], v202 offset:35840
	ds_read_b128 v[194:197], v202 offset:36864
	ds_read_b128 v[204:207], v202 offset:37888
	ds_read_b128 v[214:217], v202 offset:38912
	ds_read_b128 v[218:221], v202 offset:39936
	global_load_lds_dwordx4 v[222:223], off
	s_mov_b32 m0, s82
	v_lshl_add_u64 v[222:223], s[26:27], 0, v[178:179]
	global_load_lds_dwordx4 v[222:223], off
	s_waitcnt lgkmcnt(8)
	s_barrier
	s_waitcnt lgkmcnt(0)
	v_mfma_f32_16x16x32_bf16 v[126:129], v[130:133], v[146:149], v[126:129]
	v_mfma_f32_16x16x32_bf16 v[122:125], v[138:141], v[146:149], v[122:125]
	v_mfma_f32_16x16x32_bf16 v[110:113], v[130:133], v[186:189], v[110:113]
	v_mfma_f32_16x16x32_bf16 v[106:109], v[138:141], v[186:189], v[106:109]
	v_mfma_f32_16x16x32_bf16 v[94:97], v[130:133], v[194:197], v[94:97]
	v_mfma_f32_16x16x32_bf16 v[90:93], v[138:141], v[194:197], v[90:93]
	v_mfma_f32_16x16x32_bf16 v[78:81], v[130:133], v[214:217], v[78:81]
	v_mfma_f32_16x16x32_bf16 v[74:77], v[138:141], v[214:217], v[74:77]
	v_mfma_f32_16x16x32_bf16 v[126:129], v[134:137], v[150:153], v[126:129]
	v_mfma_f32_16x16x32_bf16 v[122:125], v[142:145], v[150:153], v[122:125]
	v_mfma_f32_16x16x32_bf16 v[110:113], v[134:137], v[190:193], v[110:113]
	v_mfma_f32_16x16x32_bf16 v[106:109], v[142:145], v[190:193], v[106:109]
	v_mfma_f32_16x16x32_bf16 v[94:97], v[134:137], v[204:207], v[94:97]
	v_mfma_f32_16x16x32_bf16 v[90:93], v[142:145], v[204:207], v[90:93]
	v_mfma_f32_16x16x32_bf16 v[78:81], v[134:137], v[218:221], v[78:81]
	v_mfma_f32_16x16x32_bf16 v[74:77], v[142:145], v[218:221], v[74:77]
	s_barrier
	s_add_i32 s38, 0, 0x1c000
	s_add_i32 s19, s19, s80
	v_add_u32_e32 v213, s38, v199
	v_lshl_add_u64 v[162:163], v[162:163], 0, s[70:71]
	s_mov_b32 m0, s19
	ds_read_b128 v[222:225], v213
	ds_read_b128 v[226:229], v213 offset:1024
	ds_read_b128 v[230:233], v213 offset:2048
	ds_read_b128 v[234:237], v213 offset:3072
	global_load_lds_dwordx4 v[162:163], off
	s_add_i32 m0, s19, 0x2000
	v_lshl_add_u64 v[162:163], v[164:165], 0, s[70:71]
	global_load_lds_dwordx4 v[162:163], off
	s_barrier
	s_waitcnt lgkmcnt(0)
	v_mfma_f32_16x16x32_bf16 v[118:121], v[222:225], v[146:149], v[118:121]
	v_mfma_f32_16x16x32_bf16 v[114:117], v[230:233], v[146:149], v[114:117]
	v_mfma_f32_16x16x32_bf16 v[102:105], v[222:225], v[186:189], v[102:105]
	v_mfma_f32_16x16x32_bf16 v[98:101], v[230:233], v[186:189], v[98:101]
	v_mfma_f32_16x16x32_bf16 v[86:89], v[222:225], v[194:197], v[86:89]
	v_mfma_f32_16x16x32_bf16 v[82:85], v[230:233], v[194:197], v[82:85]
	v_mfma_f32_16x16x32_bf16 v[70:73], v[222:225], v[214:217], v[70:73]
	v_mfma_f32_16x16x32_bf16 v[62:65], v[230:233], v[214:217], v[62:65]
	v_mfma_f32_16x16x32_bf16 v[118:121], v[226:229], v[150:153], v[118:121]
	v_mfma_f32_16x16x32_bf16 v[114:117], v[234:237], v[150:153], v[114:117]
	v_mfma_f32_16x16x32_bf16 v[102:105], v[226:229], v[190:193], v[102:105]
	v_mfma_f32_16x16x32_bf16 v[98:101], v[234:237], v[190:193], v[98:101]
	v_mfma_f32_16x16x32_bf16 v[86:89], v[226:229], v[204:207], v[86:89]
	v_mfma_f32_16x16x32_bf16 v[82:85], v[234:237], v[204:207], v[82:85]
	v_mfma_f32_16x16x32_bf16 v[70:73], v[226:229], v[218:221], v[70:73]
	v_mfma_f32_16x16x32_bf16 v[62:65], v[234:237], v[218:221], v[62:65]
	s_mov_b32 m0, s83
	v_lshl_add_u64 v[162:163], v[208:209], 0, s[70:71]
	s_barrier
	ds_read_b128 v[146:149], v202 offset:49152
	ds_read_b128 v[150:153], v202 offset:50176
	ds_read_b128 v[186:189], v202 offset:51200
	ds_read_b128 v[190:193], v202 offset:52224
	ds_read_b128 v[194:197], v202 offset:53248
	ds_read_b128 v[204:207], v202 offset:54272
	ds_read_b128 v[214:217], v202 offset:55296
	ds_read_b128 v[218:221], v202 offset:56320
	global_load_lds_dwordx4 v[162:163], off
	s_mov_b32 m0, s84
	v_lshl_add_u64 v[162:163], v[238:239], 0, s[70:71]
	global_load_lds_dwordx4 v[162:163], off
	s_barrier
; #define PG8_STAGE(bufoff, gbase, voff) do { _Pragma("unroll") for (int _i = 0; _i < 2; ++_i) \
;         __builtin_amdgcn_global_load_lds((const unsigned*)((const char*)(gbase) + (voff)[_i]), (LAS unsigned*)(lds + (bufoff) + ldsw + _i * 8192), 16, 0, 0); } while (0)
; #define PG8_MMA(ai, bj, At, Bt) do { __builtin_amdgcn_s_setprio(1); _Pragma("unroll") for (int m = 0; m < 4; ++m) _Pragma("unroll") for (int n = 0; n < 2; ++n) _Pragma("unroll") for (int k = 0; k < 2; ++k) \
;         acc[ai][bj][m][n] = __builtin_amdgcn_mfma_f32_16x16x32_bf16(Bt[n][k], At[m][k], acc[ai][bj][m][n], 0, 0, 0); __builtin_amdgcn_s_setprio(0); } while (0)
; #define PG8_WAIT_V(n) asm volatile("s_waitcnt vmcnt(" #n ")" ::: "memory")
; #define PG8_WAIT_L(n) asm volatile("s_waitcnt lgkmcnt(" #n ")" ::: "memory")
; #define PG8_BAR __builtin_amdgcn_s_barrier()
; #define PG8_SCHED __builtin_amdgcn_sched_barrier(0)
; template <class Epi>
; DEVI void gemm_phase(LAS unsigned char* lds, const Gemm g, const Epi& E) {
;     ...
;             PG8_BAR; PG8_WAIT_L(0); PG8_MMA(1, 0, At, B0); PG8_BAR; PG8_SCHED;
;             PG8_STAGE(PG8_SB(1, 1), b3 + hstepB, voffB);
;             PG8_WAIT_V(6); PG8_BAR; PG8_MMA(1, 1, At, B1); PG8_BAR;
;         }
	s_waitcnt lgkmcnt(0)
	v_mfma_f32_16x16x32_bf16 v[66:69], v[130:133], v[146:149], v[66:69]
	v_mfma_f32_16x16x32_bf16 v[54:57], v[138:141], v[146:149], v[54:57]
	v_mfma_f32_16x16x32_bf16 v[46:49], v[130:133], v[186:189], v[46:49]
	v_mfma_f32_16x16x32_bf16 v[38:41], v[138:141], v[186:189], v[38:41]
	v_mfma_f32_16x16x32_bf16 v[30:33], v[130:133], v[194:197], v[30:33]
	v_mfma_f32_16x16x32_bf16 v[22:25], v[138:141], v[194:197], v[22:25]
	v_mfma_f32_16x16x32_bf16 v[14:17], v[130:133], v[214:217], v[14:17]
	v_mfma_f32_16x16x32_bf16 v[4:7], v[138:141], v[214:217], v[4:7]
	v_mfma_f32_16x16x32_bf16 v[66:69], v[134:137], v[150:153], v[66:69]
	v_mfma_f32_16x16x32_bf16 v[54:57], v[142:145], v[150:153], v[54:57]
	v_mfma_f32_16x16x32_bf16 v[46:49], v[134:137], v[190:193], v[46:49]
	v_mfma_f32_16x16x32_bf16 v[38:41], v[142:145], v[190:193], v[38:41]
	v_mfma_f32_16x16x32_bf16 v[30:33], v[134:137], v[204:207], v[30:33]
	v_mfma_f32_16x16x32_bf16 v[22:25], v[142:145], v[204:207], v[22:25]
	v_mfma_f32_16x16x32_bf16 v[14:17], v[134:137], v[218:221], v[14:17]
	v_mfma_f32_16x16x32_bf16 v[4:7], v[142:145], v[218:221], v[4:7]
	s_barrier
	s_add_u32 s26, s68, 0x40080
	s_addc_u32 s27, s69, 0
	s_add_i32 s19, s38, s80
	s_mov_b32 m0, s19
	v_lshl_add_u64 v[130:131], s[26:27], 0, v[8:9]
	global_load_lds_dwordx4 v[130:131], off
	s_add_i32 m0, s19, 0x2000
	v_lshl_add_u64 v[130:131], s[26:27], 0, v[180:181]
	global_load_lds_dwordx4 v[130:131], off
	s_waitcnt vmcnt(6)
	s_barrier
	v_mfma_f32_16x16x32_bf16 v[58:61], v[222:225], v[146:149], v[58:61]
	v_mfma_f32_16x16x32_bf16 v[50:53], v[230:233], v[146:149], v[50:53]
	v_mfma_f32_16x16x32_bf16 v[42:45], v[222:225], v[186:189], v[42:45]
	v_mfma_f32_16x16x32_bf16 v[34:37], v[230:233], v[186:189], v[34:37]
	v_mfma_f32_16x16x32_bf16 v[26:29], v[222:225], v[194:197], v[26:29]
	v_mfma_f32_16x16x32_bf16 v[18:21], v[230:233], v[194:197], v[18:21]
	v_mfma_f32_16x16x32_bf16 v[10:13], v[222:225], v[214:217], v[10:13]
	v_mfma_f32_16x16x32_bf16 v[0:3], v[230:233], v[214:217], v[0:3]
	v_mfma_f32_16x16x32_bf16 v[58:61], v[226:229], v[150:153], v[58:61]
	v_mfma_f32_16x16x32_bf16 v[50:53], v[234:237], v[150:153], v[50:53]
	v_mfma_f32_16x16x32_bf16 v[42:45], v[226:229], v[190:193], v[42:45]
	v_mfma_f32_16x16x32_bf16 v[34:37], v[234:237], v[190:193], v[34:37]
	v_mfma_f32_16x16x32_bf16 v[26:29], v[226:229], v[204:207], v[26:29]
	v_mfma_f32_16x16x32_bf16 v[18:21], v[234:237], v[204:207], v[18:21]
	v_mfma_f32_16x16x32_bf16 v[10:13], v[226:229], v[218:221], v[10:13]
	v_mfma_f32_16x16x32_bf16 v[0:3], v[234:237], v[218:221], v[0:3]
	s_add_i32 s18, s18, 2
	s_add_u32 s6, s6, 0x100
	s_addc_u32 s7, s7, 0
	s_add_u32 s11, s11, 0x100
	s_addc_u32 s13, s13, 0
	s_cmp_gt_u32 s18, 13
	s_barrier
	s_cbranch_scc0 .LBB0_1507
; #define LAS __attribute__((address_space(3)))
; template <class Epi>
; DEVI void gemm_phase(LAS unsigned char* lds, const Gemm g, const Epi& E) {
;     ...
;             const int row0 = cur.pm * BM + wr * 64 + fr, col0 = cur.pn * BM + wc * 32 + (Epi::PERM ? 8 : 4) * fq; constexpr int NST = Epi::PERM ? 4 : 16;
;             float rsv[8];
;             if constexpr (Epi::RS) { f32x4 q4[8];
; #pragma unroll
;                 for (int i = 0; i < 8; ++i) q4[i] = *(const f32x4*)(E.ssq_in + (size_t)(row0 + (i >> 2) * HALF + (i & 3) * 16) * 4);
; #pragma unroll
;                 for (int i = 0; i < 8; ++i) rsv[i] = rsqrtf((((q4[i][0] + q4[i][1]) + q4[i][2]) + q4[i][3]) * (1.f / DM) + 1e-6f); }
;             if constexpr (Epi::SOFTMAX) {
;                 LAS float* red = (LAS float*)(lds + 131072);
; #pragma unroll
;                 for (int ai = 0; ai < 2; ++ai)
; #pragma unroll
;                     for (int m = 0; m < 4; ++m) { const float sc = rsv[ai * 4 + m] * 0.0625f; float part = 0.f;
; #pragma unroll
;                         for (int bj = 0; bj < 2; ++bj)
; #pragma unroll
;                             for (int n = 0; n < 2; ++n)
; #pragma unroll
;                                 for (int j = 0; j < 4; ++j) { const float e = __expf(fmaxf(fminf(acc[ai][bj][m][n][j] * sc, 80.f), -80.f)); acc[ai][bj][m][n][j] = e; part += e; }
;                         part += __shfl_xor(part, 16); part += __shfl_xor(part, 32);
;                         if (fq == 0) red[(wr * 4 + wc) * 128 + ai * 64 + m * 16 + fr] = part; }
	s_setprio 0
	v_lshl_add_u32 v194, s46, 8, v198
	v_or_b32_e32 v192, 16, v194
	v_ashrrev_i32_e32 v195, 31, v194
	v_ashrrev_i32_e32 v193, 31, v192
	v_lshl_add_u64 v[130:131], v[194:195], 4, s[8:9]
	v_lshl_add_u64 v[134:135], v[192:193], 4, s[8:9]
	global_load_dwordx4 v[130:133], v[130:131], off
	v_and_b32_e32 v139, 64, v155
	global_load_dwordx4 v[134:137], v[134:135], off
	v_add_u32_e32 v138, 0x90, v194
	v_add_u32_e32 v140, 0xa0, v194
	v_add_u32_e32 v205, 64, v139
	v_ashrrev_i32_e32 v139, 31, v138
	v_ashrrev_i32_e32 v141, 31, v140
	v_lshl_add_u64 v[164:165], v[138:139], 4, s[8:9]
	v_lshl_add_u64 v[206:207], v[140:141], 4, s[8:9]
	v_xor_b32_e32 v144, 16, v155
	v_or_b32_e32 v190, 32, v194
	v_or_b32_e32 v188, 48, v194
	v_add_u32_e32 v186, 0x80, v194
	v_cmp_lt_i32_e32 vcc, v144, v205
	v_add_u32_e32 v142, 0xb0, v194
	v_ashrrev_i32_e32 v191, 31, v190
	v_ashrrev_i32_e32 v189, 31, v188
	v_ashrrev_i32_e32 v187, 31, v186
	v_cndmask_b32_e32 v146, v155, v144, vcc
	v_ashrrev_i32_e32 v143, 31, v142
	v_lshl_add_u64 v[144:145], v[190:191], 4, s[8:9]
	v_lshl_add_u64 v[150:151], v[188:189], 4, s[8:9]
	v_lshl_add_u64 v[162:163], v[186:187], 4, s[8:9]
	v_lshl_add_u64 v[208:209], v[142:143], 4, s[8:9]
	v_lshlrev_b32_e32 v204, 2, v146
	global_load_dwordx4 v[146:149], v[144:145], off
	s_nop 0
	global_load_dwordx4 v[150:153], v[150:151], off
	s_waitcnt vmcnt(0)
	v_mov_b32_e32 v139, v130
	v_mov_b32_e32 v141, v132
	v_mov_b32_e32 v138, v134
	v_mov_b32_e32 v130, v135
	v_mov_b32_e32 v140, v136
	v_pk_add_f32 v[130:131], v[138:139], v[130:131]
	v_mov_b32_e32 v132, v137
	v_pk_add_f32 v[130:131], v[140:141], v[130:131]
	s_nop 0
	v_pk_add_f32 v[130:131], v[132:133], v[130:131]
	s_nop 0
	v_pk_fma_f32 v[196:197], v[130:131], s[72:73], v[160:161] op_sel_hi:[1,0,0]
	s_nop 0
	v_mul_f32_e32 v130, 0x4b800000, v197
	v_cmp_gt_f32_e32 vcc, s94, v197
	s_nop 1
	v_cndmask_b32_e32 v130, v197, v130, vcc
	v_rsq_f32_e32 v197, v130
	global_load_dwordx4 v[138:141], v[162:163], off
	global_load_dwordx4 v[142:145], v[164:165], off
	global_load_dwordx4 v[130:133], v[206:207], off
	global_load_dwordx4 v[134:137], v[208:209], off
	v_mul_f32_e32 v162, 0x45800000, v197
	v_cndmask_b32_e32 v162, v197, v162, vcc
	v_mul_f32_e32 v162, 0x3d800000, v162
	v_mul_f32_e32 v126, v126, v162
	v_mul_f32_e32 v127, v127, v162
	v_mul_f32_e32 v124, v124, v162
	v_min_f32_e32 v126, 0x42a00000, v126
	v_mul_f32_e32 v128, v128, v162
	v_mul_f32_e32 v125, v125, v162
	v_min_f32_e32 v127, 0x42a00000, v127
	v_min_f32_e32 v124, 0x42a00000, v124
	v_max_f32_e32 v126, 0xc2a00000, v126
	v_mul_f32_e32 v129, v129, v162
	v_min_f32_e32 v128, 0x42a00000, v128
	v_min_f32_e32 v125, 0x42a00000, v125
	v_max_f32_e32 v127, 0xc2a00000, v127
	v_max_f32_e32 v124, 0xc2a00000, v124
	v_mul_f32_e32 v126, 0x3fb8aa3b, v126
	v_mul_f32_e32 v122, v122, v162
	v_min_f32_e32 v129, 0x42a00000, v129
	v_max_f32_e32 v128, 0xc2a00000, v128
	v_max_f32_e32 v125, 0xc2a00000, v125
	v_mul_f32_e32 v127, 0x3fb8aa3b, v127
	v_mul_f32_e32 v163, 0x3fb8aa3b, v124
	v_exp_f32_e32 v124, v126
	v_mul_f32_e32 v123, v123, v162
	v_min_f32_e32 v122, 0x42a00000, v122
	v_max_f32_e32 v129, 0xc2a00000, v129
	v_mul_f32_e32 v128, 0x3fb8aa3b, v128
	v_mul_f32_e32 v164, 0x3fb8aa3b, v125
	v_exp_f32_e32 v125, v127
	v_min_f32_e32 v123, 0x42a00000, v123
	v_max_f32_e32 v122, 0xc2a00000, v122
	v_mul_f32_e32 v129, 0x3fb8aa3b, v129
	v_exp_f32_e32 v128, v128
	v_max_f32_e32 v123, 0xc2a00000, v123
	v_mul_f32_e32 v122, 0x3fb8aa3b, v122
	v_exp_f32_e32 v129, v129
	v_mul_f32_e32 v118, v118, v162
	v_mul_f32_e32 v123, 0x3fb8aa3b, v123
	v_exp_f32_e32 v122, v122
	v_exp_f32_e32 v126, v163
	v_add_f32_e32 v163, 0, v124
	v_mul_f32_e32 v119, v119, v162
	v_min_f32_e32 v118, 0x42a00000, v118
	v_exp_f32_e32 v123, v123
	v_add_f32_e32 v163, v125, v163
	v_mul_f32_e32 v120, v120, v162
	v_min_f32_e32 v119, 0x42a00000, v119
	v_max_f32_e32 v118, 0xc2a00000, v118
	v_add_f32_e32 v163, v128, v163
	v_max_f32_e32 v119, 0xc2a00000, v119
	v_mul_f32_e32 v118, 0x3fb8aa3b, v118
	v_exp_f32_e32 v127, v164
	v_add_f32_e32 v163, v129, v163
	v_min_f32_e32 v120, 0x42a00000, v120
	v_mul_f32_e32 v121, v121, v162
	v_mul_f32_e32 v119, 0x3fb8aa3b, v119
	v_exp_f32_e32 v118, v118
	v_add_f32_e32 v163, v122, v163
	v_max_f32_e32 v120, 0xc2a00000, v120
	v_min_f32_e32 v121, 0x42a00000, v121
	v_mul_f32_e32 v114, v114, v162
	v_exp_f32_e32 v119, v119
	v_add_f32_e32 v163, v123, v163
	v_mul_f32_e32 v120, 0x3fb8aa3b, v120
	v_max_f32_e32 v121, 0xc2a00000, v121
	v_min_f32_e32 v114, 0x42a00000, v114
	v_mul_f32_e32 v115, v115, v162
	v_add_f32_e32 v163, v126, v163
	v_exp_f32_e32 v120, v120
	v_mul_f32_e32 v121, 0x3fb8aa3b, v121
	v_max_f32_e32 v114, 0xc2a00000, v114
	v_min_f32_e32 v115, 0x42a00000, v115
	v_mul_f32_e32 v116, v116, v162
	v_add_f32_e32 v163, v127, v163
	v_exp_f32_e32 v121, v121
	v_mul_f32_e32 v114, 0x3fb8aa3b, v114
	v_max_f32_e32 v115, 0xc2a00000, v115
	v_min_f32_e32 v116, 0x42a00000, v116
	v_mul_f32_e32 v117, v117, v162
	v_add_f32_e32 v163, v118, v163
	v_exp_f32_e32 v114, v114
	v_mul_f32_e32 v115, 0x3fb8aa3b, v115
	v_max_f32_e32 v116, 0xc2a00000, v116
	v_min_f32_e32 v117, 0x42a00000, v117
	v_add_f32_e32 v163, v119, v163
	v_exp_f32_e32 v115, v115
	v_mul_f32_e32 v116, 0x3fb8aa3b, v116
	v_max_f32_e32 v117, 0xc2a00000, v117
	v_add_f32_e32 v163, v120, v163
	v_exp_f32_e32 v116, v116
	v_mul_f32_e32 v117, 0x3fb8aa3b, v117
	v_add_f32_e32 v163, v121, v163
	v_exp_f32_e32 v117, v117
	v_add_f32_e32 v162, v114, v163
	v_add_f32_e32 v162, v115, v162
	v_add_f32_e32 v162, v116, v162
	v_add_f32_e32 v162, v117, v162
	ds_bpermute_b32 v163, v204, v162
	v_xor_b32_e32 v164, 32, v155
	v_cmp_lt_i32_e32 vcc, v164, v205
	s_waitcnt lgkmcnt(0)
	v_add_f32_e32 v205, v162, v163
	v_cndmask_b32_e32 v164, v155, v164, vcc
	v_lshlrev_b32_e32 v197, 2, v164
	ds_bpermute_b32 v206, v197, v205
	v_cmp_gt_f32_e32 vcc, s94, v196
	s_and_saveexec_b64 s[6:7], s[2:3]
	s_cbranch_execz .LBB0_1510
	s_waitcnt lgkmcnt(0)
	v_add_f32_e32 v162, v205, v206
	ds_write_b32 v201, v162

; #define PG8_STAGE(bufoff, gbase, voff) do { _Pragma("unroll") for (int _i = 0; _i < 2; ++_i) \
;         __builtin_amdgcn_global_load_lds((const unsigned*)((const char*)(gbase) + (voff)[_i]), (LAS unsigned*)(lds + (bufoff) + ldsw + _i * 8192), 16, 0, 0); } while (0)
; #define PG8_LDA(dst, b, h) do { _Pragma("unroll") for (int m = 0; m < 4; ++m) _Pragma("unroll") for (int k = 0; k < 2; ++k) dst[m][k] = *(const LAS bf16x8*)(lds + PG8_SA(b, h) + aoff + m * 2048 + k * 1024); } while (0)
; #define PG8_LDB(dst, b, h) do { _Pragma("unroll") for (int n = 0; n < 2; ++n) _Pragma("unroll") for (int k = 0; k < 2; ++k) dst[n][k] = *(const LAS bf16x8*)(lds + PG8_SB(b, h) + boff + n * 2048 + k * 1024); } while (0)
; #define PG8_MMA(ai, bj, At, Bt) do { __builtin_amdgcn_s_setprio(1); _Pragma("unroll") for (int m = 0; m < 4; ++m) _Pragma("unroll") for (int n = 0; n < 2; ++n) _Pragma("unroll") for (int k = 0; k < 2; ++k) \
;         acc[ai][bj][m][n] = __builtin_amdgcn_mfma_f32_16x16x32_bf16(Bt[n][k], At[m][k], acc[ai][bj][m][n], 0, 0, 0); __builtin_amdgcn_s_setprio(0); } while (0)
; #define PG8_WAIT_L(n) asm volatile("s_waitcnt lgkmcnt(" #n ")" ::: "memory")
; #define PG8_BAR __builtin_amdgcn_s_barrier()
; #define PG8_SCHED __builtin_amdgcn_sched_barrier(0)
; template <class Epi>
; DEVI void gemm_phase(LAS unsigned char* lds, const Gemm g, const Epi& E) {
;     ...
;             const char* a1 = cA + (size_t)(t + 1) * kstep;
;             const char* a2 = last ? nA : cA + (size_t)(t + 2) * kstep; const char* b2 = last ? nB : cB + (size_t)(t + 2) * kstep;
;             const char* a3 = a2 + kstep; const char* b3 = b2 + kstep;
;             PG8_LDB(B0, 0, 0); PG8_SCHED; PG8_LDA(At, 0, 0); PG8_STAGE(PG8_SA(1, 1), a1 + hstepA, voffA);
;             PG8_WAIT_L(8); PG8_BAR; PG8_WAIT_L(0); PG8_MMA(0, 0, At, B0); PG8_BAR; PG8_SCHED;
;             PG8_LDB(B1, 0, 1); PG8_STAGE(PG8_SB(0, 0), b2, voffB);
;             PG8_BAR; PG8_WAIT_L(0); PG8_MMA(0, 1, At, B1); PG8_BAR;
;             PG8_LDA(At, 0, 1); PG8_STAGE(PG8_SA(0, 0), a2, voffA);
;             PG8_BAR; PG8_WAIT_L(0); PG8_MMA(1, 0, At, B0); PG8_BAR; PG8_SCHED;
.LBB0_1595:
	s_add_u32 s18, s8, 0xfffc0080
	s_addc_u32 s19, s9, -1
	s_add_i32 s26, 0, 0x10000
	v_add_u32_e32 v142, s26, v191
	ds_read_b128 v[130:133], v142
	ds_read_b128 v[134:137], v142 offset:1024
	ds_read_b128 v[138:141], v142 offset:2048
	ds_read_b128 v[142:145], v142 offset:3072
	s_cmp_eq_u32 s17, 12
	s_cselect_b32 s81, s0, s19
	s_cselect_b32 s80, s1, s18
	s_cselect_b32 s79, s37, s15
	s_cselect_b32 s78, s36, s13
	v_lshl_add_u64 v[162:163], s[8:9], 0, v[152:153]
	s_add_i32 m0, s69, 0xc000
	ds_read_b128 v[178:181], v196
	ds_read_b128 v[182:185], v196 offset:1024
	ds_read_b128 v[186:189], v196 offset:2048
	ds_read_b128 v[198:201], v196 offset:3072
	ds_read_b128 v[202:205], v196 offset:4096
	ds_read_b128 v[206:209], v196 offset:5120
	ds_read_b128 v[214:217], v196 offset:6144
	ds_read_b128 v[218:221], v196 offset:7168
	global_load_lds_dwordx4 v[162:163], off
	s_add_i32 m0, s69, 0xe000
	v_lshl_add_u64 v[162:163], s[8:9], 0, v[176:177]
	global_load_lds_dwordx4 v[162:163], off
	s_waitcnt lgkmcnt(8)
	s_barrier
	s_waitcnt lgkmcnt(0)
	v_mfma_f32_16x16x32_bf16 v[126:129], v[130:133], v[178:181], v[126:129]
	v_mfma_f32_16x16x32_bf16 v[122:125], v[138:141], v[178:181], v[122:125]
	v_mfma_f32_16x16x32_bf16 v[110:113], v[130:133], v[186:189], v[110:113]
	v_mfma_f32_16x16x32_bf16 v[106:109], v[138:141], v[186:189], v[106:109]
	v_mfma_f32_16x16x32_bf16 v[94:97], v[130:133], v[202:205], v[94:97]
	v_mfma_f32_16x16x32_bf16 v[90:93], v[138:141], v[202:205], v[90:93]
	v_mfma_f32_16x16x32_bf16 v[78:81], v[130:133], v[214:217], v[78:81]
	v_mfma_f32_16x16x32_bf16 v[74:77], v[138:141], v[214:217], v[74:77]
	v_mfma_f32_16x16x32_bf16 v[126:129], v[134:137], v[182:185], v[126:129]
	v_mfma_f32_16x16x32_bf16 v[122:125], v[142:145], v[182:185], v[122:125]
	v_mfma_f32_16x16x32_bf16 v[110:113], v[134:137], v[198:201], v[110:113]
	v_mfma_f32_16x16x32_bf16 v[106:109], v[142:145], v[198:201], v[106:109]
	v_mfma_f32_16x16x32_bf16 v[94:97], v[134:137], v[206:209], v[94:97]
	v_mfma_f32_16x16x32_bf16 v[90:93], v[142:145], v[206:209], v[90:93]
	v_mfma_f32_16x16x32_bf16 v[78:81], v[134:137], v[218:221], v[78:81]
	v_mfma_f32_16x16x32_bf16 v[74:77], v[142:145], v[218:221], v[74:77]
	s_barrier
	s_add_i32 s27, 0, 0x14000
	v_add_u32_e32 v162, s27, v191
	s_add_i32 s18, s26, s82
	ds_read_b128 v[222:225], v162
	ds_read_b128 v[226:229], v162 offset:1024
	ds_read_b128 v[230:233], v162 offset:2048
	ds_read_b128 v[234:237], v162 offset:3072
	v_lshl_add_u64 v[162:163], s[78:79], 0, v[8:9]
	s_mov_b32 m0, s18
	v_lshl_add_u64 v[164:165], s[78:79], 0, v[150:151]
	global_load_lds_dwordx4 v[162:163], off
	s_add_i32 m0, s18, 0x2000
	s_nop 0
	global_load_lds_dwordx4 v[164:165], off
	s_barrier
	s_waitcnt lgkmcnt(0)
	v_mfma_f32_16x16x32_bf16 v[118:121], v[222:225], v[178:181], v[118:121]
	v_mfma_f32_16x16x32_bf16 v[114:117], v[230:233], v[178:181], v[114:117]
	v_mfma_f32_16x16x32_bf16 v[102:105], v[222:225], v[186:189], v[102:105]
	v_mfma_f32_16x16x32_bf16 v[98:101], v[230:233], v[186:189], v[98:101]
	v_mfma_f32_16x16x32_bf16 v[86:89], v[222:225], v[202:205], v[86:89]
	v_mfma_f32_16x16x32_bf16 v[82:85], v[230:233], v[202:205], v[82:85]
	v_mfma_f32_16x16x32_bf16 v[70:73], v[222:225], v[214:217], v[70:73]
	v_mfma_f32_16x16x32_bf16 v[66:69], v[230:233], v[214:217], v[66:69]
	v_mfma_f32_16x16x32_bf16 v[118:121], v[226:229], v[182:185], v[118:121]
	v_mfma_f32_16x16x32_bf16 v[114:117], v[234:237], v[182:185], v[114:117]
	v_mfma_f32_16x16x32_bf16 v[102:105], v[226:229], v[198:201], v[102:105]
	v_mfma_f32_16x16x32_bf16 v[98:101], v[234:237], v[198:201], v[98:101]
	v_mfma_f32_16x16x32_bf16 v[86:89], v[226:229], v[206:209], v[86:89]
	v_mfma_f32_16x16x32_bf16 v[82:85], v[234:237], v[206:209], v[82:85]
	v_mfma_f32_16x16x32_bf16 v[70:73], v[226:229], v[218:221], v[70:73]
	v_mfma_f32_16x16x32_bf16 v[66:69], v[234:237], v[218:221], v[66:69]
	s_mov_b32 m0, s69
	v_lshl_add_u64 v[238:239], s[80:81], 0, v[146:147]
	s_barrier
	ds_read_b128 v[178:181], v196 offset:16384
	ds_read_b128 v[182:185], v196 offset:17408
	ds_read_b128 v[186:189], v196 offset:18432
	ds_read_b128 v[198:201], v196 offset:19456
	ds_read_b128 v[202:205], v196 offset:20480
	ds_read_b128 v[206:209], v196 offset:21504
	ds_read_b128 v[214:217], v196 offset:22528
	ds_read_b128 v[218:221], v196 offset:23552
	global_load_lds_dwordx4 v[238:239], off
	s_mov_b32 m0, s83
	v_lshl_add_u64 v[240:241], s[80:81], 0, v[148:149]
	global_load_lds_dwordx4 v[240:241], off
	s_barrier
	s_waitcnt lgkmcnt(0)
	v_mfma_f32_16x16x32_bf16 v[62:65], v[130:133], v[178:181], v[62:65]
	v_mfma_f32_16x16x32_bf16 v[58:61], v[138:141], v[178:181], v[58:61]
	v_mfma_f32_16x16x32_bf16 v[46:49], v[130:133], v[186:189], v[46:49]
	v_mfma_f32_16x16x32_bf16 v[42:45], v[138:141], v[186:189], v[42:45]
	v_mfma_f32_16x16x32_bf16 v[30:33], v[130:133], v[202:205], v[30:33]
	v_mfma_f32_16x16x32_bf16 v[26:29], v[138:141], v[202:205], v[26:29]
	v_mfma_f32_16x16x32_bf16 v[14:17], v[130:133], v[214:217], v[14:17]
	v_mfma_f32_16x16x32_bf16 v[10:13], v[138:141], v[214:217], v[10:13]
	v_mfma_f32_16x16x32_bf16 v[62:65], v[134:137], v[182:185], v[62:65]
	v_mfma_f32_16x16x32_bf16 v[58:61], v[142:145], v[182:185], v[58:61]
	v_mfma_f32_16x16x32_bf16 v[46:49], v[134:137], v[198:201], v[46:49]
	v_mfma_f32_16x16x32_bf16 v[42:45], v[142:145], v[198:201], v[42:45]
	v_mfma_f32_16x16x32_bf16 v[30:33], v[134:137], v[206:209], v[30:33]
	v_mfma_f32_16x16x32_bf16 v[26:29], v[142:145], v[206:209], v[26:29]
	v_mfma_f32_16x16x32_bf16 v[14:17], v[134:137], v[218:221], v[14:17]
	v_mfma_f32_16x16x32_bf16 v[10:13], v[142:145], v[218:221], v[10:13]
	s_barrier
; #define PG8_STAGE(bufoff, gbase, voff) do { _Pragma("unroll") for (int _i = 0; _i < 2; ++_i) \
;         __builtin_amdgcn_global_load_lds((const unsigned*)((const char*)(gbase) + (voff)[_i]), (LAS unsigned*)(lds + (bufoff) + ldsw + _i * 8192), 16, 0, 0); } while (0)
; #define PG8_LDA(dst, b, h) do { _Pragma("unroll") for (int m = 0; m < 4; ++m) _Pragma("unroll") for (int k = 0; k < 2; ++k) dst[m][k] = *(const LAS bf16x8*)(lds + PG8_SA(b, h) + aoff + m * 2048 + k * 1024); } while (0)
; #define PG8_LDB(dst, b, h) do { _Pragma("unroll") for (int n = 0; n < 2; ++n) _Pragma("unroll") for (int k = 0; k < 2; ++k) dst[n][k] = *(const LAS bf16x8*)(lds + PG8_SB(b, h) + boff + n * 2048 + k * 1024); } while (0)
; #define PG8_MMA(ai, bj, At, Bt) do { __builtin_amdgcn_s_setprio(1); _Pragma("unroll") for (int m = 0; m < 4; ++m) _Pragma("unroll") for (int n = 0; n < 2; ++n) _Pragma("unroll") for (int k = 0; k < 2; ++k) \
;         acc[ai][bj][m][n] = __builtin_amdgcn_mfma_f32_16x16x32_bf16(Bt[n][k], At[m][k], acc[ai][bj][m][n], 0, 0, 0); __builtin_amdgcn_s_setprio(0); } while (0)
; #define PG8_WAIT_V(n) asm volatile("s_waitcnt vmcnt(" #n ")" ::: "memory")
; #define PG8_WAIT_L(n) asm volatile("s_waitcnt lgkmcnt(" #n ")" ::: "memory")
; #define PG8_BAR __builtin_amdgcn_s_barrier()
; #define PG8_SCHED __builtin_amdgcn_sched_barrier(0)
; template <class Epi>
; DEVI void gemm_phase(LAS unsigned char* lds, const Gemm g, const Epi& E) {
;     ...
;             PG8_STAGE(PG8_SB(0, 1), b2 + hstepB, voffB);
;             PG8_WAIT_V(6); PG8_BAR; PG8_MMA(1, 1, At, B1); PG8_BAR;
;             PG8_LDB(B0, 1, 0); PG8_SCHED; PG8_LDA(At, 1, 0); PG8_STAGE(PG8_SA(0, 1), a2 + hstepA, voffA);
;             PG8_WAIT_L(8); PG8_BAR; PG8_WAIT_L(0); PG8_MMA(0, 0, At, B0); PG8_BAR; PG8_SCHED;
;             PG8_LDB(B1, 1, 1); PG8_STAGE(PG8_SB(1, 0), b3, voffB);
;             PG8_BAR; PG8_WAIT_L(0); PG8_MMA(0, 1, At, B1); PG8_BAR;
;             PG8_LDA(At, 1, 1); PG8_STAGE(PG8_SA(1, 0), a3, voffA);
	s_add_u32 s18, s78, 0x40000
	s_addc_u32 s19, s79, 0
	s_add_i32 s26, s27, s82
	s_mov_b32 m0, s26
	v_lshl_add_u64 v[130:131], s[18:19], 0, v[8:9]
	global_load_lds_dwordx4 v[130:131], off
	s_add_i32 m0, s26, 0x2000
	v_lshl_add_u64 v[130:131], s[18:19], 0, v[150:151]
	global_load_lds_dwordx4 v[130:131], off
	s_waitcnt vmcnt(6)
	s_barrier
	v_mfma_f32_16x16x32_bf16 v[54:57], v[222:225], v[178:181], v[54:57]
	v_mfma_f32_16x16x32_bf16 v[50:53], v[230:233], v[178:181], v[50:53]
	v_mfma_f32_16x16x32_bf16 v[38:41], v[222:225], v[186:189], v[38:41]
	v_mfma_f32_16x16x32_bf16 v[34:37], v[230:233], v[186:189], v[34:37]
	v_mfma_f32_16x16x32_bf16 v[22:25], v[222:225], v[202:205], v[22:25]
	v_mfma_f32_16x16x32_bf16 v[18:21], v[230:233], v[202:205], v[18:21]
	v_mfma_f32_16x16x32_bf16 v[4:7], v[222:225], v[214:217], v[4:7]
	v_mfma_f32_16x16x32_bf16 v[0:3], v[230:233], v[214:217], v[0:3]
	v_mfma_f32_16x16x32_bf16 v[54:57], v[226:229], v[182:185], v[54:57]
	v_mfma_f32_16x16x32_bf16 v[50:53], v[234:237], v[182:185], v[50:53]
	v_mfma_f32_16x16x32_bf16 v[38:41], v[226:229], v[198:201], v[38:41]
	v_mfma_f32_16x16x32_bf16 v[34:37], v[234:237], v[198:201], v[34:37]
	v_mfma_f32_16x16x32_bf16 v[22:25], v[226:229], v[206:209], v[22:25]
	v_mfma_f32_16x16x32_bf16 v[18:21], v[234:237], v[206:209], v[18:21]
	v_mfma_f32_16x16x32_bf16 v[4:7], v[226:229], v[218:221], v[4:7]
	v_mfma_f32_16x16x32_bf16 v[0:3], v[234:237], v[218:221], v[0:3]
	s_add_i32 s26, 0, 0x18000
	v_add_u32_e32 v142, s26, v191
	s_barrier
	ds_read_b128 v[130:133], v142
	ds_read_b128 v[134:137], v142 offset:1024
	ds_read_b128 v[138:141], v142 offset:2048
	ds_read_b128 v[142:145], v142 offset:3072
	s_add_u32 s18, s80, 0x40000
	s_addc_u32 s19, s81, 0
	s_mov_b32 m0, s84
	v_lshl_add_u64 v[222:223], s[18:19], 0, v[146:147]
	ds_read_b128 v[178:181], v196 offset:32768
	ds_read_b128 v[182:185], v196 offset:33792
	ds_read_b128 v[186:189], v196 offset:34816
	ds_read_b128 v[198:201], v196 offset:35840
	ds_read_b128 v[202:205], v196 offset:36864
	ds_read_b128 v[206:209], v196 offset:37888
	ds_read_b128 v[214:217], v196 offset:38912
	ds_read_b128 v[218:221], v196 offset:39936
	global_load_lds_dwordx4 v[222:223], off
	s_mov_b32 m0, s85
	v_lshl_add_u64 v[222:223], s[18:19], 0, v[148:149]
	global_load_lds_dwordx4 v[222:223], off
	s_waitcnt lgkmcnt(8)
	s_barrier
	s_waitcnt lgkmcnt(0)
	v_mfma_f32_16x16x32_bf16 v[126:129], v[130:133], v[178:181], v[126:129]
	v_mfma_f32_16x16x32_bf16 v[122:125], v[138:141], v[178:181], v[122:125]
	v_mfma_f32_16x16x32_bf16 v[110:113], v[130:133], v[186:189], v[110:113]
	v_mfma_f32_16x16x32_bf16 v[106:109], v[138:141], v[186:189], v[106:109]
	v_mfma_f32_16x16x32_bf16 v[94:97], v[130:133], v[202:205], v[94:97]
	v_mfma_f32_16x16x32_bf16 v[90:93], v[138:141], v[202:205], v[90:93]
	v_mfma_f32_16x16x32_bf16 v[78:81], v[130:133], v[214:217], v[78:81]
	v_mfma_f32_16x16x32_bf16 v[74:77], v[138:141], v[214:217], v[74:77]
	v_mfma_f32_16x16x32_bf16 v[126:129], v[134:137], v[182:185], v[126:129]
	v_mfma_f32_16x16x32_bf16 v[122:125], v[142:145], v[182:185], v[122:125]
	v_mfma_f32_16x16x32_bf16 v[110:113], v[134:137], v[198:201], v[110:113]
	v_mfma_f32_16x16x32_bf16 v[106:109], v[142:145], v[198:201], v[106:109]
	v_mfma_f32_16x16x32_bf16 v[94:97], v[134:137], v[206:209], v[94:97]
	v_mfma_f32_16x16x32_bf16 v[90:93], v[142:145], v[206:209], v[90:93]
	v_mfma_f32_16x16x32_bf16 v[78:81], v[134:137], v[218:221], v[78:81]
	v_mfma_f32_16x16x32_bf16 v[74:77], v[142:145], v[218:221], v[74:77]
	s_barrier
	s_add_i32 s27, 0, 0x1c000
	s_add_i32 s18, s26, s82
	v_add_u32_e32 v197, s27, v191
	v_lshl_add_u64 v[162:163], v[162:163], 0, s[70:71]
	s_mov_b32 m0, s18
	ds_read_b128 v[222:225], v197
	ds_read_b128 v[226:229], v197 offset:1024
	ds_read_b128 v[230:233], v197 offset:2048
	ds_read_b128 v[234:237], v197 offset:3072
	global_load_lds_dwordx4 v[162:163], off
	s_add_i32 m0, s18, 0x2000
	v_lshl_add_u64 v[162:163], v[164:165], 0, s[70:71]
	global_load_lds_dwordx4 v[162:163], off
	s_barrier
	s_waitcnt lgkmcnt(0)
	v_mfma_f32_16x16x32_bf16 v[118:121], v[222:225], v[178:181], v[118:121]
	v_mfma_f32_16x16x32_bf16 v[114:117], v[230:233], v[178:181], v[114:117]
	v_mfma_f32_16x16x32_bf16 v[102:105], v[222:225], v[186:189], v[102:105]
	v_mfma_f32_16x16x32_bf16 v[98:101], v[230:233], v[186:189], v[98:101]
	v_mfma_f32_16x16x32_bf16 v[86:89], v[222:225], v[202:205], v[86:89]
	v_mfma_f32_16x16x32_bf16 v[82:85], v[230:233], v[202:205], v[82:85]
	v_mfma_f32_16x16x32_bf16 v[70:73], v[222:225], v[214:217], v[70:73]
	v_mfma_f32_16x16x32_bf16 v[66:69], v[230:233], v[214:217], v[66:69]
	v_mfma_f32_16x16x32_bf16 v[118:121], v[226:229], v[182:185], v[118:121]
	v_mfma_f32_16x16x32_bf16 v[114:117], v[234:237], v[182:185], v[114:117]
	v_mfma_f32_16x16x32_bf16 v[102:105], v[226:229], v[198:201], v[102:105]
	v_mfma_f32_16x16x32_bf16 v[98:101], v[234:237], v[198:201], v[98:101]
	v_mfma_f32_16x16x32_bf16 v[86:89], v[226:229], v[206:209], v[86:89]
	v_mfma_f32_16x16x32_bf16 v[82:85], v[234:237], v[206:209], v[82:85]
	v_mfma_f32_16x16x32_bf16 v[70:73], v[226:229], v[218:221], v[70:73]
	v_mfma_f32_16x16x32_bf16 v[66:69], v[234:237], v[218:221], v[66:69]
	s_mov_b32 m0, s86
	v_lshl_add_u64 v[162:163], v[238:239], 0, s[70:71]
	s_barrier
	ds_read_b128 v[178:181], v196 offset:49152
	ds_read_b128 v[182:185], v196 offset:50176
	ds_read_b128 v[186:189], v196 offset:51200
	ds_read_b128 v[198:201], v196 offset:52224
	ds_read_b128 v[202:205], v196 offset:53248
	ds_read_b128 v[206:209], v196 offset:54272
	ds_read_b128 v[214:217], v196 offset:55296
	ds_read_b128 v[218:221], v196 offset:56320
	global_load_lds_dwordx4 v[162:163], off
	s_mov_b32 m0, s87
	v_lshl_add_u64 v[162:163], v[240:241], 0, s[70:71]
	global_load_lds_dwordx4 v[162:163], off
	s_barrier
; #define PG8_STAGE(bufoff, gbase, voff) do { _Pragma("unroll") for (int _i = 0; _i < 2; ++_i) \
;         __builtin_amdgcn_global_load_lds((const unsigned*)((const char*)(gbase) + (voff)[_i]), (LAS unsigned*)(lds + (bufoff) + ldsw + _i * 8192), 16, 0, 0); } while (0)
; #define PG8_MMA(ai, bj, At, Bt) do { __builtin_amdgcn_s_setprio(1); _Pragma("unroll") for (int m = 0; m < 4; ++m) _Pragma("unroll") for (int n = 0; n < 2; ++n) _Pragma("unroll") for (int k = 0; k < 2; ++k) \
;         acc[ai][bj][m][n] = __builtin_amdgcn_mfma_f32_16x16x32_bf16(Bt[n][k], At[m][k], acc[ai][bj][m][n], 0, 0, 0); __builtin_amdgcn_s_setprio(0); } while (0)
; #define PG8_WAIT_V(n) asm volatile("s_waitcnt vmcnt(" #n ")" ::: "memory")
; #define PG8_WAIT_L(n) asm volatile("s_waitcnt lgkmcnt(" #n ")" ::: "memory")
; #define PG8_BAR __builtin_amdgcn_s_barrier()
; #define PG8_SCHED __builtin_amdgcn_sched_barrier(0)
; template <class Epi>
; DEVI void gemm_phase(LAS unsigned char* lds, const Gemm g, const Epi& E) {
;     ...
;             PG8_BAR; PG8_WAIT_L(0); PG8_MMA(1, 0, At, B0); PG8_BAR; PG8_SCHED;
;             PG8_STAGE(PG8_SB(1, 1), b3 + hstepB, voffB);
;             PG8_WAIT_V(6); PG8_BAR; PG8_MMA(1, 1, At, B1); PG8_BAR;
;         }
	s_waitcnt lgkmcnt(0)
	v_mfma_f32_16x16x32_bf16 v[62:65], v[130:133], v[178:181], v[62:65]
	v_mfma_f32_16x16x32_bf16 v[58:61], v[138:141], v[178:181], v[58:61]
	v_mfma_f32_16x16x32_bf16 v[46:49], v[130:133], v[186:189], v[46:49]
	v_mfma_f32_16x16x32_bf16 v[42:45], v[138:141], v[186:189], v[42:45]
	v_mfma_f32_16x16x32_bf16 v[30:33], v[130:133], v[202:205], v[30:33]
	v_mfma_f32_16x16x32_bf16 v[26:29], v[138:141], v[202:205], v[26:29]
	v_mfma_f32_16x16x32_bf16 v[14:17], v[130:133], v[214:217], v[14:17]
	v_mfma_f32_16x16x32_bf16 v[10:13], v[138:141], v[214:217], v[10:13]
	v_mfma_f32_16x16x32_bf16 v[62:65], v[134:137], v[182:185], v[62:65]
	v_mfma_f32_16x16x32_bf16 v[58:61], v[142:145], v[182:185], v[58:61]
	v_mfma_f32_16x16x32_bf16 v[46:49], v[134:137], v[198:201], v[46:49]
	v_mfma_f32_16x16x32_bf16 v[42:45], v[142:145], v[198:201], v[42:45]
	v_mfma_f32_16x16x32_bf16 v[30:33], v[134:137], v[206:209], v[30:33]
	v_mfma_f32_16x16x32_bf16 v[26:29], v[142:145], v[206:209], v[26:29]
	v_mfma_f32_16x16x32_bf16 v[14:17], v[134:137], v[218:221], v[14:17]
	v_mfma_f32_16x16x32_bf16 v[10:13], v[142:145], v[218:221], v[10:13]
	s_barrier
	s_add_u32 s18, s78, 0x40080
	s_addc_u32 s19, s79, 0
	s_add_i32 s26, s27, s82
	s_mov_b32 m0, s26
	v_lshl_add_u64 v[130:131], s[18:19], 0, v[8:9]
	global_load_lds_dwordx4 v[130:131], off
	s_add_i32 m0, s26, 0x2000
	v_lshl_add_u64 v[130:131], s[18:19], 0, v[150:151]
	global_load_lds_dwordx4 v[130:131], off
	s_waitcnt vmcnt(6)
	s_barrier
	v_mfma_f32_16x16x32_bf16 v[54:57], v[222:225], v[178:181], v[54:57]
	v_mfma_f32_16x16x32_bf16 v[50:53], v[230:233], v[178:181], v[50:53]
	v_mfma_f32_16x16x32_bf16 v[38:41], v[222:225], v[186:189], v[38:41]
	v_mfma_f32_16x16x32_bf16 v[34:37], v[230:233], v[186:189], v[34:37]
	v_mfma_f32_16x16x32_bf16 v[22:25], v[222:225], v[202:205], v[22:25]
	v_mfma_f32_16x16x32_bf16 v[18:21], v[230:233], v[202:205], v[18:21]
	v_mfma_f32_16x16x32_bf16 v[4:7], v[222:225], v[214:217], v[4:7]
	v_mfma_f32_16x16x32_bf16 v[0:3], v[230:233], v[214:217], v[0:3]
	v_mfma_f32_16x16x32_bf16 v[54:57], v[226:229], v[182:185], v[54:57]
	v_mfma_f32_16x16x32_bf16 v[50:53], v[234:237], v[182:185], v[50:53]
	v_mfma_f32_16x16x32_bf16 v[38:41], v[226:229], v[198:201], v[38:41]
	v_mfma_f32_16x16x32_bf16 v[34:37], v[234:237], v[198:201], v[34:37]
	v_mfma_f32_16x16x32_bf16 v[22:25], v[226:229], v[206:209], v[22:25]
	v_mfma_f32_16x16x32_bf16 v[18:21], v[234:237], v[206:209], v[18:21]
	v_mfma_f32_16x16x32_bf16 v[4:7], v[226:229], v[218:221], v[4:7]
	v_mfma_f32_16x16x32_bf16 v[0:3], v[234:237], v[218:221], v[0:3]
	s_add_i32 s17, s17, 2
	s_add_u32 s8, s8, 0x100
	s_addc_u32 s9, s9, 0
	s_add_u32 s13, s13, 0x100
	s_addc_u32 s15, s15, 0
	s_cmp_gt_u32 s17, 13
	s_barrier
	s_cbranch_scc0 .LBB0_1595
	s_setprio 0
	s_lshl_b32 s0, s68, 8
	v_add_u32_e32 v182, s0, v190
	v_lshl_or_b32 v180, s12, 8, v195
	v_ashrrev_i32_e32 v183, 31, v182
	v_lshlrev_b64 v[130:131], 12, v[182:183]
	v_ashrrev_i32_e32 v181, 31, v180
	v_lshl_add_u64 v[130:131], s[30:31], 0, v[130:131]
	v_lshlrev_b64 v[184:185], 2, v[180:181]
	v_lshl_add_u64 v[162:163], v[130:131], 0, v[184:185]
	global_load_dwordx4 v[200:203], v[162:163], off
	global_load_dwordx4 v[204:207], v[162:163], off offset:16
	global_load_dwordx4 v[214:217], v[162:163], off offset:512
	global_load_dwordx4 v[218:221], v[162:163], off offset:528
	v_or_b32_e32 v188, 16, v182
	v_ashrrev_i32_e32 v189, 31, v188
	v_lshlrev_b64 v[130:131], 12, v[188:189]
	v_lshl_add_u64 v[130:131], s[30:31], 0, v[130:131]
	v_lshl_add_u64 v[186:187], v[130:131], 0, v[184:185]
	global_load_dwordx4 v[138:141], v[186:187], off offset:16
	global_load_dwordx4 v[142:145], v[186:187], off
	global_load_dwordx4 v[130:133], v[186:187], off offset:528
	global_load_dwordx4 v[134:137], v[186:187], off offset:512
	v_and_b32_e32 v165, 64, v155
	v_xor_b32_e32 v164, 16, v155
	v_add_u32_e32 v165, 64, v165
	v_xor_b32_e32 v179, 32, v155
	v_cmp_lt_i32_e32 vcc, v164, v165
	v_or_b32_e32 v178, 0x80, v180
	s_waitcnt vmcnt(0)
	v_pk_add_f32 v[128:129], v[128:129], v[202:203]
	v_cndmask_b32_e32 v164, v155, v164, vcc
	v_cmp_lt_i32_e32 vcc, v179, v165
	v_lshlrev_b32_e32 v198, 2, v164
	v_pk_add_f32 v[126:127], v[126:127], v[200:201]
	v_cndmask_b32_e32 v165, v155, v179, vcc
	v_lshlrev_b32_e32 v197, 2, v165
	v_lshlrev_b64 v[164:165], 10, v[182:183]
	v_pk_add_f32 v[124:125], v[124:125], v[206:207]
	v_pk_add_f32 v[122:123], v[122:123], v[204:205]
	v_pk_add_f32 v[120:121], v[120:121], v[216:217]
	v_pk_add_f32 v[118:119], v[118:119], v[214:215]
	v_pk_add_f32 v[202:203], v[116:117], v[220:221]
	v_pk_add_f32 v[200:201], v[114:115], v[218:219]
	v_lshl_add_u64 v[208:209], v[164:165], 0, v[180:181]
	global_store_dwordx4 v[162:163], v[126:129], off
	global_store_dwordx4 v[162:163], v[122:125], off offset:16
	v_cvt_pk_bf16_f32 v114, v126, v127
	v_cvt_pk_bf16_f32 v115, v128, v129
	v_cvt_pk_bf16_f32 v116, v122, v123
	v_cvt_pk_bf16_f32 v117, v124, v125
	v_mul_f32_e32 v127, v127, v127
	v_mul_f32_e32 v129, v129, v129
	v_mul_f32_e32 v123, v123, v123
	v_mul_f32_e32 v125, v125, v125
	v_mul_f32_e32 v183, v119, v119
	v_mul_f32_e32 v199, v121, v121
	v_mul_f32_e32 v204, v201, v201
	v_mul_f32_e32 v205, v203, v203
	v_lshl_add_u64 v[208:209], v[208:209], 1, s[24:25]
	v_fmac_f32_e32 v127, v126, v126
	v_fmac_f32_e32 v129, v128, v128
	v_fmac_f32_e32 v123, v122, v122
	v_fmac_f32_e32 v125, v124, v124
	v_fmac_f32_e32 v183, v118, v118
	v_fmac_f32_e32 v199, v120, v120
	v_fmac_f32_e32 v204, v200, v200
	v_fmac_f32_e32 v205, v202, v202
	global_store_dwordx4 v[208:209], v[114:117], off
	v_ashrrev_i32_e32 v179, 31, v178
	v_lshl_add_u64 v[164:165], v[164:165], 0, v[178:179]
	v_add_f32_e32 v114, v127, v129
	v_add_f32_e32 v115, v123, v125
	v_add_f32_e32 v116, v183, v199
	v_add_f32_e32 v117, v204, v205
	v_add_f32_e32 v114, v114, v115
	v_add_f32_e32 v115, v116, v117
	v_add_f32_e32 v114, v114, v115
	ds_bpermute_b32 v115, v198, v114
	global_store_dwordx4 v[162:163], v[118:121], off offset:512
	global_store_dwordx4 v[162:163], v[200:203], off offset:528
	v_cvt_pk_bf16_f32 v116, v118, v119
	v_cvt_pk_bf16_f32 v117, v120, v121
	v_cvt_pk_bf16_f32 v118, v200, v201
	s_waitcnt lgkmcnt(0)
	v_add_f32_e32 v114, v114, v115
	ds_bpermute_b32 v115, v197, v114
	v_cvt_pk_bf16_f32 v119, v202, v203
	v_lshl_add_u64 v[120:121], v[164:165], 1, s[24:25]
	global_store_dwordx4 v[120:121], v[116:119], off
	s_and_saveexec_b64 s[8:9], s[2:3]
	s_cbranch_execz .LBB0_1598
	s_waitcnt lgkmcnt(0)
	v_add_f32_e32 v114, v114, v115
	ds_write_b32 v192, v114

; #define PG8_STAGE(bufoff, gbase, voff) do { _Pragma("unroll") for (int _i = 0; _i < 2; ++_i) \
;         __builtin_amdgcn_global_load_lds((const unsigned*)((const char*)(gbase) + (voff)[_i]), (LAS unsigned*)(lds + (bufoff) + ldsw + _i * 8192), 16, 0, 0); } while (0)
; #define PG8_LDA(dst, b, h) do { _Pragma("unroll") for (int m = 0; m < 4; ++m) _Pragma("unroll") for (int k = 0; k < 2; ++k) dst[m][k] = *(const LAS bf16x8*)(lds + PG8_SA(b, h) + aoff + m * 2048 + k * 1024); } while (0)
; #define PG8_LDB(dst, b, h) do { _Pragma("unroll") for (int n = 0; n < 2; ++n) _Pragma("unroll") for (int k = 0; k < 2; ++k) dst[n][k] = *(const LAS bf16x8*)(lds + PG8_SB(b, h) + boff + n * 2048 + k * 1024); } while (0)
; #define PG8_MMA(ai, bj, At, Bt) do { __builtin_amdgcn_s_setprio(1); _Pragma("unroll") for (int m = 0; m < 4; ++m) _Pragma("unroll") for (int n = 0; n < 2; ++n) _Pragma("unroll") for (int k = 0; k < 2; ++k) \
;         acc[ai][bj][m][n] = __builtin_amdgcn_mfma_f32_16x16x32_bf16(Bt[n][k], At[m][k], acc[ai][bj][m][n], 0, 0, 0); __builtin_amdgcn_s_setprio(0); } while (0)
; #define PG8_WAIT_L(n) asm volatile("s_waitcnt lgkmcnt(" #n ")" ::: "memory")
; #define PG8_BAR __builtin_amdgcn_s_barrier()
; #define PG8_SCHED __builtin_amdgcn_sched_barrier(0)
; template <class Epi>
; DEVI void gemm_phase(LAS unsigned char* lds, const Gemm g, const Epi& E) {
;     ...
;             const char* a1 = cA + (size_t)(t + 1) * kstep;
;             const char* a2 = last ? nA : cA + (size_t)(t + 2) * kstep; const char* b2 = last ? nB : cB + (size_t)(t + 2) * kstep;
;             const char* a3 = a2 + kstep; const char* b3 = b2 + kstep;
;             PG8_LDB(B0, 0, 0); PG8_SCHED; PG8_LDA(At, 0, 0); PG8_STAGE(PG8_SA(1, 1), a1 + hstepA, voffA);
;             PG8_WAIT_L(8); PG8_BAR; PG8_WAIT_L(0); PG8_MMA(0, 0, At, B0); PG8_BAR; PG8_SCHED;
;             PG8_LDB(B1, 0, 1); PG8_STAGE(PG8_SB(0, 0), b2, voffB);
;             PG8_BAR; PG8_WAIT_L(0); PG8_MMA(0, 1, At, B1); PG8_BAR;
;             PG8_LDA(At, 0, 1); PG8_STAGE(PG8_SA(0, 0), a2, voffA);
;             PG8_BAR; PG8_WAIT_L(0); PG8_MMA(1, 0, At, B0); PG8_BAR; PG8_SCHED;
.LBB0_1672:
	s_add_u32 s26, s16, 0xfffc0080
	s_addc_u32 s27, s17, -1
	s_add_i32 s38, 0, 0x10000
	v_add_u32_e32 v142, s38, v197
	ds_read_b128 v[130:133], v142
	ds_read_b128 v[134:137], v142 offset:1024
	ds_read_b128 v[138:141], v142 offset:2048
	ds_read_b128 v[142:145], v142 offset:3072
	s_cmp_eq_u32 s19, 12
	s_cselect_b32 s47, s0, s27
	s_cselect_b32 s46, s1, s26
	s_cselect_b32 s37, s5, s18
	s_cselect_b32 s36, s7, s9
	v_lshl_add_u64 v[162:163], s[16:17], 0, v[152:153]
	s_add_i32 m0, s79, 0xc000
	ds_read_b128 v[178:181], v201
	ds_read_b128 v[182:185], v201 offset:1024
	ds_read_b128 v[186:189], v201 offset:2048
	ds_read_b128 v[202:205], v201 offset:3072
	ds_read_b128 v[206:209], v201 offset:4096
	ds_read_b128 v[214:217], v201 offset:5120
	ds_read_b128 v[218:221], v201 offset:6144
	ds_read_b128 v[222:225], v201 offset:7168
	global_load_lds_dwordx4 v[162:163], off
	s_add_i32 m0, s79, 0xe000
	v_lshl_add_u64 v[162:163], s[16:17], 0, v[176:177]
	global_load_lds_dwordx4 v[162:163], off
	s_waitcnt lgkmcnt(8)
	s_barrier
	s_waitcnt lgkmcnt(0)
	v_mfma_f32_16x16x32_bf16 v[126:129], v[130:133], v[178:181], v[126:129]
	v_mfma_f32_16x16x32_bf16 v[122:125], v[138:141], v[178:181], v[122:125]
	v_mfma_f32_16x16x32_bf16 v[110:113], v[130:133], v[186:189], v[110:113]
	v_mfma_f32_16x16x32_bf16 v[106:109], v[138:141], v[186:189], v[106:109]
	v_mfma_f32_16x16x32_bf16 v[94:97], v[130:133], v[206:209], v[94:97]
	v_mfma_f32_16x16x32_bf16 v[90:93], v[138:141], v[206:209], v[90:93]
	v_mfma_f32_16x16x32_bf16 v[78:81], v[130:133], v[218:221], v[78:81]
	v_mfma_f32_16x16x32_bf16 v[74:77], v[138:141], v[218:221], v[74:77]
	v_mfma_f32_16x16x32_bf16 v[126:129], v[134:137], v[182:185], v[126:129]
	v_mfma_f32_16x16x32_bf16 v[122:125], v[142:145], v[182:185], v[122:125]
	v_mfma_f32_16x16x32_bf16 v[110:113], v[134:137], v[202:205], v[110:113]
	v_mfma_f32_16x16x32_bf16 v[106:109], v[142:145], v[202:205], v[106:109]
	v_mfma_f32_16x16x32_bf16 v[94:97], v[134:137], v[214:217], v[94:97]
	v_mfma_f32_16x16x32_bf16 v[90:93], v[142:145], v[214:217], v[90:93]
	v_mfma_f32_16x16x32_bf16 v[78:81], v[134:137], v[222:225], v[78:81]
	v_mfma_f32_16x16x32_bf16 v[74:77], v[142:145], v[222:225], v[74:77]
	s_barrier
	s_add_i32 s39, 0, 0x14000
	v_add_u32_e32 v162, s39, v197
	s_add_i32 s26, s38, s78
	ds_read_b128 v[226:229], v162
	ds_read_b128 v[230:233], v162 offset:1024
	ds_read_b128 v[234:237], v162 offset:2048
	ds_read_b128 v[238:241], v162 offset:3072
	v_lshl_add_u64 v[162:163], s[36:37], 0, v[8:9]
	s_mov_b32 m0, s26
	v_lshl_add_u64 v[164:165], s[36:37], 0, v[146:147]
	global_load_lds_dwordx4 v[162:163], off
	s_add_i32 m0, s26, 0x2000
	s_nop 0
	global_load_lds_dwordx4 v[164:165], off
	s_barrier
	s_waitcnt lgkmcnt(0)
	v_mfma_f32_16x16x32_bf16 v[118:121], v[226:229], v[178:181], v[118:121]
	v_mfma_f32_16x16x32_bf16 v[114:117], v[234:237], v[178:181], v[114:117]
	v_mfma_f32_16x16x32_bf16 v[102:105], v[226:229], v[186:189], v[102:105]
	v_mfma_f32_16x16x32_bf16 v[98:101], v[234:237], v[186:189], v[98:101]
	v_mfma_f32_16x16x32_bf16 v[86:89], v[226:229], v[206:209], v[86:89]
	v_mfma_f32_16x16x32_bf16 v[82:85], v[234:237], v[206:209], v[82:85]
	v_mfma_f32_16x16x32_bf16 v[70:73], v[226:229], v[218:221], v[70:73]
	v_mfma_f32_16x16x32_bf16 v[66:69], v[234:237], v[218:221], v[66:69]
	v_mfma_f32_16x16x32_bf16 v[118:121], v[230:233], v[182:185], v[118:121]
	v_mfma_f32_16x16x32_bf16 v[114:117], v[238:241], v[182:185], v[114:117]
	v_mfma_f32_16x16x32_bf16 v[102:105], v[230:233], v[202:205], v[102:105]
	v_mfma_f32_16x16x32_bf16 v[98:101], v[238:241], v[202:205], v[98:101]
	v_mfma_f32_16x16x32_bf16 v[86:89], v[230:233], v[214:217], v[86:89]
	v_mfma_f32_16x16x32_bf16 v[82:85], v[238:241], v[214:217], v[82:85]
	v_mfma_f32_16x16x32_bf16 v[70:73], v[230:233], v[222:225], v[70:73]
	v_mfma_f32_16x16x32_bf16 v[66:69], v[238:241], v[222:225], v[66:69]
	s_mov_b32 m0, s79
	v_lshl_add_u64 v[190:191], s[46:47], 0, v[150:151]
	s_barrier
	ds_read_b128 v[178:181], v201 offset:16384
	ds_read_b128 v[182:185], v201 offset:17408
	ds_read_b128 v[186:189], v201 offset:18432
	ds_read_b128 v[202:205], v201 offset:19456
	ds_read_b128 v[206:209], v201 offset:20480
	ds_read_b128 v[214:217], v201 offset:21504
	ds_read_b128 v[218:221], v201 offset:22528
	ds_read_b128 v[222:225], v201 offset:23552
	global_load_lds_dwordx4 v[190:191], off
	s_mov_b32 m0, s80
	v_lshl_add_u64 v[194:195], s[46:47], 0, v[148:149]
	global_load_lds_dwordx4 v[194:195], off
	s_barrier
	s_waitcnt lgkmcnt(0)
	v_mfma_f32_16x16x32_bf16 v[50:53], v[130:133], v[178:181], v[50:53]
	v_mfma_f32_16x16x32_bf16 v[54:57], v[138:141], v[178:181], v[54:57]
	v_mfma_f32_16x16x32_bf16 v[34:37], v[130:133], v[186:189], v[34:37]
	v_mfma_f32_16x16x32_bf16 v[38:41], v[138:141], v[186:189], v[38:41]
	v_mfma_f32_16x16x32_bf16 v[18:21], v[130:133], v[206:209], v[18:21]
	v_mfma_f32_16x16x32_bf16 v[22:25], v[138:141], v[206:209], v[22:25]
	v_mfma_f32_16x16x32_bf16 v[0:3], v[130:133], v[218:221], v[0:3]
	v_mfma_f32_16x16x32_bf16 v[4:7], v[138:141], v[218:221], v[4:7]
	v_mfma_f32_16x16x32_bf16 v[50:53], v[134:137], v[182:185], v[50:53]
	v_mfma_f32_16x16x32_bf16 v[54:57], v[142:145], v[182:185], v[54:57]
	v_mfma_f32_16x16x32_bf16 v[34:37], v[134:137], v[202:205], v[34:37]
	v_mfma_f32_16x16x32_bf16 v[38:41], v[142:145], v[202:205], v[38:41]
	v_mfma_f32_16x16x32_bf16 v[18:21], v[134:137], v[214:217], v[18:21]
	v_mfma_f32_16x16x32_bf16 v[22:25], v[142:145], v[214:217], v[22:25]
	v_mfma_f32_16x16x32_bf16 v[0:3], v[134:137], v[222:225], v[0:3]
	v_mfma_f32_16x16x32_bf16 v[4:7], v[142:145], v[222:225], v[4:7]
	s_barrier
; #define PG8_STAGE(bufoff, gbase, voff) do { _Pragma("unroll") for (int _i = 0; _i < 2; ++_i) \
;         __builtin_amdgcn_global_load_lds((const unsigned*)((const char*)(gbase) + (voff)[_i]), (LAS unsigned*)(lds + (bufoff) + ldsw + _i * 8192), 16, 0, 0); } while (0)
; #define PG8_LDA(dst, b, h) do { _Pragma("unroll") for (int m = 0; m < 4; ++m) _Pragma("unroll") for (int k = 0; k < 2; ++k) dst[m][k] = *(const LAS bf16x8*)(lds + PG8_SA(b, h) + aoff + m * 2048 + k * 1024); } while (0)
; #define PG8_LDB(dst, b, h) do { _Pragma("unroll") for (int n = 0; n < 2; ++n) _Pragma("unroll") for (int k = 0; k < 2; ++k) dst[n][k] = *(const LAS bf16x8*)(lds + PG8_SB(b, h) + boff + n * 2048 + k * 1024); } while (0)
; #define PG8_MMA(ai, bj, At, Bt) do { __builtin_amdgcn_s_setprio(1); _Pragma("unroll") for (int m = 0; m < 4; ++m) _Pragma("unroll") for (int n = 0; n < 2; ++n) _Pragma("unroll") for (int k = 0; k < 2; ++k) \
;         acc[ai][bj][m][n] = __builtin_amdgcn_mfma_f32_16x16x32_bf16(Bt[n][k], At[m][k], acc[ai][bj][m][n], 0, 0, 0); __builtin_amdgcn_s_setprio(0); } while (0)
; #define PG8_WAIT_V(n) asm volatile("s_waitcnt vmcnt(" #n ")" ::: "memory")
; #define PG8_WAIT_L(n) asm volatile("s_waitcnt lgkmcnt(" #n ")" ::: "memory")
; #define PG8_BAR __builtin_amdgcn_s_barrier()
; #define PG8_SCHED __builtin_amdgcn_sched_barrier(0)
; template <class Epi>
; DEVI void gemm_phase(LAS unsigned char* lds, const Gemm g, const Epi& E) {
;     ...
;             PG8_STAGE(PG8_SB(0, 1), b2 + hstepB, voffB);
;             PG8_WAIT_V(6); PG8_BAR; PG8_MMA(1, 1, At, B1); PG8_BAR;
;             PG8_LDB(B0, 1, 0); PG8_SCHED; PG8_LDA(At, 1, 0); PG8_STAGE(PG8_SA(0, 1), a2 + hstepA, voffA);
;             PG8_WAIT_L(8); PG8_BAR; PG8_WAIT_L(0); PG8_MMA(0, 0, At, B0); PG8_BAR; PG8_SCHED;
;             PG8_LDB(B1, 1, 1); PG8_STAGE(PG8_SB(1, 0), b3, voffB);
;             PG8_BAR; PG8_WAIT_L(0); PG8_MMA(0, 1, At, B1); PG8_BAR;
;             PG8_LDA(At, 1, 1); PG8_STAGE(PG8_SA(1, 0), a3, voffA);
	s_add_u32 s26, s36, 0x40000
	s_addc_u32 s27, s37, 0
	s_add_i32 s38, s39, s78
	s_mov_b32 m0, s38
	v_lshl_add_u64 v[130:131], s[26:27], 0, v[8:9]
	global_load_lds_dwordx4 v[130:131], off
	s_add_i32 m0, s38, 0x2000
	v_lshl_add_u64 v[130:131], s[26:27], 0, v[146:147]
	global_load_lds_dwordx4 v[130:131], off
	s_waitcnt vmcnt(6)
	s_barrier
	v_mfma_f32_16x16x32_bf16 v[58:61], v[226:229], v[178:181], v[58:61]
	v_mfma_f32_16x16x32_bf16 v[62:65], v[234:237], v[178:181], v[62:65]
	v_mfma_f32_16x16x32_bf16 v[42:45], v[226:229], v[186:189], v[42:45]
	v_mfma_f32_16x16x32_bf16 v[46:49], v[234:237], v[186:189], v[46:49]
	v_mfma_f32_16x16x32_bf16 v[26:29], v[226:229], v[206:209], v[26:29]
	v_mfma_f32_16x16x32_bf16 v[30:33], v[234:237], v[206:209], v[30:33]
	v_mfma_f32_16x16x32_bf16 v[10:13], v[226:229], v[218:221], v[10:13]
	v_mfma_f32_16x16x32_bf16 v[14:17], v[234:237], v[218:221], v[14:17]
	v_mfma_f32_16x16x32_bf16 v[58:61], v[230:233], v[182:185], v[58:61]
	v_mfma_f32_16x16x32_bf16 v[62:65], v[238:241], v[182:185], v[62:65]
	v_mfma_f32_16x16x32_bf16 v[42:45], v[230:233], v[202:205], v[42:45]
	v_mfma_f32_16x16x32_bf16 v[46:49], v[238:241], v[202:205], v[46:49]
	v_mfma_f32_16x16x32_bf16 v[26:29], v[230:233], v[214:217], v[26:29]
	v_mfma_f32_16x16x32_bf16 v[30:33], v[238:241], v[214:217], v[30:33]
	v_mfma_f32_16x16x32_bf16 v[10:13], v[230:233], v[222:225], v[10:13]
	v_mfma_f32_16x16x32_bf16 v[14:17], v[238:241], v[222:225], v[14:17]
	s_add_i32 s38, 0, 0x18000
	v_add_u32_e32 v142, s38, v197
	s_barrier
	ds_read_b128 v[130:133], v142
	ds_read_b128 v[134:137], v142 offset:1024
	ds_read_b128 v[138:141], v142 offset:2048
	ds_read_b128 v[142:145], v142 offset:3072
	s_add_u32 s26, s46, 0x40000
	s_addc_u32 s27, s47, 0
	s_mov_b32 m0, s81
	v_lshl_add_u64 v[226:227], s[26:27], 0, v[150:151]
	ds_read_b128 v[178:181], v201 offset:32768
	ds_read_b128 v[182:185], v201 offset:33792
	ds_read_b128 v[186:189], v201 offset:34816
	ds_read_b128 v[202:205], v201 offset:35840
	ds_read_b128 v[206:209], v201 offset:36864
	ds_read_b128 v[214:217], v201 offset:37888
	ds_read_b128 v[218:221], v201 offset:38912
	ds_read_b128 v[222:225], v201 offset:39936
	global_load_lds_dwordx4 v[226:227], off
	s_mov_b32 m0, s82
	v_lshl_add_u64 v[226:227], s[26:27], 0, v[148:149]
	global_load_lds_dwordx4 v[226:227], off
	s_waitcnt lgkmcnt(8)
	s_barrier
	s_waitcnt lgkmcnt(0)
	v_mfma_f32_16x16x32_bf16 v[126:129], v[130:133], v[178:181], v[126:129]
	v_mfma_f32_16x16x32_bf16 v[122:125], v[138:141], v[178:181], v[122:125]
	v_mfma_f32_16x16x32_bf16 v[110:113], v[130:133], v[186:189], v[110:113]
	v_mfma_f32_16x16x32_bf16 v[106:109], v[138:141], v[186:189], v[106:109]
	v_mfma_f32_16x16x32_bf16 v[94:97], v[130:133], v[206:209], v[94:97]
	v_mfma_f32_16x16x32_bf16 v[90:93], v[138:141], v[206:209], v[90:93]
	v_mfma_f32_16x16x32_bf16 v[78:81], v[130:133], v[218:221], v[78:81]
	v_mfma_f32_16x16x32_bf16 v[74:77], v[138:141], v[218:221], v[74:77]
	v_mfma_f32_16x16x32_bf16 v[126:129], v[134:137], v[182:185], v[126:129]
	v_mfma_f32_16x16x32_bf16 v[122:125], v[142:145], v[182:185], v[122:125]
	v_mfma_f32_16x16x32_bf16 v[110:113], v[134:137], v[202:205], v[110:113]
	v_mfma_f32_16x16x32_bf16 v[106:109], v[142:145], v[202:205], v[106:109]
	v_mfma_f32_16x16x32_bf16 v[94:97], v[134:137], v[214:217], v[94:97]
	v_mfma_f32_16x16x32_bf16 v[90:93], v[142:145], v[214:217], v[90:93]
	v_mfma_f32_16x16x32_bf16 v[78:81], v[134:137], v[222:225], v[78:81]
	v_mfma_f32_16x16x32_bf16 v[74:77], v[142:145], v[222:225], v[74:77]
	s_barrier
	s_add_i32 s39, 0, 0x1c000
	s_add_i32 s26, s38, s78
	v_add_u32_e32 v192, s39, v197
	v_lshl_add_u64 v[162:163], v[162:163], 0, s[70:71]
	s_mov_b32 m0, s26
	ds_read_b128 v[226:229], v192
	ds_read_b128 v[230:233], v192 offset:1024
	ds_read_b128 v[234:237], v192 offset:2048
	ds_read_b128 v[238:241], v192 offset:3072
	global_load_lds_dwordx4 v[162:163], off
	s_add_i32 m0, s26, 0x2000
	v_lshl_add_u64 v[162:163], v[164:165], 0, s[70:71]
	global_load_lds_dwordx4 v[162:163], off
	s_barrier
	s_waitcnt lgkmcnt(0)
	v_mfma_f32_16x16x32_bf16 v[118:121], v[226:229], v[178:181], v[118:121]
	v_mfma_f32_16x16x32_bf16 v[114:117], v[234:237], v[178:181], v[114:117]
	v_mfma_f32_16x16x32_bf16 v[102:105], v[226:229], v[186:189], v[102:105]
	v_mfma_f32_16x16x32_bf16 v[98:101], v[234:237], v[186:189], v[98:101]
	v_mfma_f32_16x16x32_bf16 v[86:89], v[226:229], v[206:209], v[86:89]
	v_mfma_f32_16x16x32_bf16 v[82:85], v[234:237], v[206:209], v[82:85]
	v_mfma_f32_16x16x32_bf16 v[70:73], v[226:229], v[218:221], v[70:73]
	v_mfma_f32_16x16x32_bf16 v[66:69], v[234:237], v[218:221], v[66:69]
	v_mfma_f32_16x16x32_bf16 v[118:121], v[230:233], v[182:185], v[118:121]
	v_mfma_f32_16x16x32_bf16 v[114:117], v[238:241], v[182:185], v[114:117]
	v_mfma_f32_16x16x32_bf16 v[102:105], v[230:233], v[202:205], v[102:105]
	v_mfma_f32_16x16x32_bf16 v[98:101], v[238:241], v[202:205], v[98:101]
	v_mfma_f32_16x16x32_bf16 v[86:89], v[230:233], v[214:217], v[86:89]
	v_mfma_f32_16x16x32_bf16 v[82:85], v[238:241], v[214:217], v[82:85]
	v_mfma_f32_16x16x32_bf16 v[70:73], v[230:233], v[222:225], v[70:73]
	v_mfma_f32_16x16x32_bf16 v[66:69], v[238:241], v[222:225], v[66:69]
	s_mov_b32 m0, s83
	v_lshl_add_u64 v[162:163], v[190:191], 0, s[70:71]
	s_barrier
	ds_read_b128 v[178:181], v201 offset:49152
	ds_read_b128 v[182:185], v201 offset:50176
	ds_read_b128 v[186:189], v201 offset:51200
	ds_read_b128 v[202:205], v201 offset:52224
	ds_read_b128 v[206:209], v201 offset:53248
	ds_read_b128 v[214:217], v201 offset:54272
	ds_read_b128 v[218:221], v201 offset:55296
	ds_read_b128 v[222:225], v201 offset:56320
	global_load_lds_dwordx4 v[162:163], off
	s_mov_b32 m0, s84
	v_lshl_add_u64 v[162:163], v[194:195], 0, s[70:71]
	global_load_lds_dwordx4 v[162:163], off
	s_barrier
; #define PG8_STAGE(bufoff, gbase, voff) do { _Pragma("unroll") for (int _i = 0; _i < 2; ++_i) \
;         __builtin_amdgcn_global_load_lds((const unsigned*)((const char*)(gbase) + (voff)[_i]), (LAS unsigned*)(lds + (bufoff) + ldsw + _i * 8192), 16, 0, 0); } while (0)
; #define PG8_MMA(ai, bj, At, Bt) do { __builtin_amdgcn_s_setprio(1); _Pragma("unroll") for (int m = 0; m < 4; ++m) _Pragma("unroll") for (int n = 0; n < 2; ++n) _Pragma("unroll") for (int k = 0; k < 2; ++k) \
;         acc[ai][bj][m][n] = __builtin_amdgcn_mfma_f32_16x16x32_bf16(Bt[n][k], At[m][k], acc[ai][bj][m][n], 0, 0, 0); __builtin_amdgcn_s_setprio(0); } while (0)
; #define PG8_WAIT_V(n) asm volatile("s_waitcnt vmcnt(" #n ")" ::: "memory")
; #define PG8_WAIT_L(n) asm volatile("s_waitcnt lgkmcnt(" #n ")" ::: "memory")
; #define PG8_BAR __builtin_amdgcn_s_barrier()
; #define PG8_SCHED __builtin_amdgcn_sched_barrier(0)
; template <class Epi>
; DEVI void gemm_phase(LAS unsigned char* lds, const Gemm g, const Epi& E) {
;     ...
;             PG8_BAR; PG8_WAIT_L(0); PG8_MMA(1, 0, At, B0); PG8_BAR; PG8_SCHED;
;             PG8_STAGE(PG8_SB(1, 1), b3 + hstepB, voffB);
;             PG8_WAIT_V(6); PG8_BAR; PG8_MMA(1, 1, At, B1); PG8_BAR;
;         }
;     ...
;             if constexpr (Epi::RS) { f32x4 q4[8];
; #pragma unroll
;                 for (int i = 0; i < 8; ++i) q4[i] = *(const f32x4*)(E.ssq_in + (size_t)(row0 + (i >> 2) * HALF + (i & 3) * 16) * 4);
; #pragma unroll
;                 for (int i = 0; i < 8; ++i) rsv[i] = rsqrtf((((q4[i][0] + q4[i][1]) + q4[i][2]) + q4[i][3]) * (1.f / DM) + 1e-6f); }
	s_waitcnt lgkmcnt(0)
	v_mfma_f32_16x16x32_bf16 v[50:53], v[130:133], v[178:181], v[50:53]
	v_mfma_f32_16x16x32_bf16 v[54:57], v[138:141], v[178:181], v[54:57]
	v_mfma_f32_16x16x32_bf16 v[34:37], v[130:133], v[186:189], v[34:37]
	v_mfma_f32_16x16x32_bf16 v[38:41], v[138:141], v[186:189], v[38:41]
	v_mfma_f32_16x16x32_bf16 v[18:21], v[130:133], v[206:209], v[18:21]
	v_mfma_f32_16x16x32_bf16 v[22:25], v[138:141], v[206:209], v[22:25]
	v_mfma_f32_16x16x32_bf16 v[0:3], v[130:133], v[218:221], v[0:3]
	v_mfma_f32_16x16x32_bf16 v[4:7], v[138:141], v[218:221], v[4:7]
	v_mfma_f32_16x16x32_bf16 v[50:53], v[134:137], v[182:185], v[50:53]
	v_mfma_f32_16x16x32_bf16 v[54:57], v[142:145], v[182:185], v[54:57]
	v_mfma_f32_16x16x32_bf16 v[34:37], v[134:137], v[202:205], v[34:37]
	v_mfma_f32_16x16x32_bf16 v[38:41], v[142:145], v[202:205], v[38:41]
	v_mfma_f32_16x16x32_bf16 v[18:21], v[134:137], v[214:217], v[18:21]
	v_mfma_f32_16x16x32_bf16 v[22:25], v[142:145], v[214:217], v[22:25]
	v_mfma_f32_16x16x32_bf16 v[0:3], v[134:137], v[222:225], v[0:3]
	v_mfma_f32_16x16x32_bf16 v[4:7], v[142:145], v[222:225], v[4:7]
	s_barrier
	s_add_u32 s26, s36, 0x40080
	s_addc_u32 s27, s37, 0
	s_add_i32 s36, s39, s78
	s_mov_b32 m0, s36
	v_lshl_add_u64 v[130:131], s[26:27], 0, v[8:9]
	global_load_lds_dwordx4 v[130:131], off
	s_add_i32 m0, s36, 0x2000
	v_lshl_add_u64 v[130:131], s[26:27], 0, v[146:147]
	global_load_lds_dwordx4 v[130:131], off
	s_waitcnt vmcnt(6)
	s_barrier
	v_mfma_f32_16x16x32_bf16 v[58:61], v[226:229], v[178:181], v[58:61]
	v_mfma_f32_16x16x32_bf16 v[62:65], v[234:237], v[178:181], v[62:65]
	v_mfma_f32_16x16x32_bf16 v[42:45], v[226:229], v[186:189], v[42:45]
	v_mfma_f32_16x16x32_bf16 v[46:49], v[234:237], v[186:189], v[46:49]
	v_mfma_f32_16x16x32_bf16 v[26:29], v[226:229], v[206:209], v[26:29]
	v_mfma_f32_16x16x32_bf16 v[30:33], v[234:237], v[206:209], v[30:33]
	v_mfma_f32_16x16x32_bf16 v[10:13], v[226:229], v[218:221], v[10:13]
	v_mfma_f32_16x16x32_bf16 v[14:17], v[234:237], v[218:221], v[14:17]
	v_mfma_f32_16x16x32_bf16 v[58:61], v[230:233], v[182:185], v[58:61]
	v_mfma_f32_16x16x32_bf16 v[62:65], v[238:241], v[182:185], v[62:65]
	v_mfma_f32_16x16x32_bf16 v[42:45], v[230:233], v[202:205], v[42:45]
	v_mfma_f32_16x16x32_bf16 v[46:49], v[238:241], v[202:205], v[46:49]
	v_mfma_f32_16x16x32_bf16 v[26:29], v[230:233], v[214:217], v[26:29]
	v_mfma_f32_16x16x32_bf16 v[30:33], v[238:241], v[214:217], v[30:33]
	v_mfma_f32_16x16x32_bf16 v[10:13], v[230:233], v[222:225], v[10:13]
	v_mfma_f32_16x16x32_bf16 v[14:17], v[238:241], v[222:225], v[14:17]
	s_add_i32 s19, s19, 2
	s_add_u32 s16, s16, 0x100
	s_addc_u32 s17, s17, 0
	s_add_u32 s9, s9, 0x100
	s_addc_u32 s18, s18, 0
	s_cmp_gt_u32 s19, 13
	s_barrier
	s_cbranch_scc0 .LBB0_1672
	s_setprio 0
	v_lshl_add_u32 v194, s4, 8, v193
	v_add_u32_e32 v178, 0xb0, v194
	v_ashrrev_i32_e32 v195, 31, v194
	v_or_b32_e32 v190, 16, v194
	v_ashrrev_i32_e32 v179, 31, v178
	v_lshl_add_u64 v[130:131], v[194:195], 4, s[10:11]
	v_ashrrev_i32_e32 v191, 31, v190
	v_lshl_add_u64 v[134:135], v[178:179], 4, s[10:11]
	global_load_dwordx4 v[202:205], v[130:131], off
	v_or_b32_e32 v188, 32, v194
	global_load_dwordx4 v[134:137], v[134:135], off
	v_lshl_add_u64 v[130:131], v[190:191], 4, s[10:11]
	global_load_dwordx4 v[206:209], v[130:131], off
	v_ashrrev_i32_e32 v189, 31, v188
	v_or_b32_e32 v186, 48, v194
	v_lshl_add_u64 v[130:131], v[188:189], 4, s[10:11]
	v_ashrrev_i32_e32 v187, 31, v186
	global_load_dwordx4 v[214:217], v[130:131], off
	v_lshl_add_u64 v[130:131], v[186:187], 4, s[10:11]
	global_load_dwordx4 v[218:221], v[130:131], off
	v_add_u32_e32 v184, 0x80, v194
	v_ashrrev_i32_e32 v185, 31, v184
	v_add_u32_e32 v182, 0x90, v194
	v_lshl_add_u64 v[130:131], v[184:185], 4, s[10:11]
	v_ashrrev_i32_e32 v183, 31, v182
	global_load_dwordx4 v[138:141], v[130:131], off
	v_lshl_add_u64 v[130:131], v[182:183], 4, s[10:11]
	v_add_u32_e32 v180, 0xa0, v194
	global_load_dwordx4 v[142:145], v[130:131], off
	v_ashrrev_i32_e32 v181, 31, v180
	v_lshl_add_u64 v[130:131], v[180:181], 4, s[10:11]
	global_load_dwordx4 v[130:133], v[130:131], off
	s_mov_b32 s0, 0x358637bd
	s_mov_b64 s[36:37], s[14:15]
	s_mov_b64 s[16:17], s[12:13]
	s_waitcnt vmcnt(0)
	v_mov_b32_e32 v163, v202
	v_mov_b32_e32 v165, v204
	v_mov_b32_e32 v162, v206
	v_mov_b32_e32 v202, v207
	v_pk_add_f32 v[162:163], v[162:163], v[202:203]
	v_mov_b32_e32 v164, v208
	v_pk_add_f32 v[162:163], v[164:165], v[162:163]
	v_mov_b32_e32 v204, v209
	v_pk_add_f32 v[162:163], v[204:205], v[162:163]
	v_mov_b64_e32 v[202:203], s[0:1]
	v_pk_fma_f32 v[162:163], v[162:163], s[72:73], v[202:203] op_sel_hi:[1,0,0]
	v_mov_b32_e32 v165, v216
	v_mul_f32_e32 v164, 0x4b800000, v163
	v_cmp_gt_f32_e64 s[4:5], s94, v163
	v_cmp_gt_f32_e32 vcc, s94, v162
	v_mov_b32_e32 v216, v221
	v_cndmask_b32_e64 v163, v163, v164, s[4:5]
	v_rsq_f32_e32 v163, v163
	s_nop 0
	v_mul_f32_e32 v164, 0x45800000, v163
	v_cndmask_b32_e64 v200, v163, v164, s[4:5]
	v_mul_f32_e32 v163, 0x4b800000, v162
	v_cndmask_b32_e32 v162, v162, v163, vcc
	v_rsq_f32_e32 v162, v162
	v_mov_b32_e32 v164, v220
	v_pk_mul_f32 v[126:127], v[126:127], v[200:201] op_sel_hi:[1,0]
	v_pk_mul_f32 v[122:123], v[122:123], v[200:201] op_sel_hi:[1,0]
	v_mul_f32_e32 v163, 0x45800000, v162
	v_cndmask_b32_e32 v198, v162, v163, vcc
	v_mov_b32_e32 v162, v218
	v_mov_b32_e32 v163, v214
	v_mov_b32_e32 v214, v219
	v_pk_add_f32 v[162:163], v[162:163], v[214:215]
	v_pk_mul_f32 v[118:119], v[118:119], v[200:201] op_sel_hi:[1,0]
	v_pk_add_f32 v[162:163], v[164:165], v[162:163]
	v_pk_mul_f32 v[124:125], v[124:125], v[200:201] op_sel_hi:[1,0]
	v_pk_add_f32 v[162:163], v[216:217], v[162:163]
; template <class Epi>
; DEVI void gemm_phase(LAS unsigned char* lds, const Gemm g, const Epi& E) {
;     ...
;                     if constexpr (Epi::RS) rs = rsv[ai * 4 + m];
;                     if constexpr (Epi::PAIR) E.pair8(cur.b, r, cur.pn * HALF + wc * 32 + 8 * fq, acc[ai][0][m][0] * rs, acc[ai][0][m][1] * rs, acc[ai][1][m][0] * rs, acc[ai][1][m][1] * rs);
	v_pk_mul_f32 v[114:115], v[114:115], v[200:201] op_sel_hi:[1,0]
	v_pk_fma_f32 v[162:163], v[162:163], s[72:73], v[202:203] op_sel_hi:[1,0,0]
	v_pk_mul_f32 v[128:129], v[128:129], v[200:201] op_sel_hi:[1,0]
	v_mul_f32_e32 v164, 0x4b800000, v163
	v_cmp_gt_f32_e64 s[4:5], s94, v163
	v_cmp_gt_f32_e32 vcc, s94, v162
	v_pk_mul_f32 v[120:121], v[120:121], v[200:201] op_sel_hi:[1,0]
	v_cndmask_b32_e64 v163, v163, v164, s[4:5]
	v_rsq_f32_e32 v163, v163
	v_pk_mul_f32 v[116:117], v[116:117], v[200:201] op_sel_hi:[1,0]
	v_pk_mul_f32 v[106:107], v[106:107], v[198:199] op_sel_hi:[1,0]
	v_pk_mul_f32 v[110:111], v[110:111], v[198:199] op_sel_hi:[1,0]
	v_mul_f32_e32 v164, 0x45800000, v163
	v_cndmask_b32_e64 v196, v163, v164, s[4:5]
	v_mul_f32_e32 v163, 0x4b800000, v162
	v_cndmask_b32_e32 v162, v162, v163, vcc
	v_rsq_f32_e32 v162, v162
	v_pk_mul_f32 v[102:103], v[102:103], v[198:199] op_sel_hi:[1,0]
	v_pk_mul_f32 v[108:109], v[108:109], v[198:199] op_sel_hi:[1,0]
	v_pk_mul_f32 v[98:99], v[98:99], v[198:199] op_sel_hi:[1,0]
	v_mul_f32_e32 v163, 0x45800000, v162
	v_cndmask_b32_e32 v192, v162, v163, vcc
	v_mov_b32_e32 v162, v142
	v_mov_b32_e32 v163, v138
	v_mov_b32_e32 v138, v143
	v_pk_add_f32 v[138:139], v[162:163], v[138:139]
	v_mov_b32_e32 v142, v144
	v_mov_b32_e32 v143, v140
	v_pk_add_f32 v[138:139], v[142:143], v[138:139]
	v_mov_b32_e32 v142, v134
	v_mov_b32_e32 v143, v130
	v_mov_b32_e32 v130, v135
	v_pk_add_f32 v[130:131], v[142:143], v[130:131]
	v_mov_b32_e32 v134, v136
	v_mov_b32_e32 v135, v132
	v_pk_add_f32 v[130:131], v[134:135], v[130:131]
	v_mov_b32_e32 v132, v137
	v_pk_add_f32 v[130:131], v[132:133], v[130:131]
	v_mul_f32_e32 v133, 0xbfb8aa3b, v126
	v_exp_f32_e32 v133, v133
	v_mov_b32_e32 v140, v145
	v_pk_add_f32 v[138:139], v[140:141], v[138:139]
	v_pk_fma_f32 v[130:131], v[130:131], s[72:73], v[202:203] op_sel_hi:[1,0,0]
	v_add_f32_e32 v133, 1.0, v133
	v_rcp_f32_e32 v136, v133
	v_mul_f32_e32 v133, 0xbfb8aa3b, v122
	v_exp_f32_e32 v133, v133
	v_pk_fma_f32 v[138:139], v[138:139], s[72:73], v[202:203] op_sel_hi:[1,0,0]
	v_mul_f32_e32 v132, 0x4b800000, v131
	v_mul_f32_e32 v140, 0x4b800000, v139
	v_add_f32_e32 v133, 1.0, v133
	v_rcp_f32_e32 v142, v133
	v_mul_f32_e32 v133, 0xbfb8aa3b, v127
	v_exp_f32_e32 v133, v133
	v_cmp_gt_f32_e64 s[4:5], s94, v139
	v_cmp_gt_f32_e32 vcc, s94, v138
	v_pk_mul_f32 v[112:113], v[112:113], v[198:199] op_sel_hi:[1,0]
	v_add_f32_e32 v133, 1.0, v133
	v_rcp_f32_e32 v137, v133
	v_cndmask_b32_e64 v139, v139, v140, s[4:5]
	v_rsq_f32_e32 v139, v139
	v_pk_mul_f32 v[104:105], v[104:105], v[198:199] op_sel_hi:[1,0]
	v_pk_mul_f32 v[126:127], v[126:127], v[136:137]
	v_pk_mul_f32 v[100:101], v[100:101], v[198:199] op_sel_hi:[1,0]
	v_pk_mul_f32 v[118:119], v[118:119], v[126:127]
	v_mul_f32_e32 v126, 0xbfb8aa3b, v123
	v_exp_f32_e32 v126, v126
	v_mul_f32_e32 v140, 0x45800000, v139
	v_cndmask_b32_e64 v140, v139, v140, s[4:5]
	v_mul_f32_e32 v139, 0x4b800000, v138
	v_add_f32_e32 v126, 1.0, v126
	v_rcp_f32_e32 v143, v126
	v_cmp_gt_f32_e64 s[4:5], s94, v131
	v_cndmask_b32_e32 v138, v138, v139, vcc
	v_rsq_f32_e32 v138, v138
	v_pk_mul_f32 v[122:123], v[122:123], v[142:143]
	v_cndmask_b32_e64 v131, v131, v132, s[4:5]
	v_pk_mul_f32 v[122:123], v[114:115], v[122:123]
	v_mul_f32_e32 v115, 0xbfb8aa3b, v124
	v_exp_f32_e32 v115, v115
	v_mul_f32_e32 v114, 0xbfb8aa3b, v128
	v_exp_f32_e32 v114, v114
	v_rsq_f32_e32 v131, v131
	v_add_f32_e32 v115, 1.0, v115
	v_rcp_f32_e32 v126, v115
	v_mul_f32_e32 v115, 0xbfb8aa3b, v129
	v_exp_f32_e32 v115, v115
	v_add_f32_e32 v114, 1.0, v114
	v_rcp_f32_e32 v114, v114
	v_mul_f32_e32 v139, 0x45800000, v138
	v_add_f32_e32 v115, 1.0, v115
	v_rcp_f32_e32 v115, v115
	v_mul_f32_e32 v132, 0x45800000, v131
	v_cndmask_b32_e32 v138, v138, v139, vcc
	v_cmp_gt_f32_e32 vcc, s94, v130
	v_pk_mul_f32 v[114:115], v[128:129], v[114:115]
	v_cndmask_b32_e64 v134, v131, v132, s[4:5]
	v_pk_mul_f32 v[120:121], v[120:121], v[114:115]
	v_mul_f32_e32 v114, 0xbfb8aa3b, v125
	v_exp_f32_e32 v114, v114
	v_mul_f32_e32 v131, 0x4b800000, v130
	v_cndmask_b32_e32 v130, v130, v131, vcc
	v_rsq_f32_e32 v130, v130
	v_add_f32_e32 v114, 1.0, v114
	v_rcp_f32_e32 v127, v114
	v_pk_mul_f32 v[90:91], v[90:91], v[196:197] op_sel_hi:[1,0]
	v_mul_f32_e32 v131, 0x45800000, v130
	v_cndmask_b32_e32 v132, v130, v131, vcc
	v_lshl_or_b32 v130, s86, 7, v199
	v_ashrrev_i32_e32 v131, 31, v130
	v_pk_mul_f32 v[114:115], v[124:125], v[126:127]
	v_lshl_add_u64 v[130:131], v[130:131], 1, s[28:29]
	v_pk_mul_f32 v[124:125], v[116:117], v[114:115]
	v_cvt_pk_bf16_f32 v114, v118, v119
	v_cvt_pk_bf16_f32 v115, v120, v121
	v_cvt_pk_bf16_f32 v116, v122, v123
	v_cvt_pk_bf16_f32 v117, v124, v125
	v_mad_i64_i32 v[118:119], s[0:1], v194, s35, v[130:131]
	global_store_dwordx4 v[118:119], v[114:117], off
	v_pk_mul_f32 v[94:95], v[94:95], v[196:197] op_sel_hi:[1,0]
	v_pk_mul_f32 v[86:87], v[86:87], v[196:197] op_sel_hi:[1,0]
	v_mul_f32_e32 v115, 0xbfb8aa3b, v106
	v_exp_f32_e32 v115, v115
	v_mul_f32_e32 v114, 0xbfb8aa3b, v110
	v_exp_f32_e32 v114, v114
	v_pk_mul_f32 v[92:93], v[92:93], v[196:197] op_sel_hi:[1,0]
	v_add_f32_e32 v115, 1.0, v115
	v_rcp_f32_e32 v116, v115
	v_mul_f32_e32 v115, 0xbfb8aa3b, v111
	v_exp_f32_e32 v115, v115
	v_add_f32_e32 v114, 1.0, v114
	v_rcp_f32_e32 v114, v114
	v_pk_mul_f32 v[82:83], v[82:83], v[196:197] op_sel_hi:[1,0]
	v_add_f32_e32 v115, 1.0, v115
	v_rcp_f32_e32 v115, v115
	v_pk_mul_f32 v[96:97], v[96:97], v[196:197] op_sel_hi:[1,0]
	v_pk_mul_f32 v[88:89], v[88:89], v[196:197] op_sel_hi:[1,0]
	v_pk_mul_f32 v[84:85], v[84:85], v[196:197] op_sel_hi:[1,0]
	v_pk_mul_f32 v[110:111], v[110:111], v[114:115]
	v_pk_mul_f32 v[74:75], v[74:75], v[192:193] op_sel_hi:[1,0]
; template <class Epi>
; DEVI void gemm_phase(LAS unsigned char* lds, const Gemm g, const Epi& E) {
;     ...
;                     if constexpr (Epi::RS) rs = rsv[ai * 4 + m];
;                     if constexpr (Epi::PAIR) E.pair8(cur.b, r, cur.pn * HALF + wc * 32 + 8 * fq, acc[ai][0][m][0] * rs, acc[ai][0][m][1] * rs, acc[ai][1][m][0] * rs, acc[ai][1][m][1] * rs);
	v_pk_mul_f32 v[102:103], v[102:103], v[110:111]
	v_mul_f32_e32 v110, 0xbfb8aa3b, v107
	v_exp_f32_e32 v110, v110
	v_pk_mul_f32 v[78:79], v[78:79], v[192:193] op_sel_hi:[1,0]
	v_pk_mul_f32 v[70:71], v[70:71], v[192:193] op_sel_hi:[1,0]
	v_pk_mul_f32 v[76:77], v[76:77], v[192:193] op_sel_hi:[1,0]
	v_add_f32_e32 v110, 1.0, v110
	v_rcp_f32_e32 v117, v110
	v_pk_mul_f32 v[66:67], v[66:67], v[192:193] op_sel_hi:[1,0]
	v_pk_mul_f32 v[80:81], v[80:81], v[192:193] op_sel_hi:[1,0]
	v_pk_mul_f32 v[72:73], v[72:73], v[192:193] op_sel_hi:[1,0]
	v_pk_mul_f32 v[106:107], v[106:107], v[116:117]
	v_pk_mul_f32 v[68:69], v[68:69], v[192:193] op_sel_hi:[1,0]
	v_pk_mul_f32 v[106:107], v[98:99], v[106:107]
	v_mul_f32_e32 v99, 0xbfb8aa3b, v108
	v_exp_f32_e32 v99, v99
	v_mul_f32_e32 v98, 0xbfb8aa3b, v112
	v_exp_f32_e32 v98, v98
	v_pk_mul_f32 v[54:55], v[54:55], v[140:141] op_sel_hi:[1,0]
	v_add_f32_e32 v99, 1.0, v99
	v_rcp_f32_e32 v110, v99
	v_mul_f32_e32 v99, 0xbfb8aa3b, v113
	v_exp_f32_e32 v99, v99
	v_add_f32_e32 v98, 1.0, v98
	v_rcp_f32_e32 v98, v98
	v_pk_mul_f32 v[50:51], v[50:51], v[140:141] op_sel_hi:[1,0]
	v_add_f32_e32 v99, 1.0, v99
	v_rcp_f32_e32 v99, v99
	v_pk_mul_f32 v[58:59], v[58:59], v[140:141] op_sel_hi:[1,0]
	v_pk_mul_f32 v[56:57], v[56:57], v[140:141] op_sel_hi:[1,0]
	v_pk_mul_f32 v[52:53], v[52:53], v[140:141] op_sel_hi:[1,0]
	v_pk_mul_f32 v[98:99], v[112:113], v[98:99]
	v_pk_mul_f32 v[62:63], v[62:63], v[140:141] op_sel_hi:[1,0]
	v_pk_mul_f32 v[104:105], v[104:105], v[98:99]
	v_mul_f32_e32 v98, 0xbfb8aa3b, v109
	v_exp_f32_e32 v98, v98
	v_pk_mul_f32 v[60:61], v[60:61], v[140:141] op_sel_hi:[1,0]
	v_pk_mul_f32 v[64:65], v[64:65], v[140:141] op_sel_hi:[1,0]
	v_pk_mul_f32 v[38:39], v[38:39], v[138:139] op_sel_hi:[1,0]
	v_add_f32_e32 v98, 1.0, v98
	v_rcp_f32_e32 v111, v98
	v_pk_mul_f32 v[34:35], v[34:35], v[138:139] op_sel_hi:[1,0]
	v_pk_mul_f32 v[42:43], v[42:43], v[138:139] op_sel_hi:[1,0]
	v_pk_mul_f32 v[40:41], v[40:41], v[138:139] op_sel_hi:[1,0]
	v_pk_mul_f32 v[98:99], v[108:109], v[110:111]
	v_pk_mul_f32 v[36:37], v[36:37], v[138:139] op_sel_hi:[1,0]
	v_pk_mul_f32 v[108:109], v[100:101], v[98:99]
	v_cvt_pk_bf16_f32 v98, v102, v103
	v_cvt_pk_bf16_f32 v99, v104, v105
	v_cvt_pk_bf16_f32 v100, v106, v107
	v_cvt_pk_bf16_f32 v101, v108, v109
	v_mad_i64_i32 v[102:103], s[0:1], v190, s35, v[130:131]
	global_store_dwordx4 v[102:103], v[98:101], off
	v_pk_mul_f32 v[46:47], v[46:47], v[138:139] op_sel_hi:[1,0]
	v_pk_mul_f32 v[44:45], v[44:45], v[138:139] op_sel_hi:[1,0]
	v_mul_f32_e32 v99, 0xbfb8aa3b, v90
	v_exp_f32_e32 v99, v99
	v_mul_f32_e32 v98, 0xbfb8aa3b, v94
	v_exp_f32_e32 v98, v98
	v_pk_mul_f32 v[48:49], v[48:49], v[138:139] op_sel_hi:[1,0]
	v_add_f32_e32 v99, 1.0, v99
	v_rcp_f32_e32 v100, v99
	v_mul_f32_e32 v99, 0xbfb8aa3b, v95
	v_exp_f32_e32 v99, v99
	v_add_f32_e32 v98, 1.0, v98
	v_rcp_f32_e32 v98, v98
	v_pk_mul_f32 v[22:23], v[22:23], v[134:135] op_sel_hi:[1,0]
	v_add_f32_e32 v99, 1.0, v99
	v_rcp_f32_e32 v99, v99
	v_pk_mul_f32 v[18:19], v[18:19], v[134:135] op_sel_hi:[1,0]
	v_pk_mul_f32 v[26:27], v[26:27], v[134:135] op_sel_hi:[1,0]
	v_pk_mul_f32 v[24:25], v[24:25], v[134:135] op_sel_hi:[1,0]
	v_pk_mul_f32 v[94:95], v[94:95], v[98:99]
	v_pk_mul_f32 v[20:21], v[20:21], v[134:135] op_sel_hi:[1,0]
	v_pk_mul_f32 v[86:87], v[86:87], v[94:95]
	v_mul_f32_e32 v94, 0xbfb8aa3b, v91
	v_exp_f32_e32 v94, v94
	v_pk_mul_f32 v[30:31], v[30:31], v[134:135] op_sel_hi:[1,0]
	v_pk_mul_f32 v[28:29], v[28:29], v[134:135] op_sel_hi:[1,0]
	v_pk_mul_f32 v[32:33], v[32:33], v[134:135] op_sel_hi:[1,0]
	v_add_f32_e32 v94, 1.0, v94
	v_rcp_f32_e32 v101, v94
	v_pk_mul_f32 v[4:5], v[4:5], v[132:133] op_sel_hi:[1,0]
	v_pk_mul_f32 v[0:1], v[0:1], v[132:133] op_sel_hi:[1,0]
	v_pk_mul_f32 v[10:11], v[10:11], v[132:133] op_sel_hi:[1,0]
	v_pk_mul_f32 v[90:91], v[90:91], v[100:101]
	v_pk_mul_f32 v[6:7], v[6:7], v[132:133] op_sel_hi:[1,0]
	v_pk_mul_f32 v[90:91], v[82:83], v[90:91]
	v_mul_f32_e32 v83, 0xbfb8aa3b, v92
	v_exp_f32_e32 v83, v83
	v_mul_f32_e32 v82, 0xbfb8aa3b, v96
	v_exp_f32_e32 v82, v82
	v_pk_mul_f32 v[2:3], v[2:3], v[132:133] op_sel_hi:[1,0]
	v_add_f32_e32 v83, 1.0, v83
	v_rcp_f32_e32 v94, v83
	v_mul_f32_e32 v83, 0xbfb8aa3b, v97
	v_exp_f32_e32 v83, v83
	v_add_f32_e32 v82, 1.0, v82
	v_rcp_f32_e32 v82, v82
	v_pk_mul_f32 v[14:15], v[14:15], v[132:133] op_sel_hi:[1,0]
	v_add_f32_e32 v83, 1.0, v83
	v_rcp_f32_e32 v83, v83
	v_pk_mul_f32 v[12:13], v[12:13], v[132:133] op_sel_hi:[1,0]
	v_pk_mul_f32 v[16:17], v[16:17], v[132:133] op_sel_hi:[1,0]
	s_and_b64 vcc, exec, s[2:3]
	v_pk_mul_f32 v[82:83], v[96:97], v[82:83]
	s_mov_b32 s86, s8
	v_pk_mul_f32 v[88:89], v[88:89], v[82:83]
	v_mul_f32_e32 v82, 0xbfb8aa3b, v93
	v_exp_f32_e32 v82, v82
	s_mov_b32 s4, s6
	v_add_f32_e32 v82, 1.0, v82
	v_rcp_f32_e32 v95, v82
	s_nop 0
	v_pk_mul_f32 v[82:83], v[92:93], v[94:95]
	s_nop 0
	v_pk_mul_f32 v[92:93], v[84:85], v[82:83]
	v_cvt_pk_bf16_f32 v82, v86, v87
	v_cvt_pk_bf16_f32 v83, v88, v89
	v_cvt_pk_bf16_f32 v84, v90, v91
	v_cvt_pk_bf16_f32 v85, v92, v93
	v_mad_i64_i32 v[86:87], s[0:1], v188, s35, v[130:131]
	global_store_dwordx4 v[86:87], v[82:85], off
	s_nop 1
	v_mul_f32_e32 v83, 0xbfb8aa3b, v74
	v_exp_f32_e32 v83, v83
	v_mul_f32_e32 v82, 0xbfb8aa3b, v78
	v_exp_f32_e32 v82, v82
	v_add_f32_e32 v83, 1.0, v83
	v_rcp_f32_e32 v84, v83
	v_mul_f32_e32 v83, 0xbfb8aa3b, v79
	v_exp_f32_e32 v83, v83
	v_add_f32_e32 v82, 1.0, v82
	v_rcp_f32_e32 v82, v82
	v_add_f32_e32 v83, 1.0, v83
	v_rcp_f32_e32 v83, v83
	s_nop 0
	v_pk_mul_f32 v[78:79], v[78:79], v[82:83]
	s_nop 0
	v_pk_mul_f32 v[70:71], v[70:71], v[78:79]
	v_mul_f32_e32 v78, 0xbfb8aa3b, v75
	v_exp_f32_e32 v78, v78
	s_nop 0
	v_add_f32_e32 v78, 1.0, v78
	v_rcp_f32_e32 v85, v78
	s_nop 0
	v_pk_mul_f32 v[74:75], v[74:75], v[84:85]
	s_nop 0
	v_pk_mul_f32 v[74:75], v[66:67], v[74:75]
	v_mul_f32_e32 v67, 0xbfb8aa3b, v76
	v_exp_f32_e32 v67, v67
	v_mul_f32_e32 v66, 0xbfb8aa3b, v80
	v_exp_f32_e32 v66, v66
	v_add_f32_e32 v67, 1.0, v67
	v_rcp_f32_e32 v78, v67
	v_mul_f32_e32 v67, 0xbfb8aa3b, v81
	v_exp_f32_e32 v67, v67
	v_add_f32_e32 v66, 1.0, v66
	v_rcp_f32_e32 v66, v66
	v_add_f32_e32 v67, 1.0, v67
	v_rcp_f32_e32 v67, v67
	s_nop 0
	v_pk_mul_f32 v[66:67], v[80:81], v[66:67]
	s_nop 0
	v_pk_mul_f32 v[72:73], v[72:73], v[66:67]
	v_mul_f32_e32 v66, 0xbfb8aa3b, v77
	v_exp_f32_e32 v66, v66
	s_nop 0
	v_add_f32_e32 v66, 1.0, v66
	v_rcp_f32_e32 v79, v66
	s_nop 0
	v_pk_mul_f32 v[66:67], v[76:77], v[78:79]
	s_nop 0
	v_pk_mul_f32 v[76:77], v[68:69], v[66:67]
	v_cvt_pk_bf16_f32 v66, v70, v71
	v_cvt_pk_bf16_f32 v67, v72, v73
	v_cvt_pk_bf16_f32 v68, v74, v75
	v_cvt_pk_bf16_f32 v69, v76, v77
	v_mad_i64_i32 v[70:71], s[0:1], v186, s35, v[130:131]
	global_store_dwordx4 v[70:71], v[66:69], off
	s_nop 1
	v_mul_f32_e32 v67, 0xbfb8aa3b, v54
	v_exp_f32_e32 v67, v67
	v_mul_f32_e32 v66, 0xbfb8aa3b, v50
	v_exp_f32_e32 v66, v66
	v_add_f32_e32 v67, 1.0, v67
	v_rcp_f32_e32 v68, v67
	v_mul_f32_e32 v67, 0xbfb8aa3b, v51
	v_exp_f32_e32 v67, v67
	v_add_f32_e32 v66, 1.0, v66
	v_rcp_f32_e32 v66, v66
	v_add_f32_e32 v67, 1.0, v67
	v_rcp_f32_e32 v67, v67
	s_nop 0
	v_pk_mul_f32 v[50:51], v[50:51], v[66:67]
	s_nop 0
	v_pk_mul_f32 v[50:51], v[58:59], v[50:51]
	v_mul_f32_e32 v58, 0xbfb8aa3b, v55
	v_exp_f32_e32 v58, v58
	v_mul_f32_e32 v59, 0xbfb8aa3b, v56
	v_exp_f32_e32 v59, v59
	v_cvt_pk_bf16_f32 v50, v50, v51
	v_add_f32_e32 v58, 1.0, v58
	v_rcp_f32_e32 v69, v58
	v_add_f32_e32 v59, 1.0, v59
	v_mul_f32_e32 v58, 0xbfb8aa3b, v52
	v_exp_f32_e32 v58, v58
	v_pk_mul_f32 v[54:55], v[54:55], v[68:69]
	v_add_f32_e32 v58, 1.0, v58
	v_pk_mul_f32 v[54:55], v[62:63], v[54:55]
	v_rcp_f32_e32 v62, v59
	v_mul_f32_e32 v59, 0xbfb8aa3b, v53
	v_exp_f32_e32 v59, v59
	v_rcp_f32_e32 v58, v58
	v_add_f32_e32 v59, 1.0, v59
	v_rcp_f32_e32 v59, v59
	s_nop 0
	v_pk_mul_f32 v[52:53], v[52:53], v[58:59]
	v_mul_f32_e32 v58, 0xbfb8aa3b, v57
	v_exp_f32_e32 v58, v58
	v_pk_mul_f32 v[52:53], v[60:61], v[52:53]
	v_add_f32_e32 v58, 1.0, v58
	v_rcp_f32_e32 v63, v58
	v_cvt_pk_bf16_f32 v51, v52, v53
	v_cvt_pk_bf16_f32 v52, v54, v55
	v_mad_i64_i32 v[54:55], s[0:1], v184, s35, v[130:131]
	v_pk_mul_f32 v[56:57], v[56:57], v[62:63]
	s_nop 0
	v_pk_mul_f32 v[56:57], v[64:65], v[56:57]
	s_nop 0
	v_cvt_pk_bf16_f32 v53, v56, v57
	global_store_dwordx4 v[54:55], v[50:53], off
	s_nop 1
	v_mul_f32_e32 v51, 0xbfb8aa3b, v38
	v_exp_f32_e32 v51, v51
	v_mul_f32_e32 v50, 0xbfb8aa3b, v34
	v_exp_f32_e32 v50, v50
	v_add_f32_e32 v51, 1.0, v51
	v_rcp_f32_e32 v52, v51
	v_mul_f32_e32 v51, 0xbfb8aa3b, v35
	v_exp_f32_e32 v51, v51
	v_add_f32_e32 v50, 1.0, v50
	v_rcp_f32_e32 v50, v50
	v_add_f32_e32 v51, 1.0, v51
	v_rcp_f32_e32 v51, v51
	s_nop 0
	v_pk_mul_f32 v[34:35], v[34:35], v[50:51]
	s_nop 0
	v_pk_mul_f32 v[34:35], v[42:43], v[34:35]
	v_mul_f32_e32 v42, 0xbfb8aa3b, v39
	v_exp_f32_e32 v42, v42
	v_mul_f32_e32 v43, 0xbfb8aa3b, v40
	v_exp_f32_e32 v43, v43
	v_cvt_pk_bf16_f32 v34, v34, v35
	v_add_f32_e32 v42, 1.0, v42
	v_rcp_f32_e32 v53, v42
	v_add_f32_e32 v43, 1.0, v43
	v_mul_f32_e32 v42, 0xbfb8aa3b, v36
	v_exp_f32_e32 v42, v42
	v_pk_mul_f32 v[38:39], v[38:39], v[52:53]
	v_add_f32_e32 v42, 1.0, v42
	v_pk_mul_f32 v[38:39], v[46:47], v[38:39]
	v_rcp_f32_e32 v46, v43
	v_mul_f32_e32 v43, 0xbfb8aa3b, v37
	v_exp_f32_e32 v43, v43
	v_rcp_f32_e32 v42, v42
	v_add_f32_e32 v43, 1.0, v43
	v_rcp_f32_e32 v43, v43
	s_nop 0
; #define PG8_WAIT_V(n) asm volatile("s_waitcnt vmcnt(" #n ")" ::: "memory")
; #define PG8_BAR __builtin_amdgcn_s_barrier()
; template <class Epi>
; DEVI void gemm_phase(LAS unsigned char* lds, const Gemm g, const Epi& E) {
;     ...
;         if (!has_next) break;
; #pragma unroll
;         for (int a = 0; a < 2; ++a)
; #pragma unroll
;             for (int b = 0; b < 2; ++b)
; #pragma unroll
;                 for (int m = 0; m < 4; ++m)
; #pragma unroll
;                     for (int n = 0; n < 2; ++n) acc[a][b][m][n] = (f32x4){0.f, 0.f, 0.f, 0.f};
;         cur = nxt; cA = nA; cB = nB; ++ui;
;     }
;     PG8_WAIT_V(0);
;     if (wr == 0) PG8_BAR;
;     PG8_BAR;
	v_pk_mul_f32 v[36:37], v[36:37], v[42:43]
	v_mul_f32_e32 v42, 0xbfb8aa3b, v41
	v_exp_f32_e32 v42, v42
	v_pk_mul_f32 v[36:37], v[44:45], v[36:37]
	v_add_f32_e32 v42, 1.0, v42
	v_rcp_f32_e32 v47, v42
	v_cvt_pk_bf16_f32 v35, v36, v37
	v_cvt_pk_bf16_f32 v36, v38, v39
	v_mad_i64_i32 v[38:39], s[0:1], v182, s35, v[130:131]
	v_pk_mul_f32 v[40:41], v[40:41], v[46:47]
	s_nop 0
	v_pk_mul_f32 v[40:41], v[48:49], v[40:41]
	s_nop 0
	v_cvt_pk_bf16_f32 v37, v40, v41
	global_store_dwordx4 v[38:39], v[34:37], off
	s_nop 1
	v_mul_f32_e32 v35, 0xbfb8aa3b, v22
	v_exp_f32_e32 v35, v35
	v_mul_f32_e32 v34, 0xbfb8aa3b, v18
	v_exp_f32_e32 v34, v34
	v_add_f32_e32 v35, 1.0, v35
	v_rcp_f32_e32 v36, v35
	v_mul_f32_e32 v35, 0xbfb8aa3b, v19
	v_exp_f32_e32 v35, v35
	v_add_f32_e32 v34, 1.0, v34
	v_rcp_f32_e32 v34, v34
	v_add_f32_e32 v35, 1.0, v35
	v_rcp_f32_e32 v35, v35
	s_nop 0
	v_pk_mul_f32 v[18:19], v[18:19], v[34:35]
	s_nop 0
	v_pk_mul_f32 v[18:19], v[26:27], v[18:19]
	v_mul_f32_e32 v26, 0xbfb8aa3b, v23
	v_exp_f32_e32 v26, v26
	v_mul_f32_e32 v27, 0xbfb8aa3b, v24
	v_exp_f32_e32 v27, v27
	v_cvt_pk_bf16_f32 v18, v18, v19
	v_add_f32_e32 v26, 1.0, v26
	v_rcp_f32_e32 v37, v26
	v_add_f32_e32 v27, 1.0, v27
	v_mul_f32_e32 v26, 0xbfb8aa3b, v20
	v_exp_f32_e32 v26, v26
	v_pk_mul_f32 v[22:23], v[22:23], v[36:37]
	v_add_f32_e32 v26, 1.0, v26
	v_pk_mul_f32 v[22:23], v[30:31], v[22:23]
	v_rcp_f32_e32 v30, v27
	v_mul_f32_e32 v27, 0xbfb8aa3b, v21
	v_exp_f32_e32 v27, v27
	v_rcp_f32_e32 v26, v26
	v_add_f32_e32 v27, 1.0, v27
	v_rcp_f32_e32 v27, v27
	s_nop 0
	v_pk_mul_f32 v[20:21], v[20:21], v[26:27]
	v_mul_f32_e32 v26, 0xbfb8aa3b, v25
	v_exp_f32_e32 v26, v26
	v_pk_mul_f32 v[20:21], v[28:29], v[20:21]
	v_add_f32_e32 v26, 1.0, v26
	v_rcp_f32_e32 v31, v26
	v_cvt_pk_bf16_f32 v19, v20, v21
	v_cvt_pk_bf16_f32 v20, v22, v23
	v_mad_i64_i32 v[22:23], s[0:1], v180, s35, v[130:131]
	v_pk_mul_f32 v[24:25], v[24:25], v[30:31]
	s_nop 0
	v_pk_mul_f32 v[24:25], v[32:33], v[24:25]
	s_nop 0
	v_cvt_pk_bf16_f32 v21, v24, v25
	global_store_dwordx4 v[22:23], v[18:21], off
	s_nop 1
	v_mul_f32_e32 v19, 0xbfb8aa3b, v4
	v_exp_f32_e32 v19, v19
	v_mul_f32_e32 v18, 0xbfb8aa3b, v0
	v_exp_f32_e32 v18, v18
	v_add_f32_e32 v19, 1.0, v19
	v_rcp_f32_e32 v20, v19
	v_mul_f32_e32 v19, 0xbfb8aa3b, v1
	v_exp_f32_e32 v19, v19
	v_add_f32_e32 v18, 1.0, v18
	v_rcp_f32_e32 v18, v18
	v_add_f32_e32 v19, 1.0, v19
	v_rcp_f32_e32 v19, v19
	s_nop 0
	v_pk_mul_f32 v[0:1], v[0:1], v[18:19]
	s_nop 0
	v_pk_mul_f32 v[0:1], v[10:11], v[0:1]
	v_mul_f32_e32 v10, 0xbfb8aa3b, v5
	v_exp_f32_e32 v10, v10
	v_mul_f32_e32 v11, 0xbfb8aa3b, v6
	v_exp_f32_e32 v11, v11
	v_cvt_pk_bf16_f32 v0, v0, v1
	v_add_f32_e32 v10, 1.0, v10
	v_rcp_f32_e32 v21, v10
	v_add_f32_e32 v11, 1.0, v11
	v_mul_f32_e32 v10, 0xbfb8aa3b, v2
	v_exp_f32_e32 v10, v10
	v_pk_mul_f32 v[4:5], v[4:5], v[20:21]
	v_add_f32_e32 v10, 1.0, v10
	v_pk_mul_f32 v[4:5], v[14:15], v[4:5]
	v_rcp_f32_e32 v14, v11
	v_mul_f32_e32 v11, 0xbfb8aa3b, v3
	v_exp_f32_e32 v11, v11
	v_rcp_f32_e32 v10, v10
	v_add_f32_e32 v11, 1.0, v11
	v_rcp_f32_e32 v11, v11
	s_nop 0
	v_pk_mul_f32 v[2:3], v[2:3], v[10:11]
	v_mul_f32_e32 v10, 0xbfb8aa3b, v7
	v_exp_f32_e32 v10, v10
	v_pk_mul_f32 v[2:3], v[12:13], v[2:3]
	v_add_f32_e32 v10, 1.0, v10
	v_rcp_f32_e32 v15, v10
	v_cvt_pk_bf16_f32 v1, v2, v3
	v_cvt_pk_bf16_f32 v2, v4, v5
	v_mad_i64_i32 v[4:5], s[0:1], v178, s35, v[130:131]
	v_pk_mul_f32 v[6:7], v[6:7], v[14:15]
	s_nop 0
	v_pk_mul_f32 v[6:7], v[16:17], v[6:7]
	s_nop 0
	v_cvt_pk_bf16_f32 v3, v6, v7
	global_store_dwordx4 v[4:5], v[0:3], off
	s_cbranch_vccz .LBB0_1669
	s_waitcnt vmcnt(0)
	s_cmpk_gt_u32 s66, 0xff
	s_cbranch_scc1 .LBB0_1676
	s_barrier

; #define PG8_STAGE(bufoff, gbase, voff) do { _Pragma("unroll") for (int _i = 0; _i < 2; ++_i) \
;         __builtin_amdgcn_global_load_lds((const unsigned*)((const char*)(gbase) + (voff)[_i]), (LAS unsigned*)(lds + (bufoff) + ldsw + _i * 8192), 16, 0, 0); } while (0)
; #define PG8_LDA(dst, b, h) do { _Pragma("unroll") for (int m = 0; m < 4; ++m) _Pragma("unroll") for (int k = 0; k < 2; ++k) dst[m][k] = *(const LAS bf16x8*)(lds + PG8_SA(b, h) + aoff + m * 2048 + k * 1024); } while (0)
; #define PG8_LDB(dst, b, h) do { _Pragma("unroll") for (int n = 0; n < 2; ++n) _Pragma("unroll") for (int k = 0; k < 2; ++k) dst[n][k] = *(const LAS bf16x8*)(lds + PG8_SB(b, h) + boff + n * 2048 + k * 1024); } while (0)
; #define PG8_MMA(ai, bj, At, Bt) do { __builtin_amdgcn_s_setprio(1); _Pragma("unroll") for (int m = 0; m < 4; ++m) _Pragma("unroll") for (int n = 0; n < 2; ++n) _Pragma("unroll") for (int k = 0; k < 2; ++k) \
;         acc[ai][bj][m][n] = __builtin_amdgcn_mfma_f32_16x16x32_bf16(Bt[n][k], At[m][k], acc[ai][bj][m][n], 0, 0, 0); __builtin_amdgcn_s_setprio(0); } while (0)
; #define PG8_WAIT_L(n) asm volatile("s_waitcnt lgkmcnt(" #n ")" ::: "memory")
; #define PG8_BAR __builtin_amdgcn_s_barrier()
; #define PG8_SCHED __builtin_amdgcn_sched_barrier(0)
; template <class Epi>
; DEVI void gemm_phase(LAS unsigned char* lds, const Gemm g, const Epi& E) {
;     ...
;             const char* a1 = cA + (size_t)(t + 1) * kstep;
;             const char* a2 = last ? nA : cA + (size_t)(t + 2) * kstep; const char* b2 = last ? nB : cB + (size_t)(t + 2) * kstep;
;             const char* a3 = a2 + kstep; const char* b3 = b2 + kstep;
;             PG8_LDB(B0, 0, 0); PG8_SCHED; PG8_LDA(At, 0, 0); PG8_STAGE(PG8_SA(1, 1), a1 + hstepA, voffA);
;             PG8_WAIT_L(8); PG8_BAR; PG8_WAIT_L(0); PG8_MMA(0, 0, At, B0); PG8_BAR; PG8_SCHED;
;             PG8_LDB(B1, 0, 1); PG8_STAGE(PG8_SB(0, 0), b2, voffB);
;             PG8_BAR; PG8_WAIT_L(0); PG8_MMA(0, 1, At, B1); PG8_BAR;
;             PG8_LDA(At, 0, 1); PG8_STAGE(PG8_SA(0, 0), a2, voffA);
;             PG8_BAR; PG8_WAIT_L(0); PG8_MMA(1, 0, At, B0); PG8_BAR; PG8_SCHED;
.LBB0_1747:
	s_add_u32 s36, s16, 0x100
	s_addc_u32 s37, s17, 0
	s_add_i32 s19, 0, 0x10000
	v_add_u32_e32 v142, s19, v191
	ds_read_b128 v[130:133], v142
	ds_read_b128 v[134:137], v142 offset:1024
	ds_read_b128 v[138:141], v142 offset:2048
	ds_read_b128 v[142:145], v142 offset:3072
	s_cmp_eq_u32 s18, 40
	s_cselect_b32 s69, s9, s37
	s_cselect_b32 s68, s8, s36
	s_cselect_b32 s47, s11, s13
	s_cselect_b32 s46, s10, s1
	v_lshl_add_u64 v[162:163], s[16:17], 0, v[152:153]
	s_add_i32 m0, s81, 0xc000
	ds_read_b128 v[178:181], v196
	ds_read_b128 v[182:185], v196 offset:1024
	ds_read_b128 v[186:189], v196 offset:2048
	ds_read_b128 v[198:201], v196 offset:3072
	ds_read_b128 v[202:205], v196 offset:4096
	ds_read_b128 v[206:209], v196 offset:5120
	ds_read_b128 v[214:217], v196 offset:6144
	ds_read_b128 v[218:221], v196 offset:7168
	global_load_lds_dwordx4 v[162:163], off
	s_add_i32 m0, s81, 0xe000
	v_lshl_add_u64 v[162:163], s[16:17], 0, v[176:177]
	global_load_lds_dwordx4 v[162:163], off
	s_waitcnt lgkmcnt(8)
	s_barrier
	s_waitcnt lgkmcnt(0)
	v_mfma_f32_16x16x32_bf16 v[126:129], v[130:133], v[178:181], v[126:129]
	v_mfma_f32_16x16x32_bf16 v[122:125], v[138:141], v[178:181], v[122:125]
	v_mfma_f32_16x16x32_bf16 v[110:113], v[130:133], v[186:189], v[110:113]
	v_mfma_f32_16x16x32_bf16 v[106:109], v[138:141], v[186:189], v[106:109]
	v_mfma_f32_16x16x32_bf16 v[94:97], v[130:133], v[202:205], v[94:97]
	v_mfma_f32_16x16x32_bf16 v[90:93], v[138:141], v[202:205], v[90:93]
	v_mfma_f32_16x16x32_bf16 v[78:81], v[130:133], v[214:217], v[78:81]
	v_mfma_f32_16x16x32_bf16 v[74:77], v[138:141], v[214:217], v[74:77]
	v_mfma_f32_16x16x32_bf16 v[126:129], v[134:137], v[182:185], v[126:129]
	v_mfma_f32_16x16x32_bf16 v[122:125], v[142:145], v[182:185], v[122:125]
	v_mfma_f32_16x16x32_bf16 v[110:113], v[134:137], v[198:201], v[110:113]
	v_mfma_f32_16x16x32_bf16 v[106:109], v[142:145], v[198:201], v[106:109]
	v_mfma_f32_16x16x32_bf16 v[94:97], v[134:137], v[206:209], v[94:97]
	v_mfma_f32_16x16x32_bf16 v[90:93], v[142:145], v[206:209], v[90:93]
	v_mfma_f32_16x16x32_bf16 v[78:81], v[134:137], v[218:221], v[78:81]
	v_mfma_f32_16x16x32_bf16 v[74:77], v[142:145], v[218:221], v[74:77]
	s_barrier
	s_add_i32 s26, 0, 0x14000
	v_add_u32_e32 v162, s26, v191
	s_add_i32 s16, s19, s80
	ds_read_b128 v[222:225], v162
	ds_read_b128 v[226:229], v162 offset:1024
	ds_read_b128 v[230:233], v162 offset:2048
	ds_read_b128 v[234:237], v162 offset:3072
	v_lshl_add_u64 v[162:163], s[46:47], 0, v[8:9]
	s_mov_b32 m0, s16
	v_lshl_add_u64 v[164:165], s[46:47], 0, v[150:151]
	global_load_lds_dwordx4 v[162:163], off
	s_add_i32 m0, s16, 0x2000
	s_nop 0
	global_load_lds_dwordx4 v[164:165], off
	s_barrier
	s_waitcnt lgkmcnt(0)
	v_mfma_f32_16x16x32_bf16 v[118:121], v[222:225], v[178:181], v[118:121]
	v_mfma_f32_16x16x32_bf16 v[114:117], v[230:233], v[178:181], v[114:117]
	v_mfma_f32_16x16x32_bf16 v[102:105], v[222:225], v[186:189], v[102:105]
	v_mfma_f32_16x16x32_bf16 v[98:101], v[230:233], v[186:189], v[98:101]
	v_mfma_f32_16x16x32_bf16 v[86:89], v[222:225], v[202:205], v[86:89]
	v_mfma_f32_16x16x32_bf16 v[82:85], v[230:233], v[202:205], v[82:85]
	v_mfma_f32_16x16x32_bf16 v[70:73], v[222:225], v[214:217], v[70:73]
	v_mfma_f32_16x16x32_bf16 v[66:69], v[230:233], v[214:217], v[66:69]
	v_mfma_f32_16x16x32_bf16 v[118:121], v[226:229], v[182:185], v[118:121]
	v_mfma_f32_16x16x32_bf16 v[114:117], v[234:237], v[182:185], v[114:117]
	v_mfma_f32_16x16x32_bf16 v[102:105], v[226:229], v[198:201], v[102:105]
	v_mfma_f32_16x16x32_bf16 v[98:101], v[234:237], v[198:201], v[98:101]
	v_mfma_f32_16x16x32_bf16 v[86:89], v[226:229], v[206:209], v[86:89]
	v_mfma_f32_16x16x32_bf16 v[82:85], v[234:237], v[206:209], v[82:85]
	v_mfma_f32_16x16x32_bf16 v[70:73], v[226:229], v[218:221], v[70:73]
	v_mfma_f32_16x16x32_bf16 v[66:69], v[234:237], v[218:221], v[66:69]
	s_mov_b32 m0, s81
	v_lshl_add_u64 v[238:239], s[68:69], 0, v[146:147]
	s_barrier
	ds_read_b128 v[178:181], v196 offset:16384
	ds_read_b128 v[182:185], v196 offset:17408
	ds_read_b128 v[186:189], v196 offset:18432
	ds_read_b128 v[198:201], v196 offset:19456
	ds_read_b128 v[202:205], v196 offset:20480
	ds_read_b128 v[206:209], v196 offset:21504
	ds_read_b128 v[214:217], v196 offset:22528
	ds_read_b128 v[218:221], v196 offset:23552
	global_load_lds_dwordx4 v[238:239], off
	s_mov_b32 m0, s82
	v_lshl_add_u64 v[240:241], s[68:69], 0, v[148:149]
	global_load_lds_dwordx4 v[240:241], off
	s_barrier
	s_waitcnt lgkmcnt(0)
	v_mfma_f32_16x16x32_bf16 v[62:65], v[130:133], v[178:181], v[62:65]
	v_mfma_f32_16x16x32_bf16 v[58:61], v[138:141], v[178:181], v[58:61]
	v_mfma_f32_16x16x32_bf16 v[46:49], v[130:133], v[186:189], v[46:49]
	v_mfma_f32_16x16x32_bf16 v[42:45], v[138:141], v[186:189], v[42:45]
	v_mfma_f32_16x16x32_bf16 v[30:33], v[130:133], v[202:205], v[30:33]
	v_mfma_f32_16x16x32_bf16 v[26:29], v[138:141], v[202:205], v[26:29]
	v_mfma_f32_16x16x32_bf16 v[14:17], v[130:133], v[214:217], v[14:17]
	v_mfma_f32_16x16x32_bf16 v[10:13], v[138:141], v[214:217], v[10:13]
	v_mfma_f32_16x16x32_bf16 v[62:65], v[134:137], v[182:185], v[62:65]
	v_mfma_f32_16x16x32_bf16 v[58:61], v[142:145], v[182:185], v[58:61]
	v_mfma_f32_16x16x32_bf16 v[46:49], v[134:137], v[198:201], v[46:49]
	v_mfma_f32_16x16x32_bf16 v[42:45], v[142:145], v[198:201], v[42:45]
	v_mfma_f32_16x16x32_bf16 v[30:33], v[134:137], v[206:209], v[30:33]
	v_mfma_f32_16x16x32_bf16 v[26:29], v[142:145], v[206:209], v[26:29]
	v_mfma_f32_16x16x32_bf16 v[14:17], v[134:137], v[218:221], v[14:17]
	v_mfma_f32_16x16x32_bf16 v[10:13], v[142:145], v[218:221], v[10:13]
	s_barrier
; #define PG8_STAGE(bufoff, gbase, voff) do { _Pragma("unroll") for (int _i = 0; _i < 2; ++_i) \
;         __builtin_amdgcn_global_load_lds((const unsigned*)((const char*)(gbase) + (voff)[_i]), (LAS unsigned*)(lds + (bufoff) + ldsw + _i * 8192), 16, 0, 0); } while (0)
; #define PG8_LDA(dst, b, h) do { _Pragma("unroll") for (int m = 0; m < 4; ++m) _Pragma("unroll") for (int k = 0; k < 2; ++k) dst[m][k] = *(const LAS bf16x8*)(lds + PG8_SA(b, h) + aoff + m * 2048 + k * 1024); } while (0)
; #define PG8_LDB(dst, b, h) do { _Pragma("unroll") for (int n = 0; n < 2; ++n) _Pragma("unroll") for (int k = 0; k < 2; ++k) dst[n][k] = *(const LAS bf16x8*)(lds + PG8_SB(b, h) + boff + n * 2048 + k * 1024); } while (0)
; #define PG8_MMA(ai, bj, At, Bt) do { __builtin_amdgcn_s_setprio(1); _Pragma("unroll") for (int m = 0; m < 4; ++m) _Pragma("unroll") for (int n = 0; n < 2; ++n) _Pragma("unroll") for (int k = 0; k < 2; ++k) \
;         acc[ai][bj][m][n] = __builtin_amdgcn_mfma_f32_16x16x32_bf16(Bt[n][k], At[m][k], acc[ai][bj][m][n], 0, 0, 0); __builtin_amdgcn_s_setprio(0); } while (0)
; #define PG8_WAIT_V(n) asm volatile("s_waitcnt vmcnt(" #n ")" ::: "memory")
; #define PG8_WAIT_L(n) asm volatile("s_waitcnt lgkmcnt(" #n ")" ::: "memory")
; #define PG8_BAR __builtin_amdgcn_s_barrier()
; #define PG8_SCHED __builtin_amdgcn_sched_barrier(0)
; template <class Epi>
; DEVI void gemm_phase(LAS unsigned char* lds, const Gemm g, const Epi& E) {
;     ...
;             PG8_STAGE(PG8_SB(0, 1), b2 + hstepB, voffB);
;             PG8_WAIT_V(6); PG8_BAR; PG8_MMA(1, 1, At, B1); PG8_BAR;
;             PG8_LDB(B0, 1, 0); PG8_SCHED; PG8_LDA(At, 1, 0); PG8_STAGE(PG8_SA(0, 1), a2 + hstepA, voffA);
;             PG8_WAIT_L(8); PG8_BAR; PG8_WAIT_L(0); PG8_MMA(0, 0, At, B0); PG8_BAR; PG8_SCHED;
;             PG8_LDB(B1, 1, 1); PG8_STAGE(PG8_SB(1, 0), b3, voffB);
;             PG8_BAR; PG8_WAIT_L(0); PG8_MMA(0, 1, At, B1); PG8_BAR;
;             PG8_LDA(At, 1, 1); PG8_STAGE(PG8_SA(1, 0), a3, voffA);
	s_add_u32 s16, s46, 0xb0000
	s_addc_u32 s17, s47, 0
	s_add_i32 s19, s26, s80
	s_mov_b32 m0, s19
	v_lshl_add_u64 v[130:131], s[16:17], 0, v[8:9]
	global_load_lds_dwordx4 v[130:131], off
	s_add_i32 m0, s19, 0x2000
	v_lshl_add_u64 v[130:131], s[16:17], 0, v[150:151]
	global_load_lds_dwordx4 v[130:131], off
	s_waitcnt vmcnt(6)
	s_barrier
	v_mfma_f32_16x16x32_bf16 v[54:57], v[222:225], v[178:181], v[54:57]
	v_mfma_f32_16x16x32_bf16 v[50:53], v[230:233], v[178:181], v[50:53]
	v_mfma_f32_16x16x32_bf16 v[38:41], v[222:225], v[186:189], v[38:41]
	v_mfma_f32_16x16x32_bf16 v[34:37], v[230:233], v[186:189], v[34:37]
	v_mfma_f32_16x16x32_bf16 v[22:25], v[222:225], v[202:205], v[22:25]
	v_mfma_f32_16x16x32_bf16 v[18:21], v[230:233], v[202:205], v[18:21]
	v_mfma_f32_16x16x32_bf16 v[4:7], v[222:225], v[214:217], v[4:7]
	v_mfma_f32_16x16x32_bf16 v[0:3], v[230:233], v[214:217], v[0:3]
	v_mfma_f32_16x16x32_bf16 v[54:57], v[226:229], v[182:185], v[54:57]
	v_mfma_f32_16x16x32_bf16 v[50:53], v[234:237], v[182:185], v[50:53]
	v_mfma_f32_16x16x32_bf16 v[38:41], v[226:229], v[198:201], v[38:41]
	v_mfma_f32_16x16x32_bf16 v[34:37], v[234:237], v[198:201], v[34:37]
	v_mfma_f32_16x16x32_bf16 v[22:25], v[226:229], v[206:209], v[22:25]
	v_mfma_f32_16x16x32_bf16 v[18:21], v[234:237], v[206:209], v[18:21]
	v_mfma_f32_16x16x32_bf16 v[4:7], v[226:229], v[218:221], v[4:7]
	v_mfma_f32_16x16x32_bf16 v[0:3], v[234:237], v[218:221], v[0:3]
	s_add_i32 s19, 0, 0x18000
	v_add_u32_e32 v142, s19, v191
	s_barrier
	ds_read_b128 v[130:133], v142
	ds_read_b128 v[134:137], v142 offset:1024
	ds_read_b128 v[138:141], v142 offset:2048
	ds_read_b128 v[142:145], v142 offset:3072
	s_add_u32 s16, s68, 0xb0000
	s_addc_u32 s17, s69, 0
	s_mov_b32 m0, s83
	v_lshl_add_u64 v[222:223], s[16:17], 0, v[146:147]
	ds_read_b128 v[178:181], v196 offset:32768
	ds_read_b128 v[182:185], v196 offset:33792
	ds_read_b128 v[186:189], v196 offset:34816
	ds_read_b128 v[198:201], v196 offset:35840
	ds_read_b128 v[202:205], v196 offset:36864
	ds_read_b128 v[206:209], v196 offset:37888
	ds_read_b128 v[214:217], v196 offset:38912
	ds_read_b128 v[218:221], v196 offset:39936
	global_load_lds_dwordx4 v[222:223], off
	s_mov_b32 m0, s84
	v_lshl_add_u64 v[222:223], s[16:17], 0, v[148:149]
	global_load_lds_dwordx4 v[222:223], off
	s_waitcnt lgkmcnt(8)
	s_barrier
	s_waitcnt lgkmcnt(0)
	v_mfma_f32_16x16x32_bf16 v[126:129], v[130:133], v[178:181], v[126:129]
	v_mfma_f32_16x16x32_bf16 v[122:125], v[138:141], v[178:181], v[122:125]
	v_mfma_f32_16x16x32_bf16 v[110:113], v[130:133], v[186:189], v[110:113]
	v_mfma_f32_16x16x32_bf16 v[106:109], v[138:141], v[186:189], v[106:109]
	v_mfma_f32_16x16x32_bf16 v[94:97], v[130:133], v[202:205], v[94:97]
	v_mfma_f32_16x16x32_bf16 v[90:93], v[138:141], v[202:205], v[90:93]
	v_mfma_f32_16x16x32_bf16 v[78:81], v[130:133], v[214:217], v[78:81]
	v_mfma_f32_16x16x32_bf16 v[74:77], v[138:141], v[214:217], v[74:77]
	v_mfma_f32_16x16x32_bf16 v[126:129], v[134:137], v[182:185], v[126:129]
	v_mfma_f32_16x16x32_bf16 v[122:125], v[142:145], v[182:185], v[122:125]
	v_mfma_f32_16x16x32_bf16 v[110:113], v[134:137], v[198:201], v[110:113]
	v_mfma_f32_16x16x32_bf16 v[106:109], v[142:145], v[198:201], v[106:109]
	v_mfma_f32_16x16x32_bf16 v[94:97], v[134:137], v[206:209], v[94:97]
	v_mfma_f32_16x16x32_bf16 v[90:93], v[142:145], v[206:209], v[90:93]
	v_mfma_f32_16x16x32_bf16 v[78:81], v[134:137], v[218:221], v[78:81]
	v_mfma_f32_16x16x32_bf16 v[74:77], v[142:145], v[218:221], v[74:77]
	s_barrier
	s_add_i32 s26, 0, 0x1c000
	s_add_i32 s16, s19, s80
	v_add_u32_e32 v197, s26, v191
	v_lshl_add_u64 v[162:163], v[162:163], 0, s[70:71]
	s_mov_b32 m0, s16
	ds_read_b128 v[222:225], v197
	ds_read_b128 v[226:229], v197 offset:1024
	ds_read_b128 v[230:233], v197 offset:2048
	ds_read_b128 v[234:237], v197 offset:3072
	global_load_lds_dwordx4 v[162:163], off
	s_add_i32 m0, s16, 0x2000
	v_lshl_add_u64 v[162:163], v[164:165], 0, s[70:71]
	global_load_lds_dwordx4 v[162:163], off
	s_barrier
	s_waitcnt lgkmcnt(0)
	v_mfma_f32_16x16x32_bf16 v[118:121], v[222:225], v[178:181], v[118:121]
	v_mfma_f32_16x16x32_bf16 v[114:117], v[230:233], v[178:181], v[114:117]
	v_mfma_f32_16x16x32_bf16 v[102:105], v[222:225], v[186:189], v[102:105]
	v_mfma_f32_16x16x32_bf16 v[98:101], v[230:233], v[186:189], v[98:101]
	v_mfma_f32_16x16x32_bf16 v[86:89], v[222:225], v[202:205], v[86:89]
	v_mfma_f32_16x16x32_bf16 v[82:85], v[230:233], v[202:205], v[82:85]
	v_mfma_f32_16x16x32_bf16 v[70:73], v[222:225], v[214:217], v[70:73]
	v_mfma_f32_16x16x32_bf16 v[66:69], v[230:233], v[214:217], v[66:69]
	v_mfma_f32_16x16x32_bf16 v[118:121], v[226:229], v[182:185], v[118:121]
	v_mfma_f32_16x16x32_bf16 v[114:117], v[234:237], v[182:185], v[114:117]
	v_mfma_f32_16x16x32_bf16 v[102:105], v[226:229], v[198:201], v[102:105]
	v_mfma_f32_16x16x32_bf16 v[98:101], v[234:237], v[198:201], v[98:101]
	v_mfma_f32_16x16x32_bf16 v[86:89], v[226:229], v[206:209], v[86:89]
	v_mfma_f32_16x16x32_bf16 v[82:85], v[234:237], v[206:209], v[82:85]
	v_mfma_f32_16x16x32_bf16 v[70:73], v[226:229], v[218:221], v[70:73]
	v_mfma_f32_16x16x32_bf16 v[66:69], v[234:237], v[218:221], v[66:69]
	s_mov_b32 m0, s76
	v_lshl_add_u64 v[162:163], v[238:239], 0, s[70:71]
	s_barrier
	ds_read_b128 v[178:181], v196 offset:49152
	ds_read_b128 v[182:185], v196 offset:50176
	ds_read_b128 v[186:189], v196 offset:51200
	ds_read_b128 v[198:201], v196 offset:52224
	ds_read_b128 v[202:205], v196 offset:53248
	ds_read_b128 v[206:209], v196 offset:54272
	ds_read_b128 v[214:217], v196 offset:55296
	ds_read_b128 v[218:221], v196 offset:56320
	global_load_lds_dwordx4 v[162:163], off
	s_mov_b32 m0, s77
	v_lshl_add_u64 v[162:163], v[240:241], 0, s[70:71]
	global_load_lds_dwordx4 v[162:163], off
	s_barrier
; #define PG8_STAGE(bufoff, gbase, voff) do { _Pragma("unroll") for (int _i = 0; _i < 2; ++_i) \
;         __builtin_amdgcn_global_load_lds((const unsigned*)((const char*)(gbase) + (voff)[_i]), (LAS unsigned*)(lds + (bufoff) + ldsw + _i * 8192), 16, 0, 0); } while (0)
; #define PG8_MMA(ai, bj, At, Bt) do { __builtin_amdgcn_s_setprio(1); _Pragma("unroll") for (int m = 0; m < 4; ++m) _Pragma("unroll") for (int n = 0; n < 2; ++n) _Pragma("unroll") for (int k = 0; k < 2; ++k) \
;         acc[ai][bj][m][n] = __builtin_amdgcn_mfma_f32_16x16x32_bf16(Bt[n][k], At[m][k], acc[ai][bj][m][n], 0, 0, 0); __builtin_amdgcn_s_setprio(0); } while (0)
; #define PG8_WAIT_V(n) asm volatile("s_waitcnt vmcnt(" #n ")" ::: "memory")
; #define PG8_WAIT_L(n) asm volatile("s_waitcnt lgkmcnt(" #n ")" ::: "memory")
; #define PG8_BAR __builtin_amdgcn_s_barrier()
; #define PG8_SCHED __builtin_amdgcn_sched_barrier(0)
; template <class Epi>
; DEVI void gemm_phase(LAS unsigned char* lds, const Gemm g, const Epi& E) {
;     ...
;             PG8_BAR; PG8_WAIT_L(0); PG8_MMA(1, 0, At, B0); PG8_BAR; PG8_SCHED;
;             PG8_STAGE(PG8_SB(1, 1), b3 + hstepB, voffB);
;             PG8_WAIT_V(6); PG8_BAR; PG8_MMA(1, 1, At, B1); PG8_BAR;
;         }
	s_waitcnt lgkmcnt(0)
	v_mfma_f32_16x16x32_bf16 v[62:65], v[130:133], v[178:181], v[62:65]
	v_mfma_f32_16x16x32_bf16 v[58:61], v[138:141], v[178:181], v[58:61]
	v_mfma_f32_16x16x32_bf16 v[46:49], v[130:133], v[186:189], v[46:49]
	v_mfma_f32_16x16x32_bf16 v[42:45], v[138:141], v[186:189], v[42:45]
	v_mfma_f32_16x16x32_bf16 v[30:33], v[130:133], v[202:205], v[30:33]
	v_mfma_f32_16x16x32_bf16 v[26:29], v[138:141], v[202:205], v[26:29]
	v_mfma_f32_16x16x32_bf16 v[14:17], v[130:133], v[214:217], v[14:17]
	v_mfma_f32_16x16x32_bf16 v[10:13], v[138:141], v[214:217], v[10:13]
	v_mfma_f32_16x16x32_bf16 v[62:65], v[134:137], v[182:185], v[62:65]
	v_mfma_f32_16x16x32_bf16 v[58:61], v[142:145], v[182:185], v[58:61]
	v_mfma_f32_16x16x32_bf16 v[46:49], v[134:137], v[198:201], v[46:49]
	v_mfma_f32_16x16x32_bf16 v[42:45], v[142:145], v[198:201], v[42:45]
	v_mfma_f32_16x16x32_bf16 v[30:33], v[134:137], v[206:209], v[30:33]
	v_mfma_f32_16x16x32_bf16 v[26:29], v[142:145], v[206:209], v[26:29]
	v_mfma_f32_16x16x32_bf16 v[14:17], v[134:137], v[218:221], v[14:17]
	v_mfma_f32_16x16x32_bf16 v[10:13], v[142:145], v[218:221], v[10:13]
	s_barrier
	s_add_u32 s16, s46, 0xb0080
	s_addc_u32 s17, s47, 0
	s_add_i32 s19, s26, s80
	s_mov_b32 m0, s19
	v_lshl_add_u64 v[130:131], s[16:17], 0, v[8:9]
	global_load_lds_dwordx4 v[130:131], off
	s_add_i32 m0, s19, 0x2000
	v_lshl_add_u64 v[130:131], s[16:17], 0, v[150:151]
	global_load_lds_dwordx4 v[130:131], off
	s_waitcnt vmcnt(6)
	s_barrier
	v_mfma_f32_16x16x32_bf16 v[54:57], v[222:225], v[178:181], v[54:57]
	v_mfma_f32_16x16x32_bf16 v[50:53], v[230:233], v[178:181], v[50:53]
	v_mfma_f32_16x16x32_bf16 v[38:41], v[222:225], v[186:189], v[38:41]
	v_mfma_f32_16x16x32_bf16 v[34:37], v[230:233], v[186:189], v[34:37]
	v_mfma_f32_16x16x32_bf16 v[22:25], v[222:225], v[202:205], v[22:25]
	v_mfma_f32_16x16x32_bf16 v[18:21], v[230:233], v[202:205], v[18:21]
	v_mfma_f32_16x16x32_bf16 v[4:7], v[222:225], v[214:217], v[4:7]
	v_mfma_f32_16x16x32_bf16 v[0:3], v[230:233], v[214:217], v[0:3]
	v_mfma_f32_16x16x32_bf16 v[54:57], v[226:229], v[182:185], v[54:57]
	v_mfma_f32_16x16x32_bf16 v[50:53], v[234:237], v[182:185], v[50:53]
	v_mfma_f32_16x16x32_bf16 v[38:41], v[226:229], v[198:201], v[38:41]
	v_mfma_f32_16x16x32_bf16 v[34:37], v[234:237], v[198:201], v[34:37]
	v_mfma_f32_16x16x32_bf16 v[22:25], v[226:229], v[206:209], v[22:25]
	v_mfma_f32_16x16x32_bf16 v[18:21], v[234:237], v[206:209], v[18:21]
	v_mfma_f32_16x16x32_bf16 v[4:7], v[226:229], v[218:221], v[4:7]
	v_mfma_f32_16x16x32_bf16 v[0:3], v[234:237], v[218:221], v[0:3]
	s_add_i32 s18, s18, 2
	s_add_u32 s1, s1, 0x100
	s_addc_u32 s13, s13, 0
	s_cmp_gt_u32 s18, 41
	s_mov_b64 s[16:17], s[36:37]
	s_barrier
	s_cbranch_scc0 .LBB0_1747
	s_setprio 0
	s_lshl_b32 s0, s0, 8
	v_add_u32_e32 v182, s0, v190
	v_lshl_or_b32 v180, s12, 8, v195
	v_ashrrev_i32_e32 v183, 31, v182
	v_lshlrev_b64 v[130:131], 12, v[182:183]
	v_ashrrev_i32_e32 v181, 31, v180
	v_lshl_add_u64 v[130:131], s[30:31], 0, v[130:131]
	v_lshlrev_b64 v[184:185], 2, v[180:181]
	v_lshl_add_u64 v[162:163], v[130:131], 0, v[184:185]
	global_load_dwordx4 v[200:203], v[162:163], off
	global_load_dwordx4 v[204:207], v[162:163], off offset:16
	global_load_dwordx4 v[214:217], v[162:163], off offset:512
	global_load_dwordx4 v[218:221], v[162:163], off offset:528
	v_or_b32_e32 v188, 16, v182
	v_ashrrev_i32_e32 v189, 31, v188
	v_lshlrev_b64 v[130:131], 12, v[188:189]
	v_lshl_add_u64 v[130:131], s[30:31], 0, v[130:131]
	v_lshl_add_u64 v[186:187], v[130:131], 0, v[184:185]
	global_load_dwordx4 v[138:141], v[186:187], off offset:16
	global_load_dwordx4 v[142:145], v[186:187], off
	global_load_dwordx4 v[130:133], v[186:187], off offset:528
	global_load_dwordx4 v[134:137], v[186:187], off offset:512
	v_and_b32_e32 v165, 64, v155
	v_xor_b32_e32 v164, 16, v155
	v_add_u32_e32 v165, 64, v165
	v_xor_b32_e32 v179, 32, v155
	v_cmp_lt_i32_e32 vcc, v164, v165
	v_or_b32_e32 v178, 0x80, v180
	s_waitcnt vmcnt(0)
	v_pk_add_f32 v[128:129], v[128:129], v[202:203]
	v_cndmask_b32_e32 v164, v155, v164, vcc
	v_cmp_lt_i32_e32 vcc, v179, v165
	v_lshlrev_b32_e32 v198, 2, v164
	v_pk_add_f32 v[126:127], v[126:127], v[200:201]
	v_cndmask_b32_e32 v165, v155, v179, vcc
	v_lshlrev_b32_e32 v197, 2, v165
	v_lshlrev_b64 v[164:165], 10, v[182:183]
	v_pk_add_f32 v[124:125], v[124:125], v[206:207]
	v_pk_add_f32 v[122:123], v[122:123], v[204:205]
	v_pk_add_f32 v[120:121], v[120:121], v[216:217]
	v_pk_add_f32 v[118:119], v[118:119], v[214:215]
	v_pk_add_f32 v[202:203], v[116:117], v[220:221]
	v_pk_add_f32 v[200:201], v[114:115], v[218:219]
	v_lshl_add_u64 v[208:209], v[164:165], 0, v[180:181]
	global_store_dwordx4 v[162:163], v[126:129], off
	global_store_dwordx4 v[162:163], v[122:125], off offset:16
	v_cvt_pk_bf16_f32 v114, v126, v127
	v_cvt_pk_bf16_f32 v115, v128, v129
	v_cvt_pk_bf16_f32 v116, v122, v123
	v_cvt_pk_bf16_f32 v117, v124, v125
	v_mul_f32_e32 v127, v127, v127
	v_mul_f32_e32 v129, v129, v129
	v_mul_f32_e32 v123, v123, v123
	v_mul_f32_e32 v125, v125, v125
	v_mul_f32_e32 v183, v119, v119
	v_mul_f32_e32 v199, v121, v121
	v_mul_f32_e32 v204, v201, v201
	v_mul_f32_e32 v205, v203, v203
	v_lshl_add_u64 v[208:209], v[208:209], 1, s[24:25]
	v_fmac_f32_e32 v127, v126, v126
	v_fmac_f32_e32 v129, v128, v128
	v_fmac_f32_e32 v123, v122, v122
	v_fmac_f32_e32 v125, v124, v124
	v_fmac_f32_e32 v183, v118, v118
	v_fmac_f32_e32 v199, v120, v120
	v_fmac_f32_e32 v204, v200, v200
	v_fmac_f32_e32 v205, v202, v202
	global_store_dwordx4 v[208:209], v[114:117], off
	v_ashrrev_i32_e32 v179, 31, v178
	v_lshl_add_u64 v[164:165], v[164:165], 0, v[178:179]
	v_add_f32_e32 v114, v127, v129
	v_add_f32_e32 v115, v123, v125
	v_add_f32_e32 v116, v183, v199
	v_add_f32_e32 v117, v204, v205
	v_add_f32_e32 v114, v114, v115
	v_add_f32_e32 v115, v116, v117
	v_add_f32_e32 v114, v114, v115
	ds_bpermute_b32 v115, v198, v114
	global_store_dwordx4 v[162:163], v[118:121], off offset:512
	global_store_dwordx4 v[162:163], v[200:203], off offset:528
	v_cvt_pk_bf16_f32 v116, v118, v119
	v_cvt_pk_bf16_f32 v117, v120, v121
	v_cvt_pk_bf16_f32 v118, v200, v201
	s_waitcnt lgkmcnt(0)
	v_add_f32_e32 v114, v114, v115
	ds_bpermute_b32 v115, v197, v114
	v_cvt_pk_bf16_f32 v119, v202, v203
	v_lshl_add_u64 v[120:121], v[164:165], 1, s[24:25]
	global_store_dwordx4 v[120:121], v[116:119], off
	s_and_saveexec_b64 s[16:17], s[2:3]
	s_cbranch_execz .LBB0_1750
	s_waitcnt lgkmcnt(0)
	v_add_f32_e32 v114, v114, v115
	ds_write_b32 v192, v114
